# removed s_setprio in GEMM K-loops; moved LDS-DMA issue of 12-read phases to following phase; counted waits; attention LDS swizzle
# speedup vs baseline: 1.0163x; 1.0119x over previous
.LBB0_377:
	s_add_u32 s75, s46, 0xfff80080
	s_addc_u32 s80, s47, -1
	s_add_i32 s96, 0, 0x10000
	v_add_u32_e32 v76, s96, v239
	ds_read_b128 v[64:67], v76
	ds_read_b128 v[68:71], v76 offset:1024
	ds_read_b128 v[72:75], v76 offset:2048
	ds_read_b128 v[76:79], v76 offset:3072
	s_cmp_eq_u32 s73, 28
	s_cselect_b32 s83, s14, s80
	s_cselect_b32 s82, s15, s75
	s_cselect_b32 s81, s67, s13
	s_cselect_b32 s80, s68, s12
	ds_read_b128 v[80:83], v248
	ds_read_b128 v[84:87], v248 offset:1024
	ds_read_b128 v[88:91], v248 offset:2048
	ds_read_b128 v[92:95], v248 offset:3072
	ds_read_b128 v[184:187], v248 offset:4096
	ds_read_b128 v[188:191], v248 offset:5120
	ds_read_b128 v[192:195], v248 offset:6144
	ds_read_b128 v[196:199], v248 offset:7168
	s_waitcnt lgkmcnt(8)
	s_barrier
	s_waitcnt lgkmcnt(0)
	s_waitcnt lgkmcnt(0)
	v_mfma_f32_16x16x32_bf16 v[156:159], v[64:67], v[80:83], v[156:159]
	v_mfma_f32_16x16x32_bf16 v[152:155], v[72:75], v[80:83], v[152:155]
	v_mfma_f32_16x16x32_bf16 v[148:151], v[64:67], v[88:91], v[148:151]
	v_mfma_f32_16x16x32_bf16 v[140:143], v[72:75], v[88:91], v[140:143]
	v_mfma_f32_16x16x32_bf16 v[132:135], v[64:67], v[184:187], v[132:135]
	v_mfma_f32_16x16x32_bf16 v[124:127], v[72:75], v[184:187], v[124:127]
	v_mfma_f32_16x16x32_bf16 v[116:119], v[64:67], v[192:195], v[116:119]
	v_mfma_f32_16x16x32_bf16 v[108:111], v[72:75], v[192:195], v[108:111]
	v_mfma_f32_16x16x32_bf16 v[156:159], v[68:71], v[84:87], v[156:159]
	v_mfma_f32_16x16x32_bf16 v[152:155], v[76:79], v[84:87], v[152:155]
	v_mfma_f32_16x16x32_bf16 v[148:151], v[68:71], v[92:95], v[148:151]
	v_mfma_f32_16x16x32_bf16 v[140:143], v[76:79], v[92:95], v[140:143]
	v_mfma_f32_16x16x32_bf16 v[132:135], v[68:71], v[188:191], v[132:135]
	v_mfma_f32_16x16x32_bf16 v[124:127], v[76:79], v[188:191], v[124:127]
	v_mfma_f32_16x16x32_bf16 v[116:119], v[68:71], v[196:199], v[116:119]
	v_mfma_f32_16x16x32_bf16 v[108:111], v[76:79], v[196:199], v[108:111]
	s_barrier
	v_lshl_add_u64 v[200:201], s[46:47], 0, v[180:181]
	s_add_i32 m0, s20, 0xc000
	s_nop 0
	global_load_lds_dwordx4 v[200:201], off
	v_lshl_add_u64 v[200:201], s[46:47], 0, v[182:183]
	s_add_i32 m0, s20, 0xe000
	s_nop 0
	global_load_lds_dwordx4 v[200:201], off
	s_add_i32 s75, 0, 0x14000
	s_add_i32 s96, s96, s19
	v_add_u32_e32 v160, s75, v239
	v_lshl_add_u64 v[224:225], s[80:81], 0, v[174:175]
	s_mov_b32 m0, s96
	ds_read_b128 v[200:203], v160
	ds_read_b128 v[204:207], v160 offset:1024
	ds_read_b128 v[208:211], v160 offset:2048
	ds_read_b128 v[212:215], v160 offset:3072
	global_load_lds_dwordx4 v[224:225], off
	v_lshl_add_u64 v[226:227], s[80:81], 0, v[170:171]
	s_add_i32 m0, s96, 0x2000
	s_nop 0
	global_load_lds_dwordx4 v[226:227], off
	s_barrier
	s_waitcnt lgkmcnt(0)
	s_waitcnt lgkmcnt(0)
	v_mfma_f32_16x16x32_bf16 v[144:147], v[200:203], v[80:83], v[144:147]
	v_mfma_f32_16x16x32_bf16 v[80:83], v[208:211], v[80:83], v[136:139]
	v_mfma_f32_16x16x32_bf16 v[144:147], v[204:207], v[84:87], v[144:147]
	v_mfma_f32_16x16x32_bf16 v[80:83], v[212:215], v[84:87], v[80:83]
	v_mfma_f32_16x16x32_bf16 v[84:87], v[200:203], v[88:91], v[128:131]
	v_mfma_f32_16x16x32_bf16 v[88:91], v[208:211], v[88:91], v[120:123]
	v_mfma_f32_16x16x32_bf16 v[104:107], v[208:211], v[184:187], v[104:107]
	v_mfma_f32_16x16x32_bf16 v[100:103], v[200:203], v[192:195], v[100:103]
	v_mfma_f32_16x16x32_bf16 v[96:99], v[208:211], v[192:195], v[96:99]
	v_mfma_f32_16x16x32_bf16 v[84:87], v[204:207], v[92:95], v[84:87]
	v_mfma_f32_16x16x32_bf16 v[88:91], v[212:215], v[92:95], v[88:91]
	v_mfma_f32_16x16x32_bf16 v[92:95], v[200:203], v[184:187], v[112:115]
	v_mfma_f32_16x16x32_bf16 v[104:107], v[212:215], v[188:191], v[104:107]
	v_mfma_f32_16x16x32_bf16 v[100:103], v[204:207], v[196:199], v[100:103]
	v_mfma_f32_16x16x32_bf16 v[96:99], v[212:215], v[196:199], v[96:99]
	v_mfma_f32_16x16x32_bf16 v[92:95], v[204:207], v[188:191], v[92:95]
	s_mov_b32 m0, s20
	v_lshl_add_u64 v[228:229], s[82:83], 0, v[176:177]
	s_barrier
	ds_read_b128 v[112:115], v248 offset:16384
	ds_read_b128 v[120:123], v248 offset:17408
	ds_read_b128 v[128:131], v248 offset:18432
	ds_read_b128 v[136:139], v248 offset:19456
	ds_read_b128 v[184:187], v248 offset:20480
	ds_read_b128 v[188:191], v248 offset:21504
	ds_read_b128 v[192:195], v248 offset:22528
	ds_read_b128 v[196:199], v248 offset:23552
	global_load_lds_dwordx4 v[228:229], off
	v_lshl_add_u64 v[230:231], s[82:83], 0, v[172:173]
	s_mov_b32 m0, s21
	s_nop 0
	global_load_lds_dwordx4 v[230:231], off
	s_barrier
	s_waitcnt lgkmcnt(0)
	s_waitcnt lgkmcnt(0)
	v_mfma_f32_16x16x32_bf16 v[60:63], v[64:67], v[112:115], v[60:63]
	v_mfma_f32_16x16x32_bf16 v[56:59], v[72:75], v[112:115], v[56:59]
	v_mfma_f32_16x16x32_bf16 v[44:47], v[64:67], v[128:131], v[44:47]
	v_mfma_f32_16x16x32_bf16 v[40:43], v[72:75], v[128:131], v[40:43]
	v_mfma_f32_16x16x32_bf16 v[28:31], v[64:67], v[184:187], v[28:31]
	v_mfma_f32_16x16x32_bf16 v[24:27], v[72:75], v[184:187], v[24:27]
	v_mfma_f32_16x16x32_bf16 v[12:15], v[64:67], v[192:195], v[12:15]
	v_mfma_f32_16x16x32_bf16 v[8:11], v[72:75], v[192:195], v[8:11]
	v_mfma_f32_16x16x32_bf16 v[60:63], v[68:71], v[120:123], v[60:63]
	v_mfma_f32_16x16x32_bf16 v[56:59], v[76:79], v[120:123], v[56:59]
	v_mfma_f32_16x16x32_bf16 v[44:47], v[68:71], v[136:139], v[44:47]
	v_mfma_f32_16x16x32_bf16 v[40:43], v[76:79], v[136:139], v[40:43]
	v_mfma_f32_16x16x32_bf16 v[28:31], v[68:71], v[188:191], v[28:31]
	v_mfma_f32_16x16x32_bf16 v[24:27], v[76:79], v[188:191], v[24:27]
	v_mfma_f32_16x16x32_bf16 v[12:15], v[68:71], v[196:199], v[12:15]
	v_mfma_f32_16x16x32_bf16 v[8:11], v[76:79], v[196:199], v[8:11]
	s_barrier
	s_add_u32 s96, s80, 0x80000
	s_addc_u32 s97, s81, 0
	s_add_i32 s75, s75, s19
	v_lshl_add_u64 v[64:65], s[96:97], 0, v[174:175]
	s_mov_b32 m0, s75
	s_nop 0
	global_load_lds_dwordx4 v[64:65], off
	v_lshl_add_u64 v[64:65], s[96:97], 0, v[170:171]
	s_add_i32 m0, s75, 0x2000
	s_nop 0
	global_load_lds_dwordx4 v[64:65], off
	s_waitcnt vmcnt(6)
	s_barrier
	v_mfma_f32_16x16x32_bf16 v[52:55], v[200:203], v[112:115], v[52:55]
	v_mfma_f32_16x16x32_bf16 v[48:51], v[208:211], v[112:115], v[48:51]
	v_mfma_f32_16x16x32_bf16 v[36:39], v[200:203], v[128:131], v[36:39]
	v_mfma_f32_16x16x32_bf16 v[32:35], v[208:211], v[128:131], v[32:35]
	v_mfma_f32_16x16x32_bf16 v[20:23], v[200:203], v[184:187], v[20:23]
	v_mfma_f32_16x16x32_bf16 v[16:19], v[208:211], v[184:187], v[16:19]
	v_mfma_f32_16x16x32_bf16 v[4:7], v[200:203], v[192:195], v[4:7]
	v_mfma_f32_16x16x32_bf16 v[0:3], v[208:211], v[192:195], v[0:3]
	v_mfma_f32_16x16x32_bf16 v[52:55], v[204:207], v[120:123], v[52:55]
	v_mfma_f32_16x16x32_bf16 v[48:51], v[212:215], v[120:123], v[48:51]
	v_mfma_f32_16x16x32_bf16 v[36:39], v[204:207], v[136:139], v[36:39]
	v_mfma_f32_16x16x32_bf16 v[32:35], v[212:215], v[136:139], v[32:35]
	v_mfma_f32_16x16x32_bf16 v[20:23], v[204:207], v[188:191], v[20:23]
	v_mfma_f32_16x16x32_bf16 v[16:19], v[212:215], v[188:191], v[16:19]
	v_mfma_f32_16x16x32_bf16 v[4:7], v[204:207], v[196:199], v[4:7]
	v_mfma_f32_16x16x32_bf16 v[0:3], v[212:215], v[196:199], v[0:3]
	s_add_i32 s75, 0, 0x18000
	v_add_u32_e32 v76, s75, v239
	s_barrier
	ds_read_b128 v[64:67], v76
	ds_read_b128 v[68:71], v76 offset:1024
	ds_read_b128 v[72:75], v76 offset:2048
	ds_read_b128 v[76:79], v76 offset:3072
	ds_read_b128 v[112:115], v248 offset:32768
	ds_read_b128 v[120:123], v248 offset:33792
	ds_read_b128 v[184:187], v248 offset:34816
	ds_read_b128 v[188:191], v248 offset:35840
	ds_read_b128 v[192:195], v248 offset:36864
	ds_read_b128 v[196:199], v248 offset:37888
	ds_read_b128 v[200:203], v248 offset:38912
	ds_read_b128 v[204:207], v248 offset:39936
	s_waitcnt lgkmcnt(8)
	s_barrier
	s_waitcnt lgkmcnt(0)
	s_waitcnt lgkmcnt(0)
	v_mfma_f32_16x16x32_bf16 v[128:131], v[64:67], v[112:115], v[156:159]
	v_mfma_f32_16x16x32_bf16 v[156:159], v[68:71], v[120:123], v[128:131]
	v_mfma_f32_16x16x32_bf16 v[128:131], v[72:75], v[112:115], v[152:155]
	v_mfma_f32_16x16x32_bf16 v[152:155], v[76:79], v[120:123], v[128:131]
	v_mfma_f32_16x16x32_bf16 v[128:131], v[64:67], v[184:187], v[148:151]
	v_mfma_f32_16x16x32_bf16 v[148:151], v[68:71], v[188:191], v[128:131]
	v_mfma_f32_16x16x32_bf16 v[128:131], v[72:75], v[184:187], v[140:143]
	v_mfma_f32_16x16x32_bf16 v[140:143], v[76:79], v[188:191], v[128:131]
	v_mfma_f32_16x16x32_bf16 v[128:131], v[64:67], v[192:195], v[132:135]
	v_mfma_f32_16x16x32_bf16 v[124:127], v[72:75], v[192:195], v[124:127]
	v_mfma_f32_16x16x32_bf16 v[116:119], v[64:67], v[200:203], v[116:119]
	v_mfma_f32_16x16x32_bf16 v[108:111], v[72:75], v[200:203], v[108:111]
	v_mfma_f32_16x16x32_bf16 v[132:135], v[68:71], v[196:199], v[128:131]
	v_mfma_f32_16x16x32_bf16 v[124:127], v[76:79], v[196:199], v[124:127]
	v_mfma_f32_16x16x32_bf16 v[116:119], v[68:71], v[204:207], v[116:119]
	v_mfma_f32_16x16x32_bf16 v[108:111], v[76:79], v[204:207], v[108:111]
	s_barrier
	s_add_u32 s82, s82, 0x80000
	s_addc_u32 s83, s83, 0
	v_lshl_add_u64 v[128:129], s[82:83], 0, v[176:177]
	s_mov_b32 m0, s22
	s_nop 0
	global_load_lds_dwordx4 v[128:129], off
	v_lshl_add_u64 v[128:129], s[82:83], 0, v[172:173]
	s_mov_b32 m0, s23
	s_nop 0
	global_load_lds_dwordx4 v[128:129], off
	s_add_i32 s82, 0, 0x1c000
	v_add_u32_e32 v128, s82, v239
	s_add_i32 s75, s75, s19
	ds_read_b128 v[208:211], v128
	ds_read_b128 v[212:215], v128 offset:1024
	ds_read_b128 v[216:219], v128 offset:2048
	ds_read_b128 v[220:223], v128 offset:3072
	v_lshl_add_u64 v[128:129], v[224:225], 0, s[92:93]
	s_mov_b32 m0, s75
	s_nop 0
	global_load_lds_dwordx4 v[128:129], off
	v_lshl_add_u64 v[128:129], v[226:227], 0, s[92:93]
	s_add_i32 m0, s75, 0x2000
	s_nop 0
	global_load_lds_dwordx4 v[128:129], off
	s_barrier
	s_waitcnt lgkmcnt(0)
	s_waitcnt lgkmcnt(0)
	v_mfma_f32_16x16x32_bf16 v[80:83], v[216:219], v[112:115], v[80:83]
	v_mfma_f32_16x16x32_bf16 v[128:131], v[208:211], v[112:115], v[144:147]
	v_mfma_f32_16x16x32_bf16 v[136:139], v[220:223], v[120:123], v[80:83]
	v_mfma_f32_16x16x32_bf16 v[80:83], v[208:211], v[184:187], v[84:87]
	v_mfma_f32_16x16x32_bf16 v[144:147], v[212:215], v[120:123], v[128:131]
	v_mfma_f32_16x16x32_bf16 v[128:131], v[212:215], v[188:191], v[80:83]
	v_mfma_f32_16x16x32_bf16 v[80:83], v[216:219], v[184:187], v[88:91]
	v_mfma_f32_16x16x32_bf16 v[120:123], v[220:223], v[188:191], v[80:83]
	v_mfma_f32_16x16x32_bf16 v[80:83], v[208:211], v[192:195], v[92:95]
	v_mfma_f32_16x16x32_bf16 v[112:115], v[212:215], v[196:199], v[80:83]
	v_mfma_f32_16x16x32_bf16 v[80:83], v[216:219], v[192:195], v[104:107]
	v_mfma_f32_16x16x32_bf16 v[104:107], v[220:223], v[196:199], v[80:83]
	v_mfma_f32_16x16x32_bf16 v[80:83], v[208:211], v[200:203], v[100:103]
	v_mfma_f32_16x16x32_bf16 v[100:103], v[212:215], v[204:207], v[80:83]
	v_mfma_f32_16x16x32_bf16 v[80:83], v[216:219], v[200:203], v[96:99]
	v_mfma_f32_16x16x32_bf16 v[96:99], v[220:223], v[204:207], v[80:83]
	s_mov_b32 m0, s25
	v_lshl_add_u64 v[200:201], v[228:229], 0, s[92:93]
	s_barrier
	s_nop 2
	ds_read_b128 v[80:83], v248 offset:49152
	ds_read_b128 v[84:87], v248 offset:50176
	ds_read_b128 v[88:91], v248 offset:51200
	ds_read_b128 v[92:95], v248 offset:52224
	ds_read_b128 v[184:187], v248 offset:53248
	ds_read_b128 v[188:191], v248 offset:54272
	ds_read_b128 v[192:195], v248 offset:55296
	ds_read_b128 v[196:199], v248 offset:56320
	global_load_lds_dwordx4 v[200:201], off
	v_lshl_add_u64 v[200:201], v[230:231], 0, s[92:93]
	s_mov_b32 m0, s26
	s_nop 0
	global_load_lds_dwordx4 v[200:201], off
	s_barrier
	s_waitcnt lgkmcnt(0)
	s_waitcnt lgkmcnt(0)
	v_mfma_f32_16x16x32_bf16 v[60:63], v[64:67], v[80:83], v[60:63]
	v_mfma_f32_16x16x32_bf16 v[56:59], v[72:75], v[80:83], v[56:59]
	v_mfma_f32_16x16x32_bf16 v[44:47], v[64:67], v[88:91], v[44:47]
	v_mfma_f32_16x16x32_bf16 v[40:43], v[72:75], v[88:91], v[40:43]
	v_mfma_f32_16x16x32_bf16 v[28:31], v[64:67], v[184:187], v[28:31]
	v_mfma_f32_16x16x32_bf16 v[24:27], v[72:75], v[184:187], v[24:27]
	v_mfma_f32_16x16x32_bf16 v[12:15], v[64:67], v[192:195], v[12:15]
	v_mfma_f32_16x16x32_bf16 v[8:11], v[72:75], v[192:195], v[8:11]
	v_mfma_f32_16x16x32_bf16 v[60:63], v[68:71], v[84:87], v[60:63]
	v_mfma_f32_16x16x32_bf16 v[56:59], v[76:79], v[84:87], v[56:59]
	v_mfma_f32_16x16x32_bf16 v[44:47], v[68:71], v[92:95], v[44:47]
	v_mfma_f32_16x16x32_bf16 v[40:43], v[76:79], v[92:95], v[40:43]
	v_mfma_f32_16x16x32_bf16 v[28:31], v[68:71], v[188:191], v[28:31]
	v_mfma_f32_16x16x32_bf16 v[24:27], v[76:79], v[188:191], v[24:27]
	v_mfma_f32_16x16x32_bf16 v[12:15], v[68:71], v[196:199], v[12:15]
	v_mfma_f32_16x16x32_bf16 v[8:11], v[76:79], v[196:199], v[8:11]
	s_barrier
	s_add_u32 s80, s80, 0x80080
	s_addc_u32 s81, s81, 0
	s_add_i32 s75, s82, s19
	v_lshl_add_u64 v[64:65], s[80:81], 0, v[174:175]
	s_mov_b32 m0, s75
	s_nop 0
	global_load_lds_dwordx4 v[64:65], off
	v_lshl_add_u64 v[64:65], s[80:81], 0, v[170:171]
	s_add_i32 m0, s75, 0x2000
	s_nop 0
	global_load_lds_dwordx4 v[64:65], off
	s_waitcnt vmcnt(6)
	s_barrier
	v_mfma_f32_16x16x32_bf16 v[52:55], v[208:211], v[80:83], v[52:55]
	v_mfma_f32_16x16x32_bf16 v[48:51], v[216:219], v[80:83], v[48:51]
	v_mfma_f32_16x16x32_bf16 v[36:39], v[208:211], v[88:91], v[36:39]
	v_mfma_f32_16x16x32_bf16 v[32:35], v[216:219], v[88:91], v[32:35]
	v_mfma_f32_16x16x32_bf16 v[20:23], v[208:211], v[184:187], v[20:23]
	v_mfma_f32_16x16x32_bf16 v[16:19], v[216:219], v[184:187], v[16:19]
	v_mfma_f32_16x16x32_bf16 v[4:7], v[208:211], v[192:195], v[4:7]
	v_mfma_f32_16x16x32_bf16 v[0:3], v[216:219], v[192:195], v[0:3]
	v_mfma_f32_16x16x32_bf16 v[52:55], v[212:215], v[84:87], v[52:55]
	v_mfma_f32_16x16x32_bf16 v[48:51], v[220:223], v[84:87], v[48:51]
	v_mfma_f32_16x16x32_bf16 v[36:39], v[212:215], v[92:95], v[36:39]
	v_mfma_f32_16x16x32_bf16 v[32:35], v[220:223], v[92:95], v[32:35]
	v_mfma_f32_16x16x32_bf16 v[20:23], v[212:215], v[188:191], v[20:23]
	v_mfma_f32_16x16x32_bf16 v[16:19], v[220:223], v[188:191], v[16:19]
	v_mfma_f32_16x16x32_bf16 v[4:7], v[212:215], v[196:199], v[4:7]
	v_mfma_f32_16x16x32_bf16 v[0:3], v[220:223], v[196:199], v[0:3]
	s_add_i32 s73, s73, 2
	s_add_u32 s46, s46, 0x100
	s_addc_u32 s47, s47, 0
	s_add_u32 s12, s12, 0x100
	s_addc_u32 s13, s13, 0
	s_cmp_gt_u32 s73, 29
	s_barrier
	s_cbranch_scc0 .LBB0_377
	s_lshl_b32 s14, s45, 8
	v_or_b32_e32 v64, s14, v240
	v_ashrrev_i32_e32 v65, 31, v64
	v_readlane_b32 s12, v255, 15
	v_lshl_add_u32 v184, s66, 8, v238
	v_lshlrev_b64 v[66:67], 2, v[64:65]
	v_readlane_b32 s13, v255, 16
	v_or_b32_e32 v64, 0x80, v64
	v_ashrrev_i32_e32 v65, 31, v64
	v_lshl_add_u64 v[76:77], s[12:13], 0, v[66:67]
	v_lshl_add_u64 v[66:67], s[84:85], 0, v[66:67]
	v_ashrrev_i32_e32 v185, 31, v184
	global_load_dwordx4 v[80:83], v[76:77], off offset:16
	global_load_dwordx4 v[92:95], v[76:77], off
	global_load_dwordx4 v[72:75], v[66:67], off offset:16
	global_load_dwordx4 v[88:91], v[66:67], off
	global_load_dwordx4 v[68:71], v[76:77], off offset:528
	global_load_dwordx4 v[84:87], v[76:77], off offset:512
	v_lshl_add_u64 v[76:77], v[64:65], 2, s[84:85]
	v_lshl_add_u64 v[196:197], v[184:185], 3, s[34:35]
	global_load_dwordx4 v[64:67], v[76:77], off offset:16
	s_nop 0
	global_load_dwordx4 v[76:79], v[76:77], off
	v_add_co_u32_e32 v194, vcc, s89, v196
	global_load_dwordx2 v[186:187], v[196:197], off
	s_nop 0
	v_addc_co_u32_e32 v195, vcc, 0, v197, vcc
	global_load_dwordx2 v[188:189], v[194:195], off
	global_load_dwordx2 v[198:199], v[196:197], off offset:128
	global_load_dwordx2 v[200:201], v[194:195], off offset:128
	global_load_dwordx2 v[202:203], v[196:197], off offset:256
	global_load_dwordx2 v[204:205], v[194:195], off offset:256
	global_load_dwordx2 v[206:207], v[196:197], off offset:384
	global_load_dwordx2 v[208:209], v[194:195], off offset:384
	v_readlane_b32 s96, v255, 3
	s_mov_b64 s[12:13], -1
	s_cmp_gt_i32 s45, 3
	v_readlane_b32 s97, v255, 4
	v_readlane_b32 s82, v255, 5
	v_readlane_b32 s83, v255, 6
	s_waitcnt vmcnt(0)
	v_xor_b32_e32 v231, 0x80000000, v83
	v_xor_b32_e32 v230, 0x80000000, v82
	v_xor_b32_e32 v227, 0x80000000, v71
	v_xor_b32_e32 v226, 0x80000000, v70
	v_xor_b32_e32 v233, 0x80000000, v95
	v_xor_b32_e32 v232, 0x80000000, v94
	v_cvt_f32_u32_e32 v190, v188
	v_xor_b32_e32 v229, 0x80000000, v87
	v_xor_b32_e32 v228, 0x80000000, v86
	v_cvt_f32_u32_e32 v191, v186
	v_cvt_f32_i32_e32 v186, v189
	v_cvt_f32_i32_e32 v187, v187
	v_pk_fma_f32 v[186:187], v[190:191], s[88:89], v[186:187] op_sel_hi:[1,0,1]
	s_nop 0
	v_pk_mul_f32 v[210:211], v[186:187], s[94:95] op_sel_hi:[1,0]
	s_nop 0
	v_fma_f32 v160, -v211, v211, v210
	v_add_f32_e32 v160, 0x3727c5ac, v160
	v_rsq_f32_e32 v160, v160
	v_pk_fma_f32 v[82:83], v[230:231], v[210:211], v[154:155] op_sel:[0,1,0]
	v_pk_fma_f32 v[156:157], v[92:93], v[210:211], v[156:157] op_sel:[0,1,0] neg_lo:[1,0,0] neg_hi:[1,0,0]
	v_pk_fma_f32 v[70:71], v[226:227], v[210:211], v[138:139] op_sel:[0,1,0]
	v_pk_fma_f32 v[190:191], v[82:83], v[160:161], v[74:75] op_sel_hi:[1,0,1]
	v_pk_fma_f32 v[82:83], v[84:85], v[210:211], v[144:145] op_sel:[0,1,0] neg_lo:[1,0,0] neg_hi:[1,0,0]
	v_pk_fma_f32 v[94:95], v[232:233], v[210:211], v[158:159] op_sel:[0,1,0]
	v_pk_fma_f32 v[154:155], v[82:83], v[160:161], v[76:77] op_sel_hi:[1,0,1]
	v_pk_fma_f32 v[82:83], v[68:69], v[210:211], v[136:137] op_sel:[0,1,0] neg_lo:[1,0,0] neg_hi:[1,0,0]
	v_pk_fma_f32 v[188:189], v[156:157], v[160:161], v[88:89] op_sel_hi:[1,0,1]
	v_pk_fma_f32 v[156:157], v[70:71], v[160:161], v[66:67] op_sel_hi:[1,0,1]
	v_pk_fma_f32 v[158:159], v[82:83], v[160:161], v[64:65] op_sel_hi:[1,0,1]
	v_cvt_f32_u32_e32 v70, v200
	v_cvt_f32_u32_e32 v71, v198
	v_cvt_f32_i32_e32 v82, v201
	v_cvt_f32_i32_e32 v83, v199
	v_pk_fma_f32 v[86:87], v[228:229], v[210:211], v[146:147] op_sel:[0,1,0]
	v_pk_fma_f32 v[186:187], v[94:95], v[160:161], v[90:91] op_sel_hi:[1,0,1]
	v_pk_fma_f32 v[94:95], v[80:81], v[210:211], v[152:153] op_sel:[0,1,0] neg_lo:[1,0,0] neg_hi:[1,0,0]
	v_pk_fma_f32 v[70:71], v[70:71], s[88:89], v[82:83] op_sel_hi:[1,0,1]
	v_pk_fma_f32 v[152:153], v[86:87], v[160:161], v[78:79] op_sel_hi:[1,0,1]
	v_pk_mul_f32 v[70:71], v[70:71], s[94:95] op_sel_hi:[1,0]
	v_pk_fma_f32 v[192:193], v[94:95], v[160:161], v[72:73] op_sel_hi:[1,0,1]
	v_fma_f32 v82, -v71, v71, v70
	v_add_f32_e32 v82, 0x3727c5ac, v82
	v_rsq_f32_e32 v82, v82
	v_pk_fma_f32 v[86:87], v[92:93], v[70:71], v[148:149] op_sel:[0,1,0] neg_lo:[1,0,0] neg_hi:[1,0,0]
	v_pk_fma_f32 v[94:95], v[232:233], v[70:71], v[150:151] op_sel:[0,1,0]
	v_pk_fma_f32 v[148:149], v[86:87], v[82:83], v[88:89] op_sel_hi:[1,0,1]
	v_pk_fma_f32 v[86:87], v[80:81], v[70:71], v[140:141] op_sel:[0,1,0] neg_lo:[1,0,0] neg_hi:[1,0,0]
	v_pk_fma_f32 v[144:145], v[94:95], v[82:83], v[90:91] op_sel_hi:[1,0,1]
	v_pk_fma_f32 v[94:95], v[230:231], v[70:71], v[142:143] op_sel:[0,1,0]
	v_pk_fma_f32 v[150:151], v[86:87], v[82:83], v[72:73] op_sel_hi:[1,0,1]
	v_pk_fma_f32 v[86:87], v[84:85], v[70:71], v[128:129] op_sel:[0,1,0] neg_lo:[1,0,0] neg_hi:[1,0,0]
	v_pk_fma_f32 v[146:147], v[94:95], v[82:83], v[74:75] op_sel_hi:[1,0,1]
	v_pk_fma_f32 v[94:95], v[228:229], v[70:71], v[130:131] op_sel:[0,1,0]
	v_pk_fma_f32 v[140:141], v[86:87], v[82:83], v[76:77] op_sel_hi:[1,0,1]
	v_pk_fma_f32 v[86:87], v[68:69], v[70:71], v[120:121] op_sel:[0,1,0] neg_lo:[1,0,0] neg_hi:[1,0,0]
	v_pk_fma_f32 v[70:71], v[226:227], v[70:71], v[122:123] op_sel:[0,1,0]
	v_pk_fma_f32 v[136:137], v[94:95], v[82:83], v[78:79] op_sel_hi:[1,0,1]
	v_pk_fma_f32 v[138:139], v[70:71], v[82:83], v[66:67] op_sel_hi:[1,0,1]
	v_pk_fma_f32 v[142:143], v[86:87], v[82:83], v[64:65] op_sel_hi:[1,0,1]
	v_cvt_f32_u32_e32 v70, v204
	v_cvt_f32_u32_e32 v71, v202
	v_cvt_f32_i32_e32 v82, v205
	v_cvt_f32_i32_e32 v83, v203
	v_pk_fma_f32 v[70:71], v[70:71], s[88:89], v[82:83] op_sel_hi:[1,0,1]
	s_nop 0
	v_pk_mul_f32 v[70:71], v[70:71], s[94:95] op_sel_hi:[1,0]
	s_nop 0
	v_fma_f32 v82, -v71, v71, v70
	v_add_f32_e32 v82, 0x3727c5ac, v82
	v_rsq_f32_e32 v82, v82
	v_pk_fma_f32 v[86:87], v[92:93], v[70:71], v[132:133] op_sel:[0,1,0] neg_lo:[1,0,0] neg_hi:[1,0,0]
	v_pk_fma_f32 v[94:95], v[232:233], v[70:71], v[134:135] op_sel:[0,1,0]
	v_pk_fma_f32 v[130:131], v[86:87], v[82:83], v[88:89] op_sel_hi:[1,0,1]
	v_pk_fma_f32 v[86:87], v[80:81], v[70:71], v[124:125] op_sel:[0,1,0] neg_lo:[1,0,0] neg_hi:[1,0,0]
	v_pk_fma_f32 v[128:129], v[94:95], v[82:83], v[90:91] op_sel_hi:[1,0,1]
	v_pk_fma_f32 v[94:95], v[230:231], v[70:71], v[126:127] op_sel:[0,1,0]
	v_pk_fma_f32 v[132:133], v[86:87], v[82:83], v[72:73] op_sel_hi:[1,0,1]
	v_pk_fma_f32 v[86:87], v[84:85], v[70:71], v[112:113] op_sel:[0,1,0] neg_lo:[1,0,0] neg_hi:[1,0,0]
	v_pk_fma_f32 v[126:127], v[94:95], v[82:83], v[74:75] op_sel_hi:[1,0,1]
	v_pk_fma_f32 v[94:95], v[228:229], v[70:71], v[114:115] op_sel:[0,1,0]
	v_pk_fma_f32 v[122:123], v[86:87], v[82:83], v[76:77] op_sel_hi:[1,0,1]
	v_pk_fma_f32 v[86:87], v[68:69], v[70:71], v[104:105] op_sel:[0,1,0] neg_lo:[1,0,0] neg_hi:[1,0,0]
	v_pk_fma_f32 v[70:71], v[226:227], v[70:71], v[106:107] op_sel:[0,1,0]
	v_pk_fma_f32 v[114:115], v[94:95], v[82:83], v[78:79] op_sel_hi:[1,0,1]
	v_pk_fma_f32 v[120:121], v[70:71], v[82:83], v[66:67] op_sel_hi:[1,0,1]
	v_pk_fma_f32 v[124:125], v[86:87], v[82:83], v[64:65] op_sel_hi:[1,0,1]
	v_cvt_f32_u32_e32 v70, v208
	v_cvt_f32_u32_e32 v71, v206
	v_cvt_f32_i32_e32 v82, v209
	v_cvt_f32_i32_e32 v83, v207
	v_pk_fma_f32 v[70:71], v[70:71], s[88:89], v[82:83] op_sel_hi:[1,0,1]
	s_nop 0
	v_pk_mul_f32 v[82:83], v[70:71], s[94:95] op_sel_hi:[1,0]
	s_nop 0
	v_fma_f32 v70, -v83, v83, v82
	v_add_f32_e32 v70, 0x3727c5ac, v70
	v_rsq_f32_e32 v94, v70
	v_pk_fma_f32 v[70:71], v[92:93], v[82:83], v[116:117] op_sel:[0,1,0] neg_lo:[1,0,0] neg_hi:[1,0,0]
	v_pk_fma_f32 v[86:87], v[232:233], v[82:83], v[118:119] op_sel:[0,1,0]
	v_pk_fma_f32 v[96:97], v[68:69], v[82:83], v[96:97] op_sel:[0,1,0] neg_lo:[1,0,0] neg_hi:[1,0,0]
	v_pk_fma_f32 v[104:105], v[86:87], v[94:95], v[90:91] op_sel_hi:[1,0,1]
	v_pk_fma_f32 v[112:113], v[70:71], v[94:95], v[88:89] op_sel_hi:[1,0,1]
	v_pk_fma_f32 v[70:71], v[80:81], v[82:83], v[108:109] op_sel:[0,1,0] neg_lo:[1,0,0] neg_hi:[1,0,0]
	v_pk_fma_f32 v[86:87], v[230:231], v[82:83], v[110:111] op_sel:[0,1,0]
	v_pk_fma_f32 v[108:109], v[70:71], v[94:95], v[72:73] op_sel_hi:[1,0,1]
	v_pk_fma_f32 v[106:107], v[86:87], v[94:95], v[74:75] op_sel_hi:[1,0,1]
	v_pk_fma_f32 v[86:87], v[84:85], v[82:83], v[100:101] op_sel:[0,1,0] neg_lo:[1,0,0] neg_hi:[1,0,0]
	v_pk_fma_f32 v[70:71], v[228:229], v[82:83], v[102:103] op_sel:[0,1,0]
	v_pk_fma_f32 v[82:83], v[226:227], v[82:83], v[98:99] op_sel:[0,1,0]
	v_pk_fma_f32 v[70:71], v[70:71], v[94:95], v[78:79] op_sel_hi:[1,0,1]
	v_pk_fma_f32 v[86:87], v[86:87], v[94:95], v[76:77] op_sel_hi:[1,0,1]
	v_pk_fma_f32 v[82:83], v[82:83], v[94:95], v[66:67] op_sel_hi:[1,0,1]
	v_pk_fma_f32 v[94:95], v[96:97], v[94:95], v[64:65] op_sel_hi:[1,0,1]
	global_load_dwordx2 v[102:103], v[196:197], off offset:1024
	global_load_dwordx2 v[110:111], v[194:195], off offset:1024
	global_load_dwordx2 v[98:99], v[196:197], off offset:1152
	global_load_dwordx2 v[100:101], v[194:195], off offset:1152
	global_load_dwordx2 v[96:97], v[196:197], off offset:1280
	global_load_dwordx2 v[116:117], v[194:195], off offset:1280
	global_load_dwordx2 v[234:235], v[196:197], off offset:1408
	global_load_dwordx2 v[236:237], v[194:195], off offset:1408
	s_waitcnt vmcnt(0)
	v_cvt_f32_u32_e32 v119, v102
	v_cvt_f32_u32_e32 v118, v110
	v_cvt_f32_i32_e32 v102, v111
	v_cvt_f32_i32_e32 v103, v103
	v_pk_fma_f32 v[102:103], v[118:119], s[88:89], v[102:103] op_sel_hi:[1,0,1]
	s_nop 0
	v_pk_mul_f32 v[102:103], v[102:103], s[94:95] op_sel_hi:[1,0]
	s_nop 0
	v_fma_f32 v110, -v103, v103, v102
	v_add_f32_e32 v110, 0x3727c5ac, v110
	v_rsq_f32_e32 v110, v110
	v_pk_fma_f32 v[48:49], v[68:69], v[102:103], v[48:49] op_sel:[0,1,0] neg_lo:[1,0,0] neg_hi:[1,0,0]
	v_pk_fma_f32 v[50:51], v[226:227], v[102:103], v[50:51] op_sel:[0,1,0]
	v_pk_fma_f32 v[60:61], v[92:93], v[102:103], v[60:61] op_sel:[0,1,0] neg_lo:[1,0,0] neg_hi:[1,0,0]
	v_pk_fma_f32 v[212:213], v[50:51], v[110:111], v[66:67] op_sel_hi:[1,0,1]
	v_pk_fma_f32 v[216:217], v[48:49], v[110:111], v[64:65] op_sel_hi:[1,0,1]
	v_cvt_f32_u32_e32 v48, v100
	v_cvt_f32_u32_e32 v49, v98
	v_cvt_f32_i32_e32 v50, v101
	v_cvt_f32_i32_e32 v51, v99
	v_pk_fma_f32 v[62:63], v[232:233], v[102:103], v[62:63] op_sel:[0,1,0]
	v_pk_fma_f32 v[56:57], v[80:81], v[102:103], v[56:57] op_sel:[0,1,0] neg_lo:[1,0,0] neg_hi:[1,0,0]
	v_pk_fma_f32 v[58:59], v[230:231], v[102:103], v[58:59] op_sel:[0,1,0]
	v_pk_fma_f32 v[48:49], v[48:49], s[88:89], v[50:51] op_sel_hi:[1,0,1]
	v_pk_fma_f32 v[52:53], v[84:85], v[102:103], v[52:53] op_sel:[0,1,0] neg_lo:[1,0,0] neg_hi:[1,0,0]
	v_pk_mul_f32 v[48:49], v[48:49], s[94:95] op_sel_hi:[1,0]
	v_pk_fma_f32 v[54:55], v[228:229], v[102:103], v[54:55] op_sel:[0,1,0]
	v_fma_f32 v50, -v49, v49, v48
	v_add_f32_e32 v50, 0x3727c5ac, v50
	v_rsq_f32_e32 v50, v50
	v_pk_fma_f32 v[32:33], v[68:69], v[48:49], v[32:33] op_sel:[0,1,0] neg_lo:[1,0,0] neg_hi:[1,0,0]
	v_pk_fma_f32 v[34:35], v[226:227], v[48:49], v[34:35] op_sel:[0,1,0]
	v_pk_fma_f32 v[44:45], v[92:93], v[48:49], v[44:45] op_sel:[0,1,0] neg_lo:[1,0,0] neg_hi:[1,0,0]
	v_pk_fma_f32 v[196:197], v[34:35], v[50:51], v[66:67] op_sel_hi:[1,0,1]
	v_pk_fma_f32 v[200:201], v[32:33], v[50:51], v[64:65] op_sel_hi:[1,0,1]
	v_cvt_f32_u32_e32 v32, v116
	v_cvt_f32_u32_e32 v33, v96
	v_cvt_f32_i32_e32 v34, v117
	v_cvt_f32_i32_e32 v35, v97
	v_pk_fma_f32 v[46:47], v[232:233], v[48:49], v[46:47] op_sel:[0,1,0]
	v_pk_fma_f32 v[40:41], v[80:81], v[48:49], v[40:41] op_sel:[0,1,0] neg_lo:[1,0,0] neg_hi:[1,0,0]
	v_pk_fma_f32 v[42:43], v[230:231], v[48:49], v[42:43] op_sel:[0,1,0]
	v_pk_fma_f32 v[32:33], v[32:33], s[88:89], v[34:35] op_sel_hi:[1,0,1]
	v_pk_fma_f32 v[36:37], v[84:85], v[48:49], v[36:37] op_sel:[0,1,0] neg_lo:[1,0,0] neg_hi:[1,0,0]
	v_pk_mul_f32 v[32:33], v[32:33], s[94:95] op_sel_hi:[1,0]
	v_pk_fma_f32 v[38:39], v[228:229], v[48:49], v[38:39] op_sel:[0,1,0]
	v_fma_f32 v34, -v33, v33, v32
	v_add_f32_e32 v34, 0x3727c5ac, v34
	v_rsq_f32_e32 v34, v34
	v_pk_fma_f32 v[16:17], v[68:69], v[32:33], v[16:17] op_sel:[0,1,0] neg_lo:[1,0,0] neg_hi:[1,0,0]
	v_pk_fma_f32 v[18:19], v[226:227], v[32:33], v[18:19] op_sel:[0,1,0]
	v_pk_fma_f32 v[28:29], v[92:93], v[32:33], v[28:29] op_sel:[0,1,0] neg_lo:[1,0,0] neg_hi:[1,0,0]
	v_pk_fma_f32 v[98:99], v[18:19], v[34:35], v[66:67] op_sel_hi:[1,0,1]
	v_pk_fma_f32 v[102:103], v[16:17], v[34:35], v[64:65] op_sel_hi:[1,0,1]
	v_cvt_f32_u32_e32 v16, v236
	v_cvt_f32_u32_e32 v17, v234
	v_cvt_f32_i32_e32 v18, v237
	v_cvt_f32_i32_e32 v19, v235
	v_pk_fma_f32 v[30:31], v[232:233], v[32:33], v[30:31] op_sel:[0,1,0]
	v_pk_fma_f32 v[24:25], v[80:81], v[32:33], v[24:25] op_sel:[0,1,0] neg_lo:[1,0,0] neg_hi:[1,0,0]
	v_pk_fma_f32 v[26:27], v[230:231], v[32:33], v[26:27] op_sel:[0,1,0]
	v_pk_fma_f32 v[16:17], v[16:17], s[88:89], v[18:19] op_sel_hi:[1,0,1]
	v_pk_fma_f32 v[20:21], v[84:85], v[32:33], v[20:21] op_sel:[0,1,0] neg_lo:[1,0,0] neg_hi:[1,0,0]
	v_pk_mul_f32 v[16:17], v[16:17], s[94:95] op_sel_hi:[1,0]
	v_pk_fma_f32 v[22:23], v[228:229], v[32:33], v[22:23] op_sel:[0,1,0]
	v_fma_f32 v18, -v17, v17, v16
	v_add_f32_e32 v18, 0x3727c5ac, v18
	v_rsq_f32_e32 v18, v18
	v_pk_fma_f32 v[12:13], v[92:93], v[16:17], v[12:13] op_sel:[0,1,0] neg_lo:[1,0,0] neg_hi:[1,0,0]
	v_pk_fma_f32 v[14:15], v[232:233], v[16:17], v[14:15] op_sel:[0,1,0]
	v_pk_fma_f32 v[8:9], v[80:81], v[16:17], v[8:9] op_sel:[0,1,0] neg_lo:[1,0,0] neg_hi:[1,0,0]
	v_pk_fma_f32 v[10:11], v[230:231], v[16:17], v[10:11] op_sel:[0,1,0]
	v_pk_fma_f32 v[4:5], v[84:85], v[16:17], v[4:5] op_sel:[0,1,0] neg_lo:[1,0,0] neg_hi:[1,0,0]
	v_pk_fma_f32 v[6:7], v[228:229], v[16:17], v[6:7] op_sel:[0,1,0]
	v_pk_fma_f32 v[0:1], v[68:69], v[16:17], v[0:1] op_sel:[0,1,0] neg_lo:[1,0,0] neg_hi:[1,0,0]
	v_pk_fma_f32 v[2:3], v[226:227], v[16:17], v[2:3] op_sel:[0,1,0]
	v_pk_fma_f32 v[218:219], v[62:63], v[110:111], v[90:91] op_sel_hi:[1,0,1]
	v_pk_fma_f32 v[220:221], v[60:61], v[110:111], v[88:89] op_sel_hi:[1,0,1]
	v_pk_fma_f32 v[222:223], v[58:59], v[110:111], v[74:75] op_sel_hi:[1,0,1]
	v_pk_fma_f32 v[224:225], v[56:57], v[110:111], v[72:73] op_sel_hi:[1,0,1]
	v_pk_fma_f32 v[210:211], v[54:55], v[110:111], v[78:79] op_sel_hi:[1,0,1]
	v_pk_fma_f32 v[214:215], v[52:53], v[110:111], v[76:77] op_sel_hi:[1,0,1]
	v_pk_fma_f32 v[202:203], v[46:47], v[50:51], v[90:91] op_sel_hi:[1,0,1]
	v_pk_fma_f32 v[204:205], v[44:45], v[50:51], v[88:89] op_sel_hi:[1,0,1]
	v_pk_fma_f32 v[206:207], v[42:43], v[50:51], v[74:75] op_sel_hi:[1,0,1]
	v_pk_fma_f32 v[208:209], v[40:41], v[50:51], v[72:73] op_sel_hi:[1,0,1]
	v_pk_fma_f32 v[194:195], v[38:39], v[50:51], v[78:79] op_sel_hi:[1,0,1]
	v_pk_fma_f32 v[198:199], v[36:37], v[50:51], v[76:77] op_sel_hi:[1,0,1]
	v_pk_fma_f32 v[110:111], v[30:31], v[34:35], v[90:91] op_sel_hi:[1,0,1]
	v_pk_fma_f32 v[116:117], v[28:29], v[34:35], v[88:89] op_sel_hi:[1,0,1]
	v_pk_fma_f32 v[118:119], v[26:27], v[34:35], v[74:75] op_sel_hi:[1,0,1]
	v_pk_fma_f32 v[134:135], v[24:25], v[34:35], v[72:73] op_sel_hi:[1,0,1]
	v_pk_fma_f32 v[96:97], v[22:23], v[34:35], v[78:79] op_sel_hi:[1,0,1]
	v_pk_fma_f32 v[100:101], v[20:21], v[34:35], v[76:77] op_sel_hi:[1,0,1]
	v_pk_fma_f32 v[90:91], v[14:15], v[18:19], v[90:91] op_sel_hi:[1,0,1]
	v_pk_fma_f32 v[88:89], v[12:13], v[18:19], v[88:89] op_sel_hi:[1,0,1]
	v_pk_fma_f32 v[74:75], v[10:11], v[18:19], v[74:75] op_sel_hi:[1,0,1]
	v_pk_fma_f32 v[72:73], v[8:9], v[18:19], v[72:73] op_sel_hi:[1,0,1]
	v_pk_fma_f32 v[60:61], v[6:7], v[18:19], v[78:79] op_sel_hi:[1,0,1]
	v_pk_fma_f32 v[62:63], v[4:5], v[18:19], v[76:77] op_sel_hi:[1,0,1]
	v_pk_fma_f32 v[66:67], v[2:3], v[18:19], v[66:67] op_sel_hi:[1,0,1]
	v_pk_fma_f32 v[64:65], v[0:1], v[18:19], v[64:65] op_sel_hi:[1,0,1]
	s_cbranch_scc0 .LBB0_390
	s_cmp_gt_u32 s45, 7
	s_cbranch_scc0 .LBB0_387
	s_cmp_gt_u32 s45, 11
	s_cbranch_scc0 .LBB0_384
	s_andn2_b64 vcc, exec, s[70:71]
	s_cbranch_vccnz .LBB0_383
	v_lshlrev_b64 v[68:69], 7, v[184:185]
	v_readlane_b32 s42, v252, 2
	v_readlane_b32 s40, v252, 4
	v_or_b32_e32 v0, v68, v249
	v_mov_b32_e32 v1, v69
	v_readlane_b32 s43, v252, 3
	v_readlane_b32 s41, v252, 5
	s_mov_b64 s[12:13], 0x4800
	v_lshl_add_u64 v[2:3], s[42:43], 0, v[0:1]
	v_lshl_add_u64 v[0:1], s[40:41], 0, v[0:1]
	global_load_dwordx4 v[48:51], v[2:3], off offset:16
	global_load_dwordx4 v[52:55], v[2:3], off
	global_load_dwordx4 v[56:59], v[0:1], off offset:16
	global_load_dwordx4 v[226:229], v[0:1], off
	v_or_b32_e32 v0, 16, v184
	v_ashrrev_i32_e32 v1, 31, v0
	v_lshlrev_b64 v[80:81], 7, v[0:1]
	v_or_b32_e32 v0, v80, v249
	v_mov_b32_e32 v1, v81
	v_lshl_add_u64 v[2:3], s[42:43], 0, v[0:1]
	v_lshl_add_u64 v[0:1], s[40:41], 0, v[0:1]
	global_load_dwordx4 v[28:31], v[2:3], off offset:16
	global_load_dwordx4 v[36:39], v[2:3], off
	global_load_dwordx4 v[40:43], v[0:1], off offset:16
	global_load_dwordx4 v[44:47], v[0:1], off
	v_or_b32_e32 v0, 32, v184
	v_ashrrev_i32_e32 v1, 31, v0
	v_lshlrev_b64 v[78:79], 7, v[0:1]
	v_or_b32_e32 v0, v78, v249
	v_mov_b32_e32 v1, v79
	v_lshl_add_u64 v[2:3], s[42:43], 0, v[0:1]
	v_lshl_add_u64 v[0:1], s[40:41], 0, v[0:1]
	global_load_dwordx4 v[16:19], v[2:3], off offset:16
	global_load_dwordx4 v[20:23], v[2:3], off
	global_load_dwordx4 v[24:27], v[0:1], off offset:16
	global_load_dwordx4 v[32:35], v[0:1], off
	v_or_b32_e32 v0, 48, v184
	v_ashrrev_i32_e32 v1, 31, v0
	v_lshlrev_b64 v[76:77], 7, v[0:1]
	v_or_b32_e32 v8, v76, v249
	v_mov_b32_e32 v9, v77
	v_lshl_add_u64 v[4:5], s[42:43], 0, v[8:9]
	v_lshl_add_u64 v[12:13], s[40:41], 0, v[8:9]
	global_load_dwordx4 v[0:3], v[4:5], off offset:16
	s_nop 0
	global_load_dwordx4 v[4:7], v[4:5], off
	s_nop 0
	global_load_dwordx4 v[8:11], v[12:13], off offset:16
	s_nop 0
	global_load_dwordx4 v[12:15], v[12:13], off
	s_waitcnt vmcnt(0)
	v_pk_mul_f32 v[230:231], v[156:157], v[58:59]
	v_pk_mul_f32 v[84:85], v[152:153], v[228:229]
	v_pk_mul_f32 v[92:93], v[154:155], v[226:227]
	v_pk_fma_f32 v[84:85], v[186:187], v[54:55], v[84:85] neg_lo:[0,0,1] neg_hi:[0,0,1]
	v_pk_fma_f32 v[92:93], v[188:189], v[52:53], v[92:93] neg_lo:[0,0,1] neg_hi:[0,0,1]
	v_pk_mul_f32 v[232:233], v[158:159], v[56:57]
	v_pk_mul_f32 v[58:59], v[190:191], v[58:59]
	v_pk_mul_f32 v[56:57], v[192:193], v[56:57]
	v_pk_fma_f32 v[234:235], v[190:191], v[50:51], v[230:231] neg_lo:[0,0,1] neg_hi:[0,0,1]
	v_pk_fma_f32 v[232:233], v[192:193], v[48:49], v[232:233] neg_lo:[0,0,1] neg_hi:[0,0,1]
	v_cvt_pk_bf16_f32 v230, v92, v93
	v_cvt_pk_bf16_f32 v231, v84, v85
	v_lshl_add_u64 v[84:85], v[178:179], 0, v[68:69]
	v_pk_mul_f32 v[92:93], v[186:187], v[228:229]
	v_pk_mul_f32 v[226:227], v[188:189], v[226:227]
	v_pk_fma_f32 v[58:59], v[156:157], v[50:51], v[58:59]
	v_pk_fma_f32 v[50:51], v[158:159], v[48:49], v[56:57]
	v_cvt_pk_bf16_f32 v232, v232, v233
	v_cvt_pk_bf16_f32 v233, v234, v235
	global_store_dwordx4 v[84:85], v[230:233], off
	v_pk_fma_f32 v[54:55], v[152:153], v[54:55], v[92:93]
	v_pk_fma_f32 v[52:53], v[154:155], v[52:53], v[226:227]
	s_nop 0
	v_cvt_pk_bf16_f32 v48, v52, v53
	v_cvt_pk_bf16_f32 v49, v54, v55
	v_cvt_pk_bf16_f32 v50, v50, v51
	v_cvt_pk_bf16_f32 v51, v58, v59
	global_store_dwordx4 v[84:85], v[48:51], off offset:64
	v_pk_mul_f32 v[54:55], v[142:143], v[40:41]
	v_pk_mul_f32 v[40:41], v[150:151], v[40:41]
	v_pk_mul_f32 v[48:49], v[136:137], v[46:47]
	v_pk_mul_f32 v[50:51], v[140:141], v[44:45]
	v_pk_fma_f32 v[52:53], v[144:145], v[38:39], v[48:49] neg_lo:[0,0,1] neg_hi:[0,0,1]
	v_pk_fma_f32 v[48:49], v[148:149], v[36:37], v[50:51] neg_lo:[0,0,1] neg_hi:[0,0,1]
	v_pk_mul_f32 v[50:51], v[138:139], v[42:43]
	v_pk_mul_f32 v[42:43], v[146:147], v[42:43]
	v_pk_fma_f32 v[56:57], v[146:147], v[30:31], v[50:51] neg_lo:[0,0,1] neg_hi:[0,0,1]
	v_pk_fma_f32 v[50:51], v[150:151], v[28:29], v[54:55] neg_lo:[0,0,1] neg_hi:[0,0,1]
	v_cvt_pk_bf16_f32 v48, v48, v49
	v_cvt_pk_bf16_f32 v49, v52, v53
	v_lshl_add_u64 v[52:53], v[178:179], 0, v[80:81]
	v_pk_mul_f32 v[46:47], v[144:145], v[46:47]
	v_pk_mul_f32 v[44:45], v[148:149], v[44:45]
	v_pk_fma_f32 v[42:43], v[138:139], v[30:31], v[42:43]
	v_pk_fma_f32 v[30:31], v[142:143], v[28:29], v[40:41]
	v_cvt_pk_bf16_f32 v50, v50, v51
	v_cvt_pk_bf16_f32 v51, v56, v57
	global_store_dwordx4 v[52:53], v[48:51], off
	v_pk_fma_f32 v[38:39], v[136:137], v[38:39], v[46:47]
	v_pk_fma_f32 v[36:37], v[140:141], v[36:37], v[44:45]
	v_lshl_add_u64 v[58:59], v[68:69], 0, s[10:11]
	v_cvt_pk_bf16_f32 v28, v36, v37
	v_cvt_pk_bf16_f32 v29, v38, v39
	v_cvt_pk_bf16_f32 v30, v30, v31
	v_cvt_pk_bf16_f32 v31, v42, v43
	global_store_dwordx4 v[52:53], v[28:31], off offset:64
	v_pk_mul_f32 v[38:39], v[124:125], v[24:25]
	v_pk_mul_f32 v[24:25], v[132:133], v[24:25]
	v_pk_mul_f32 v[28:29], v[114:115], v[34:35]
	v_pk_mul_f32 v[30:31], v[122:123], v[32:33]
	v_pk_fma_f32 v[36:37], v[128:129], v[22:23], v[28:29] neg_lo:[0,0,1] neg_hi:[0,0,1]
	v_pk_fma_f32 v[28:29], v[130:131], v[20:21], v[30:31] neg_lo:[0,0,1] neg_hi:[0,0,1]
	v_pk_mul_f32 v[30:31], v[120:121], v[26:27]
	v_cvt_pk_bf16_f32 v28, v28, v29
	v_cvt_pk_bf16_f32 v29, v36, v37
	v_lshl_add_u64 v[36:37], v[178:179], 0, v[78:79]
	v_pk_fma_f32 v[40:41], v[126:127], v[18:19], v[30:31] neg_lo:[0,0,1] neg_hi:[0,0,1]
	v_pk_fma_f32 v[30:31], v[132:133], v[16:17], v[38:39] neg_lo:[0,0,1] neg_hi:[0,0,1]
	v_pk_mul_f32 v[26:27], v[126:127], v[26:27]
	v_cvt_pk_bf16_f32 v30, v30, v31
	v_cvt_pk_bf16_f32 v31, v40, v41
	global_store_dwordx4 v[36:37], v[28:31], off
	v_pk_fma_f32 v[26:27], v[120:121], v[18:19], v[26:27]
	v_pk_fma_f32 v[18:19], v[124:125], v[16:17], v[24:25]
	v_pk_mul_f32 v[28:29], v[128:129], v[34:35]
	v_pk_mul_f32 v[30:31], v[130:131], v[32:33]
	v_pk_fma_f32 v[22:23], v[114:115], v[22:23], v[28:29]
	v_pk_fma_f32 v[20:21], v[122:123], v[20:21], v[30:31]
	v_lshl_add_u64 v[80:81], v[68:69], 0, s[12:13]
	v_cvt_pk_bf16_f32 v16, v20, v21
	v_cvt_pk_bf16_f32 v17, v22, v23
	v_cvt_pk_bf16_f32 v18, v18, v19
	v_cvt_pk_bf16_f32 v19, v26, v27
	global_store_dwordx4 v[36:37], v[16:19], off offset:64
	v_pk_mul_f32 v[22:23], v[94:95], v[8:9]
	v_pk_mul_f32 v[8:9], v[108:109], v[8:9]
	v_pk_mul_f32 v[16:17], v[70:71], v[14:15]
	v_pk_mul_f32 v[18:19], v[86:87], v[12:13]
	v_pk_fma_f32 v[20:21], v[104:105], v[6:7], v[16:17] neg_lo:[0,0,1] neg_hi:[0,0,1]
	v_pk_fma_f32 v[16:17], v[112:113], v[4:5], v[18:19] neg_lo:[0,0,1] neg_hi:[0,0,1]
	v_pk_mul_f32 v[18:19], v[82:83], v[10:11]
	v_cvt_pk_bf16_f32 v16, v16, v17
	v_cvt_pk_bf16_f32 v17, v20, v21
	v_lshl_add_u64 v[20:21], v[178:179], 0, v[76:77]
	v_pk_fma_f32 v[24:25], v[106:107], v[2:3], v[18:19] neg_lo:[0,0,1] neg_hi:[0,0,1]
	v_pk_fma_f32 v[18:19], v[108:109], v[0:1], v[22:23] neg_lo:[0,0,1] neg_hi:[0,0,1]
	v_pk_mul_f32 v[14:15], v[104:105], v[14:15]
	v_pk_mul_f32 v[12:13], v[112:113], v[12:13]
	v_pk_mul_f32 v[10:11], v[106:107], v[10:11]
	v_cvt_pk_bf16_f32 v18, v18, v19
	v_cvt_pk_bf16_f32 v19, v24, v25
	global_store_dwordx4 v[20:21], v[16:19], off
	v_pk_fma_f32 v[6:7], v[70:71], v[6:7], v[14:15]
	v_pk_fma_f32 v[4:5], v[86:87], v[4:5], v[12:13]
	v_pk_fma_f32 v[10:11], v[82:83], v[2:3], v[10:11]
	v_pk_fma_f32 v[2:3], v[94:95], v[0:1], v[8:9]
	v_cvt_pk_bf16_f32 v0, v4, v5
	v_cvt_pk_bf16_f32 v1, v6, v7
	s_mov_b64 s[12:13], 0x5000
	v_cvt_pk_bf16_f32 v2, v2, v3
	v_cvt_pk_bf16_f32 v3, v10, v11
	global_store_dwordx4 v[20:21], v[0:3], off offset:64
	v_lshl_add_u64 v[84:85], v[68:69], 0, s[12:13]
	s_mov_b64 s[12:13], 0x5800
	v_or_b32_e32 v0, v58, v249
	v_mov_b32_e32 v1, v59
	v_lshl_add_u64 v[2:3], s[42:43], 0, v[0:1]
	v_lshl_add_u64 v[0:1], s[40:41], 0, v[0:1]
	global_load_dwordx4 v[10:13], v[2:3], off offset:16
	global_load_dwordx4 v[14:17], v[2:3], off
	global_load_dwordx4 v[18:21], v[0:1], off offset:16
	global_load_dwordx4 v[22:25], v[0:1], off
	v_or_b32_e32 v0, v80, v249
	v_mov_b32_e32 v1, v81
	v_lshl_add_u64 v[2:3], s[42:43], 0, v[0:1]
	v_lshl_add_u64 v[0:1], s[40:41], 0, v[0:1]
	global_load_dwordx4 v[26:29], v[2:3], off offset:16
	global_load_dwordx4 v[30:33], v[2:3], off
	global_load_dwordx4 v[34:37], v[0:1], off offset:16
	global_load_dwordx4 v[38:41], v[0:1], off
	v_or_b32_e32 v0, v84, v249
	v_mov_b32_e32 v1, v85
	v_lshl_add_u64 v[2:3], s[42:43], 0, v[0:1]
	v_lshl_add_u64 v[0:1], s[40:41], 0, v[0:1]
	global_load_dwordx4 v[42:45], v[2:3], off offset:16
	global_load_dwordx4 v[46:49], v[2:3], off
	global_load_dwordx4 v[50:53], v[0:1], off offset:16
	global_load_dwordx4 v[54:57], v[0:1], off
	v_lshl_add_u64 v[8:9], v[68:69], 0, s[12:13]
	v_or_b32_e32 v68, v8, v249
	v_mov_b32_e32 v69, v9
	v_lshl_add_u64 v[4:5], s[42:43], 0, v[68:69]
	v_lshl_add_u64 v[68:69], s[40:41], 0, v[68:69]
	global_load_dwordx4 v[0:3], v[4:5], off offset:16
	s_nop 0
	global_load_dwordx4 v[4:7], v[4:5], off
	s_nop 0
	global_load_dwordx4 v[76:79], v[68:69], off offset:16
	global_load_dwordx4 v[226:229], v[68:69], off
	v_lshl_add_u64 v[58:59], v[178:179], 0, v[58:59]
	v_lshl_add_u64 v[8:9], v[178:179], 0, v[8:9]
	s_waitcnt vmcnt(0)
	v_pk_mul_f32 v[230:231], v[212:213], v[20:21]
	v_pk_mul_f32 v[232:233], v[216:217], v[18:19]
	v_pk_mul_f32 v[20:21], v[222:223], v[20:21]
	v_pk_mul_f32 v[18:19], v[224:225], v[18:19]
	v_pk_mul_f32 v[68:69], v[210:211], v[24:25]
	v_pk_mul_f32 v[92:93], v[214:215], v[22:23]
	v_pk_fma_f32 v[234:235], v[222:223], v[12:13], v[230:231] neg_lo:[0,0,1] neg_hi:[0,0,1]
	v_pk_fma_f32 v[232:233], v[224:225], v[10:11], v[232:233] neg_lo:[0,0,1] neg_hi:[0,0,1]
	v_pk_mul_f32 v[24:25], v[218:219], v[24:25]
	v_pk_mul_f32 v[22:23], v[220:221], v[22:23]
	v_pk_fma_f32 v[20:21], v[212:213], v[12:13], v[20:21]
	v_pk_fma_f32 v[12:13], v[216:217], v[10:11], v[18:19]
	v_pk_fma_f32 v[68:69], v[218:219], v[16:17], v[68:69] neg_lo:[0,0,1] neg_hi:[0,0,1]
	v_pk_fma_f32 v[92:93], v[220:221], v[14:15], v[92:93] neg_lo:[0,0,1] neg_hi:[0,0,1]
	v_pk_fma_f32 v[16:17], v[210:211], v[16:17], v[24:25]
	v_cvt_pk_bf16_f32 v230, v92, v93
	v_cvt_pk_bf16_f32 v231, v68, v69
	v_cvt_pk_bf16_f32 v232, v232, v233
	v_cvt_pk_bf16_f32 v233, v234, v235
	global_store_dwordx4 v[58:59], v[230:233], off
	v_pk_fma_f32 v[14:15], v[214:215], v[14:15], v[22:23]
	s_nop 0
	v_cvt_pk_bf16_f32 v10, v14, v15
	v_cvt_pk_bf16_f32 v11, v16, v17
	v_cvt_pk_bf16_f32 v12, v12, v13
	v_cvt_pk_bf16_f32 v13, v20, v21
	global_store_dwordx4 v[58:59], v[10:13], off offset:64
	v_pk_mul_f32 v[16:17], v[200:201], v[34:35]
	s_nop 0
	v_pk_mul_f32 v[10:11], v[194:195], v[40:41]
	v_pk_mul_f32 v[12:13], v[198:199], v[38:39]
	v_pk_fma_f32 v[14:15], v[202:203], v[32:33], v[10:11] neg_lo:[0,0,1] neg_hi:[0,0,1]
	v_pk_fma_f32 v[10:11], v[204:205], v[30:31], v[12:13] neg_lo:[0,0,1] neg_hi:[0,0,1]
	v_pk_mul_f32 v[12:13], v[196:197], v[36:37]
	v_cvt_pk_bf16_f32 v10, v10, v11
	v_cvt_pk_bf16_f32 v11, v14, v15
	v_lshl_add_u64 v[14:15], v[178:179], 0, v[80:81]
	v_pk_fma_f32 v[18:19], v[206:207], v[28:29], v[12:13] neg_lo:[0,0,1] neg_hi:[0,0,1]
	v_pk_fma_f32 v[12:13], v[208:209], v[26:27], v[16:17] neg_lo:[0,0,1] neg_hi:[0,0,1]
	s_nop 0
	v_cvt_pk_bf16_f32 v12, v12, v13
	v_cvt_pk_bf16_f32 v13, v18, v19
	global_store_dwordx4 v[14:15], v[10:13], off
	v_pk_mul_f32 v[18:19], v[208:209], v[34:35]
	s_nop 0
	v_pk_mul_f32 v[10:11], v[202:203], v[40:41]
	v_pk_mul_f32 v[12:13], v[204:205], v[38:39]
	v_pk_fma_f32 v[16:17], v[194:195], v[32:33], v[10:11]
	v_pk_fma_f32 v[10:11], v[198:199], v[30:31], v[12:13]
	v_pk_mul_f32 v[12:13], v[206:207], v[36:37]
	v_cvt_pk_bf16_f32 v10, v10, v11
	v_cvt_pk_bf16_f32 v11, v16, v17
	v_pk_mul_f32 v[16:17], v[102:103], v[50:51]
	v_pk_fma_f32 v[20:21], v[196:197], v[28:29], v[12:13]
	v_pk_fma_f32 v[12:13], v[200:201], v[26:27], v[18:19]
	s_nop 0
	v_cvt_pk_bf16_f32 v12, v12, v13
	v_cvt_pk_bf16_f32 v13, v20, v21
	global_store_dwordx4 v[14:15], v[10:13], off offset:64
	s_nop 1
	v_pk_mul_f32 v[10:11], v[96:97], v[56:57]
	v_pk_mul_f32 v[12:13], v[100:101], v[54:55]
	v_pk_fma_f32 v[14:15], v[110:111], v[48:49], v[10:11] neg_lo:[0,0,1] neg_hi:[0,0,1]
	v_pk_fma_f32 v[10:11], v[116:117], v[46:47], v[12:13] neg_lo:[0,0,1] neg_hi:[0,0,1]
	v_pk_mul_f32 v[12:13], v[98:99], v[52:53]
	v_cvt_pk_bf16_f32 v10, v10, v11
	v_cvt_pk_bf16_f32 v11, v14, v15
	v_lshl_add_u64 v[14:15], v[178:179], 0, v[84:85]
	v_pk_fma_f32 v[18:19], v[118:119], v[44:45], v[12:13] neg_lo:[0,0,1] neg_hi:[0,0,1]
	v_pk_fma_f32 v[12:13], v[134:135], v[42:43], v[16:17] neg_lo:[0,0,1] neg_hi:[0,0,1]
	s_nop 0
	v_cvt_pk_bf16_f32 v12, v12, v13
	v_cvt_pk_bf16_f32 v13, v18, v19
	global_store_dwordx4 v[14:15], v[10:13], off
	v_pk_mul_f32 v[18:19], v[134:135], v[50:51]
	s_nop 0
	v_pk_mul_f32 v[10:11], v[110:111], v[56:57]
	v_pk_mul_f32 v[12:13], v[116:117], v[54:55]
	v_pk_fma_f32 v[16:17], v[96:97], v[48:49], v[10:11]
	v_pk_fma_f32 v[10:11], v[100:101], v[46:47], v[12:13]
	v_pk_mul_f32 v[12:13], v[118:119], v[52:53]
	v_cvt_pk_bf16_f32 v10, v10, v11
	v_cvt_pk_bf16_f32 v11, v16, v17
	v_pk_mul_f32 v[16:17], v[64:65], v[76:77]
	v_pk_fma_f32 v[20:21], v[98:99], v[44:45], v[12:13]
	v_pk_fma_f32 v[12:13], v[102:103], v[42:43], v[18:19]
	s_nop 0
	v_cvt_pk_bf16_f32 v12, v12, v13
	v_cvt_pk_bf16_f32 v13, v20, v21
	global_store_dwordx4 v[14:15], v[10:13], off offset:64
	s_nop 1
	v_pk_mul_f32 v[10:11], v[60:61], v[228:229]
	v_pk_mul_f32 v[12:13], v[62:63], v[226:227]
	v_pk_fma_f32 v[14:15], v[90:91], v[6:7], v[10:11] neg_lo:[0,0,1] neg_hi:[0,0,1]
	v_pk_fma_f32 v[10:11], v[88:89], v[4:5], v[12:13] neg_lo:[0,0,1] neg_hi:[0,0,1]
	v_pk_mul_f32 v[12:13], v[66:67], v[78:79]
	v_cvt_pk_bf16_f32 v10, v10, v11
	v_cvt_pk_bf16_f32 v11, v14, v15
	s_nop 0
	v_pk_fma_f32 v[18:19], v[74:75], v[2:3], v[12:13] neg_lo:[0,0,1] neg_hi:[0,0,1]
	v_pk_fma_f32 v[12:13], v[72:73], v[0:1], v[16:17] neg_lo:[0,0,1] neg_hi:[0,0,1]
	s_nop 0
	v_cvt_pk_bf16_f32 v12, v12, v13
	v_cvt_pk_bf16_f32 v13, v18, v19
	global_store_dwordx4 v[8:9], v[10:13], off
	s_nop 1
	v_pk_mul_f32 v[10:11], v[90:91], v[228:229]
	v_pk_mul_f32 v[12:13], v[88:89], v[226:227]
	v_pk_fma_f32 v[6:7], v[60:61], v[6:7], v[10:11]
	v_pk_fma_f32 v[4:5], v[62:63], v[4:5], v[12:13]
	v_pk_mul_f32 v[10:11], v[74:75], v[78:79]
	v_pk_mul_f32 v[12:13], v[72:73], v[76:77]
	v_pk_fma_f32 v[10:11], v[66:67], v[2:3], v[10:11]
	v_pk_fma_f32 v[2:3], v[64:65], v[0:1], v[12:13]
	v_cvt_pk_bf16_f32 v0, v4, v5
	v_cvt_pk_bf16_f32 v1, v6, v7
	s_nop 0
	v_cvt_pk_bf16_f32 v2, v2, v3
	v_cvt_pk_bf16_f32 v3, v10, v11
	global_store_dwordx4 v[8:9], v[0:3], off offset:64

.LBB0_474:
	s_add_u32 s68, s72, 0xfffe0080
	s_addc_u32 s74, s73, -1
	s_add_i32 s78, 0, 0x10000
	v_add_u32_e32 v140, s78, v173
	ds_read_b128 v[128:131], v140
	ds_read_b128 v[132:135], v140 offset:1024
	ds_read_b128 v[136:139], v140 offset:2048
	ds_read_b128 v[140:143], v140 offset:3072
	s_cmp_eq_u32 s67, 4
	s_cselect_b32 s77, s5, s74
	s_cselect_b32 s76, s12, s68
	s_cselect_b32 s75, s13, s66
	s_cselect_b32 s74, s45, s47
	ds_read_b128 v[174:177], v185
	ds_read_b128 v[180:183], v185 offset:1024
	ds_read_b128 v[186:189], v185 offset:2048
	ds_read_b128 v[190:193], v185 offset:3072
	ds_read_b128 v[194:197], v185 offset:4096
	ds_read_b128 v[198:201], v185 offset:5120
	ds_read_b128 v[202:205], v185 offset:6144
	ds_read_b128 v[206:209], v185 offset:7168
	s_waitcnt lgkmcnt(8)
	s_barrier
	s_waitcnt lgkmcnt(0)
	s_waitcnt lgkmcnt(0)
	v_mfma_f32_16x16x32_bf16 v[124:127], v[128:131], v[174:177], v[124:127]
	v_mfma_f32_16x16x32_bf16 v[120:123], v[136:139], v[174:177], v[120:123]
	v_mfma_f32_16x16x32_bf16 v[112:115], v[128:131], v[186:189], v[112:115]
	v_mfma_f32_16x16x32_bf16 v[104:107], v[136:139], v[186:189], v[104:107]
	v_mfma_f32_16x16x32_bf16 v[96:99], v[128:131], v[194:197], v[96:99]
	v_mfma_f32_16x16x32_bf16 v[88:91], v[136:139], v[194:197], v[88:91]
	v_mfma_f32_16x16x32_bf16 v[80:83], v[128:131], v[202:205], v[80:83]
	v_mfma_f32_16x16x32_bf16 v[72:75], v[136:139], v[202:205], v[72:75]
	v_mfma_f32_16x16x32_bf16 v[124:127], v[132:135], v[180:183], v[124:127]
	v_mfma_f32_16x16x32_bf16 v[120:123], v[140:143], v[180:183], v[120:123]
	v_mfma_f32_16x16x32_bf16 v[112:115], v[132:135], v[190:193], v[112:115]
	v_mfma_f32_16x16x32_bf16 v[104:107], v[140:143], v[190:193], v[104:107]
	v_mfma_f32_16x16x32_bf16 v[96:99], v[132:135], v[198:201], v[96:99]
	v_mfma_f32_16x16x32_bf16 v[88:91], v[140:143], v[198:201], v[88:91]
	v_mfma_f32_16x16x32_bf16 v[80:83], v[132:135], v[206:209], v[80:83]
	v_mfma_f32_16x16x32_bf16 v[72:75], v[140:143], v[206:209], v[72:75]
	s_barrier
	v_lshl_add_u64 v[158:159], s[72:73], 0, v[154:155]
	s_add_i32 m0, s18, 0xc000
	s_nop 0
	global_load_lds_dwordx4 v[158:159], off
	v_lshl_add_u64 v[158:159], s[72:73], 0, v[156:157]
	s_add_i32 m0, s18, 0xe000
	s_nop 0
	global_load_lds_dwordx4 v[158:159], off
	s_add_i32 s68, 0, 0x14000
	v_add_u32_e32 v158, s68, v173
	s_add_i32 s78, s78, s17
	ds_read_b128 v[210:213], v158
	ds_read_b128 v[214:217], v158 offset:1024
	ds_read_b128 v[218:221], v158 offset:2048
	ds_read_b128 v[222:225], v158 offset:3072
	v_lshl_add_u64 v[158:159], s[74:75], 0, v[148:149]
	s_mov_b32 m0, s78
	v_lshl_add_u64 v[170:171], s[74:75], 0, v[144:145]
	global_load_lds_dwordx4 v[158:159], off
	s_add_i32 m0, s78, 0x2000
	s_nop 0
	global_load_lds_dwordx4 v[170:171], off
	s_barrier
	s_waitcnt lgkmcnt(0)
	s_waitcnt lgkmcnt(0)
	v_mfma_f32_16x16x32_bf16 v[116:119], v[210:213], v[174:177], v[116:119]
	v_mfma_f32_16x16x32_bf16 v[108:111], v[218:221], v[174:177], v[108:111]
	v_mfma_f32_16x16x32_bf16 v[100:103], v[210:213], v[186:189], v[100:103]
	v_mfma_f32_16x16x32_bf16 v[92:95], v[218:221], v[186:189], v[92:95]
	v_mfma_f32_16x16x32_bf16 v[84:87], v[210:213], v[194:197], v[84:87]
	v_mfma_f32_16x16x32_bf16 v[76:79], v[218:221], v[194:197], v[76:79]
	v_mfma_f32_16x16x32_bf16 v[68:71], v[210:213], v[202:205], v[68:71]
	v_mfma_f32_16x16x32_bf16 v[64:67], v[218:221], v[202:205], v[64:67]
	v_mfma_f32_16x16x32_bf16 v[116:119], v[214:217], v[180:183], v[116:119]
	v_mfma_f32_16x16x32_bf16 v[108:111], v[222:225], v[180:183], v[108:111]
	v_mfma_f32_16x16x32_bf16 v[100:103], v[214:217], v[190:193], v[100:103]
	v_mfma_f32_16x16x32_bf16 v[92:95], v[222:225], v[190:193], v[92:95]
	v_mfma_f32_16x16x32_bf16 v[84:87], v[214:217], v[198:201], v[84:87]
	v_mfma_f32_16x16x32_bf16 v[76:79], v[222:225], v[198:201], v[76:79]
	v_mfma_f32_16x16x32_bf16 v[68:71], v[214:217], v[206:209], v[68:71]
	v_mfma_f32_16x16x32_bf16 v[64:67], v[222:225], v[206:209], v[64:67]
	s_mov_b32 m0, s18
	v_lshl_add_u64 v[226:227], s[76:77], 0, v[150:151]
	s_barrier
	ds_read_b128 v[174:177], v185 offset:16384
	ds_read_b128 v[180:183], v185 offset:17408
	ds_read_b128 v[186:189], v185 offset:18432
	ds_read_b128 v[190:193], v185 offset:19456
	ds_read_b128 v[194:197], v185 offset:20480
	ds_read_b128 v[198:201], v185 offset:21504
	ds_read_b128 v[202:205], v185 offset:22528
	ds_read_b128 v[206:209], v185 offset:23552
	global_load_lds_dwordx4 v[226:227], off
	v_lshl_add_u64 v[228:229], s[76:77], 0, v[146:147]
	s_mov_b32 m0, s19
	s_nop 0
	global_load_lds_dwordx4 v[228:229], off
	s_barrier
	s_waitcnt lgkmcnt(0)
	s_waitcnt lgkmcnt(0)
	v_mfma_f32_16x16x32_bf16 v[60:63], v[128:131], v[174:177], v[60:63]
	v_mfma_f32_16x16x32_bf16 v[56:59], v[136:139], v[174:177], v[56:59]
	v_mfma_f32_16x16x32_bf16 v[48:51], v[128:131], v[186:189], v[48:51]
	v_mfma_f32_16x16x32_bf16 v[40:43], v[136:139], v[186:189], v[40:43]
	v_mfma_f32_16x16x32_bf16 v[32:35], v[128:131], v[194:197], v[32:35]
	v_mfma_f32_16x16x32_bf16 v[24:27], v[136:139], v[194:197], v[24:27]
	v_mfma_f32_16x16x32_bf16 v[16:19], v[128:131], v[202:205], v[16:19]
	v_mfma_f32_16x16x32_bf16 v[8:11], v[136:139], v[202:205], v[8:11]
	v_mfma_f32_16x16x32_bf16 v[60:63], v[132:135], v[180:183], v[60:63]
	v_mfma_f32_16x16x32_bf16 v[56:59], v[140:143], v[180:183], v[56:59]
	v_mfma_f32_16x16x32_bf16 v[48:51], v[132:135], v[190:193], v[48:51]
	v_mfma_f32_16x16x32_bf16 v[40:43], v[140:143], v[190:193], v[40:43]
	v_mfma_f32_16x16x32_bf16 v[32:35], v[132:135], v[198:201], v[32:35]
	v_mfma_f32_16x16x32_bf16 v[24:27], v[140:143], v[198:201], v[24:27]
	v_mfma_f32_16x16x32_bf16 v[16:19], v[132:135], v[206:209], v[16:19]
	v_mfma_f32_16x16x32_bf16 v[8:11], v[140:143], v[206:209], v[8:11]
	s_barrier
	s_add_u32 s78, s74, 0x20000
	s_addc_u32 s79, s75, 0
	s_add_i32 s68, s68, s17
	v_lshl_add_u64 v[128:129], s[78:79], 0, v[148:149]
	s_mov_b32 m0, s68
	s_nop 0
	global_load_lds_dwordx4 v[128:129], off
	v_lshl_add_u64 v[128:129], s[78:79], 0, v[144:145]
	s_add_i32 m0, s68, 0x2000
	s_nop 0
	global_load_lds_dwordx4 v[128:129], off
	s_waitcnt vmcnt(6)
	s_barrier
	v_mfma_f32_16x16x32_bf16 v[52:55], v[210:213], v[174:177], v[52:55]
	v_mfma_f32_16x16x32_bf16 v[44:47], v[218:221], v[174:177], v[44:47]
	v_mfma_f32_16x16x32_bf16 v[36:39], v[210:213], v[186:189], v[36:39]
	v_mfma_f32_16x16x32_bf16 v[28:31], v[218:221], v[186:189], v[28:31]
	v_mfma_f32_16x16x32_bf16 v[20:23], v[210:213], v[194:197], v[20:23]
	v_mfma_f32_16x16x32_bf16 v[12:15], v[218:221], v[194:197], v[12:15]
	v_mfma_f32_16x16x32_bf16 v[4:7], v[210:213], v[202:205], v[4:7]
	v_mfma_f32_16x16x32_bf16 v[0:3], v[218:221], v[202:205], v[0:3]
	v_mfma_f32_16x16x32_bf16 v[52:55], v[214:217], v[180:183], v[52:55]
	v_mfma_f32_16x16x32_bf16 v[44:47], v[222:225], v[180:183], v[44:47]
	v_mfma_f32_16x16x32_bf16 v[36:39], v[214:217], v[190:193], v[36:39]
	v_mfma_f32_16x16x32_bf16 v[28:31], v[222:225], v[190:193], v[28:31]
	v_mfma_f32_16x16x32_bf16 v[20:23], v[214:217], v[198:201], v[20:23]
	v_mfma_f32_16x16x32_bf16 v[12:15], v[222:225], v[198:201], v[12:15]
	v_mfma_f32_16x16x32_bf16 v[4:7], v[214:217], v[206:209], v[4:7]
	v_mfma_f32_16x16x32_bf16 v[0:3], v[222:225], v[206:209], v[0:3]
	s_add_i32 s68, 0, 0x18000
	v_add_u32_e32 v140, s68, v173
	s_barrier
	ds_read_b128 v[128:131], v140
	ds_read_b128 v[132:135], v140 offset:1024
	ds_read_b128 v[136:139], v140 offset:2048
	ds_read_b128 v[140:143], v140 offset:3072
	ds_read_b128 v[174:177], v185 offset:32768
	ds_read_b128 v[180:183], v185 offset:33792
	ds_read_b128 v[186:189], v185 offset:34816
	ds_read_b128 v[190:193], v185 offset:35840
	ds_read_b128 v[194:197], v185 offset:36864
	ds_read_b128 v[198:201], v185 offset:37888
	ds_read_b128 v[202:205], v185 offset:38912
	ds_read_b128 v[206:209], v185 offset:39936
	s_waitcnt lgkmcnt(8)
	s_barrier
	s_waitcnt lgkmcnt(0)
	s_waitcnt lgkmcnt(0)
	v_mfma_f32_16x16x32_bf16 v[124:127], v[128:131], v[174:177], v[124:127]
	v_mfma_f32_16x16x32_bf16 v[120:123], v[136:139], v[174:177], v[120:123]
	v_mfma_f32_16x16x32_bf16 v[112:115], v[128:131], v[186:189], v[112:115]
	v_mfma_f32_16x16x32_bf16 v[104:107], v[136:139], v[186:189], v[104:107]
	v_mfma_f32_16x16x32_bf16 v[96:99], v[128:131], v[194:197], v[96:99]
	v_mfma_f32_16x16x32_bf16 v[88:91], v[136:139], v[194:197], v[88:91]
	v_mfma_f32_16x16x32_bf16 v[80:83], v[128:131], v[202:205], v[80:83]
	v_mfma_f32_16x16x32_bf16 v[72:75], v[136:139], v[202:205], v[72:75]
	v_mfma_f32_16x16x32_bf16 v[124:127], v[132:135], v[180:183], v[124:127]
	v_mfma_f32_16x16x32_bf16 v[120:123], v[140:143], v[180:183], v[120:123]
	v_mfma_f32_16x16x32_bf16 v[112:115], v[132:135], v[190:193], v[112:115]
	v_mfma_f32_16x16x32_bf16 v[104:107], v[140:143], v[190:193], v[104:107]
	v_mfma_f32_16x16x32_bf16 v[96:99], v[132:135], v[198:201], v[96:99]
	v_mfma_f32_16x16x32_bf16 v[88:91], v[140:143], v[198:201], v[88:91]
	v_mfma_f32_16x16x32_bf16 v[80:83], v[132:135], v[206:209], v[80:83]
	v_mfma_f32_16x16x32_bf16 v[72:75], v[140:143], v[206:209], v[72:75]
	s_barrier
	s_add_u32 s76, s76, 0x20000
	s_addc_u32 s77, s77, 0
	v_lshl_add_u64 v[210:211], s[76:77], 0, v[150:151]
	s_mov_b32 m0, s20
	s_nop 0
	global_load_lds_dwordx4 v[210:211], off
	v_lshl_add_u64 v[210:211], s[76:77], 0, v[146:147]
	s_mov_b32 m0, s21
	s_nop 0
	global_load_lds_dwordx4 v[210:211], off
	s_add_i32 s76, 0, 0x1c000
	s_add_i32 s68, s68, s17
	v_add_u32_e32 v160, s76, v173
	v_lshl_add_u64 v[158:159], v[158:159], 0, s[92:93]
	s_mov_b32 m0, s68
	ds_read_b128 v[210:213], v160
	ds_read_b128 v[214:217], v160 offset:1024
	ds_read_b128 v[218:221], v160 offset:2048
	ds_read_b128 v[222:225], v160 offset:3072
	global_load_lds_dwordx4 v[158:159], off
	v_lshl_add_u64 v[158:159], v[170:171], 0, s[92:93]
	s_add_i32 m0, s68, 0x2000
	s_nop 0
	global_load_lds_dwordx4 v[158:159], off
	s_barrier
	s_waitcnt lgkmcnt(0)
	s_waitcnt lgkmcnt(0)
	v_mfma_f32_16x16x32_bf16 v[116:119], v[210:213], v[174:177], v[116:119]
	v_mfma_f32_16x16x32_bf16 v[108:111], v[218:221], v[174:177], v[108:111]
	v_mfma_f32_16x16x32_bf16 v[100:103], v[210:213], v[186:189], v[100:103]
	v_mfma_f32_16x16x32_bf16 v[92:95], v[218:221], v[186:189], v[92:95]
	v_mfma_f32_16x16x32_bf16 v[84:87], v[210:213], v[194:197], v[84:87]
	v_mfma_f32_16x16x32_bf16 v[76:79], v[218:221], v[194:197], v[76:79]
	v_mfma_f32_16x16x32_bf16 v[68:71], v[210:213], v[202:205], v[68:71]
	v_mfma_f32_16x16x32_bf16 v[64:67], v[218:221], v[202:205], v[64:67]
	v_mfma_f32_16x16x32_bf16 v[116:119], v[214:217], v[180:183], v[116:119]
	v_mfma_f32_16x16x32_bf16 v[108:111], v[222:225], v[180:183], v[108:111]
	v_mfma_f32_16x16x32_bf16 v[100:103], v[214:217], v[190:193], v[100:103]
	v_mfma_f32_16x16x32_bf16 v[92:95], v[222:225], v[190:193], v[92:95]
	v_mfma_f32_16x16x32_bf16 v[84:87], v[214:217], v[198:201], v[84:87]
	v_mfma_f32_16x16x32_bf16 v[76:79], v[222:225], v[198:201], v[76:79]
	v_mfma_f32_16x16x32_bf16 v[68:71], v[214:217], v[206:209], v[68:71]
	v_mfma_f32_16x16x32_bf16 v[64:67], v[222:225], v[206:209], v[64:67]
	s_mov_b32 m0, s22
	v_lshl_add_u64 v[158:159], v[226:227], 0, s[92:93]
	s_barrier
	ds_read_b128 v[174:177], v185 offset:49152
	ds_read_b128 v[180:183], v185 offset:50176
	ds_read_b128 v[186:189], v185 offset:51200
	ds_read_b128 v[190:193], v185 offset:52224
	ds_read_b128 v[194:197], v185 offset:53248
	ds_read_b128 v[198:201], v185 offset:54272
	ds_read_b128 v[202:205], v185 offset:55296
	ds_read_b128 v[206:209], v185 offset:56320
	global_load_lds_dwordx4 v[158:159], off
	v_lshl_add_u64 v[158:159], v[228:229], 0, s[92:93]
	s_mov_b32 m0, s23
	s_nop 0
	global_load_lds_dwordx4 v[158:159], off
	s_barrier
	s_waitcnt lgkmcnt(0)
	s_waitcnt lgkmcnt(0)
	v_mfma_f32_16x16x32_bf16 v[60:63], v[128:131], v[174:177], v[60:63]
	v_mfma_f32_16x16x32_bf16 v[56:59], v[136:139], v[174:177], v[56:59]
	v_mfma_f32_16x16x32_bf16 v[48:51], v[128:131], v[186:189], v[48:51]
	v_mfma_f32_16x16x32_bf16 v[40:43], v[136:139], v[186:189], v[40:43]
	v_mfma_f32_16x16x32_bf16 v[32:35], v[128:131], v[194:197], v[32:35]
	v_mfma_f32_16x16x32_bf16 v[24:27], v[136:139], v[194:197], v[24:27]
	v_mfma_f32_16x16x32_bf16 v[16:19], v[128:131], v[202:205], v[16:19]
	v_mfma_f32_16x16x32_bf16 v[8:11], v[136:139], v[202:205], v[8:11]
	v_mfma_f32_16x16x32_bf16 v[60:63], v[132:135], v[180:183], v[60:63]
	v_mfma_f32_16x16x32_bf16 v[56:59], v[140:143], v[180:183], v[56:59]
	v_mfma_f32_16x16x32_bf16 v[48:51], v[132:135], v[190:193], v[48:51]
	v_mfma_f32_16x16x32_bf16 v[40:43], v[140:143], v[190:193], v[40:43]
	v_mfma_f32_16x16x32_bf16 v[32:35], v[132:135], v[198:201], v[32:35]
	v_mfma_f32_16x16x32_bf16 v[24:27], v[140:143], v[198:201], v[24:27]
	v_mfma_f32_16x16x32_bf16 v[16:19], v[132:135], v[206:209], v[16:19]
	v_mfma_f32_16x16x32_bf16 v[8:11], v[140:143], v[206:209], v[8:11]
	s_barrier
	s_add_u32 s74, s74, 0x20080
	s_addc_u32 s75, s75, 0
	s_add_i32 s68, s76, s17
	v_lshl_add_u64 v[128:129], s[74:75], 0, v[148:149]
	s_mov_b32 m0, s68
	s_nop 0
	global_load_lds_dwordx4 v[128:129], off
	v_lshl_add_u64 v[128:129], s[74:75], 0, v[144:145]
	s_add_i32 m0, s68, 0x2000
	s_nop 0
	global_load_lds_dwordx4 v[128:129], off
	s_waitcnt vmcnt(6)
	s_barrier
	v_mfma_f32_16x16x32_bf16 v[52:55], v[210:213], v[174:177], v[52:55]
	v_mfma_f32_16x16x32_bf16 v[44:47], v[218:221], v[174:177], v[44:47]
	v_mfma_f32_16x16x32_bf16 v[36:39], v[210:213], v[186:189], v[36:39]
	v_mfma_f32_16x16x32_bf16 v[28:31], v[218:221], v[186:189], v[28:31]
	v_mfma_f32_16x16x32_bf16 v[20:23], v[210:213], v[194:197], v[20:23]
	v_mfma_f32_16x16x32_bf16 v[12:15], v[218:221], v[194:197], v[12:15]
	v_mfma_f32_16x16x32_bf16 v[4:7], v[210:213], v[202:205], v[4:7]
	v_mfma_f32_16x16x32_bf16 v[0:3], v[218:221], v[202:205], v[0:3]
	v_mfma_f32_16x16x32_bf16 v[52:55], v[214:217], v[180:183], v[52:55]
	v_mfma_f32_16x16x32_bf16 v[44:47], v[222:225], v[180:183], v[44:47]
	v_mfma_f32_16x16x32_bf16 v[36:39], v[214:217], v[190:193], v[36:39]
	v_mfma_f32_16x16x32_bf16 v[28:31], v[222:225], v[190:193], v[28:31]
	v_mfma_f32_16x16x32_bf16 v[20:23], v[214:217], v[198:201], v[20:23]
	v_mfma_f32_16x16x32_bf16 v[12:15], v[222:225], v[198:201], v[12:15]
	v_mfma_f32_16x16x32_bf16 v[4:7], v[214:217], v[206:209], v[4:7]
	v_mfma_f32_16x16x32_bf16 v[0:3], v[222:225], v[206:209], v[0:3]
	s_add_i32 s67, s67, 2
	s_add_u32 s72, s72, 0x100
	s_addc_u32 s73, s73, 0
	s_add_u32 s47, s47, 0x100
	s_addc_u32 s66, s66, 0
	s_cmp_gt_u32 s67, 5
	s_barrier
	s_cbranch_scc0 .LBB0_474
	v_lshl_add_u32 v188, s27, 8, v153
	v_ashrrev_i32_e32 v189, 31, v188
	v_lshlrev_b64 v[128:129], 6, v[188:189]
	v_lshl_add_u64 v[132:133], s[6:7], 0, v[128:129]
	global_load_dwordx4 v[128:131], v[132:133], off offset:16
	s_nop 0
	global_load_dwordx4 v[132:135], v[132:133], off
	v_or_b32_e32 v180, 16, v188
	v_ashrrev_i32_e32 v181, 31, v180
	v_lshlrev_b64 v[136:137], 6, v[180:181]
	v_lshl_add_u64 v[140:141], s[6:7], 0, v[136:137]
	global_load_dwordx4 v[136:139], v[140:141], off offset:16
	s_nop 0
	global_load_dwordx4 v[140:143], v[140:141], off
	v_or_b32_e32 v174, 32, v188
	v_ashrrev_i32_e32 v175, 31, v174
	v_lshlrev_b64 v[158:159], 6, v[174:175]
	v_lshl_add_u64 v[158:159], s[6:7], 0, v[158:159]
	global_load_dwordx4 v[192:195], v[158:159], off offset:16
	global_load_dwordx4 v[196:199], v[158:159], off
	v_or_b32_e32 v158, 48, v188
	v_ashrrev_i32_e32 v159, 31, v158
	v_lshlrev_b64 v[170:171], 6, v[158:159]
	v_lshl_add_u64 v[170:171], s[6:7], 0, v[170:171]
	global_load_dwordx4 v[200:203], v[170:171], off offset:16
	global_load_dwordx4 v[204:207], v[170:171], off
	v_add_u32_e32 v186, 0x80, v188
	v_ashrrev_i32_e32 v187, 31, v186
	v_add_u32_e32 v182, 0x90, v188
	v_ashrrev_i32_e32 v183, 31, v182
	v_add_u32_e32 v176, 0xa0, v188
	v_ashrrev_i32_e32 v177, 31, v176
	v_lshlrev_b64 v[170:171], 6, v[176:177]
	v_lshl_add_u64 v[170:171], s[6:7], 0, v[170:171]
	s_lshl_b32 s5, s26, 8
	s_cmp_gt_i32 s26, 3
	s_mov_b64 s[12:13], -1
	s_waitcnt vmcnt(0)
	v_add_f32_e32 v128, v128, v129
	v_add_f32_e32 v132, v132, v133
	v_add_f32_e32 v133, v134, v135
	v_add_f32_e32 v129, v130, v131
	v_add_f32_e32 v132, v132, v133
	v_add_f32_e32 v128, v128, v129
	v_add_f32_e32 v128, v132, v128
	v_fmamk_f32 v128, v128, 0x3b000000, v246
	v_rsq_f32_e32 v190, v128
	v_add_f32_e32 v128, v140, v141
	v_add_f32_e32 v129, v142, v143
	v_add_f32_e32 v128, v128, v129
	v_add_f32_e32 v129, v136, v137
	v_add_f32_e32 v130, v138, v139
	v_add_f32_e32 v129, v129, v130
	v_add_f32_e32 v128, v128, v129
	v_fmamk_f32 v128, v128, 0x3b000000, v246
	v_rsq_f32_e32 v184, v128
	v_add_f32_e32 v128, v196, v197
	v_add_f32_e32 v129, v198, v199
	v_add_f32_e32 v128, v128, v129
	v_add_f32_e32 v129, v192, v193
	v_add_f32_e32 v130, v194, v195
	v_add_f32_e32 v129, v129, v130
	v_add_f32_e32 v128, v128, v129
	v_fmamk_f32 v128, v128, 0x3b000000, v246
	v_rsq_f32_e32 v178, v128
	v_add_f32_e32 v128, v204, v205
	v_add_f32_e32 v129, v206, v207
	v_add_f32_e32 v128, v128, v129
	v_add_f32_e32 v129, v200, v201
	v_add_f32_e32 v130, v202, v203
	v_add_f32_e32 v129, v129, v130
	v_add_f32_e32 v128, v128, v129
	v_fmamk_f32 v128, v128, 0x3b000000, v246
	v_rsq_f32_e32 v172, v128
	v_lshlrev_b64 v[128:129], 6, v[186:187]
	v_lshl_add_u64 v[132:133], s[6:7], 0, v[128:129]
	global_load_dwordx4 v[128:131], v[132:133], off offset:16
	s_nop 0
	global_load_dwordx4 v[132:135], v[132:133], off
	v_lshlrev_b64 v[136:137], 6, v[182:183]
	v_lshl_add_u64 v[140:141], s[6:7], 0, v[136:137]
	global_load_dwordx4 v[136:139], v[140:141], off offset:16
	s_nop 0
	global_load_dwordx4 v[140:143], v[140:141], off
	s_nop 0
	global_load_dwordx4 v[192:195], v[170:171], off offset:16
	global_load_dwordx4 v[200:203], v[170:171], off
	v_add_u32_e32 v170, 0xb0, v188
	v_ashrrev_i32_e32 v171, 31, v170
	v_lshlrev_b64 v[196:197], 6, v[170:171]
	v_lshl_add_u64 v[196:197], s[6:7], 0, v[196:197]
	global_load_dwordx4 v[204:207], v[196:197], off offset:16
	global_load_dwordx4 v[208:211], v[196:197], off
	s_waitcnt vmcnt(0)
	v_add_f32_e32 v128, v128, v129
	v_add_f32_e32 v132, v132, v133
	v_add_f32_e32 v133, v134, v135
	v_add_f32_e32 v129, v130, v131
	v_add_f32_e32 v132, v132, v133
	v_add_f32_e32 v128, v128, v129
	v_add_f32_e32 v128, v132, v128
	v_fmamk_f32 v128, v128, 0x3b000000, v246
	v_rsq_f32_e32 v198, v128
	v_add_f32_e32 v128, v140, v141
	v_add_f32_e32 v129, v142, v143
	v_add_f32_e32 v128, v128, v129
	v_add_f32_e32 v129, v136, v137
	v_add_f32_e32 v130, v138, v139
	v_add_f32_e32 v129, v129, v130
	v_add_f32_e32 v128, v128, v129
	v_fmamk_f32 v128, v128, 0x3b000000, v246
	v_rsq_f32_e32 v196, v128
	v_add_f32_e32 v128, v200, v201
	v_add_f32_e32 v129, v202, v203
	v_add_f32_e32 v128, v128, v129
	v_add_f32_e32 v129, v192, v193
	v_add_f32_e32 v130, v194, v195
	v_add_f32_e32 v129, v129, v130
	v_add_f32_e32 v128, v128, v129
	v_fmamk_f32 v128, v128, 0x3b000000, v246
	v_rsq_f32_e32 v194, v128
	v_add_f32_e32 v128, v208, v209
	v_add_f32_e32 v129, v210, v211
	v_add_f32_e32 v128, v128, v129
	v_add_f32_e32 v129, v204, v205
	v_add_f32_e32 v130, v206, v207
	v_add_f32_e32 v129, v129, v130
	v_add_f32_e32 v128, v128, v129
	v_fmamk_f32 v128, v128, 0x3b000000, v246
	v_rsq_f32_e32 v192, v128
	s_cbranch_scc0 .LBB0_477
	v_lshlrev_b64 v[128:129], 7, v[188:189]
	v_lshlrev_b32_e32 v189, 2, v152
	v_readlane_b32 s26, v252, 4
	v_or_b32_e32 v128, v128, v189
	v_readlane_b32 s27, v252, 5
	v_lshl_add_u64 v[130:131], s[42:43], 0, v[128:129]
	global_load_dwordx4 v[202:205], v[130:131], off offset:16
	global_load_dwordx4 v[206:209], v[130:131], off
	v_lshl_add_u64 v[128:129], s[26:27], 0, v[128:129]
	global_load_dwordx4 v[210:213], v[128:129], off offset:16
	global_load_dwordx4 v[214:217], v[128:129], off
	v_lshlrev_b64 v[132:133], 7, v[180:181]
	v_or_b32_e32 v132, v132, v189
	v_lshl_add_u64 v[134:135], s[42:43], 0, v[132:133]
	v_lshl_add_u64 v[140:141], s[26:27], 0, v[132:133]
	global_load_dwordx4 v[128:131], v[134:135], off offset:16
	global_load_dwordx4 v[136:139], v[134:135], off
	s_nop 0
	global_load_dwordx4 v[132:135], v[140:141], off offset:16
	s_nop 0
	global_load_dwordx4 v[140:143], v[140:141], off
	v_pk_mul_f32 v[230:231], v[118:119], v[190:191] op_sel_hi:[1,0]
	v_pk_mul_f32 v[232:233], v[116:117], v[190:191] op_sel_hi:[1,0]
	v_pk_mul_f32 v[222:223], v[126:127], v[190:191] op_sel_hi:[1,0]
	v_pk_mul_f32 v[224:225], v[124:125], v[190:191] op_sel_hi:[1,0]
	v_readlane_b32 s72, v254, 50
	v_pk_mul_f32 v[234:235], v[110:111], v[190:191] op_sel_hi:[1,0]
	v_pk_mul_f32 v[236:237], v[108:109], v[190:191] op_sel_hi:[1,0]
	v_readlane_b32 s73, v254, 51
	v_pk_mul_f32 v[226:227], v[122:123], v[190:191] op_sel_hi:[1,0]
	v_pk_mul_f32 v[228:229], v[120:121], v[190:191] op_sel_hi:[1,0]
	s_mov_b32 s57, s73
	s_add_i32 s56, s24, s5
	v_lshlrev_b32_e32 v160, 1, v152
	v_readlane_b32 s74, v254, 52
	v_readlane_b32 s75, v254, 53
	v_readlane_b32 s76, v254, 54
	v_readlane_b32 s77, v254, 55
	v_readlane_b32 s78, v254, 56
	v_readlane_b32 s79, v254, 57
	v_readlane_b32 s80, v254, 58
	v_readlane_b32 s81, v254, 59
	v_readlane_b32 s82, v254, 60
	v_readlane_b32 s83, v254, 61
	v_readlane_b32 s84, v254, 62
	v_readlane_b32 s85, v254, 63
	v_readlane_b32 s86, v255, 0
	v_readlane_b32 s87, v255, 1
	s_waitcnt vmcnt(0)
	v_pk_mul_f32 v[220:221], v[234:235], v[212:213]
	v_pk_mul_f32 v[200:201], v[230:231], v[216:217]
	v_pk_mul_f32 v[218:219], v[232:233], v[214:215]
	v_pk_fma_f32 v[200:201], v[222:223], v[208:209], v[200:201] neg_lo:[0,0,1] neg_hi:[0,0,1]
	v_pk_fma_f32 v[218:219], v[224:225], v[206:207], v[218:219] neg_lo:[0,0,1] neg_hi:[0,0,1]
	v_pk_mul_f32 v[238:239], v[236:237], v[210:211]
	v_cvt_pk_bf16_f32 v218, v218, v219
	v_cvt_pk_bf16_f32 v219, v200, v201
	v_mov_b64_e32 v[200:201], s[48:49]
	v_pk_fma_f32 v[240:241], v[226:227], v[204:205], v[220:221] neg_lo:[0,0,1] neg_hi:[0,0,1]
	v_pk_fma_f32 v[220:221], v[228:229], v[202:203], v[238:239] neg_lo:[0,0,1] neg_hi:[0,0,1]
	v_mad_i64_i32 v[238:239], s[12:13], v188, s91, v[200:201]
	s_mov_b32 s13, s73
	s_lshl_b64 s[72:73], s[56:57], 1
	v_lshl_add_u64 v[238:239], v[238:239], 0, s[72:73]
	v_cvt_pk_bf16_f32 v220, v220, v221
	v_cvt_pk_bf16_f32 v221, v240, v241
	v_lshl_add_u64 v[238:239], v[238:239], 0, v[160:161]
	v_pk_mul_f32 v[216:217], v[222:223], v[216:217]
	v_pk_mul_f32 v[212:213], v[226:227], v[212:213]
	v_pk_mul_f32 v[210:211], v[228:229], v[210:211]
	global_store_dwordx4 v[238:239], v[218:221], off offset:2048
	v_pk_mul_f32 v[214:215], v[224:225], v[214:215]
	v_pk_fma_f32 v[208:209], v[230:231], v[208:209], v[216:217]
	v_pk_fma_f32 v[212:213], v[234:235], v[204:205], v[212:213]
	v_pk_fma_f32 v[204:205], v[236:237], v[202:203], v[210:211]
	v_pk_mul_f32 v[218:219], v[102:103], v[184:185] op_sel_hi:[1,0]
	v_pk_mul_f32 v[220:221], v[100:101], v[184:185] op_sel_hi:[1,0]
	v_pk_fma_f32 v[206:207], v[232:233], v[206:207], v[214:215]
	v_pk_mul_f32 v[214:215], v[112:113], v[184:185] op_sel_hi:[1,0]
	v_cvt_pk_bf16_f32 v202, v206, v207
	v_cvt_pk_bf16_f32 v203, v208, v209
	v_cvt_pk_bf16_f32 v204, v204, v205
	v_cvt_pk_bf16_f32 v205, v212, v213
	v_pk_mul_f32 v[212:213], v[114:115], v[184:185] op_sel_hi:[1,0]
	v_pk_mul_f32 v[208:209], v[218:219], v[142:143]
	v_pk_mul_f32 v[210:211], v[220:221], v[140:141]
	v_writelane_b32 v254, s12, 50
	v_pk_fma_f32 v[222:223], v[212:213], v[138:139], v[208:209] neg_lo:[0,0,1] neg_hi:[0,0,1]
	v_pk_fma_f32 v[208:209], v[214:215], v[136:137], v[210:211] neg_lo:[0,0,1] neg_hi:[0,0,1]
	v_writelane_b32 v255, s26, 0
	v_writelane_b32 v254, s13, 51
	v_writelane_b32 v255, s27, 1
	global_store_dwordx4 v[238:239], v[202:205], off offset:2112
	v_pk_mul_f32 v[206:207], v[92:93], v[184:185] op_sel_hi:[1,0]
	v_cvt_pk_bf16_f32 v208, v208, v209
	v_cvt_pk_bf16_f32 v209, v222, v223
	v_mad_i64_i32 v[222:223], s[12:13], v180, s91, v[200:201]
	v_pk_mul_f32 v[204:205], v[94:95], v[184:185] op_sel_hi:[1,0]
	v_pk_mul_f32 v[216:217], v[106:107], v[184:185] op_sel_hi:[1,0]
	v_pk_mul_f32 v[202:203], v[104:105], v[184:185] op_sel_hi:[1,0]
	v_pk_mul_f32 v[210:211], v[204:205], v[134:135]
	v_pk_mul_f32 v[224:225], v[206:207], v[132:133]
	v_lshl_add_u64 v[222:223], v[222:223], 0, s[72:73]
	v_pk_fma_f32 v[226:227], v[216:217], v[130:131], v[210:211] neg_lo:[0,0,1] neg_hi:[0,0,1]
	v_pk_fma_f32 v[210:211], v[202:203], v[128:129], v[224:225] neg_lo:[0,0,1] neg_hi:[0,0,1]
	v_lshl_add_u64 v[222:223], v[222:223], 0, v[160:161]
	v_pk_mul_f32 v[142:143], v[212:213], v[142:143]
	v_pk_mul_f32 v[140:141], v[214:215], v[140:141]
	v_pk_mul_f32 v[134:135], v[216:217], v[134:135]
	v_pk_mul_f32 v[132:133], v[202:203], v[132:133]
	v_cvt_pk_bf16_f32 v210, v210, v211
	v_cvt_pk_bf16_f32 v211, v226, v227
	global_store_dwordx4 v[222:223], v[208:211], off offset:2048
	v_pk_fma_f32 v[138:139], v[218:219], v[138:139], v[142:143]
	v_pk_fma_f32 v[136:137], v[220:221], v[136:137], v[140:141]
	v_pk_fma_f32 v[134:135], v[204:205], v[130:131], v[134:135]
	v_pk_fma_f32 v[130:131], v[206:207], v[128:129], v[132:133]
	v_cvt_pk_bf16_f32 v128, v136, v137
	v_cvt_pk_bf16_f32 v129, v138, v139
	v_lshlrev_b64 v[136:137], 7, v[158:159]
	v_cvt_pk_bf16_f32 v130, v130, v131
	v_cvt_pk_bf16_f32 v131, v134, v135
	global_store_dwordx4 v[222:223], v[128:131], off offset:2112
	v_or_b32_e32 v136, v136, v189
	v_lshl_add_u64 v[132:133], s[42:43], 0, v[136:137]
	v_lshlrev_b64 v[128:129], 7, v[174:175]
	v_or_b32_e32 v128, v128, v189
	v_lshl_add_u64 v[130:131], s[42:43], 0, v[128:129]
	v_lshl_add_u64 v[128:129], s[26:27], 0, v[128:129]
	global_load_dwordx4 v[202:205], v[130:131], off offset:16
	global_load_dwordx4 v[206:209], v[130:131], off
	global_load_dwordx4 v[210:213], v[128:129], off offset:16
	global_load_dwordx4 v[214:217], v[128:129], off
	v_lshl_add_u64 v[140:141], s[26:27], 0, v[136:137]
	global_load_dwordx4 v[128:131], v[132:133], off offset:16
	s_nop 0
	global_load_dwordx4 v[132:135], v[132:133], off
	s_nop 0
	global_load_dwordx4 v[136:139], v[140:141], off offset:16
	s_nop 0
	global_load_dwordx4 v[140:143], v[140:141], off
	v_pk_mul_f32 v[230:231], v[86:87], v[178:179] op_sel_hi:[1,0]
	v_pk_mul_f32 v[232:233], v[84:85], v[178:179] op_sel_hi:[1,0]
	v_pk_mul_f32 v[222:223], v[98:99], v[178:179] op_sel_hi:[1,0]
	v_pk_mul_f32 v[224:225], v[96:97], v[178:179] op_sel_hi:[1,0]
	v_pk_mul_f32 v[226:227], v[90:91], v[178:179] op_sel_hi:[1,0]
	v_pk_mul_f32 v[228:229], v[88:89], v[178:179] op_sel_hi:[1,0]
	v_pk_mul_f32 v[234:235], v[78:79], v[178:179] op_sel_hi:[1,0]
	v_pk_mul_f32 v[236:237], v[76:77], v[178:179] op_sel_hi:[1,0]
	v_or_b32_e32 v159, 16, v186
	v_writelane_b32 v254, s14, 52
	v_writelane_b32 v254, s15, 53
	v_writelane_b32 v254, s16, 54
	v_writelane_b32 v254, s17, 55
	v_writelane_b32 v254, s18, 56
	v_writelane_b32 v254, s19, 57
	v_writelane_b32 v254, s20, 58
	v_writelane_b32 v254, s21, 59
	v_writelane_b32 v254, s22, 60
	v_writelane_b32 v254, s23, 61
	v_writelane_b32 v254, s24, 62
	v_writelane_b32 v254, s25, 63
	s_waitcnt vmcnt(0)
	v_pk_mul_f32 v[240:241], v[236:237], v[210:211]
	v_pk_mul_f32 v[218:219], v[230:231], v[216:217]
	v_pk_mul_f32 v[220:221], v[232:233], v[214:215]
	v_pk_fma_f32 v[238:239], v[222:223], v[208:209], v[218:219] neg_lo:[0,0,1] neg_hi:[0,0,1]
	v_pk_fma_f32 v[218:219], v[224:225], v[206:207], v[220:221] neg_lo:[0,0,1] neg_hi:[0,0,1]
	v_pk_mul_f32 v[220:221], v[234:235], v[212:213]
	v_cvt_pk_bf16_f32 v218, v218, v219
	v_cvt_pk_bf16_f32 v219, v238, v239
	v_mad_i64_i32 v[238:239], s[12:13], v174, s91, v[200:201]
	v_lshl_add_u64 v[238:239], v[238:239], 0, s[72:73]
	v_pk_mul_f32 v[212:213], v[226:227], v[212:213]
	v_pk_mul_f32 v[210:211], v[228:229], v[210:211]
	v_pk_fma_f32 v[248:249], v[226:227], v[204:205], v[220:221] neg_lo:[0,0,1] neg_hi:[0,0,1]
	v_pk_fma_f32 v[220:221], v[228:229], v[202:203], v[240:241] neg_lo:[0,0,1] neg_hi:[0,0,1]
	v_lshl_add_u64 v[238:239], v[238:239], 0, v[160:161]
	v_pk_mul_f32 v[216:217], v[222:223], v[216:217]
	v_pk_mul_f32 v[214:215], v[224:225], v[214:215]
	v_pk_fma_f32 v[212:213], v[234:235], v[204:205], v[212:213]
	v_pk_fma_f32 v[204:205], v[236:237], v[202:203], v[210:211]
	v_cvt_pk_bf16_f32 v220, v220, v221
	v_cvt_pk_bf16_f32 v221, v248, v249
	global_store_dwordx4 v[238:239], v[218:221], off offset:2048
	v_pk_fma_f32 v[208:209], v[230:231], v[208:209], v[216:217]
	v_pk_fma_f32 v[206:207], v[232:233], v[206:207], v[214:215]
	v_pk_mul_f32 v[210:211], v[70:71], v[172:173] op_sel_hi:[1,0]
	v_cvt_pk_bf16_f32 v202, v206, v207
	v_cvt_pk_bf16_f32 v203, v208, v209
	v_cvt_pk_bf16_f32 v204, v204, v205
	v_cvt_pk_bf16_f32 v205, v212, v213
	v_pk_mul_f32 v[212:213], v[68:69], v[172:173] op_sel_hi:[1,0]
	global_store_dwordx4 v[238:239], v[202:205], off offset:2112
	v_pk_mul_f32 v[218:219], v[210:211], v[142:143]
	v_pk_mul_f32 v[220:221], v[212:213], v[140:141]
	v_pk_mul_f32 v[202:203], v[82:83], v[172:173] op_sel_hi:[1,0]
	v_pk_mul_f32 v[204:205], v[80:81], v[172:173] op_sel_hi:[1,0]
	v_pk_fma_f32 v[222:223], v[202:203], v[134:135], v[218:219] neg_lo:[0,0,1] neg_hi:[0,0,1]
	v_pk_fma_f32 v[218:219], v[204:205], v[132:133], v[220:221] neg_lo:[0,0,1] neg_hi:[0,0,1]
	v_pk_mul_f32 v[214:215], v[66:67], v[172:173] op_sel_hi:[1,0]
	v_pk_mul_f32 v[216:217], v[64:65], v[172:173] op_sel_hi:[1,0]
	v_cvt_pk_bf16_f32 v218, v218, v219
	v_cvt_pk_bf16_f32 v219, v222, v223
	v_mad_i64_i32 v[222:223], s[12:13], v158, s91, v[200:201]
	v_pk_mul_f32 v[206:207], v[74:75], v[172:173] op_sel_hi:[1,0]
	v_pk_mul_f32 v[208:209], v[72:73], v[172:173] op_sel_hi:[1,0]
	v_pk_mul_f32 v[220:221], v[214:215], v[138:139]
	v_pk_mul_f32 v[224:225], v[216:217], v[136:137]
	v_lshl_add_u64 v[222:223], v[222:223], 0, s[72:73]
	v_pk_fma_f32 v[226:227], v[206:207], v[130:131], v[220:221] neg_lo:[0,0,1] neg_hi:[0,0,1]
	v_pk_fma_f32 v[220:221], v[208:209], v[128:129], v[224:225] neg_lo:[0,0,1] neg_hi:[0,0,1]
	v_lshl_add_u64 v[222:223], v[222:223], 0, v[160:161]
	v_pk_mul_f32 v[142:143], v[202:203], v[142:143]
	v_pk_mul_f32 v[140:141], v[204:205], v[140:141]
	v_pk_mul_f32 v[138:139], v[206:207], v[138:139]
	v_pk_mul_f32 v[136:137], v[208:209], v[136:137]
	v_cvt_pk_bf16_f32 v220, v220, v221
	v_cvt_pk_bf16_f32 v221, v226, v227
	global_store_dwordx4 v[222:223], v[218:221], off offset:2048
	v_pk_fma_f32 v[134:135], v[210:211], v[134:135], v[142:143]
	v_pk_fma_f32 v[132:133], v[212:213], v[132:133], v[140:141]
	v_pk_fma_f32 v[138:139], v[214:215], v[130:131], v[138:139]
	v_pk_fma_f32 v[130:131], v[216:217], v[128:129], v[136:137]
	v_cvt_pk_bf16_f32 v128, v132, v133
	v_cvt_pk_bf16_f32 v129, v134, v135
	v_lshlrev_b64 v[136:137], 7, v[182:183]
	v_cvt_pk_bf16_f32 v130, v130, v131
	v_cvt_pk_bf16_f32 v131, v138, v139
	global_store_dwordx4 v[222:223], v[128:131], off offset:2112
	v_or_b32_e32 v136, v136, v189
	v_lshl_add_u64 v[132:133], s[42:43], 0, v[136:137]
	v_lshlrev_b64 v[128:129], 7, v[186:187]
	v_or_b32_e32 v128, v128, v189
	v_lshl_add_u64 v[130:131], s[42:43], 0, v[128:129]
	v_lshl_add_u64 v[128:129], s[26:27], 0, v[128:129]
	global_load_dwordx4 v[202:205], v[130:131], off offset:16
	global_load_dwordx4 v[206:209], v[130:131], off
	global_load_dwordx4 v[210:213], v[128:129], off offset:16
	global_load_dwordx4 v[214:217], v[128:129], off
	v_lshl_add_u64 v[140:141], s[26:27], 0, v[136:137]
	global_load_dwordx4 v[128:131], v[132:133], off offset:16
	s_nop 0
	global_load_dwordx4 v[132:135], v[132:133], off
	s_nop 0
	global_load_dwordx4 v[136:139], v[140:141], off offset:16
	s_nop 0
	global_load_dwordx4 v[140:143], v[140:141], off
	v_pk_mul_f32 v[230:231], v[54:55], v[198:199] op_sel_hi:[1,0]
	v_pk_mul_f32 v[232:233], v[52:53], v[198:199] op_sel_hi:[1,0]
	v_pk_mul_f32 v[222:223], v[62:63], v[198:199] op_sel_hi:[1,0]
	v_pk_mul_f32 v[224:225], v[60:61], v[198:199] op_sel_hi:[1,0]
	v_pk_mul_f32 v[226:227], v[58:59], v[198:199] op_sel_hi:[1,0]
	v_pk_mul_f32 v[228:229], v[56:57], v[198:199] op_sel_hi:[1,0]
	v_pk_mul_f32 v[234:235], v[46:47], v[198:199] op_sel_hi:[1,0]
	v_pk_mul_f32 v[236:237], v[44:45], v[198:199] op_sel_hi:[1,0]
	s_waitcnt vmcnt(0)
	v_pk_mul_f32 v[218:219], v[230:231], v[216:217]
	v_pk_mul_f32 v[220:221], v[232:233], v[214:215]
	v_pk_fma_f32 v[238:239], v[222:223], v[208:209], v[218:219] neg_lo:[0,0,1] neg_hi:[0,0,1]
	v_pk_fma_f32 v[218:219], v[224:225], v[206:207], v[220:221] neg_lo:[0,0,1] neg_hi:[0,0,1]
	v_pk_mul_f32 v[220:221], v[234:235], v[212:213]
	v_cvt_pk_bf16_f32 v218, v218, v219
	v_cvt_pk_bf16_f32 v219, v238, v239
	v_mad_i64_i32 v[238:239], s[12:13], v186, s91, v[200:201]
	v_pk_mul_f32 v[240:241], v[236:237], v[210:211]
	v_lshl_add_u64 v[238:239], v[238:239], 0, s[72:73]
	v_pk_mul_f32 v[212:213], v[226:227], v[212:213]
	v_pk_mul_f32 v[210:211], v[228:229], v[210:211]
	v_pk_fma_f32 v[248:249], v[226:227], v[204:205], v[220:221] neg_lo:[0,0,1] neg_hi:[0,0,1]
	v_pk_fma_f32 v[220:221], v[228:229], v[202:203], v[240:241] neg_lo:[0,0,1] neg_hi:[0,0,1]
	v_lshl_add_u64 v[238:239], v[238:239], 0, v[160:161]
	v_pk_mul_f32 v[216:217], v[222:223], v[216:217]
	v_pk_mul_f32 v[214:215], v[224:225], v[214:215]
	v_pk_fma_f32 v[212:213], v[234:235], v[204:205], v[212:213]
	v_pk_fma_f32 v[204:205], v[236:237], v[202:203], v[210:211]
	v_cvt_pk_bf16_f32 v220, v220, v221
	v_cvt_pk_bf16_f32 v221, v248, v249
	global_store_dwordx4 v[238:239], v[218:221], off offset:2048
	v_pk_fma_f32 v[208:209], v[230:231], v[208:209], v[216:217]
	v_pk_fma_f32 v[206:207], v[232:233], v[206:207], v[214:215]
	v_pk_mul_f32 v[214:215], v[38:39], v[196:197] op_sel_hi:[1,0]
	v_cvt_pk_bf16_f32 v202, v206, v207
	v_cvt_pk_bf16_f32 v203, v208, v209
	v_cvt_pk_bf16_f32 v204, v204, v205
	v_cvt_pk_bf16_f32 v205, v212, v213
	v_pk_mul_f32 v[216:217], v[36:37], v[196:197] op_sel_hi:[1,0]
	global_store_dwordx4 v[238:239], v[202:205], off offset:2112
	v_pk_mul_f32 v[206:207], v[50:51], v[196:197] op_sel_hi:[1,0]
	v_pk_mul_f32 v[208:209], v[48:49], v[196:197] op_sel_hi:[1,0]
	v_pk_mul_f32 v[202:203], v[214:215], v[142:143]
	v_pk_mul_f32 v[204:205], v[216:217], v[140:141]
	v_pk_fma_f32 v[222:223], v[206:207], v[134:135], v[202:203] neg_lo:[0,0,1] neg_hi:[0,0,1]
	v_pk_fma_f32 v[202:203], v[208:209], v[132:133], v[204:205] neg_lo:[0,0,1] neg_hi:[0,0,1]
	v_pk_mul_f32 v[218:219], v[30:31], v[196:197] op_sel_hi:[1,0]
	v_pk_mul_f32 v[220:221], v[28:29], v[196:197] op_sel_hi:[1,0]
	v_cvt_pk_bf16_f32 v202, v202, v203
	v_cvt_pk_bf16_f32 v203, v222, v223
	v_mad_i64_i32 v[222:223], s[12:13], v159, s91, v[200:201]
	v_pk_mul_f32 v[210:211], v[42:43], v[196:197] op_sel_hi:[1,0]
	v_pk_mul_f32 v[212:213], v[40:41], v[196:197] op_sel_hi:[1,0]
	v_pk_mul_f32 v[204:205], v[218:219], v[138:139]
	v_pk_mul_f32 v[224:225], v[220:221], v[136:137]
	v_lshl_add_u64 v[222:223], v[222:223], 0, s[72:73]
	v_pk_fma_f32 v[226:227], v[210:211], v[130:131], v[204:205] neg_lo:[0,0,1] neg_hi:[0,0,1]
	v_pk_fma_f32 v[204:205], v[212:213], v[128:129], v[224:225] neg_lo:[0,0,1] neg_hi:[0,0,1]
	v_lshl_add_u64 v[222:223], v[222:223], 0, v[160:161]
	v_pk_mul_f32 v[142:143], v[206:207], v[142:143]
	v_pk_mul_f32 v[140:141], v[208:209], v[140:141]
	v_pk_mul_f32 v[138:139], v[210:211], v[138:139]
	v_pk_mul_f32 v[136:137], v[212:213], v[136:137]
	v_cvt_pk_bf16_f32 v204, v204, v205
	v_cvt_pk_bf16_f32 v205, v226, v227
	global_store_dwordx4 v[222:223], v[202:205], off offset:2048
	v_pk_fma_f32 v[134:135], v[214:215], v[134:135], v[142:143]
	v_pk_fma_f32 v[132:133], v[216:217], v[132:133], v[140:141]
	v_pk_fma_f32 v[138:139], v[218:219], v[130:131], v[138:139]
	v_pk_fma_f32 v[130:131], v[220:221], v[128:129], v[136:137]
	v_cvt_pk_bf16_f32 v128, v132, v133
	v_cvt_pk_bf16_f32 v129, v134, v135
	v_lshlrev_b64 v[136:137], 7, v[170:171]
	v_cvt_pk_bf16_f32 v130, v130, v131
	v_cvt_pk_bf16_f32 v131, v138, v139
	global_store_dwordx4 v[222:223], v[128:131], off offset:2112
	v_or_b32_e32 v136, v136, v189
	v_lshl_add_u64 v[132:133], s[42:43], 0, v[136:137]
	v_lshlrev_b64 v[128:129], 7, v[176:177]
	v_or_b32_e32 v128, v128, v189
	v_lshl_add_u64 v[130:131], s[42:43], 0, v[128:129]
	v_lshl_add_u64 v[128:129], s[26:27], 0, v[128:129]
	global_load_dwordx4 v[202:205], v[130:131], off offset:16
	global_load_dwordx4 v[206:209], v[130:131], off
	global_load_dwordx4 v[210:213], v[128:129], off offset:16
	global_load_dwordx4 v[214:217], v[128:129], off
	v_lshl_add_u64 v[140:141], s[26:27], 0, v[136:137]
	global_load_dwordx4 v[128:131], v[132:133], off offset:16
	s_nop 0
	global_load_dwordx4 v[132:135], v[132:133], off
	s_nop 0
	global_load_dwordx4 v[136:139], v[140:141], off offset:16
	s_nop 0
	global_load_dwordx4 v[140:143], v[140:141], off
	v_pk_mul_f32 v[230:231], v[22:23], v[194:195] op_sel_hi:[1,0]
	v_pk_mul_f32 v[232:233], v[20:21], v[194:195] op_sel_hi:[1,0]
	v_pk_mul_f32 v[222:223], v[34:35], v[194:195] op_sel_hi:[1,0]
	v_pk_mul_f32 v[224:225], v[32:33], v[194:195] op_sel_hi:[1,0]
	v_or_b32_e32 v159, 32, v186
	v_pk_mul_f32 v[226:227], v[26:27], v[194:195] op_sel_hi:[1,0]
	v_pk_mul_f32 v[228:229], v[24:25], v[194:195] op_sel_hi:[1,0]
	v_pk_mul_f32 v[234:235], v[14:15], v[194:195] op_sel_hi:[1,0]
	v_pk_mul_f32 v[236:237], v[12:13], v[194:195] op_sel_hi:[1,0]
	s_waitcnt vmcnt(0)
	v_pk_mul_f32 v[218:219], v[230:231], v[216:217]
	v_pk_mul_f32 v[220:221], v[232:233], v[214:215]
	v_pk_fma_f32 v[238:239], v[222:223], v[208:209], v[218:219] neg_lo:[0,0,1] neg_hi:[0,0,1]
	v_pk_fma_f32 v[218:219], v[224:225], v[206:207], v[220:221] neg_lo:[0,0,1] neg_hi:[0,0,1]
	v_pk_mul_f32 v[220:221], v[234:235], v[212:213]
	v_cvt_pk_bf16_f32 v218, v218, v219
	v_cvt_pk_bf16_f32 v219, v238, v239
	v_mad_i64_i32 v[238:239], s[12:13], v159, s91, v[200:201]
	v_pk_mul_f32 v[240:241], v[236:237], v[210:211]
	v_lshl_add_u64 v[238:239], v[238:239], 0, s[72:73]
	v_pk_mul_f32 v[212:213], v[226:227], v[212:213]
	v_pk_mul_f32 v[210:211], v[228:229], v[210:211]
	v_pk_fma_f32 v[248:249], v[226:227], v[204:205], v[220:221] neg_lo:[0,0,1] neg_hi:[0,0,1]
	v_pk_fma_f32 v[220:221], v[228:229], v[202:203], v[240:241] neg_lo:[0,0,1] neg_hi:[0,0,1]
	v_lshl_add_u64 v[238:239], v[238:239], 0, v[160:161]
	v_pk_mul_f32 v[216:217], v[222:223], v[216:217]
	v_pk_mul_f32 v[214:215], v[224:225], v[214:215]
	v_pk_fma_f32 v[212:213], v[234:235], v[204:205], v[212:213]
	v_pk_fma_f32 v[204:205], v[236:237], v[202:203], v[210:211]
	v_cvt_pk_bf16_f32 v220, v220, v221
	v_cvt_pk_bf16_f32 v221, v248, v249
	global_store_dwordx4 v[238:239], v[218:221], off offset:2048
	v_pk_fma_f32 v[208:209], v[230:231], v[208:209], v[216:217]
	v_pk_fma_f32 v[206:207], v[232:233], v[206:207], v[214:215]
	v_or_b32_e32 v159, 48, v186
	v_cvt_pk_bf16_f32 v202, v206, v207
	v_cvt_pk_bf16_f32 v203, v208, v209
	v_cvt_pk_bf16_f32 v204, v204, v205
	v_cvt_pk_bf16_f32 v205, v212, v213
	v_pk_mul_f32 v[214:215], v[6:7], v[192:193] op_sel_hi:[1,0]
	v_pk_mul_f32 v[216:217], v[4:5], v[192:193] op_sel_hi:[1,0]
	global_store_dwordx4 v[238:239], v[202:205], off offset:2112
	v_pk_mul_f32 v[206:207], v[18:19], v[192:193] op_sel_hi:[1,0]
	v_pk_mul_f32 v[208:209], v[16:17], v[192:193] op_sel_hi:[1,0]
	v_pk_mul_f32 v[210:211], v[10:11], v[192:193] op_sel_hi:[1,0]
	v_pk_mul_f32 v[212:213], v[8:9], v[192:193] op_sel_hi:[1,0]
	v_pk_mul_f32 v[218:219], v[2:3], v[192:193] op_sel_hi:[1,0]
	v_pk_mul_f32 v[220:221], v[0:1], v[192:193] op_sel_hi:[1,0]
	v_pk_mul_f32 v[202:203], v[214:215], v[142:143]
	v_pk_mul_f32 v[204:205], v[216:217], v[140:141]
	v_mad_i64_i32 v[200:201], s[12:13], v159, s91, v[200:201]
	v_pk_fma_f32 v[222:223], v[206:207], v[134:135], v[202:203] neg_lo:[0,0,1] neg_hi:[0,0,1]
	v_pk_fma_f32 v[202:203], v[208:209], v[132:133], v[204:205] neg_lo:[0,0,1] neg_hi:[0,0,1]
	v_pk_mul_f32 v[204:205], v[218:219], v[138:139]
	v_pk_mul_f32 v[224:225], v[220:221], v[136:137]
	v_lshl_add_u64 v[200:201], v[200:201], 0, s[72:73]
	v_pk_mul_f32 v[138:139], v[210:211], v[138:139]
	v_pk_mul_f32 v[136:137], v[212:213], v[136:137]
	v_pk_fma_f32 v[226:227], v[210:211], v[130:131], v[204:205] neg_lo:[0,0,1] neg_hi:[0,0,1]
	v_pk_fma_f32 v[204:205], v[212:213], v[128:129], v[224:225] neg_lo:[0,0,1] neg_hi:[0,0,1]
	v_lshl_add_u64 v[200:201], v[200:201], 0, v[160:161]
	v_pk_mul_f32 v[142:143], v[206:207], v[142:143]
	v_pk_mul_f32 v[140:141], v[208:209], v[140:141]
	v_pk_fma_f32 v[138:139], v[218:219], v[130:131], v[138:139]
	v_pk_fma_f32 v[130:131], v[220:221], v[128:129], v[136:137]
	v_cvt_pk_bf16_f32 v202, v202, v203
	v_cvt_pk_bf16_f32 v203, v222, v223
	v_cvt_pk_bf16_f32 v204, v204, v205
	v_cvt_pk_bf16_f32 v205, v226, v227
	global_store_dwordx4 v[200:201], v[202:205], off offset:2048
	v_pk_fma_f32 v[134:135], v[214:215], v[134:135], v[142:143]
	v_pk_fma_f32 v[132:133], v[216:217], v[132:133], v[140:141]
	s_mov_b64 s[12:13], 0
	v_cvt_pk_bf16_f32 v128, v132, v133
	v_cvt_pk_bf16_f32 v129, v134, v135
	v_cvt_pk_bf16_f32 v130, v130, v131
	v_cvt_pk_bf16_f32 v131, v138, v139
	global_store_dwordx4 v[200:201], v[128:131], off offset:2112

.LBB0_493:
	s_add_u32 s0, s76, 0xfffe0080
	s_addc_u32 s1, s77, -1
	s_add_i32 s68, 0, 0x10000
	v_add_u32_e32 v146, s68, v153
	ds_read_b128 v[128:131], v146
	ds_read_b128 v[132:135], v146 offset:1024
	ds_read_b128 v[154:157], v146 offset:2048
	ds_read_b128 v[170:173], v146 offset:3072
	s_cmp_eq_u32 s67, 4
	s_cselect_b32 s79, s12, s1
	s_cselect_b32 s78, s13, s0
	s_cselect_b32 s1, s14, s66
	s_cselect_b32 s0, s15, s47
	ds_read_b128 v[178:181], v177
	ds_read_b128 v[182:185], v177 offset:1024
	ds_read_b128 v[186:189], v177 offset:2048
	ds_read_b128 v[190:193], v177 offset:3072
	ds_read_b128 v[194:197], v177 offset:4096
	ds_read_b128 v[198:201], v177 offset:5120
	ds_read_b128 v[202:205], v177 offset:6144
	ds_read_b128 v[206:209], v177 offset:7168
	s_waitcnt lgkmcnt(8)
	s_barrier
	s_waitcnt lgkmcnt(0)
	s_waitcnt lgkmcnt(0)
	v_mfma_f32_16x16x32_bf16 v[124:127], v[128:131], v[178:181], v[124:127]
	v_mfma_f32_16x16x32_bf16 v[120:123], v[154:157], v[178:181], v[120:123]
	v_mfma_f32_16x16x32_bf16 v[112:115], v[128:131], v[186:189], v[112:115]
	v_mfma_f32_16x16x32_bf16 v[104:107], v[154:157], v[186:189], v[104:107]
	v_mfma_f32_16x16x32_bf16 v[96:99], v[128:131], v[194:197], v[96:99]
	v_mfma_f32_16x16x32_bf16 v[88:91], v[154:157], v[194:197], v[88:91]
	v_mfma_f32_16x16x32_bf16 v[80:83], v[128:131], v[202:205], v[80:83]
	v_mfma_f32_16x16x32_bf16 v[72:75], v[154:157], v[202:205], v[72:75]
	v_mfma_f32_16x16x32_bf16 v[124:127], v[132:135], v[182:185], v[124:127]
	v_mfma_f32_16x16x32_bf16 v[120:123], v[170:173], v[182:185], v[120:123]
	v_mfma_f32_16x16x32_bf16 v[112:115], v[132:135], v[190:193], v[112:115]
	v_mfma_f32_16x16x32_bf16 v[104:107], v[170:173], v[190:193], v[104:107]
	v_mfma_f32_16x16x32_bf16 v[96:99], v[132:135], v[198:201], v[96:99]
	v_mfma_f32_16x16x32_bf16 v[88:91], v[170:173], v[198:201], v[88:91]
	v_mfma_f32_16x16x32_bf16 v[80:83], v[132:135], v[206:209], v[80:83]
	v_mfma_f32_16x16x32_bf16 v[72:75], v[170:173], v[206:209], v[72:75]
	s_barrier
	v_lshl_add_u64 v[146:147], s[76:77], 0, v[142:143]
	s_add_i32 m0, s20, 0xc000
	s_nop 0
	global_load_lds_dwordx4 v[146:147], off
	v_lshl_add_u64 v[146:147], s[76:77], 0, v[144:145]
	s_add_i32 m0, s20, 0xe000
	s_nop 0
	global_load_lds_dwordx4 v[146:147], off
	s_add_i32 s71, 0, 0x14000
	v_add_u32_e32 v146, s71, v153
	s_add_i32 s68, s68, s19
	ds_read_b128 v[210:213], v146
	ds_read_b128 v[214:217], v146 offset:1024
	ds_read_b128 v[218:221], v146 offset:2048
	ds_read_b128 v[222:225], v146 offset:3072
	v_lshl_add_u64 v[146:147], s[0:1], 0, v[160:161]
	s_mov_b32 m0, s68
	v_lshl_add_u64 v[150:151], s[0:1], 0, v[136:137]
	global_load_lds_dwordx4 v[146:147], off
	s_add_i32 m0, s68, 0x2000
	s_nop 0
	global_load_lds_dwordx4 v[150:151], off
	s_barrier
	s_waitcnt lgkmcnt(0)
	s_waitcnt lgkmcnt(0)
	v_mfma_f32_16x16x32_bf16 v[116:119], v[210:213], v[178:181], v[116:119]
	v_mfma_f32_16x16x32_bf16 v[108:111], v[218:221], v[178:181], v[108:111]
	v_mfma_f32_16x16x32_bf16 v[100:103], v[210:213], v[186:189], v[100:103]
	v_mfma_f32_16x16x32_bf16 v[92:95], v[218:221], v[186:189], v[92:95]
	v_mfma_f32_16x16x32_bf16 v[84:87], v[210:213], v[194:197], v[84:87]
	v_mfma_f32_16x16x32_bf16 v[76:79], v[218:221], v[194:197], v[76:79]
	v_mfma_f32_16x16x32_bf16 v[68:71], v[210:213], v[202:205], v[68:71]
	v_mfma_f32_16x16x32_bf16 v[64:67], v[218:221], v[202:205], v[64:67]
	v_mfma_f32_16x16x32_bf16 v[116:119], v[214:217], v[182:185], v[116:119]
	v_mfma_f32_16x16x32_bf16 v[108:111], v[222:225], v[182:185], v[108:111]
	v_mfma_f32_16x16x32_bf16 v[100:103], v[214:217], v[190:193], v[100:103]
	v_mfma_f32_16x16x32_bf16 v[92:95], v[222:225], v[190:193], v[92:95]
	v_mfma_f32_16x16x32_bf16 v[84:87], v[214:217], v[198:201], v[84:87]
	v_mfma_f32_16x16x32_bf16 v[76:79], v[222:225], v[198:201], v[76:79]
	v_mfma_f32_16x16x32_bf16 v[68:71], v[214:217], v[206:209], v[68:71]
	v_mfma_f32_16x16x32_bf16 v[64:67], v[222:225], v[206:209], v[64:67]
	s_mov_b32 m0, s20
	v_lshl_add_u64 v[174:175], s[78:79], 0, v[140:141]
	s_barrier
	ds_read_b128 v[178:181], v177 offset:16384
	ds_read_b128 v[182:185], v177 offset:17408
	ds_read_b128 v[186:189], v177 offset:18432
	ds_read_b128 v[190:193], v177 offset:19456
	ds_read_b128 v[194:197], v177 offset:20480
	ds_read_b128 v[198:201], v177 offset:21504
	ds_read_b128 v[202:205], v177 offset:22528
	ds_read_b128 v[206:209], v177 offset:23552
	global_load_lds_dwordx4 v[174:175], off
	v_lshl_add_u64 v[226:227], s[78:79], 0, v[138:139]
	s_mov_b32 m0, s21
	s_nop 0
	global_load_lds_dwordx4 v[226:227], off
	s_barrier
	s_waitcnt lgkmcnt(0)
	s_waitcnt lgkmcnt(0)
	v_mfma_f32_16x16x32_bf16 v[60:63], v[128:131], v[178:181], v[60:63]
	v_mfma_f32_16x16x32_bf16 v[56:59], v[154:157], v[178:181], v[56:59]
	v_mfma_f32_16x16x32_bf16 v[48:51], v[128:131], v[186:189], v[48:51]
	v_mfma_f32_16x16x32_bf16 v[40:43], v[154:157], v[186:189], v[40:43]
	v_mfma_f32_16x16x32_bf16 v[32:35], v[128:131], v[194:197], v[32:35]
	v_mfma_f32_16x16x32_bf16 v[24:27], v[154:157], v[194:197], v[24:27]
	v_mfma_f32_16x16x32_bf16 v[16:19], v[128:131], v[202:205], v[16:19]
	v_mfma_f32_16x16x32_bf16 v[8:11], v[154:157], v[202:205], v[8:11]
	v_mfma_f32_16x16x32_bf16 v[60:63], v[132:135], v[182:185], v[60:63]
	v_mfma_f32_16x16x32_bf16 v[56:59], v[170:173], v[182:185], v[56:59]
	v_mfma_f32_16x16x32_bf16 v[48:51], v[132:135], v[190:193], v[48:51]
	v_mfma_f32_16x16x32_bf16 v[40:43], v[170:173], v[190:193], v[40:43]
	v_mfma_f32_16x16x32_bf16 v[32:35], v[132:135], v[198:201], v[32:35]
	v_mfma_f32_16x16x32_bf16 v[24:27], v[170:173], v[198:201], v[24:27]
	v_mfma_f32_16x16x32_bf16 v[16:19], v[132:135], v[206:209], v[16:19]
	v_mfma_f32_16x16x32_bf16 v[8:11], v[170:173], v[206:209], v[8:11]
	s_barrier
	s_add_u32 s80, s0, 0x20000
	s_addc_u32 s81, s1, 0
	s_add_i32 s68, s71, s19
	v_lshl_add_u64 v[128:129], s[80:81], 0, v[160:161]
	s_mov_b32 m0, s68
	s_nop 0
	global_load_lds_dwordx4 v[128:129], off
	v_lshl_add_u64 v[128:129], s[80:81], 0, v[136:137]
	s_add_i32 m0, s68, 0x2000
	s_nop 0
	global_load_lds_dwordx4 v[128:129], off
	s_waitcnt vmcnt(6)
	s_barrier
	v_mfma_f32_16x16x32_bf16 v[52:55], v[210:213], v[178:181], v[52:55]
	v_mfma_f32_16x16x32_bf16 v[44:47], v[218:221], v[178:181], v[44:47]
	v_mfma_f32_16x16x32_bf16 v[36:39], v[210:213], v[186:189], v[36:39]
	v_mfma_f32_16x16x32_bf16 v[28:31], v[218:221], v[186:189], v[28:31]
	v_mfma_f32_16x16x32_bf16 v[20:23], v[210:213], v[194:197], v[20:23]
	v_mfma_f32_16x16x32_bf16 v[12:15], v[218:221], v[194:197], v[12:15]
	v_mfma_f32_16x16x32_bf16 v[4:7], v[210:213], v[202:205], v[4:7]
	v_mfma_f32_16x16x32_bf16 v[0:3], v[218:221], v[202:205], v[0:3]
	v_mfma_f32_16x16x32_bf16 v[52:55], v[214:217], v[182:185], v[52:55]
	v_mfma_f32_16x16x32_bf16 v[44:47], v[222:225], v[182:185], v[44:47]
	v_mfma_f32_16x16x32_bf16 v[36:39], v[214:217], v[190:193], v[36:39]
	v_mfma_f32_16x16x32_bf16 v[28:31], v[222:225], v[190:193], v[28:31]
	v_mfma_f32_16x16x32_bf16 v[20:23], v[214:217], v[198:201], v[20:23]
	v_mfma_f32_16x16x32_bf16 v[12:15], v[222:225], v[198:201], v[12:15]
	v_mfma_f32_16x16x32_bf16 v[4:7], v[214:217], v[206:209], v[4:7]
	v_mfma_f32_16x16x32_bf16 v[0:3], v[222:225], v[206:209], v[0:3]
	s_add_i32 s68, 0, 0x18000
	v_add_u32_e32 v148, s68, v153
	s_barrier
	ds_read_b128 v[128:131], v148
	ds_read_b128 v[132:135], v148 offset:1024
	ds_read_b128 v[154:157], v148 offset:2048
	ds_read_b128 v[170:173], v148 offset:3072
	ds_read_b128 v[178:181], v177 offset:32768
	ds_read_b128 v[182:185], v177 offset:33792
	ds_read_b128 v[186:189], v177 offset:34816
	ds_read_b128 v[190:193], v177 offset:35840
	ds_read_b128 v[194:197], v177 offset:36864
	ds_read_b128 v[198:201], v177 offset:37888
	ds_read_b128 v[202:205], v177 offset:38912
	ds_read_b128 v[206:209], v177 offset:39936
	s_waitcnt lgkmcnt(8)
	s_barrier
	s_waitcnt lgkmcnt(0)
	s_waitcnt lgkmcnt(0)
	v_mfma_f32_16x16x32_bf16 v[124:127], v[128:131], v[178:181], v[124:127]
	v_mfma_f32_16x16x32_bf16 v[120:123], v[154:157], v[178:181], v[120:123]
	v_mfma_f32_16x16x32_bf16 v[112:115], v[128:131], v[186:189], v[112:115]
	v_mfma_f32_16x16x32_bf16 v[104:107], v[154:157], v[186:189], v[104:107]
	v_mfma_f32_16x16x32_bf16 v[96:99], v[128:131], v[194:197], v[96:99]
	v_mfma_f32_16x16x32_bf16 v[88:91], v[154:157], v[194:197], v[88:91]
	v_mfma_f32_16x16x32_bf16 v[80:83], v[128:131], v[202:205], v[80:83]
	v_mfma_f32_16x16x32_bf16 v[72:75], v[154:157], v[202:205], v[72:75]
	v_mfma_f32_16x16x32_bf16 v[124:127], v[132:135], v[182:185], v[124:127]
	v_mfma_f32_16x16x32_bf16 v[120:123], v[170:173], v[182:185], v[120:123]
	v_mfma_f32_16x16x32_bf16 v[112:115], v[132:135], v[190:193], v[112:115]
	v_mfma_f32_16x16x32_bf16 v[104:107], v[170:173], v[190:193], v[104:107]
	v_mfma_f32_16x16x32_bf16 v[96:99], v[132:135], v[198:201], v[96:99]
	v_mfma_f32_16x16x32_bf16 v[88:91], v[170:173], v[198:201], v[88:91]
	v_mfma_f32_16x16x32_bf16 v[80:83], v[132:135], v[206:209], v[80:83]
	v_mfma_f32_16x16x32_bf16 v[72:75], v[170:173], v[206:209], v[72:75]
	s_barrier
	s_add_u32 s78, s78, 0x20000
	s_addc_u32 s79, s79, 0
	v_lshl_add_u64 v[210:211], s[78:79], 0, v[140:141]
	s_mov_b32 m0, s22
	s_nop 0
	global_load_lds_dwordx4 v[210:211], off
	v_lshl_add_u64 v[210:211], s[78:79], 0, v[138:139]
	s_mov_b32 m0, s23
	s_nop 0
	global_load_lds_dwordx4 v[210:211], off
	s_add_i32 s71, 0, 0x1c000
	s_add_i32 s68, s68, s19
	v_add_u32_e32 v148, s71, v153
	v_lshl_add_u64 v[146:147], v[146:147], 0, s[92:93]
	s_mov_b32 m0, s68
	ds_read_b128 v[210:213], v148
	ds_read_b128 v[214:217], v148 offset:1024
	ds_read_b128 v[218:221], v148 offset:2048
	ds_read_b128 v[222:225], v148 offset:3072
	global_load_lds_dwordx4 v[146:147], off
	v_lshl_add_u64 v[146:147], v[150:151], 0, s[92:93]
	s_add_i32 m0, s68, 0x2000
	s_nop 0
	global_load_lds_dwordx4 v[146:147], off
	s_barrier
	s_waitcnt lgkmcnt(0)
	s_waitcnt lgkmcnt(0)
	v_mfma_f32_16x16x32_bf16 v[116:119], v[210:213], v[178:181], v[116:119]
	v_mfma_f32_16x16x32_bf16 v[108:111], v[218:221], v[178:181], v[108:111]
	v_mfma_f32_16x16x32_bf16 v[100:103], v[210:213], v[186:189], v[100:103]
	v_mfma_f32_16x16x32_bf16 v[92:95], v[218:221], v[186:189], v[92:95]
	v_mfma_f32_16x16x32_bf16 v[84:87], v[210:213], v[194:197], v[84:87]
	v_mfma_f32_16x16x32_bf16 v[76:79], v[218:221], v[194:197], v[76:79]
	v_mfma_f32_16x16x32_bf16 v[68:71], v[210:213], v[202:205], v[68:71]
	v_mfma_f32_16x16x32_bf16 v[64:67], v[218:221], v[202:205], v[64:67]
	v_mfma_f32_16x16x32_bf16 v[116:119], v[214:217], v[182:185], v[116:119]
	v_mfma_f32_16x16x32_bf16 v[108:111], v[222:225], v[182:185], v[108:111]
	v_mfma_f32_16x16x32_bf16 v[100:103], v[214:217], v[190:193], v[100:103]
	v_mfma_f32_16x16x32_bf16 v[92:95], v[222:225], v[190:193], v[92:95]
	v_mfma_f32_16x16x32_bf16 v[84:87], v[214:217], v[198:201], v[84:87]
	v_mfma_f32_16x16x32_bf16 v[76:79], v[222:225], v[198:201], v[76:79]
	v_mfma_f32_16x16x32_bf16 v[68:71], v[214:217], v[206:209], v[68:71]
	v_mfma_f32_16x16x32_bf16 v[64:67], v[222:225], v[206:209], v[64:67]
	s_mov_b32 m0, s24
	v_lshl_add_u64 v[146:147], v[174:175], 0, s[92:93]
	s_barrier
	ds_read_b128 v[178:181], v177 offset:49152
	ds_read_b128 v[182:185], v177 offset:50176
	ds_read_b128 v[186:189], v177 offset:51200
	ds_read_b128 v[190:193], v177 offset:52224
	ds_read_b128 v[194:197], v177 offset:53248
	ds_read_b128 v[198:201], v177 offset:54272
	ds_read_b128 v[202:205], v177 offset:55296
	ds_read_b128 v[206:209], v177 offset:56320
	global_load_lds_dwordx4 v[146:147], off
	v_lshl_add_u64 v[146:147], v[226:227], 0, s[92:93]
	s_mov_b32 m0, s25
	s_nop 0
	global_load_lds_dwordx4 v[146:147], off
	s_barrier
	s_waitcnt lgkmcnt(0)
	s_waitcnt lgkmcnt(0)
	v_mfma_f32_16x16x32_bf16 v[60:63], v[128:131], v[178:181], v[60:63]
	v_mfma_f32_16x16x32_bf16 v[56:59], v[154:157], v[178:181], v[56:59]
	v_mfma_f32_16x16x32_bf16 v[48:51], v[128:131], v[186:189], v[48:51]
	v_mfma_f32_16x16x32_bf16 v[40:43], v[154:157], v[186:189], v[40:43]
	v_mfma_f32_16x16x32_bf16 v[32:35], v[128:131], v[194:197], v[32:35]
	v_mfma_f32_16x16x32_bf16 v[24:27], v[154:157], v[194:197], v[24:27]
	v_mfma_f32_16x16x32_bf16 v[16:19], v[128:131], v[202:205], v[16:19]
	v_mfma_f32_16x16x32_bf16 v[8:11], v[154:157], v[202:205], v[8:11]
	v_mfma_f32_16x16x32_bf16 v[60:63], v[132:135], v[182:185], v[60:63]
	v_mfma_f32_16x16x32_bf16 v[56:59], v[170:173], v[182:185], v[56:59]
	v_mfma_f32_16x16x32_bf16 v[48:51], v[132:135], v[190:193], v[48:51]
	v_mfma_f32_16x16x32_bf16 v[40:43], v[170:173], v[190:193], v[40:43]
	v_mfma_f32_16x16x32_bf16 v[32:35], v[132:135], v[198:201], v[32:35]
	v_mfma_f32_16x16x32_bf16 v[24:27], v[170:173], v[198:201], v[24:27]
	v_mfma_f32_16x16x32_bf16 v[16:19], v[132:135], v[206:209], v[16:19]
	v_mfma_f32_16x16x32_bf16 v[8:11], v[170:173], v[206:209], v[8:11]
	s_barrier
	s_add_u32 s0, s0, 0x20080
	s_addc_u32 s1, s1, 0
	s_add_i32 s68, s71, s19
	v_lshl_add_u64 v[128:129], s[0:1], 0, v[160:161]
	s_mov_b32 m0, s68
	s_nop 0
	global_load_lds_dwordx4 v[128:129], off
	v_lshl_add_u64 v[128:129], s[0:1], 0, v[136:137]
	s_add_i32 m0, s68, 0x2000
	s_nop 0
	global_load_lds_dwordx4 v[128:129], off
	s_waitcnt vmcnt(6)
	s_barrier
	v_mfma_f32_16x16x32_bf16 v[52:55], v[210:213], v[178:181], v[52:55]
	v_mfma_f32_16x16x32_bf16 v[44:47], v[218:221], v[178:181], v[44:47]
	v_mfma_f32_16x16x32_bf16 v[36:39], v[210:213], v[186:189], v[36:39]
	v_mfma_f32_16x16x32_bf16 v[28:31], v[218:221], v[186:189], v[28:31]
	v_mfma_f32_16x16x32_bf16 v[20:23], v[210:213], v[194:197], v[20:23]
	v_mfma_f32_16x16x32_bf16 v[12:15], v[218:221], v[194:197], v[12:15]
	v_mfma_f32_16x16x32_bf16 v[4:7], v[210:213], v[202:205], v[4:7]
	v_mfma_f32_16x16x32_bf16 v[0:3], v[218:221], v[202:205], v[0:3]
	v_mfma_f32_16x16x32_bf16 v[52:55], v[214:217], v[182:185], v[52:55]
	v_mfma_f32_16x16x32_bf16 v[44:47], v[222:225], v[182:185], v[44:47]
	v_mfma_f32_16x16x32_bf16 v[36:39], v[214:217], v[190:193], v[36:39]
	v_mfma_f32_16x16x32_bf16 v[28:31], v[222:225], v[190:193], v[28:31]
	v_mfma_f32_16x16x32_bf16 v[20:23], v[214:217], v[198:201], v[20:23]
	v_mfma_f32_16x16x32_bf16 v[12:15], v[222:225], v[198:201], v[12:15]
	v_mfma_f32_16x16x32_bf16 v[4:7], v[214:217], v[206:209], v[4:7]
	v_mfma_f32_16x16x32_bf16 v[0:3], v[222:225], v[206:209], v[0:3]
	s_add_i32 s67, s67, 2
	s_add_u32 s76, s76, 0x100
	s_addc_u32 s77, s77, 0
	s_add_u32 s47, s47, 0x100
	s_addc_u32 s66, s66, 0
	s_cmp_gt_u32 s67, 5
	s_barrier
	s_cbranch_scc0 .LBB0_493
	v_lshl_add_u32 v174, s45, 8, v149
	v_ashrrev_i32_e32 v175, 31, v174
	v_lshlrev_b64 v[128:129], 6, v[174:175]
	v_lshl_add_u64 v[132:133], s[6:7], 0, v[128:129]
	global_load_dwordx4 v[128:131], v[132:133], off
	s_nop 0
	global_load_dwordx4 v[132:135], v[132:133], off offset:16
	v_or_b32_e32 v156, 16, v174
	v_ashrrev_i32_e32 v157, 31, v156
	v_lshlrev_b64 v[146:147], 6, v[156:157]
	v_lshl_add_u64 v[146:147], s[6:7], 0, v[146:147]
	global_load_dwordx4 v[178:181], v[146:147], off
	global_load_dwordx4 v[182:185], v[146:147], off offset:16
	v_or_b32_e32 v150, 32, v174
	v_ashrrev_i32_e32 v151, 31, v150
	v_lshlrev_b64 v[146:147], 6, v[150:151]
	v_lshl_add_u64 v[146:147], s[6:7], 0, v[146:147]
	global_load_dwordx4 v[186:189], v[146:147], off
	global_load_dwordx4 v[190:193], v[146:147], off offset:16
	v_or_b32_e32 v146, 48, v174
	v_ashrrev_i32_e32 v147, 31, v146
	v_lshlrev_b64 v[154:155], 6, v[146:147]
	v_lshl_add_u64 v[154:155], s[6:7], 0, v[154:155]
	global_load_dwordx4 v[194:197], v[154:155], off
	global_load_dwordx4 v[198:201], v[154:155], off offset:16
	v_add_u32_e32 v172, 0xa0, v174
	v_ashrrev_i32_e32 v173, 31, v172
	v_lshl_or_b32 v170, s27, 8, v159
	s_and_b64 vcc, exec, s[4:5]
	s_mov_b32 s27, s70
	s_mov_b32 s45, s46
	s_mov_b64 s[0:1], s[74:75]
	s_mov_b64 s[76:77], s[72:73]
	s_waitcnt vmcnt(0)
	v_mov_b32_e32 v154, v128
	v_mov_b32_e32 v155, v132
	v_mov_b32_e32 v132, v129
	v_pk_add_f32 v[128:129], v[154:155], v[132:133]
	v_mov_b32_e32 v132, v130
	v_mov_b32_e32 v133, v134
	v_mov_b32_e32 v134, v131
	v_pk_add_f32 v[130:131], v[132:133], v[134:135]
	v_add_u32_e32 v154, 0xb0, v174
	v_pk_add_f32 v[128:129], v[128:129], v[130:131]
	v_mov_b32_e32 v130, v180
	v_add_f32_e32 v128, v128, v129
	v_fmamk_f32 v128, v128, 0x3b000000, v246
	v_rsq_f32_e32 v176, v128
	v_mov_b32_e32 v128, v178
	v_mov_b32_e32 v129, v182
	v_mov_b32_e32 v182, v179
	v_mov_b32_e32 v131, v184
	v_mov_b32_e32 v184, v181
	v_pk_add_f32 v[128:129], v[128:129], v[182:183]
	v_pk_add_f32 v[130:131], v[130:131], v[184:185]
	v_add_u32_e32 v180, 0x80, v174
	v_pk_add_f32 v[128:129], v[128:129], v[130:131]
	v_mov_b32_e32 v130, v188
	v_add_f32_e32 v128, v128, v129
	v_fmamk_f32 v128, v128, 0x3b000000, v246
	v_rsq_f32_e32 v158, v128
	v_mov_b32_e32 v128, v186
	v_mov_b32_e32 v129, v190
	v_mov_b32_e32 v190, v187
	v_mov_b32_e32 v131, v192
	v_mov_b32_e32 v192, v189
	v_pk_add_f32 v[128:129], v[128:129], v[190:191]
	v_pk_add_f32 v[130:131], v[130:131], v[192:193]
	v_ashrrev_i32_e32 v181, 31, v180
	v_pk_add_f32 v[128:129], v[128:129], v[130:131]
	v_mov_b32_e32 v130, v196
	v_add_f32_e32 v128, v128, v129
	v_fmamk_f32 v128, v128, 0x3b000000, v246
	v_rsq_f32_e32 v152, v128
	v_mov_b32_e32 v128, v194
	v_mov_b32_e32 v129, v198
	v_mov_b32_e32 v198, v195
	v_mov_b32_e32 v131, v200
	v_mov_b32_e32 v200, v197
	v_pk_add_f32 v[128:129], v[128:129], v[198:199]
	v_pk_add_f32 v[130:131], v[130:131], v[200:201]
	v_add_u32_e32 v178, 0x90, v174
	v_pk_add_f32 v[128:129], v[128:129], v[130:131]
	v_ashrrev_i32_e32 v179, 31, v178
	v_add_f32_e32 v128, v128, v129
	v_fmamk_f32 v128, v128, 0x3b000000, v246
	v_rsq_f32_e32 v148, v128
	v_lshlrev_b64 v[128:129], 6, v[180:181]
	v_lshl_add_u64 v[128:129], s[6:7], 0, v[128:129]
	global_load_dwordx4 v[182:185], v[128:129], off
	global_load_dwordx4 v[186:189], v[128:129], off offset:16
	v_lshlrev_b64 v[128:129], 6, v[178:179]
	v_lshl_add_u64 v[128:129], s[6:7], 0, v[128:129]
	global_load_dwordx4 v[190:193], v[128:129], off
	global_load_dwordx4 v[194:197], v[128:129], off offset:16
	v_lshlrev_b64 v[128:129], 6, v[172:173]
	v_lshl_add_u64 v[128:129], s[6:7], 0, v[128:129]
	global_load_dwordx4 v[198:201], v[128:129], off
	global_load_dwordx4 v[202:205], v[128:129], off offset:16
	v_ashrrev_i32_e32 v155, 31, v154
	v_lshlrev_b64 v[128:129], 6, v[154:155]
	v_lshl_add_u64 v[128:129], s[6:7], 0, v[128:129]
	global_load_dwordx4 v[132:135], v[128:129], off
	s_nop 0
	global_load_dwordx4 v[128:131], v[128:129], off offset:16
	v_pk_mul_f32 v[126:127], v[126:127], v[176:177] op_sel_hi:[1,0]
	v_pk_mul_f32 v[124:125], v[124:125], v[176:177] op_sel_hi:[1,0]
	v_pk_mul_f32 v[120:121], v[120:121], v[176:177] op_sel_hi:[1,0]
	v_pk_mul_f32 v[118:119], v[118:119], v[176:177] op_sel_hi:[1,0]
	v_pk_mul_f32 v[116:117], v[116:117], v[176:177] op_sel_hi:[1,0]
	v_pk_mul_f32 v[112:113], v[112:113], v[158:159] op_sel_hi:[1,0]
	v_pk_mul_f32 v[102:103], v[102:103], v[158:159] op_sel_hi:[1,0]
	v_pk_mul_f32 v[100:101], v[100:101], v[158:159] op_sel_hi:[1,0]
	v_pk_mul_f32 v[96:97], v[96:97], v[152:153] op_sel_hi:[1,0]
	v_pk_mul_f32 v[86:87], v[86:87], v[152:153] op_sel_hi:[1,0]
	v_pk_mul_f32 v[84:85], v[84:85], v[152:153] op_sel_hi:[1,0]
	v_pk_mul_f32 v[80:81], v[80:81], v[148:149] op_sel_hi:[1,0]
	v_pk_mul_f32 v[70:71], v[70:71], v[148:149] op_sel_hi:[1,0]
	v_pk_mul_f32 v[68:69], v[68:69], v[148:149] op_sel_hi:[1,0]
	s_waitcnt vmcnt(0)
	v_mov_b32_e32 v206, v182
	v_mov_b32_e32 v207, v186
	v_mov_b32_e32 v186, v183
	v_pk_add_f32 v[182:183], v[206:207], v[186:187]
	v_mov_b32_e32 v186, v184
	v_mov_b32_e32 v187, v188
	v_mov_b32_e32 v188, v185
	v_pk_add_f32 v[184:185], v[186:187], v[188:189]
	v_mov_b32_e32 v188, v200
	v_pk_add_f32 v[182:183], v[182:183], v[184:185]
	v_mov_b32_e32 v184, v192
	v_add_f32_e32 v171, v182, v183
	v_mov_b32_e32 v182, v190
	v_mov_b32_e32 v183, v194
	v_mov_b32_e32 v194, v191
	v_mov_b32_e32 v185, v196
	v_mov_b32_e32 v196, v193
	v_pk_add_f32 v[182:183], v[182:183], v[194:195]
	v_pk_add_f32 v[184:185], v[184:185], v[196:197]
	v_fmamk_f32 v171, v171, 0x3b000000, v246
	v_pk_add_f32 v[182:183], v[182:183], v[184:185]
	v_rsq_f32_e32 v186, v171
	v_add_f32_e32 v171, v182, v183
	v_mov_b32_e32 v182, v198
	v_mov_b32_e32 v183, v202
	v_mov_b32_e32 v202, v199
	v_mov_b32_e32 v189, v204
	v_mov_b32_e32 v204, v201
	v_pk_add_f32 v[182:183], v[182:183], v[202:203]
	v_pk_add_f32 v[188:189], v[188:189], v[204:205]
	v_fmamk_f32 v171, v171, 0x3b000000, v246
	v_pk_add_f32 v[182:183], v[182:183], v[188:189]
	v_rsq_f32_e32 v184, v171
	v_add_f32_e32 v171, v182, v183
	v_mov_b32_e32 v188, v132
	v_mov_b32_e32 v189, v128
	v_mov_b32_e32 v128, v133
	v_mov_b32_e32 v132, v134
	v_mov_b32_e32 v133, v130
	v_mov_b32_e32 v130, v135
	v_fmamk_f32 v171, v171, 0x3b000000, v246
	v_pk_add_f32 v[128:129], v[188:189], v[128:129]
	v_pk_add_f32 v[130:131], v[132:133], v[130:131]
	v_rsq_f32_e32 v182, v171
	v_pk_add_f32 v[128:129], v[128:129], v[130:131]
	v_ashrrev_i32_e32 v171, 31, v170
	v_lshlrev_b64 v[130:131], 12, v[174:175]
	v_pk_mul_f32 v[132:133], v[122:123], v[176:177] op_sel_hi:[1,0]
	v_cvt_pk_bf16_f32 v122, v124, v125
	v_cvt_pk_bf16_f32 v123, v126, v127
	v_cvt_pk_bf16_f32 v124, v120, v121
	v_lshl_add_u64 v[126:127], s[50:51], 0, v[130:131]
	v_lshlrev_b64 v[120:121], 1, v[170:171]
	v_lshl_add_u64 v[126:127], v[126:127], 0, v[120:121]
	v_cvt_pk_bf16_f32 v125, v132, v133
	global_store_dwordx4 v[126:127], v[122:125], off
	v_pk_mul_f32 v[60:61], v[60:61], v[186:187] op_sel_hi:[1,0]
	v_pk_mul_f32 v[62:63], v[62:63], v[186:187] op_sel_hi:[1,0]
	v_pk_mul_f32 v[122:123], v[110:111], v[176:177] op_sel_hi:[1,0]
	v_pk_mul_f32 v[110:111], v[108:109], v[176:177] op_sel_hi:[1,0]
	v_cvt_pk_bf16_f32 v108, v116, v117
	v_cvt_pk_bf16_f32 v109, v118, v119
	v_pk_mul_f32 v[54:55], v[54:55], v[186:187] op_sel_hi:[1,0]
	v_cvt_pk_bf16_f32 v110, v110, v111
	v_cvt_pk_bf16_f32 v111, v122, v123
	global_store_dwordx4 v[126:127], v[108:111], off offset:256
	v_pk_mul_f32 v[52:53], v[52:53], v[186:187] op_sel_hi:[1,0]
	v_pk_mul_f32 v[48:49], v[48:49], v[184:185] op_sel_hi:[1,0]
	v_lshlrev_b64 v[108:109], 12, v[156:157]
	v_lshl_add_u64 v[108:109], s[50:51], 0, v[108:109]
	v_pk_mul_f32 v[110:111], v[114:115], v[158:159] op_sel_hi:[1,0]
	v_pk_mul_f32 v[114:115], v[106:107], v[158:159] op_sel_hi:[1,0]
	v_pk_mul_f32 v[106:107], v[104:105], v[158:159] op_sel_hi:[1,0]
	v_cvt_pk_bf16_f32 v104, v112, v113
	v_cvt_pk_bf16_f32 v105, v110, v111
	v_lshl_add_u64 v[108:109], v[108:109], 0, v[120:121]
	v_cvt_pk_bf16_f32 v106, v106, v107
	v_cvt_pk_bf16_f32 v107, v114, v115
	global_store_dwordx4 v[108:109], v[104:107], off
	v_pk_mul_f32 v[38:39], v[38:39], v[184:185] op_sel_hi:[1,0]
	v_pk_mul_f32 v[36:37], v[36:37], v[184:185] op_sel_hi:[1,0]
	v_pk_mul_f32 v[104:105], v[94:95], v[158:159] op_sel_hi:[1,0]
	v_pk_mul_f32 v[94:95], v[92:93], v[158:159] op_sel_hi:[1,0]
	v_cvt_pk_bf16_f32 v92, v100, v101
	v_cvt_pk_bf16_f32 v93, v102, v103
	v_add_f32_e32 v128, v128, v129
	v_cvt_pk_bf16_f32 v94, v94, v95
	v_cvt_pk_bf16_f32 v95, v104, v105
	global_store_dwordx4 v[108:109], v[92:95], off offset:256
	v_fmamk_f32 v128, v128, 0x3b000000, v246
	v_rsq_f32_e32 v128, v128
	v_lshlrev_b64 v[92:93], 12, v[150:151]
	v_lshl_add_u64 v[92:93], s[50:51], 0, v[92:93]
	v_pk_mul_f32 v[94:95], v[98:99], v[152:153] op_sel_hi:[1,0]
	v_pk_mul_f32 v[98:99], v[90:91], v[152:153] op_sel_hi:[1,0]
	v_pk_mul_f32 v[90:91], v[88:89], v[152:153] op_sel_hi:[1,0]
	v_cvt_pk_bf16_f32 v88, v96, v97
	v_cvt_pk_bf16_f32 v89, v94, v95
	v_lshl_add_u64 v[92:93], v[92:93], 0, v[120:121]
	v_cvt_pk_bf16_f32 v90, v90, v91
	v_cvt_pk_bf16_f32 v91, v98, v99
	global_store_dwordx4 v[92:93], v[88:91], off
	v_pk_mul_f32 v[32:33], v[32:33], v[182:183] op_sel_hi:[1,0]
	v_pk_mul_f32 v[22:23], v[22:23], v[182:183] op_sel_hi:[1,0]
	v_pk_mul_f32 v[88:89], v[78:79], v[152:153] op_sel_hi:[1,0]
	v_pk_mul_f32 v[78:79], v[76:77], v[152:153] op_sel_hi:[1,0]
	v_cvt_pk_bf16_f32 v76, v84, v85
	v_cvt_pk_bf16_f32 v77, v86, v87
	v_pk_mul_f32 v[20:21], v[20:21], v[182:183] op_sel_hi:[1,0]
	v_cvt_pk_bf16_f32 v78, v78, v79
	v_cvt_pk_bf16_f32 v79, v88, v89
	global_store_dwordx4 v[92:93], v[76:79], off offset:256
	v_pk_mul_f32 v[16:17], v[16:17], v[128:129] op_sel_hi:[1,0]
	v_pk_mul_f32 v[6:7], v[6:7], v[128:129] op_sel_hi:[1,0]
	v_lshlrev_b64 v[76:77], 12, v[146:147]
	v_lshl_add_u64 v[76:77], s[50:51], 0, v[76:77]
	v_pk_mul_f32 v[78:79], v[82:83], v[148:149] op_sel_hi:[1,0]
	v_pk_mul_f32 v[82:83], v[74:75], v[148:149] op_sel_hi:[1,0]
	v_pk_mul_f32 v[74:75], v[72:73], v[148:149] op_sel_hi:[1,0]
	v_cvt_pk_bf16_f32 v72, v80, v81
	v_cvt_pk_bf16_f32 v73, v78, v79
	v_lshl_add_u64 v[76:77], v[76:77], 0, v[120:121]
	v_cvt_pk_bf16_f32 v74, v74, v75
	v_cvt_pk_bf16_f32 v75, v82, v83
	global_store_dwordx4 v[76:77], v[72:75], off
	v_pk_mul_f32 v[4:5], v[4:5], v[128:129] op_sel_hi:[1,0]
	s_nop 0
	v_pk_mul_f32 v[72:73], v[66:67], v[148:149] op_sel_hi:[1,0]
	v_pk_mul_f32 v[66:67], v[64:65], v[148:149] op_sel_hi:[1,0]
	v_cvt_pk_bf16_f32 v64, v68, v69
	v_cvt_pk_bf16_f32 v65, v70, v71
	s_nop 0
	v_cvt_pk_bf16_f32 v66, v66, v67
	v_cvt_pk_bf16_f32 v67, v72, v73
	global_store_dwordx4 v[76:77], v[64:67], off offset:256
	s_nop 1
	v_lshlrev_b64 v[64:65], 12, v[180:181]
	v_pk_mul_f32 v[66:67], v[58:59], v[186:187] op_sel_hi:[1,0]
	v_pk_mul_f32 v[58:59], v[56:57], v[186:187] op_sel_hi:[1,0]
	v_cvt_pk_bf16_f32 v56, v60, v61
	v_lshl_add_u64 v[60:61], s[50:51], 0, v[64:65]
	v_cvt_pk_bf16_f32 v57, v62, v63
	v_lshl_add_u64 v[60:61], v[60:61], 0, v[120:121]
	v_cvt_pk_bf16_f32 v58, v58, v59
	v_cvt_pk_bf16_f32 v59, v66, v67
	global_store_dwordx4 v[60:61], v[56:59], off
	s_nop 1
	v_pk_mul_f32 v[56:57], v[46:47], v[186:187] op_sel_hi:[1,0]
	v_pk_mul_f32 v[46:47], v[44:45], v[186:187] op_sel_hi:[1,0]
	v_cvt_pk_bf16_f32 v44, v52, v53
	v_cvt_pk_bf16_f32 v45, v54, v55
	s_nop 0
	v_cvt_pk_bf16_f32 v46, v46, v47
	v_cvt_pk_bf16_f32 v47, v56, v57
	global_store_dwordx4 v[60:61], v[44:47], off offset:256
	s_nop 1
	v_lshlrev_b64 v[44:45], 12, v[178:179]
	v_lshl_add_u64 v[44:45], s[50:51], 0, v[44:45]
	v_pk_mul_f32 v[46:47], v[50:51], v[184:185] op_sel_hi:[1,0]
	v_pk_mul_f32 v[50:51], v[42:43], v[184:185] op_sel_hi:[1,0]
	v_pk_mul_f32 v[42:43], v[40:41], v[184:185] op_sel_hi:[1,0]
	v_cvt_pk_bf16_f32 v40, v48, v49
	v_cvt_pk_bf16_f32 v41, v46, v47
	v_lshl_add_u64 v[44:45], v[44:45], 0, v[120:121]
	v_cvt_pk_bf16_f32 v42, v42, v43
	v_cvt_pk_bf16_f32 v43, v50, v51
	global_store_dwordx4 v[44:45], v[40:43], off
	s_nop 1
	v_pk_mul_f32 v[40:41], v[30:31], v[184:185] op_sel_hi:[1,0]
	v_pk_mul_f32 v[30:31], v[28:29], v[184:185] op_sel_hi:[1,0]
	v_cvt_pk_bf16_f32 v28, v36, v37
	v_cvt_pk_bf16_f32 v29, v38, v39
	s_nop 0
	v_cvt_pk_bf16_f32 v30, v30, v31
	v_cvt_pk_bf16_f32 v31, v40, v41
	global_store_dwordx4 v[44:45], v[28:31], off offset:256
	s_nop 1
	v_lshlrev_b64 v[28:29], 12, v[172:173]
	v_lshl_add_u64 v[28:29], s[50:51], 0, v[28:29]
	v_pk_mul_f32 v[30:31], v[34:35], v[182:183] op_sel_hi:[1,0]
	v_pk_mul_f32 v[34:35], v[26:27], v[182:183] op_sel_hi:[1,0]
	v_pk_mul_f32 v[26:27], v[24:25], v[182:183] op_sel_hi:[1,0]
	v_cvt_pk_bf16_f32 v24, v32, v33
	v_cvt_pk_bf16_f32 v25, v30, v31
	v_lshl_add_u64 v[28:29], v[28:29], 0, v[120:121]
	v_cvt_pk_bf16_f32 v26, v26, v27
	v_cvt_pk_bf16_f32 v27, v34, v35
	global_store_dwordx4 v[28:29], v[24:27], off
	s_nop 1
	v_pk_mul_f32 v[24:25], v[14:15], v[182:183] op_sel_hi:[1,0]
	v_pk_mul_f32 v[14:15], v[12:13], v[182:183] op_sel_hi:[1,0]
	v_cvt_pk_bf16_f32 v12, v20, v21
	v_cvt_pk_bf16_f32 v13, v22, v23
	s_nop 0
	v_cvt_pk_bf16_f32 v14, v14, v15
	v_cvt_pk_bf16_f32 v15, v24, v25
	global_store_dwordx4 v[28:29], v[12:15], off offset:256
	s_nop 1
	v_lshlrev_b64 v[12:13], 12, v[154:155]
	v_lshl_add_u64 v[12:13], s[50:51], 0, v[12:13]
	v_pk_mul_f32 v[14:15], v[18:19], v[128:129] op_sel_hi:[1,0]
	v_pk_mul_f32 v[18:19], v[10:11], v[128:129] op_sel_hi:[1,0]
	v_pk_mul_f32 v[10:11], v[8:9], v[128:129] op_sel_hi:[1,0]
	v_cvt_pk_bf16_f32 v8, v16, v17
	v_cvt_pk_bf16_f32 v9, v14, v15
	v_lshl_add_u64 v[12:13], v[12:13], 0, v[120:121]
	v_cvt_pk_bf16_f32 v10, v10, v11
	v_cvt_pk_bf16_f32 v11, v18, v19
	global_store_dwordx4 v[12:13], v[8:11], off
	s_nop 1
	v_pk_mul_f32 v[8:9], v[2:3], v[128:129] op_sel_hi:[1,0]
	v_pk_mul_f32 v[2:3], v[0:1], v[128:129] op_sel_hi:[1,0]
	v_cvt_pk_bf16_f32 v0, v4, v5
	v_cvt_pk_bf16_f32 v1, v6, v7
	s_nop 0
	v_cvt_pk_bf16_f32 v2, v2, v3
	v_cvt_pk_bf16_f32 v3, v8, v9
	global_store_dwordx4 v[12:13], v[0:3], off offset:256
	s_cbranch_vccz .LBB0_486
	s_waitcnt vmcnt(0)
	s_cmpk_gt_u32 s16, 0xff
	s_cbranch_scc1 .LBB0_497
	s_barrier

.LBB0_577:
	s_add_i32 s8, 0, 0x10000
	v_add_u32_e32 v12, s8, v215
	ds_read_b128 v[0:3], v12
	ds_read_b128 v[4:7], v12 offset:1024
	ds_read_b128 v[8:11], v12 offset:2048
	ds_read_b128 v[12:15], v12 offset:3072
	s_add_u32 s0, s0, 0x40080
	s_addc_u32 s1, s1, 0
	v_lshl_add_u64 v[48:49], s[0:1], 0, v[144:145]
	s_add_i32 m0, s16, 0xc000
	ds_read_b128 v[16:19], v217
	ds_read_b128 v[20:23], v217 offset:1024
	ds_read_b128 v[24:27], v217 offset:2048
	ds_read_b128 v[28:31], v217 offset:3072
	ds_read_b128 v[32:35], v217 offset:4096
	ds_read_b128 v[36:39], v217 offset:5120
	ds_read_b128 v[40:43], v217 offset:6144
	ds_read_b128 v[44:47], v217 offset:7168
	global_load_lds_dwordx4 v[48:49], off
	v_lshl_add_u64 v[48:49], s[0:1], 0, v[142:143]
	s_add_i32 m0, s16, 0xe000
	s_nop 0
	global_load_lds_dwordx4 v[48:49], off
	s_waitcnt lgkmcnt(8)
	s_barrier
	s_waitcnt lgkmcnt(0)
	s_waitcnt lgkmcnt(0)
	v_mfma_f32_16x16x32_bf16 v[56:59], v[0:3], v[24:27], 0
	v_mfma_f32_16x16x32_bf16 v[60:63], v[4:7], v[28:31], v[56:59]
	v_mfma_f32_16x16x32_bf16 v[56:59], v[8:11], v[24:27], 0
	v_mfma_f32_16x16x32_bf16 v[64:67], v[12:15], v[28:31], v[56:59]
	v_mfma_f32_16x16x32_bf16 v[56:59], v[0:3], v[32:35], 0
	v_mfma_f32_16x16x32_bf16 v[68:71], v[4:7], v[36:39], v[56:59]
	v_mfma_f32_16x16x32_bf16 v[56:59], v[8:11], v[32:35], 0
	v_mfma_f32_16x16x32_bf16 v[72:75], v[12:15], v[36:39], v[56:59]
	v_mfma_f32_16x16x32_bf16 v[56:59], v[0:3], v[40:43], 0
	v_mfma_f32_16x16x32_bf16 v[48:51], v[0:3], v[16:19], 0
	v_mfma_f32_16x16x32_bf16 v[52:55], v[8:11], v[16:19], 0
	v_mfma_f32_16x16x32_bf16 v[76:79], v[4:7], v[44:47], v[56:59]
	v_mfma_f32_16x16x32_bf16 v[56:59], v[8:11], v[40:43], 0
	v_mfma_f32_16x16x32_bf16 v[48:51], v[4:7], v[20:23], v[48:51]
	v_mfma_f32_16x16x32_bf16 v[52:55], v[12:15], v[20:23], v[52:55]
	v_mfma_f32_16x16x32_bf16 v[80:83], v[12:15], v[44:47], v[56:59]
	s_barrier
	s_add_i32 s9, 0, 0x14000
	s_add_i32 s0, s8, s15
	v_add_u32_e32 v92, s9, v215
	v_lshl_add_u64 v[132:133], s[70:71], 0, v[160:161]
	s_mov_b32 m0, s0
	ds_read_b128 v[56:59], v92
	ds_read_b128 v[84:87], v92 offset:1024
	ds_read_b128 v[88:91], v92 offset:2048
	ds_read_b128 v[92:95], v92 offset:3072
	global_load_lds_dwordx4 v[132:133], off
	v_lshl_add_u64 v[134:135], s[70:71], 0, v[140:141]
	s_add_i32 m0, s0, 0x2000
	s_nop 0
	global_load_lds_dwordx4 v[134:135], off
	s_barrier
	s_waitcnt lgkmcnt(0)
	s_waitcnt lgkmcnt(0)
	v_mfma_f32_16x16x32_bf16 v[96:99], v[56:59], v[16:19], 0
	v_mfma_f32_16x16x32_bf16 v[16:19], v[88:91], v[16:19], 0
	v_mfma_f32_16x16x32_bf16 v[96:99], v[84:87], v[20:23], v[96:99]
	v_mfma_f32_16x16x32_bf16 v[16:19], v[92:95], v[20:23], v[16:19]
	v_mfma_f32_16x16x32_bf16 v[20:23], v[56:59], v[24:27], 0
	v_mfma_f32_16x16x32_bf16 v[24:27], v[88:91], v[24:27], 0
	v_mfma_f32_16x16x32_bf16 v[20:23], v[84:87], v[28:31], v[20:23]
	v_mfma_f32_16x16x32_bf16 v[24:27], v[92:95], v[28:31], v[24:27]
	v_mfma_f32_16x16x32_bf16 v[28:31], v[56:59], v[32:35], 0
	v_mfma_f32_16x16x32_bf16 v[32:35], v[88:91], v[32:35], 0
	v_mfma_f32_16x16x32_bf16 v[28:31], v[84:87], v[36:39], v[28:31]
	v_mfma_f32_16x16x32_bf16 v[36:39], v[92:95], v[36:39], v[32:35]
	v_mfma_f32_16x16x32_bf16 v[32:35], v[56:59], v[40:43], 0
	v_mfma_f32_16x16x32_bf16 v[100:103], v[84:87], v[44:47], v[32:35]
	v_mfma_f32_16x16x32_bf16 v[32:35], v[88:91], v[40:43], 0
	v_mfma_f32_16x16x32_bf16 v[136:139], v[92:95], v[44:47], v[32:35]
	s_mov_b32 m0, s16
	v_lshl_add_u64 v[158:159], s[6:7], 0, v[144:145]
	s_barrier
	s_nop 2
	ds_read_b128 v[32:35], v217 offset:16384
	ds_read_b128 v[40:43], v217 offset:17408
	ds_read_b128 v[44:47], v217 offset:18432
	ds_read_b128 v[104:107], v217 offset:19456
	ds_read_b128 v[108:111], v217 offset:20480
	ds_read_b128 v[112:115], v217 offset:21504
	ds_read_b128 v[116:119], v217 offset:22528
	ds_read_b128 v[120:123], v217 offset:23552
	global_load_lds_dwordx4 v[158:159], off
	v_lshl_add_u64 v[242:243], s[6:7], 0, v[142:143]
	s_mov_b32 m0, s17
	s_nop 0
	global_load_lds_dwordx4 v[242:243], off
	s_barrier
	s_waitcnt lgkmcnt(0)
	s_waitcnt lgkmcnt(0)
	v_mfma_f32_16x16x32_bf16 v[124:127], v[0:3], v[32:35], 0
	v_mfma_f32_16x16x32_bf16 v[146:149], v[4:7], v[40:43], v[124:127]
	v_mfma_f32_16x16x32_bf16 v[124:127], v[8:11], v[32:35], 0
	v_mfma_f32_16x16x32_bf16 v[150:153], v[12:15], v[40:43], v[124:127]
	v_mfma_f32_16x16x32_bf16 v[124:127], v[0:3], v[44:47], 0
	v_mfma_f32_16x16x32_bf16 v[154:157], v[4:7], v[104:107], v[124:127]
	v_mfma_f32_16x16x32_bf16 v[124:127], v[8:11], v[44:47], 0
	v_mfma_f32_16x16x32_bf16 v[170:173], v[12:15], v[104:107], v[124:127]
	v_mfma_f32_16x16x32_bf16 v[124:127], v[0:3], v[108:111], 0
	v_mfma_f32_16x16x32_bf16 v[0:3], v[0:3], v[116:119], 0
	v_mfma_f32_16x16x32_bf16 v[174:177], v[4:7], v[112:115], v[124:127]
	v_mfma_f32_16x16x32_bf16 v[124:127], v[8:11], v[108:111], 0
	v_mfma_f32_16x16x32_bf16 v[0:3], v[4:7], v[120:123], v[0:3]
	v_mfma_f32_16x16x32_bf16 v[4:7], v[8:11], v[116:119], 0
	v_mfma_f32_16x16x32_bf16 v[178:181], v[12:15], v[112:115], v[124:127]
	v_mfma_f32_16x16x32_bf16 v[4:7], v[12:15], v[120:123], v[4:7]
	s_barrier
	s_add_u32 s0, s70, 0x8000
	s_addc_u32 s1, s71, 0
	s_add_i32 s8, s9, s15
	v_lshl_add_u64 v[8:9], s[0:1], 0, v[160:161]
	s_mov_b32 m0, s8
	s_nop 0
	global_load_lds_dwordx4 v[8:9], off
	v_lshl_add_u64 v[8:9], s[0:1], 0, v[140:141]
	s_add_i32 m0, s8, 0x2000
	s_nop 0
	global_load_lds_dwordx4 v[8:9], off
	s_waitcnt vmcnt(6)
	s_barrier
	v_mfma_f32_16x16x32_bf16 v[8:11], v[56:59], v[32:35], 0
	v_mfma_f32_16x16x32_bf16 v[12:15], v[84:87], v[40:43], v[8:11]
	v_mfma_f32_16x16x32_bf16 v[8:11], v[88:91], v[32:35], 0
	v_mfma_f32_16x16x32_bf16 v[182:185], v[92:95], v[40:43], v[8:11]
	v_mfma_f32_16x16x32_bf16 v[8:11], v[56:59], v[44:47], 0
	v_mfma_f32_16x16x32_bf16 v[186:189], v[84:87], v[104:107], v[8:11]
	v_mfma_f32_16x16x32_bf16 v[8:11], v[88:91], v[44:47], 0
	v_mfma_f32_16x16x32_bf16 v[190:193], v[92:95], v[104:107], v[8:11]
	v_mfma_f32_16x16x32_bf16 v[8:11], v[56:59], v[108:111], 0
	v_mfma_f32_16x16x32_bf16 v[194:197], v[84:87], v[112:115], v[8:11]
	v_mfma_f32_16x16x32_bf16 v[8:11], v[88:91], v[108:111], 0
	v_mfma_f32_16x16x32_bf16 v[198:201], v[92:95], v[112:115], v[8:11]
	v_mfma_f32_16x16x32_bf16 v[8:11], v[56:59], v[116:119], 0
	v_mfma_f32_16x16x32_bf16 v[202:205], v[84:87], v[120:123], v[8:11]
	v_mfma_f32_16x16x32_bf16 v[8:11], v[88:91], v[116:119], 0
	v_mfma_f32_16x16x32_bf16 v[206:209], v[92:95], v[120:123], v[8:11]
	s_add_i32 s8, 0, 0x18000
	s_nop 4
	v_add_u32_e32 v8, s8, v215
	s_barrier
	ds_read_b128 v[84:87], v8
	ds_read_b128 v[92:95], v8 offset:1024
	ds_read_b128 v[210:213], v8 offset:2048
	ds_read_b128 v[218:221], v8 offset:3072
	s_add_u32 s0, s6, 0x40000
	s_addc_u32 s1, s7, 0
	s_mov_b32 m0, s18
	v_lshl_add_u64 v[32:33], s[0:1], 0, v[144:145]
	ds_read_b128 v[8:11], v217 offset:32768
	ds_read_b128 v[44:47], v217 offset:33792
	ds_read_b128 v[88:91], v217 offset:34816
	ds_read_b128 v[108:111], v217 offset:35840
	ds_read_b128 v[222:225], v217 offset:36864
	ds_read_b128 v[226:229], v217 offset:37888
	ds_read_b128 v[230:233], v217 offset:38912
	ds_read_b128 v[234:237], v217 offset:39936
	global_load_lds_dwordx4 v[32:33], off
	v_lshl_add_u64 v[32:33], s[0:1], 0, v[142:143]
	s_mov_b32 m0, s19
	s_nop 0
	global_load_lds_dwordx4 v[32:33], off
	s_waitcnt lgkmcnt(8)
	s_barrier
	s_waitcnt lgkmcnt(0)
	s_waitcnt lgkmcnt(0)
	v_mfma_f32_16x16x32_bf16 v[32:35], v[84:87], v[8:11], v[48:51]
	v_mfma_f32_16x16x32_bf16 v[128:131], v[92:95], v[44:47], v[32:35]
	v_mfma_f32_16x16x32_bf16 v[32:35], v[210:213], v[8:11], v[52:55]
	v_mfma_f32_16x16x32_bf16 v[56:59], v[218:221], v[44:47], v[32:35]
	v_mfma_f32_16x16x32_bf16 v[32:35], v[84:87], v[88:91], v[60:63]
	v_mfma_f32_16x16x32_bf16 v[120:123], v[92:95], v[108:111], v[32:35]
	v_mfma_f32_16x16x32_bf16 v[32:35], v[210:213], v[88:91], v[64:67]
	v_mfma_f32_16x16x32_bf16 v[48:51], v[218:221], v[108:111], v[32:35]
	v_mfma_f32_16x16x32_bf16 v[32:35], v[84:87], v[222:225], v[68:71]
	v_mfma_f32_16x16x32_bf16 v[112:115], v[92:95], v[226:229], v[32:35]
	v_mfma_f32_16x16x32_bf16 v[32:35], v[210:213], v[222:225], v[72:75]
	v_mfma_f32_16x16x32_bf16 v[40:43], v[218:221], v[226:229], v[32:35]
	v_mfma_f32_16x16x32_bf16 v[32:35], v[84:87], v[230:233], v[76:79]
	v_mfma_f32_16x16x32_bf16 v[104:107], v[92:95], v[234:237], v[32:35]
	v_mfma_f32_16x16x32_bf16 v[32:35], v[210:213], v[230:233], v[80:83]
	v_mfma_f32_16x16x32_bf16 v[32:35], v[218:221], v[234:237], v[32:35]
	s_barrier
	s_add_i32 s9, 0, 0x1c000
	v_add_u32_e32 v52, s9, v215
	s_add_i32 s0, s8, s15
	ds_read_b128 v[68:71], v52
	ds_read_b128 v[72:75], v52 offset:1024
	ds_read_b128 v[76:79], v52 offset:2048
	ds_read_b128 v[238:241], v52 offset:3072
	v_lshl_add_u64 v[52:53], v[132:133], 0, s[92:93]
	s_mov_b32 m0, s0
	s_nop 0
	global_load_lds_dwordx4 v[52:53], off
	v_lshl_add_u64 v[52:53], v[134:135], 0, s[92:93]
	s_add_i32 m0, s0, 0x2000
	s_nop 0
	global_load_lds_dwordx4 v[52:53], off
	s_barrier
	s_waitcnt lgkmcnt(0)
	s_waitcnt lgkmcnt(0)
	v_mfma_f32_16x16x32_bf16 v[52:55], v[68:71], v[8:11], v[96:99]
	v_mfma_f32_16x16x32_bf16 v[8:11], v[76:79], v[8:11], v[16:19]
	v_mfma_f32_16x16x32_bf16 v[60:63], v[238:241], v[44:47], v[8:11]
	v_mfma_f32_16x16x32_bf16 v[8:11], v[68:71], v[88:91], v[20:23]
	v_mfma_f32_16x16x32_bf16 v[124:127], v[72:75], v[108:111], v[8:11]
	v_mfma_f32_16x16x32_bf16 v[8:11], v[76:79], v[88:91], v[24:27]
	v_mfma_f32_16x16x32_bf16 v[132:135], v[72:75], v[44:47], v[52:55]
	v_mfma_f32_16x16x32_bf16 v[52:55], v[238:241], v[108:111], v[8:11]
	v_mfma_f32_16x16x32_bf16 v[8:11], v[68:71], v[222:225], v[28:31]
	v_mfma_f32_16x16x32_bf16 v[116:119], v[72:75], v[226:229], v[8:11]
	v_mfma_f32_16x16x32_bf16 v[8:11], v[76:79], v[222:225], v[36:39]
	v_mfma_f32_16x16x32_bf16 v[44:47], v[238:241], v[226:229], v[8:11]
	v_mfma_f32_16x16x32_bf16 v[8:11], v[68:71], v[230:233], v[100:103]
	v_mfma_f32_16x16x32_bf16 v[108:111], v[72:75], v[234:237], v[8:11]
	v_mfma_f32_16x16x32_bf16 v[8:11], v[76:79], v[230:233], v[136:139]
	v_mfma_f32_16x16x32_bf16 v[36:39], v[238:241], v[234:237], v[8:11]
	s_mov_b32 m0, s45
	s_nop 4
	v_lshl_add_u64 v[8:9], v[158:159], 0, s[92:93]
	s_barrier
	ds_read_b128 v[20:23], v217 offset:49152
	ds_read_b128 v[28:31], v217 offset:50176
	ds_read_b128 v[136:139], v217 offset:51200
	ds_read_b128 v[222:225], v217 offset:52224
	ds_read_b128 v[226:229], v217 offset:53248
	ds_read_b128 v[230:233], v217 offset:54272
	ds_read_b128 v[234:237], v217 offset:55296
	ds_read_b128 v[248:251], v217 offset:56320
	global_load_lds_dwordx4 v[8:9], off
	v_lshl_add_u64 v[8:9], v[242:243], 0, s[92:93]
	s_mov_b32 m0, s48
	s_nop 0
	global_load_lds_dwordx4 v[8:9], off
	s_barrier
	s_waitcnt lgkmcnt(0)
	s_waitcnt lgkmcnt(0)
	v_mfma_f32_16x16x32_bf16 v[8:11], v[84:87], v[20:23], v[146:149]
	v_mfma_f32_16x16x32_bf16 v[96:99], v[92:95], v[28:31], v[8:11]
	v_mfma_f32_16x16x32_bf16 v[8:11], v[210:213], v[20:23], v[150:153]
	v_mfma_f32_16x16x32_bf16 v[24:27], v[218:221], v[28:31], v[8:11]
	v_mfma_f32_16x16x32_bf16 v[8:11], v[84:87], v[136:139], v[154:157]
	v_mfma_f32_16x16x32_bf16 v[88:91], v[92:95], v[222:225], v[8:11]
	v_mfma_f32_16x16x32_bf16 v[8:11], v[210:213], v[136:139], v[170:173]
	v_mfma_f32_16x16x32_bf16 v[16:19], v[218:221], v[222:225], v[8:11]
	v_mfma_f32_16x16x32_bf16 v[8:11], v[84:87], v[226:229], v[174:177]
	v_mfma_f32_16x16x32_bf16 v[0:3], v[84:87], v[234:237], v[0:3]
	v_mfma_f32_16x16x32_bf16 v[80:83], v[92:95], v[230:233], v[8:11]
	v_mfma_f32_16x16x32_bf16 v[8:11], v[210:213], v[226:229], v[178:181]
	v_mfma_f32_16x16x32_bf16 v[64:67], v[92:95], v[248:251], v[0:3]
	v_mfma_f32_16x16x32_bf16 v[0:3], v[210:213], v[234:237], v[4:7]
	v_mfma_f32_16x16x32_bf16 v[8:11], v[218:221], v[230:233], v[8:11]
	v_mfma_f32_16x16x32_bf16 v[0:3], v[218:221], v[248:251], v[0:3]
	s_barrier
	s_add_u32 s0, s70, 0x8080
	s_addc_u32 s1, s71, 0
	s_add_i32 s8, s9, s15
	v_lshl_add_u64 v[4:5], s[0:1], 0, v[160:161]
	s_mov_b32 m0, s8
	s_nop 0
	global_load_lds_dwordx4 v[4:5], off
	v_lshl_add_u64 v[4:5], s[0:1], 0, v[140:141]
	s_add_i32 m0, s8, 0x2000
	s_nop 0
	global_load_lds_dwordx4 v[4:5], off
	s_waitcnt vmcnt(6)
	s_barrier
	v_mfma_f32_16x16x32_bf16 v[4:7], v[68:71], v[20:23], v[12:15]
	v_mfma_f32_16x16x32_bf16 v[100:103], v[72:75], v[28:31], v[4:7]
	v_mfma_f32_16x16x32_bf16 v[4:7], v[76:79], v[20:23], v[182:185]
	v_mfma_f32_16x16x32_bf16 v[28:31], v[238:241], v[28:31], v[4:7]
	v_mfma_f32_16x16x32_bf16 v[4:7], v[68:71], v[136:139], v[186:189]
	v_mfma_f32_16x16x32_bf16 v[92:95], v[72:75], v[222:225], v[4:7]
	v_mfma_f32_16x16x32_bf16 v[4:7], v[76:79], v[136:139], v[190:193]
	v_mfma_f32_16x16x32_bf16 v[20:23], v[238:241], v[222:225], v[4:7]
	v_mfma_f32_16x16x32_bf16 v[4:7], v[68:71], v[226:229], v[194:197]
	v_mfma_f32_16x16x32_bf16 v[84:87], v[72:75], v[230:233], v[4:7]
	v_mfma_f32_16x16x32_bf16 v[4:7], v[76:79], v[226:229], v[198:201]
	v_mfma_f32_16x16x32_bf16 v[12:15], v[238:241], v[230:233], v[4:7]
	v_mfma_f32_16x16x32_bf16 v[4:7], v[68:71], v[234:237], v[202:205]
	v_mfma_f32_16x16x32_bf16 v[68:71], v[72:75], v[248:251], v[4:7]
	v_mfma_f32_16x16x32_bf16 v[4:7], v[76:79], v[234:237], v[206:209]
	v_mfma_f32_16x16x32_bf16 v[4:7], v[238:241], v[248:251], v[4:7]
	s_lshl_b32 s0, s46, 10
	v_lshl_or_b32 v146, s47, 7, v216
	s_ashr_i32 s47, s46, 31
	s_ashr_i32 s1, s0, 31
	s_lshl_b64 s[80:81], s[46:47], 25
	s_lshl_b64 s[0:1], s[0:1], 2
	s_add_u32 s8, s22, s0
	v_ashrrev_i32_e32 v147, 31, v146
	s_addc_u32 s9, s23, s1
	v_lshlrev_b64 v[136:137], 2, v[146:147]
	v_lshl_add_u64 v[148:149], s[8:9], 0, v[136:137]
	s_barrier
	global_load_dwordx4 v[76:79], v[148:149], off
	s_add_u32 s8, s24, s0
	s_addc_u32 s9, s25, s1
	v_lshl_add_u32 v210, s49, 8, v214
	s_add_u32 s0, s26, s0
	s_addc_u32 s1, s27, s1
	v_lshlrev_b64 v[158:159], 1, v[146:147]
	v_ashrrev_i32_e32 v211, 31, v210
	v_lshl_add_u64 v[152:153], s[0:1], 0, v[136:137]
	v_lshl_add_u64 v[188:189], s[50:51], 0, v[158:159]
	v_lshlrev_b64 v[154:155], 11, v[210:211]
	v_lshl_add_u64 v[150:151], s[8:9], 0, v[136:137]
	global_load_dwordx4 v[136:139], v[152:153], off
	v_lshl_add_u64 v[156:157], v[188:189], 0, v[154:155]
	global_load_dwordx2 v[186:187], v[156:157], off
	global_load_dwordx4 v[72:75], v[150:151], off
	s_mov_b32 s40, 0xc138aa3b
	s_mov_b32 s41, 0x3b808081
	v_or_b32_e32 v206, 16, v210
	v_ashrrev_i32_e32 v207, 31, v206
	v_lshlrev_b64 v[156:157], 11, v[206:207]
	v_lshl_add_u64 v[170:171], v[188:189], 0, v[156:157]
	global_load_dwordx2 v[212:213], v[170:171], off
	v_or_b32_e32 v202, 32, v210
	v_ashrrev_i32_e32 v203, 31, v202
	v_lshlrev_b64 v[170:171], 11, v[202:203]
	v_or_b32_e32 v198, 48, v210
	v_lshl_add_u64 v[172:173], v[188:189], 0, v[170:171]
	v_ashrrev_i32_e32 v199, 31, v198
	global_load_dwordx2 v[208:209], v[172:173], off
	v_lshlrev_b64 v[172:173], 11, v[198:199]
	v_add_u32_e32 v194, 0x80, v210
	v_lshl_add_u64 v[174:175], v[188:189], 0, v[172:173]
	v_ashrrev_i32_e32 v195, 31, v194
	global_load_dwordx2 v[204:205], v[174:175], off
	v_lshlrev_b64 v[174:175], 11, v[194:195]
	v_add_u32_e32 v190, 0x90, v210
	v_lshl_add_u64 v[176:177], v[188:189], 0, v[174:175]
	v_ashrrev_i32_e32 v191, 31, v190
	global_load_dwordx2 v[200:201], v[176:177], off
	v_lshlrev_b64 v[176:177], 11, v[190:191]
	v_add_u32_e32 v184, 0xa0, v210
	v_lshl_add_u64 v[178:179], v[188:189], 0, v[176:177]
	v_ashrrev_i32_e32 v185, 31, v184
	global_load_dwordx2 v[196:197], v[178:179], off
	v_lshlrev_b64 v[178:179], 11, v[184:185]
	v_add_u32_e32 v182, 0xb0, v210
	v_lshl_add_u64 v[180:181], v[188:189], 0, v[178:179]
	v_ashrrev_i32_e32 v183, 31, v182
	s_lshl_b64 s[0:1], s[46:47], 26
	global_load_dwordx2 v[192:193], v[180:181], off
	v_lshlrev_b64 v[180:181], 11, v[182:183]
	s_add_u32 s8, s36, s0
	v_lshl_add_u64 v[188:189], v[188:189], 0, v[180:181]
	s_addc_u32 s9, s58, s1
	global_load_dwordx2 v[188:189], v[188:189], off
	s_add_u32 s46, s20, s80
	s_addc_u32 s47, s21, s81
	s_andn2_b64 vcc, exec, s[4:5]
	s_mov_b32 s49, s76
	s_mov_b64 s[0:1], s[6:7]
	s_waitcnt vmcnt(0)
	v_add_f32_e32 v128, v128, v76
	v_mul_f32_e32 v128, 0xbfb8aa3b, v128
	v_exp_f32_e32 v128, v128
	v_add_f32_e32 v129, v129, v77
	v_mul_f32_e32 v129, 0xbfb8aa3b, v129
	v_exp_f32_e32 v129, v129
	v_add_f32_e32 v128, 1.0, v128
	v_rcp_f32_e32 v128, v128
	v_add_f32_e32 v130, v130, v78
	v_add_f32_e32 v129, 1.0, v129
	v_rcp_f32_e32 v129, v129
	v_mul_f32_e32 v128, 0x437f0000, v128
	v_rndne_f32_e32 v221, v128
	v_mov_b32_e32 v220, v136
	v_lshlrev_b32_e32 v219, 16, v186
	v_and_b32_e32 v222, 0xffff0000, v186
	v_lshlrev_b32_e32 v223, 16, v187
	v_and_b32_e32 v218, 0xffff0000, v187
	v_pk_mul_f32 v[186:187], v[220:221], s[40:41]
	v_add_f32_e32 v132, v132, v72
	v_mul_f32_e32 v128, v186, v187
	v_mul_f32_e32 v132, 0xbfb8aa3b, v132
	v_exp_f32_e32 v128, v128
	v_exp_f32_e32 v132, v132
	v_mul_f32_e32 v129, 0x437f0000, v129
	v_mov_b32_e32 v220, v137
	v_sub_f32_e32 v136, 1.0, v128
	v_add_f32_e32 v128, 1.0, v128
	v_add_f32_e32 v132, 1.0, v132
	v_mul_f32_e32 v128, v136, v128
	v_rcp_f32_e32 v132, v132
	v_sqrt_f32_e32 v128, v128
	v_cvt_u32_f32_e32 v136, v221
	v_rndne_f32_e32 v221, v129
	v_mul_f32_e32 v130, 0xbfb8aa3b, v130
	v_mul_f32_e32 v128, v132, v128
	v_add_f32_e32 v132, v133, v73
	v_mul_f32_e32 v132, 0xbfb8aa3b, v132
	v_exp_f32_e32 v132, v132
	v_exp_f32_e32 v130, v130
	v_add_f32_e32 v134, v134, v74
	v_mul_f32_e32 v134, 0xbfb8aa3b, v134
	v_add_f32_e32 v132, 1.0, v132
	v_rcp_f32_e32 v187, v132
	v_pk_mul_f32 v[132:133], v[220:221], s[40:41]
	v_add_f32_e32 v130, 1.0, v130
	v_mul_f32_e32 v129, v132, v133
	v_exp_f32_e32 v129, v129
	v_rcp_f32_e32 v130, v130
	v_mov_b32_e32 v220, v138
	v_exp_f32_e32 v134, v134
	v_sub_f32_e32 v133, 1.0, v129
	v_add_f32_e32 v129, 1.0, v129
	v_mul_f32_e32 v129, v133, v129
	v_cvt_u32_f32_e32 v133, v221
	v_mul_f32_e32 v130, 0x437f0000, v130
	v_rndne_f32_e32 v221, v130
	v_add_f32_e32 v134, 1.0, v134
	v_lshl_or_b32 v133, v133, 8, v136
	v_pk_mul_f32 v[136:137], v[220:221], s[40:41]
	v_rcp_f32_e32 v134, v134
	v_mul_f32_e32 v130, v136, v137
	v_exp_f32_e32 v130, v130
	v_sqrt_f32_e32 v129, v129
	v_add_f32_e32 v120, v120, v76
	v_mul_f32_e32 v120, 0xbfb8aa3b, v120
	v_sub_f32_e32 v137, 1.0, v130
	v_add_f32_e32 v130, 1.0, v130
	v_mul_f32_e32 v130, v137, v130
	v_sqrt_f32_e32 v130, v130
	v_mul_f32_e32 v129, v187, v129
	v_exp_f32_e32 v120, v120
	v_cvt_u32_f32_sdwa v138, v221 dst_sel:WORD_1 dst_unused:UNUSED_PAD src0_sel:DWORD
	v_mul_f32_e32 v130, v134, v130
	v_mul_f32_e32 v137, v130, v223
	v_add_f32_e32 v130, v131, v79
	v_mul_f32_e32 v130, 0xbfb8aa3b, v130
	v_exp_f32_e32 v130, v130
	v_add_f32_e32 v131, v135, v75
	v_mul_f32_e32 v131, 0xbfb8aa3b, v131
	v_exp_f32_e32 v131, v131
	v_add_f32_e32 v130, 1.0, v130
	v_rcp_f32_e32 v130, v130
	v_add_f32_e32 v120, 1.0, v120
	v_add_f32_e32 v131, 1.0, v131
	v_rcp_f32_e32 v187, v131
	v_mul_f32_e32 v130, 0x437f0000, v130
	v_rndne_f32_e32 v131, v130
	v_mov_b32_e32 v130, v139
	v_pk_mul_f32 v[134:135], v[130:131], s[40:41]
	v_rcp_f32_e32 v120, v120
	v_mul_f32_e32 v130, v134, v135
	v_exp_f32_e32 v130, v130
	v_mul_f32_e32 v128, v128, v219
	v_mul_f32_e32 v129, v129, v222
	v_mul_f32_e32 v120, 0x437f0000, v120
	v_sub_f32_e32 v135, 1.0, v130
	v_add_f32_e32 v130, 1.0, v130
	v_mul_f32_e32 v130, v135, v130
	v_sqrt_f32_e32 v130, v130
	v_rndne_f32_e32 v120, v120
	v_add_f32_e32 v121, v121, v77
	v_add_f32_e32 v124, v124, v72
	v_mul_f32_e32 v130, v187, v130
	v_mul_f32_e32 v135, v130, v218
	v_cvt_u32_f32_sdwa v130, v131 dst_sel:BYTE_3 dst_unused:UNUSED_PAD src0_sel:DWORD
	v_mul_f32_e32 v121, 0xbfb8aa3b, v121
	v_mul_f32_e32 v124, 0xbfb8aa3b, v124
	v_exp_f32_e32 v121, v121
	v_or3_b32 v133, v133, v138, v130
	v_cvt_pk_bf16_f32 v130, v128, v129
	v_lshl_add_u64 v[128:129], s[8:9], 0, v[154:155]
	v_cvt_pk_bf16_f32 v131, v137, v135
	v_lshlrev_b64 v[138:139], 10, v[210:211]
	v_lshl_add_u64 v[128:129], v[128:129], 0, v[158:159]
	global_store_dwordx2 v[128:129], v[130:131], off
	v_lshl_add_u64 v[130:131], s[46:47], 0, v[138:139]
	v_mul_f32_e32 v139, 0x3b808081, v120
	v_mul_f32_e32 v139, v186, v139
	v_exp_f32_e32 v139, v139
	v_exp_f32_e32 v124, v124
	v_add_f32_e32 v121, 1.0, v121
	v_rcp_f32_e32 v121, v121
	v_sub_f32_e32 v187, 1.0, v139
	v_add_f32_e32 v139, 1.0, v139
	v_add_f32_e32 v124, 1.0, v124
	v_mul_f32_e32 v139, v187, v139
	v_rcp_f32_e32 v124, v124
	v_sqrt_f32_e32 v139, v139
	v_lshl_add_u64 v[130:131], v[130:131], 0, v[146:147]
	v_mul_f32_e32 v121, 0x437f0000, v121
	global_store_dword v[130:131], v133, off
	v_lshlrev_b32_e32 v133, 16, v212
	v_mul_f32_e32 v124, v124, v139
	v_rndne_f32_e32 v121, v121
	v_mul_f32_e32 v124, v124, v133
	v_cvt_u32_f32_e32 v120, v120
	v_mul_f32_e32 v133, 0x3b808081, v121
	v_cvt_u32_f32_e32 v121, v121
	v_add_f32_e32 v125, v125, v73
	v_mul_f32_e32 v133, v132, v133
	v_mul_f32_e32 v125, 0xbfb8aa3b, v125
	v_lshl_or_b32 v120, v121, 8, v120
	v_add_f32_e32 v121, v122, v78
	v_mul_f32_e32 v121, 0xbfb8aa3b, v121
	v_exp_f32_e32 v121, v121
	v_exp_f32_e32 v133, v133
	v_exp_f32_e32 v125, v125
	v_add_f32_e32 v122, v126, v74
	v_add_f32_e32 v121, 1.0, v121
	v_rcp_f32_e32 v121, v121
	v_sub_f32_e32 v139, 1.0, v133
	v_add_f32_e32 v133, 1.0, v133
	v_add_f32_e32 v125, 1.0, v125
	v_mul_f32_e32 v121, 0x437f0000, v121
	v_rndne_f32_e32 v121, v121
	v_mul_f32_e32 v126, 0x3b808081, v121
	v_mul_f32_e32 v133, v139, v133
	v_mul_f32_e32 v126, v136, v126
	v_rcp_f32_e32 v125, v125
	v_sqrt_f32_e32 v133, v133
	v_mul_f32_e32 v122, 0xbfb8aa3b, v122
	v_exp_f32_e32 v126, v126
	v_exp_f32_e32 v122, v122
	v_mul_f32_e32 v125, v125, v133
	v_lshlrev_b32_e32 v137, 16, v213
	v_sub_f32_e32 v133, 1.0, v126
	v_add_f32_e32 v126, 1.0, v126
	v_add_f32_e32 v122, 1.0, v122
	v_mul_f32_e32 v126, v133, v126
	v_rcp_f32_e32 v122, v122
	v_sqrt_f32_e32 v126, v126
	v_add_f32_e32 v112, v112, v76
	v_mul_f32_e32 v112, 0xbfb8aa3b, v112
	v_exp_f32_e32 v112, v112
	v_mul_f32_e32 v122, v122, v126
	v_mul_f32_e32 v126, v122, v137
	v_add_f32_e32 v122, v123, v79
	v_mul_f32_e32 v122, 0xbfb8aa3b, v122
	v_exp_f32_e32 v122, v122
	v_add_f32_e32 v123, v127, v75
	v_add_f32_e32 v112, 1.0, v112
	v_rcp_f32_e32 v112, v112
	v_add_f32_e32 v122, 1.0, v122
	v_rcp_f32_e32 v122, v122
	v_mul_f32_e32 v123, 0xbfb8aa3b, v123
	v_mul_f32_e32 v112, 0x437f0000, v112
	v_rndne_f32_e32 v112, v112
	v_mul_f32_e32 v122, 0x437f0000, v122
	v_rndne_f32_e32 v122, v122
	v_mul_f32_e32 v127, 0x3b808081, v122
	v_mul_f32_e32 v127, v134, v127
	v_exp_f32_e32 v127, v127
	v_exp_f32_e32 v123, v123
	v_add_f32_e32 v113, v113, v77
	v_add_f32_e32 v116, v116, v72
	v_sub_f32_e32 v133, 1.0, v127
	v_add_f32_e32 v127, 1.0, v127
	v_mul_f32_e32 v127, v133, v127
	v_mul_f32_e32 v133, 0x3b808081, v112
	v_mul_f32_e32 v133, v186, v133
	v_mul_f32_e32 v113, 0xbfb8aa3b, v113
	v_mul_f32_e32 v116, 0xbfb8aa3b, v116
	v_exp_f32_e32 v133, v133
	v_exp_f32_e32 v113, v113
	v_exp_f32_e32 v116, v116
	v_add_f32_e32 v123, 1.0, v123
	v_and_b32_e32 v135, 0xffff0000, v212
	v_rcp_f32_e32 v123, v123
	v_sqrt_f32_e32 v127, v127
	v_mul_f32_e32 v125, v125, v135
	v_cvt_u32_f32_sdwa v121, v121 dst_sel:WORD_1 dst_unused:UNUSED_PAD src0_sel:DWORD
	v_cvt_u32_f32_sdwa v122, v122 dst_sel:BYTE_3 dst_unused:UNUSED_PAD src0_sel:DWORD
	v_sub_f32_e32 v135, 1.0, v133
	v_add_f32_e32 v133, 1.0, v133
	v_add_f32_e32 v113, 1.0, v113
	v_add_f32_e32 v116, 1.0, v116
	v_mul_f32_e32 v133, v135, v133
	v_rcp_f32_e32 v113, v113
	v_rcp_f32_e32 v116, v116
	v_sqrt_f32_e32 v133, v133
	v_and_b32_e32 v138, 0xffff0000, v213
	v_mul_f32_e32 v123, v123, v127
	v_mul_f32_e32 v123, v123, v138
	v_or3_b32 v127, v120, v121, v122
	v_lshl_add_u64 v[120:121], s[8:9], 0, v[156:157]
	v_cvt_pk_bf16_f32 v122, v124, v125
	v_cvt_pk_bf16_f32 v123, v126, v123
	v_lshlrev_b64 v[124:125], 10, v[206:207]
	v_lshl_add_u64 v[120:121], v[120:121], 0, v[158:159]
	v_mul_f32_e32 v113, 0x437f0000, v113
	global_store_dwordx2 v[120:121], v[122:123], off
	v_lshl_add_u64 v[122:123], s[46:47], 0, v[124:125]
	v_lshlrev_b32_e32 v124, 16, v208
	v_mul_f32_e32 v116, v116, v133
	v_rndne_f32_e32 v113, v113
	v_mul_f32_e32 v116, v116, v124
	v_cvt_u32_f32_e32 v112, v112
	v_mul_f32_e32 v124, 0x3b808081, v113
	v_cvt_u32_f32_e32 v113, v113
	v_add_f32_e32 v117, v117, v73
	v_mul_f32_e32 v124, v132, v124
	v_mul_f32_e32 v117, 0xbfb8aa3b, v117
	v_lshl_or_b32 v112, v113, 8, v112
	v_add_f32_e32 v113, v114, v78
	v_mul_f32_e32 v113, 0xbfb8aa3b, v113
	v_exp_f32_e32 v113, v113
	v_exp_f32_e32 v124, v124
	v_exp_f32_e32 v117, v117
	v_add_f32_e32 v114, v118, v74
	v_add_f32_e32 v113, 1.0, v113
	v_rcp_f32_e32 v113, v113
	v_sub_f32_e32 v133, 1.0, v124
	v_add_f32_e32 v124, 1.0, v124
	v_add_f32_e32 v117, 1.0, v117
	v_mul_f32_e32 v113, 0x437f0000, v113
	v_rndne_f32_e32 v113, v113
	v_mul_f32_e32 v118, 0x3b808081, v113
	v_mul_f32_e32 v124, v133, v124
	v_mul_f32_e32 v118, v136, v118
	v_rcp_f32_e32 v117, v117
	v_sqrt_f32_e32 v124, v124
	v_mul_f32_e32 v114, 0xbfb8aa3b, v114
	v_exp_f32_e32 v118, v118
	v_exp_f32_e32 v114, v114
	v_mul_f32_e32 v117, v117, v124
	v_lshlrev_b32_e32 v126, 16, v209
	v_sub_f32_e32 v124, 1.0, v118
	v_add_f32_e32 v118, 1.0, v118
	v_add_f32_e32 v114, 1.0, v114
	v_mul_f32_e32 v118, v124, v118
	v_rcp_f32_e32 v114, v114
	v_sqrt_f32_e32 v118, v118
	v_add_f32_e32 v104, v104, v76
	v_mul_f32_e32 v104, 0xbfb8aa3b, v104
	v_exp_f32_e32 v104, v104
	v_mul_f32_e32 v114, v114, v118
	v_mul_f32_e32 v118, v114, v126
	v_add_f32_e32 v114, v115, v79
	v_mul_f32_e32 v114, 0xbfb8aa3b, v114
	v_exp_f32_e32 v114, v114
	v_add_f32_e32 v115, v119, v75
	v_add_f32_e32 v104, 1.0, v104
	v_rcp_f32_e32 v104, v104
	v_add_f32_e32 v114, 1.0, v114
	v_rcp_f32_e32 v114, v114
	v_mul_f32_e32 v115, 0xbfb8aa3b, v115
	v_mul_f32_e32 v104, 0x437f0000, v104
	v_rndne_f32_e32 v104, v104
	v_mul_f32_e32 v114, 0x437f0000, v114
	v_rndne_f32_e32 v114, v114
	v_mul_f32_e32 v119, 0x3b808081, v114
	v_mul_f32_e32 v119, v134, v119
	v_exp_f32_e32 v119, v119
	v_exp_f32_e32 v115, v115
	v_add_f32_e32 v105, v105, v77
	v_add_f32_e32 v108, v108, v72
	v_sub_f32_e32 v124, 1.0, v119
	v_add_f32_e32 v119, 1.0, v119
	v_mul_f32_e32 v119, v124, v119
	v_mul_f32_e32 v124, 0x3b808081, v104
	v_mul_f32_e32 v124, v186, v124
	v_mul_f32_e32 v105, 0xbfb8aa3b, v105
	v_mul_f32_e32 v108, 0xbfb8aa3b, v108
	v_exp_f32_e32 v124, v124
	v_exp_f32_e32 v105, v105
	v_exp_f32_e32 v108, v108
	v_add_f32_e32 v115, 1.0, v115
	v_and_b32_e32 v125, 0xffff0000, v208
	v_rcp_f32_e32 v115, v115
	v_sqrt_f32_e32 v119, v119
	v_mul_f32_e32 v117, v117, v125
	v_cvt_u32_f32_sdwa v113, v113 dst_sel:WORD_1 dst_unused:UNUSED_PAD src0_sel:DWORD
	v_cvt_u32_f32_sdwa v114, v114 dst_sel:BYTE_3 dst_unused:UNUSED_PAD src0_sel:DWORD
	v_sub_f32_e32 v125, 1.0, v124
	v_add_f32_e32 v124, 1.0, v124
	v_add_f32_e32 v105, 1.0, v105
	v_add_f32_e32 v108, 1.0, v108
	v_mul_f32_e32 v124, v125, v124
	v_rcp_f32_e32 v105, v105
	v_lshl_add_u64 v[122:123], v[122:123], 0, v[146:147]
	v_rcp_f32_e32 v108, v108
	v_sqrt_f32_e32 v124, v124
	global_store_dword v[122:123], v127, off
	v_and_b32_e32 v127, 0xffff0000, v209
	v_mul_f32_e32 v115, v115, v119
	v_mul_f32_e32 v115, v115, v127
	v_or3_b32 v119, v112, v113, v114
	v_lshl_add_u64 v[112:113], s[8:9], 0, v[170:171]
	v_cvt_pk_bf16_f32 v114, v116, v117
	v_cvt_pk_bf16_f32 v115, v118, v115
	v_lshlrev_b64 v[116:117], 10, v[202:203]
	v_lshl_add_u64 v[112:113], v[112:113], 0, v[158:159]
	v_mul_f32_e32 v105, 0x437f0000, v105
	global_store_dwordx2 v[112:113], v[114:115], off
	v_lshl_add_u64 v[114:115], s[46:47], 0, v[116:117]
	v_lshlrev_b32_e32 v116, 16, v204
	v_mul_f32_e32 v108, v108, v124
	v_rndne_f32_e32 v105, v105
	v_mul_f32_e32 v108, v108, v116
	v_cvt_u32_f32_e32 v104, v104
	v_mul_f32_e32 v116, 0x3b808081, v105
	v_cvt_u32_f32_e32 v105, v105
	v_add_f32_e32 v109, v109, v73
	v_mul_f32_e32 v116, v132, v116
	v_mul_f32_e32 v109, 0xbfb8aa3b, v109
	v_lshl_or_b32 v104, v105, 8, v104
	v_add_f32_e32 v105, v106, v78
	v_mul_f32_e32 v105, 0xbfb8aa3b, v105
	v_exp_f32_e32 v105, v105
	v_exp_f32_e32 v116, v116
	v_exp_f32_e32 v109, v109
	v_add_f32_e32 v106, v110, v74
	v_add_f32_e32 v105, 1.0, v105
	v_rcp_f32_e32 v105, v105
	v_sub_f32_e32 v124, 1.0, v116
	v_add_f32_e32 v116, 1.0, v116
	v_add_f32_e32 v109, 1.0, v109
	v_mul_f32_e32 v105, 0x437f0000, v105
	v_rndne_f32_e32 v105, v105
	v_mul_f32_e32 v110, 0x3b808081, v105
	v_mul_f32_e32 v116, v124, v116
	v_mul_f32_e32 v110, v136, v110
	v_rcp_f32_e32 v109, v109
	v_sqrt_f32_e32 v116, v116
	v_mul_f32_e32 v106, 0xbfb8aa3b, v106
	v_exp_f32_e32 v110, v110
	v_exp_f32_e32 v106, v106
	v_mul_f32_e32 v109, v109, v116
	v_lshlrev_b32_e32 v118, 16, v205
	v_sub_f32_e32 v116, 1.0, v110
	v_add_f32_e32 v110, 1.0, v110
	v_add_f32_e32 v106, 1.0, v106
	v_mul_f32_e32 v110, v116, v110
	v_rcp_f32_e32 v106, v106
	v_sqrt_f32_e32 v110, v110
	v_add_f32_e32 v96, v96, v76
	v_mul_f32_e32 v96, 0xbfb8aa3b, v96
	v_exp_f32_e32 v96, v96
	v_mul_f32_e32 v106, v106, v110
	v_mul_f32_e32 v110, v106, v118
	v_add_f32_e32 v106, v107, v79
	v_mul_f32_e32 v106, 0xbfb8aa3b, v106
	v_exp_f32_e32 v106, v106
	v_add_f32_e32 v107, v111, v75
	v_add_f32_e32 v96, 1.0, v96
	v_rcp_f32_e32 v96, v96
	v_add_f32_e32 v106, 1.0, v106
	v_rcp_f32_e32 v106, v106
	v_mul_f32_e32 v107, 0xbfb8aa3b, v107
	v_mul_f32_e32 v96, 0x437f0000, v96
	v_rndne_f32_e32 v96, v96
	v_mul_f32_e32 v106, 0x437f0000, v106
	v_rndne_f32_e32 v106, v106
	v_mul_f32_e32 v111, 0x3b808081, v106
	v_mul_f32_e32 v111, v134, v111
	v_exp_f32_e32 v111, v111
	v_exp_f32_e32 v107, v107
	v_add_f32_e32 v97, v97, v77
	v_add_f32_e32 v100, v100, v72
	v_sub_f32_e32 v116, 1.0, v111
	v_add_f32_e32 v111, 1.0, v111
	v_mul_f32_e32 v111, v116, v111
	v_mul_f32_e32 v116, 0x3b808081, v96
	v_mul_f32_e32 v116, v186, v116
	v_mul_f32_e32 v97, 0xbfb8aa3b, v97
	v_mul_f32_e32 v100, 0xbfb8aa3b, v100
	v_exp_f32_e32 v116, v116
	v_exp_f32_e32 v97, v97
	v_exp_f32_e32 v100, v100
	v_add_f32_e32 v107, 1.0, v107
	v_and_b32_e32 v117, 0xffff0000, v204
	v_rcp_f32_e32 v107, v107
	v_sqrt_f32_e32 v111, v111
	v_mul_f32_e32 v109, v109, v117
	v_cvt_u32_f32_sdwa v105, v105 dst_sel:WORD_1 dst_unused:UNUSED_PAD src0_sel:DWORD
	v_cvt_u32_f32_sdwa v106, v106 dst_sel:BYTE_3 dst_unused:UNUSED_PAD src0_sel:DWORD
	v_sub_f32_e32 v117, 1.0, v116
	v_add_f32_e32 v116, 1.0, v116
	v_add_f32_e32 v97, 1.0, v97
	v_add_f32_e32 v100, 1.0, v100
	v_mul_f32_e32 v116, v117, v116
	v_rcp_f32_e32 v97, v97
	v_lshl_add_u64 v[114:115], v[114:115], 0, v[146:147]
	v_rcp_f32_e32 v100, v100
	v_sqrt_f32_e32 v116, v116
	global_store_dword v[114:115], v119, off
	v_and_b32_e32 v119, 0xffff0000, v205
	v_mul_f32_e32 v107, v107, v111
	v_mul_f32_e32 v107, v107, v119
	v_or3_b32 v111, v104, v105, v106
	v_lshl_add_u64 v[104:105], s[8:9], 0, v[172:173]
	v_cvt_pk_bf16_f32 v106, v108, v109
	v_cvt_pk_bf16_f32 v107, v110, v107
	v_lshlrev_b64 v[108:109], 10, v[198:199]
	v_lshl_add_u64 v[104:105], v[104:105], 0, v[158:159]
	v_mul_f32_e32 v97, 0x437f0000, v97
	global_store_dwordx2 v[104:105], v[106:107], off
	v_lshl_add_u64 v[106:107], s[46:47], 0, v[108:109]
	v_lshlrev_b32_e32 v108, 16, v200
	v_mul_f32_e32 v100, v100, v116
	v_rndne_f32_e32 v97, v97
	v_mul_f32_e32 v100, v100, v108
	v_cvt_u32_f32_e32 v96, v96
	v_mul_f32_e32 v108, 0x3b808081, v97
	v_cvt_u32_f32_e32 v97, v97
	v_add_f32_e32 v101, v101, v73
	v_mul_f32_e32 v108, v132, v108
	v_mul_f32_e32 v101, 0xbfb8aa3b, v101
	v_lshl_or_b32 v96, v97, 8, v96
	v_add_f32_e32 v97, v98, v78
	v_mul_f32_e32 v97, 0xbfb8aa3b, v97
	v_exp_f32_e32 v97, v97
	v_exp_f32_e32 v108, v108
	v_exp_f32_e32 v101, v101
	v_add_f32_e32 v98, v102, v74
	v_add_f32_e32 v97, 1.0, v97
	v_rcp_f32_e32 v97, v97
	v_sub_f32_e32 v116, 1.0, v108
	v_add_f32_e32 v108, 1.0, v108
	v_add_f32_e32 v101, 1.0, v101
	v_mul_f32_e32 v97, 0x437f0000, v97
	v_rndne_f32_e32 v97, v97
	v_mul_f32_e32 v102, 0x3b808081, v97
	v_mul_f32_e32 v108, v116, v108
	v_mul_f32_e32 v102, v136, v102
	v_rcp_f32_e32 v101, v101
	v_sqrt_f32_e32 v108, v108
	v_mul_f32_e32 v98, 0xbfb8aa3b, v98
	v_exp_f32_e32 v102, v102
	v_exp_f32_e32 v98, v98
	v_mul_f32_e32 v101, v101, v108
	v_lshlrev_b32_e32 v110, 16, v201
	v_sub_f32_e32 v108, 1.0, v102
	v_add_f32_e32 v102, 1.0, v102
	v_add_f32_e32 v98, 1.0, v98
	v_mul_f32_e32 v102, v108, v102
	v_rcp_f32_e32 v98, v98
	v_sqrt_f32_e32 v102, v102
	v_add_f32_e32 v88, v88, v76
	v_mul_f32_e32 v88, 0xbfb8aa3b, v88
	v_exp_f32_e32 v88, v88
	v_mul_f32_e32 v98, v98, v102
	v_mul_f32_e32 v102, v98, v110
	v_add_f32_e32 v98, v99, v79
	v_mul_f32_e32 v98, 0xbfb8aa3b, v98
	v_exp_f32_e32 v98, v98
	v_add_f32_e32 v99, v103, v75
	v_add_f32_e32 v88, 1.0, v88
	v_rcp_f32_e32 v88, v88
	v_add_f32_e32 v98, 1.0, v98
	v_rcp_f32_e32 v98, v98
	v_mul_f32_e32 v99, 0xbfb8aa3b, v99
	v_mul_f32_e32 v88, 0x437f0000, v88
	v_rndne_f32_e32 v88, v88
	v_mul_f32_e32 v98, 0x437f0000, v98
	v_rndne_f32_e32 v98, v98
	v_mul_f32_e32 v103, 0x3b808081, v98
	v_mul_f32_e32 v103, v134, v103
	v_exp_f32_e32 v103, v103
	v_exp_f32_e32 v99, v99
	v_add_f32_e32 v89, v89, v77
	v_add_f32_e32 v92, v92, v72
	v_sub_f32_e32 v108, 1.0, v103
	v_add_f32_e32 v103, 1.0, v103
	v_mul_f32_e32 v103, v108, v103
	v_mul_f32_e32 v108, 0x3b808081, v88
	v_mul_f32_e32 v108, v186, v108
	v_mul_f32_e32 v89, 0xbfb8aa3b, v89
	v_mul_f32_e32 v92, 0xbfb8aa3b, v92
	v_exp_f32_e32 v108, v108
	v_exp_f32_e32 v89, v89
	v_exp_f32_e32 v92, v92
	v_add_f32_e32 v99, 1.0, v99
	v_and_b32_e32 v109, 0xffff0000, v200
	v_rcp_f32_e32 v99, v99
	v_sqrt_f32_e32 v103, v103
	v_mul_f32_e32 v101, v101, v109
	v_cvt_u32_f32_sdwa v97, v97 dst_sel:WORD_1 dst_unused:UNUSED_PAD src0_sel:DWORD
	v_cvt_u32_f32_sdwa v98, v98 dst_sel:BYTE_3 dst_unused:UNUSED_PAD src0_sel:DWORD
	v_sub_f32_e32 v109, 1.0, v108
	v_add_f32_e32 v108, 1.0, v108
	v_add_f32_e32 v89, 1.0, v89
	v_add_f32_e32 v92, 1.0, v92
	v_mul_f32_e32 v108, v109, v108
	v_rcp_f32_e32 v89, v89
	v_lshl_add_u64 v[106:107], v[106:107], 0, v[146:147]
	v_rcp_f32_e32 v92, v92
	v_sqrt_f32_e32 v108, v108
	global_store_dword v[106:107], v111, off
	v_and_b32_e32 v111, 0xffff0000, v201
	v_mul_f32_e32 v99, v99, v103
	v_mul_f32_e32 v99, v99, v111
	v_or3_b32 v103, v96, v97, v98
	v_lshl_add_u64 v[96:97], s[8:9], 0, v[174:175]
	v_cvt_pk_bf16_f32 v98, v100, v101
	v_cvt_pk_bf16_f32 v99, v102, v99
	v_lshlrev_b64 v[100:101], 10, v[194:195]
	v_lshl_add_u64 v[96:97], v[96:97], 0, v[158:159]
	v_mul_f32_e32 v89, 0x437f0000, v89
	global_store_dwordx2 v[96:97], v[98:99], off
	v_lshl_add_u64 v[98:99], s[46:47], 0, v[100:101]
	v_lshlrev_b32_e32 v100, 16, v196
	v_mul_f32_e32 v92, v92, v108
	v_rndne_f32_e32 v89, v89
	v_mul_f32_e32 v92, v92, v100
	v_cvt_u32_f32_e32 v88, v88
	v_mul_f32_e32 v100, 0x3b808081, v89
	v_cvt_u32_f32_e32 v89, v89
	v_add_f32_e32 v93, v93, v73
	v_mul_f32_e32 v100, v132, v100
	v_mul_f32_e32 v93, 0xbfb8aa3b, v93
	v_lshl_or_b32 v88, v89, 8, v88
	v_add_f32_e32 v89, v90, v78
	v_mul_f32_e32 v89, 0xbfb8aa3b, v89
	v_exp_f32_e32 v89, v89
	v_exp_f32_e32 v100, v100
	v_exp_f32_e32 v93, v93
	v_add_f32_e32 v90, v94, v74
	v_add_f32_e32 v89, 1.0, v89
	v_rcp_f32_e32 v89, v89
	v_sub_f32_e32 v108, 1.0, v100
	v_add_f32_e32 v100, 1.0, v100
	v_add_f32_e32 v93, 1.0, v93
	v_mul_f32_e32 v89, 0x437f0000, v89
	v_rndne_f32_e32 v89, v89
	v_mul_f32_e32 v94, 0x3b808081, v89
	v_mul_f32_e32 v100, v108, v100
	v_mul_f32_e32 v94, v136, v94
	v_rcp_f32_e32 v93, v93
	v_sqrt_f32_e32 v100, v100
	v_mul_f32_e32 v90, 0xbfb8aa3b, v90
	v_exp_f32_e32 v94, v94
	v_exp_f32_e32 v90, v90
	v_mul_f32_e32 v93, v93, v100
	v_lshlrev_b32_e32 v102, 16, v197
	v_sub_f32_e32 v100, 1.0, v94
	v_add_f32_e32 v94, 1.0, v94
	v_add_f32_e32 v90, 1.0, v90
	v_mul_f32_e32 v94, v100, v94
	v_rcp_f32_e32 v90, v90
	v_sqrt_f32_e32 v94, v94
	v_add_f32_e32 v80, v80, v76
	v_mul_f32_e32 v80, 0xbfb8aa3b, v80
	v_exp_f32_e32 v80, v80
	v_mul_f32_e32 v90, v90, v94
	v_mul_f32_e32 v94, v90, v102
	v_add_f32_e32 v90, v91, v79
	v_mul_f32_e32 v90, 0xbfb8aa3b, v90
	v_exp_f32_e32 v90, v90
	v_add_f32_e32 v91, v95, v75
	v_add_f32_e32 v80, 1.0, v80
	v_rcp_f32_e32 v80, v80
	v_add_f32_e32 v90, 1.0, v90
	v_rcp_f32_e32 v90, v90
	v_mul_f32_e32 v91, 0xbfb8aa3b, v91
	v_mul_f32_e32 v80, 0x437f0000, v80
	v_rndne_f32_e32 v80, v80
	v_mul_f32_e32 v90, 0x437f0000, v90
	v_rndne_f32_e32 v90, v90
	v_mul_f32_e32 v95, 0x3b808081, v90
	v_mul_f32_e32 v95, v134, v95
	v_exp_f32_e32 v95, v95
	v_exp_f32_e32 v91, v91
	v_add_f32_e32 v81, v81, v77
	v_add_f32_e32 v84, v84, v72
	v_sub_f32_e32 v100, 1.0, v95
	v_add_f32_e32 v95, 1.0, v95
	v_mul_f32_e32 v95, v100, v95
	v_mul_f32_e32 v100, 0x3b808081, v80
	v_mul_f32_e32 v100, v186, v100
	v_mul_f32_e32 v81, 0xbfb8aa3b, v81
	v_mul_f32_e32 v84, 0xbfb8aa3b, v84
	v_exp_f32_e32 v100, v100
	v_exp_f32_e32 v81, v81
	v_exp_f32_e32 v84, v84
	v_add_f32_e32 v91, 1.0, v91
	v_and_b32_e32 v101, 0xffff0000, v196
	v_rcp_f32_e32 v91, v91
	v_sqrt_f32_e32 v95, v95
	v_mul_f32_e32 v93, v93, v101
	v_cvt_u32_f32_sdwa v89, v89 dst_sel:WORD_1 dst_unused:UNUSED_PAD src0_sel:DWORD
	v_cvt_u32_f32_sdwa v90, v90 dst_sel:BYTE_3 dst_unused:UNUSED_PAD src0_sel:DWORD
	v_sub_f32_e32 v101, 1.0, v100
	v_add_f32_e32 v100, 1.0, v100
	v_add_f32_e32 v81, 1.0, v81
	v_add_f32_e32 v84, 1.0, v84
	v_mul_f32_e32 v100, v101, v100
	v_rcp_f32_e32 v81, v81
	v_add_f32_e32 v64, v64, v76
	v_lshl_add_u64 v[98:99], v[98:99], 0, v[146:147]
	v_rcp_f32_e32 v84, v84
	v_sqrt_f32_e32 v100, v100
	v_mul_f32_e32 v64, 0xbfb8aa3b, v64
	global_store_dword v[98:99], v103, off
	v_and_b32_e32 v103, 0xffff0000, v197
	v_mul_f32_e32 v91, v91, v95
	v_exp_f32_e32 v64, v64
	v_mul_f32_e32 v91, v91, v103
	v_or3_b32 v95, v88, v89, v90
	v_lshl_add_u64 v[88:89], s[8:9], 0, v[176:177]
	v_cvt_pk_bf16_f32 v90, v92, v93
	v_cvt_pk_bf16_f32 v91, v94, v91
	v_lshlrev_b64 v[92:93], 10, v[190:191]
	v_lshl_add_u64 v[88:89], v[88:89], 0, v[158:159]
	v_mul_f32_e32 v81, 0x437f0000, v81
	global_store_dwordx2 v[88:89], v[90:91], off
	v_lshl_add_u64 v[90:91], s[46:47], 0, v[92:93]
	v_lshlrev_b32_e32 v92, 16, v192
	v_mul_f32_e32 v84, v84, v100
	v_rndne_f32_e32 v81, v81
	v_mul_f32_e32 v84, v84, v92
	v_cvt_u32_f32_e32 v80, v80
	v_mul_f32_e32 v92, 0x3b808081, v81
	v_cvt_u32_f32_e32 v81, v81
	v_add_f32_e32 v64, 1.0, v64
	v_rcp_f32_e32 v64, v64
	v_add_f32_e32 v65, v65, v77
	v_lshl_or_b32 v80, v81, 8, v80
	v_add_f32_e32 v81, v82, v78
	v_mul_f32_e32 v81, 0xbfb8aa3b, v81
	v_mul_f32_e32 v64, 0x437f0000, v64
	v_exp_f32_e32 v81, v81
	v_rndne_f32_e32 v64, v64
	v_add_f32_e32 v68, v68, v72
	v_mul_f32_e32 v72, 0x3b808081, v64
	v_mul_f32_e32 v65, 0xbfb8aa3b, v65
	v_mul_f32_e32 v72, v186, v72
	v_exp_f32_e32 v65, v65
	v_mul_f32_e32 v68, 0xbfb8aa3b, v68
	v_exp_f32_e32 v72, v72
	v_add_f32_e32 v81, 1.0, v81
	v_exp_f32_e32 v68, v68
	v_rcp_f32_e32 v81, v81
	v_add_f32_e32 v85, v85, v73
	v_mul_f32_e32 v92, v132, v92
	v_add_f32_e32 v65, 1.0, v65
	v_mul_f32_e32 v85, 0xbfb8aa3b, v85
	v_exp_f32_e32 v92, v92
	v_sub_f32_e32 v76, 1.0, v72
	v_add_f32_e32 v72, 1.0, v72
	v_rcp_f32_e32 v65, v65
	v_exp_f32_e32 v85, v85
	v_add_f32_e32 v68, 1.0, v68
	v_mul_f32_e32 v72, v76, v72
	v_mul_f32_e32 v81, 0x437f0000, v81
	v_rcp_f32_e32 v68, v68
	v_sqrt_f32_e32 v72, v72
	v_rndne_f32_e32 v81, v81
	v_sub_f32_e32 v100, 1.0, v92
	v_add_f32_e32 v92, 1.0, v92
	v_add_f32_e32 v82, v86, v74
	v_mul_f32_e32 v86, 0x3b808081, v81
	v_mul_f32_e32 v65, 0x437f0000, v65
	v_add_f32_e32 v85, 1.0, v85
	v_mul_f32_e32 v92, v100, v92
	v_mul_f32_e32 v86, v136, v86
	v_rndne_f32_e32 v65, v65
	v_rcp_f32_e32 v85, v85
	v_sqrt_f32_e32 v92, v92
	v_mul_f32_e32 v82, 0xbfb8aa3b, v82
	v_exp_f32_e32 v86, v86
	v_mul_f32_e32 v68, v68, v72
	v_cvt_u32_f32_e32 v64, v64
	v_mul_f32_e32 v72, 0x3b808081, v65
	v_cvt_u32_f32_e32 v65, v65
	v_exp_f32_e32 v82, v82
	v_mul_f32_e32 v85, v85, v92
	v_sub_f32_e32 v92, 1.0, v86
	v_add_f32_e32 v86, 1.0, v86
	v_lshl_or_b32 v64, v65, 8, v64
	v_add_f32_e32 v65, v66, v78
	v_add_f32_e32 v82, 1.0, v82
	v_mul_f32_e32 v86, v92, v86
	v_mul_f32_e32 v65, 0xbfb8aa3b, v65
	v_rcp_f32_e32 v82, v82
	v_sqrt_f32_e32 v86, v86
	v_exp_f32_e32 v65, v65
	v_lshlrev_b32_e32 v94, 16, v193
	v_add_f32_e32 v69, v69, v73
	v_mul_f32_e32 v82, v82, v86
	v_add_f32_e32 v65, 1.0, v65
	v_mul_f32_e32 v86, v82, v94
	v_add_f32_e32 v82, v83, v79
	v_rcp_f32_e32 v65, v65
	v_mul_f32_e32 v82, 0xbfb8aa3b, v82
	v_mul_f32_e32 v72, v132, v72
	v_exp_f32_e32 v82, v82
	v_mul_f32_e32 v69, 0xbfb8aa3b, v69
	v_exp_f32_e32 v72, v72
	v_exp_f32_e32 v69, v69
	v_mul_f32_e32 v65, 0x437f0000, v65
	v_rndne_f32_e32 v65, v65
	v_add_f32_e32 v67, v67, v79
	v_add_f32_e32 v82, 1.0, v82
	v_sub_f32_e32 v73, 1.0, v72
	v_add_f32_e32 v72, 1.0, v72
	v_add_f32_e32 v66, v70, v74
	v_mul_f32_e32 v70, 0x3b808081, v65
	v_mul_f32_e32 v67, 0xbfb8aa3b, v67
	v_rcp_f32_e32 v82, v82
	v_add_f32_e32 v69, 1.0, v69
	v_mul_f32_e32 v72, v73, v72
	v_mul_f32_e32 v70, v136, v70
	v_exp_f32_e32 v67, v67
	v_rcp_f32_e32 v69, v69
	v_sqrt_f32_e32 v72, v72
	v_mul_f32_e32 v66, 0xbfb8aa3b, v66
	v_exp_f32_e32 v70, v70
	v_exp_f32_e32 v66, v66
	v_mul_f32_e32 v82, 0x437f0000, v82
	v_add_f32_e32 v67, 1.0, v67
	v_rndne_f32_e32 v82, v82
	v_mul_f32_e32 v69, v69, v72
	v_sub_f32_e32 v72, 1.0, v70
	v_add_f32_e32 v70, 1.0, v70
	v_rcp_f32_e32 v67, v67
	v_add_f32_e32 v83, v87, v75
	v_mul_f32_e32 v87, 0x3b808081, v82
	v_add_f32_e32 v66, 1.0, v66
	v_mul_f32_e32 v70, v72, v70
	v_mul_f32_e32 v87, v134, v87
	v_rcp_f32_e32 v66, v66
	v_sqrt_f32_e32 v70, v70
	v_mul_f32_e32 v83, 0xbfb8aa3b, v83
	v_exp_f32_e32 v87, v87
	v_exp_f32_e32 v83, v83
	v_mul_f32_e32 v67, 0x437f0000, v67
	v_rndne_f32_e32 v67, v67
	v_mul_f32_e32 v66, v66, v70
	v_add_f32_e32 v70, v71, v75
	v_mul_f32_e32 v71, 0x3b808081, v67
	v_sub_f32_e32 v92, 1.0, v87
	v_add_f32_e32 v87, 1.0, v87
	v_mul_f32_e32 v71, v134, v71
	v_add_f32_e32 v83, 1.0, v83
	v_mul_f32_e32 v87, v92, v87
	v_mul_f32_e32 v70, 0xbfb8aa3b, v70
	v_exp_f32_e32 v71, v71
	v_rcp_f32_e32 v83, v83
	v_sqrt_f32_e32 v87, v87
	v_exp_f32_e32 v70, v70
	v_cvt_u32_f32_sdwa v81, v81 dst_sel:WORD_1 dst_unused:UNUSED_PAD src0_sel:DWORD
	v_cvt_u32_f32_sdwa v82, v82 dst_sel:BYTE_3 dst_unused:UNUSED_PAD src0_sel:DWORD
	v_lshl_add_u64 v[90:91], v[90:91], 0, v[146:147]
	v_sub_f32_e32 v72, 1.0, v71
	v_add_f32_e32 v71, 1.0, v71
	global_store_dword v[90:91], v95, off
	v_and_b32_e32 v93, 0xffff0000, v192
	v_and_b32_e32 v95, 0xffff0000, v193
	v_mul_f32_e32 v83, v83, v87
	v_add_f32_e32 v70, 1.0, v70
	v_mul_f32_e32 v71, v72, v71
	v_mul_f32_e32 v85, v85, v93
	v_mul_f32_e32 v83, v83, v95
	v_or3_b32 v87, v80, v81, v82
	v_lshl_add_u64 v[80:81], s[8:9], 0, v[178:179]
	v_cvt_u32_f32_sdwa v65, v65 dst_sel:WORD_1 dst_unused:UNUSED_PAD src0_sel:DWORD
	v_rcp_f32_e32 v70, v70
	v_sqrt_f32_e32 v71, v71
	v_cvt_u32_f32_sdwa v67, v67 dst_sel:BYTE_3 dst_unused:UNUSED_PAD src0_sel:DWORD
	v_cvt_pk_bf16_f32 v82, v84, v85
	v_cvt_pk_bf16_f32 v83, v86, v83
	v_lshlrev_b64 v[84:85], 10, v[184:185]
	v_lshl_add_u64 v[80:81], v[80:81], 0, v[158:159]
	global_store_dwordx2 v[80:81], v[82:83], off
	v_lshl_add_u64 v[82:83], s[46:47], 0, v[84:85]
	v_lshlrev_b32_e32 v84, 16, v188
	v_and_b32_e32 v85, 0xffff0000, v188
	v_lshl_add_u64 v[82:83], v[82:83], 0, v[146:147]
	v_lshlrev_b32_e32 v86, 16, v189
	v_mul_f32_e32 v68, v68, v84
	v_mul_f32_e32 v69, v69, v85
	global_store_dword v[82:83], v87, off
	v_and_b32_e32 v87, 0xffff0000, v189
	v_mul_f32_e32 v66, v66, v86
	v_mul_f32_e32 v70, v70, v71
	v_or3_b32 v71, v64, v65, v67
	v_cvt_pk_bf16_f32 v64, v68, v69
	v_lshl_add_u64 v[68:69], s[8:9], 0, v[180:181]
	v_mul_f32_e32 v70, v70, v87
	v_cvt_pk_bf16_f32 v65, v66, v70
	v_lshlrev_b64 v[66:67], 10, v[182:183]
	v_lshl_add_u64 v[76:77], v[68:69], 0, v[158:159]
	global_store_dwordx2 v[76:77], v[64:65], off
	v_lshl_add_u64 v[64:65], s[46:47], 0, v[66:67]
	v_lshl_add_u64 v[78:79], v[64:65], 0, v[146:147]
	global_store_dword v[78:79], v71, off
	global_load_dwordx4 v[68:71], v[148:149], off offset:16
	s_nop 0
	global_load_dwordx4 v[64:67], v[150:151], off offset:16
	global_load_dwordx4 v[72:75], v[152:153], off offset:16
	v_or_b32_e32 v84, 4, v146
	v_ashrrev_i32_e32 v85, 31, v84
	v_lshl_add_u64 v[86:87], s[50:51], 0, v[154:155]
	v_lshlrev_b64 v[84:85], 1, v[84:85]
	v_lshl_add_u64 v[86:87], v[86:87], 0, v[84:85]
	global_load_dwordx2 v[86:87], v[86:87], off
	v_lshl_add_u64 v[92:93], s[50:51], 0, v[156:157]
	v_lshl_add_u64 v[92:93], v[92:93], 0, v[84:85]
	global_load_dwordx2 v[110:111], v[92:93], off
	v_lshl_add_u64 v[92:93], s[50:51], 0, v[170:171]
	v_lshl_add_u64 v[92:93], v[92:93], 0, v[84:85]
	global_load_dwordx2 v[108:109], v[92:93], off
	v_lshl_add_u64 v[92:93], s[50:51], 0, v[172:173]
	v_lshl_add_u64 v[92:93], v[92:93], 0, v[84:85]
	global_load_dwordx2 v[102:103], v[92:93], off
	v_lshl_add_u64 v[92:93], s[50:51], 0, v[174:175]
	v_lshl_add_u64 v[92:93], v[92:93], 0, v[84:85]
	global_load_dwordx2 v[100:101], v[92:93], off
	v_lshl_add_u64 v[92:93], s[50:51], 0, v[176:177]
	v_lshl_add_u64 v[92:93], v[92:93], 0, v[84:85]
	global_load_dwordx2 v[94:95], v[92:93], off
	v_lshl_add_u64 v[92:93], s[50:51], 0, v[178:179]
	v_lshl_add_u64 v[116:117], s[50:51], 0, v[180:181]
	v_lshl_add_u64 v[92:93], v[92:93], 0, v[84:85]
	v_lshl_add_u64 v[84:85], v[116:117], 0, v[84:85]
	global_load_dwordx2 v[84:85], v[84:85], off
	s_mov_b32 s47, s74
	global_load_dwordx2 v[92:93], v[92:93], off
	s_mov_b32 s46, s78
	s_waitcnt vmcnt(0)
	v_add_f32_e32 v56, v56, v68
	v_mul_f32_e32 v56, 0xbfb8aa3b, v56
	v_exp_f32_e32 v56, v56
	v_mov_b32_e32 v116, v72
	v_add_f32_e32 v60, v60, v64
	v_mul_f32_e32 v60, 0xbfb8aa3b, v60
	v_add_f32_e32 v56, 1.0, v56
	v_rcp_f32_e32 v56, v56
	v_lshlrev_b32_e32 v118, 16, v86
	v_and_b32_e32 v119, 0xffff0000, v86
	v_lshlrev_b32_e32 v124, 16, v87
	v_mul_f32_e32 v56, 0x437f0000, v56
	v_rndne_f32_e32 v117, v56
	v_and_b32_e32 v125, 0xffff0000, v87
	v_pk_mul_f32 v[86:87], v[116:117], s[40:41]
	v_exp_f32_e32 v60, v60
	v_mul_f32_e32 v56, v86, v87
	v_exp_f32_e32 v56, v56
	v_add_f32_e32 v58, v58, v70
	v_add_f32_e32 v60, 1.0, v60
	v_rcp_f32_e32 v60, v60
	v_sub_f32_e32 v72, 1.0, v56
	v_add_f32_e32 v56, 1.0, v56
	v_mul_f32_e32 v56, v72, v56
	v_sqrt_f32_e32 v56, v56
	v_mul_f32_e32 v58, 0xbfb8aa3b, v58
	v_cvt_u32_f32_e32 v72, v117
	v_exp_f32_e32 v58, v58
	v_mul_f32_e32 v56, v60, v56
	v_mul_f32_e32 v87, v56, v118
	v_add_f32_e32 v56, v57, v69
	v_mul_f32_e32 v56, 0xbfb8aa3b, v56
	v_exp_f32_e32 v56, v56
	v_add_f32_e32 v57, v61, v65
	v_mul_f32_e32 v57, 0xbfb8aa3b, v57
	v_exp_f32_e32 v57, v57
	v_add_f32_e32 v56, 1.0, v56
	v_rcp_f32_e32 v56, v56
	v_mov_b32_e32 v60, v73
	v_add_f32_e32 v57, 1.0, v57
	v_rcp_f32_e32 v116, v57
	v_mul_f32_e32 v56, 0x437f0000, v56
	v_rndne_f32_e32 v61, v56
	v_pk_mul_f32 v[56:57], v[60:61], s[40:41]
	v_add_f32_e32 v58, 1.0, v58
	v_mul_f32_e32 v57, v56, v57
	v_exp_f32_e32 v57, v57
	v_rcp_f32_e32 v58, v58
	v_add_f32_e32 v48, v48, v68
	v_mul_f32_e32 v48, 0xbfb8aa3b, v48
	v_sub_f32_e32 v60, 1.0, v57
	v_add_f32_e32 v57, 1.0, v57
	v_mul_f32_e32 v57, v60, v57
	v_sqrt_f32_e32 v57, v57
	v_cvt_u32_f32_e32 v60, v61
	v_mul_f32_e32 v58, 0x437f0000, v58
	v_rndne_f32_e32 v73, v58
	v_mul_f32_e32 v57, v116, v57
	v_lshl_or_b32 v116, v60, 8, v72
	v_add_f32_e32 v60, v62, v66
	v_mul_f32_e32 v60, 0xbfb8aa3b, v60
	v_exp_f32_e32 v60, v60
	v_mov_b32_e32 v72, v74
	v_exp_f32_e32 v48, v48
	v_mul_f32_e32 v57, v57, v119
	v_add_f32_e32 v60, 1.0, v60
	v_rcp_f32_e32 v62, v60
	v_pk_mul_f32 v[60:61], v[72:73], s[40:41]
	v_cvt_u32_f32_sdwa v72, v73 dst_sel:WORD_1 dst_unused:UNUSED_PAD src0_sel:DWORD
	v_mul_f32_e32 v58, v60, v61
	v_exp_f32_e32 v58, v58
	v_add_f32_e32 v48, 1.0, v48
	v_rcp_f32_e32 v48, v48
	v_add_f32_e32 v49, v49, v69
	v_sub_f32_e32 v61, 1.0, v58
	v_add_f32_e32 v58, 1.0, v58
	v_mul_f32_e32 v58, v61, v58
	v_sqrt_f32_e32 v58, v58
	v_mul_f32_e32 v48, 0x437f0000, v48
	v_rndne_f32_e32 v48, v48
	v_add_f32_e32 v52, v52, v64
	v_mul_f32_e32 v58, v62, v58
	v_mul_f32_e32 v61, v58, v124
	v_add_f32_e32 v58, v59, v71
	v_mul_f32_e32 v58, 0xbfb8aa3b, v58
	v_exp_f32_e32 v58, v58
	v_add_f32_e32 v59, v63, v67
	v_mul_f32_e32 v59, 0xbfb8aa3b, v59
	v_exp_f32_e32 v59, v59
	v_add_f32_e32 v58, 1.0, v58
	v_rcp_f32_e32 v58, v58
	v_mov_b32_e32 v62, v75
	v_add_f32_e32 v59, 1.0, v59
	v_rcp_f32_e32 v73, v59
	v_mul_f32_e32 v58, 0x437f0000, v58
	v_rndne_f32_e32 v63, v58
	v_pk_mul_f32 v[58:59], v[62:63], s[40:41]
	v_mul_f32_e32 v49, 0xbfb8aa3b, v49
	v_mul_f32_e32 v59, v58, v59
	v_exp_f32_e32 v59, v59
	v_mul_f32_e32 v52, 0xbfb8aa3b, v52
	v_exp_f32_e32 v49, v49
	v_exp_f32_e32 v52, v52
	v_sub_f32_e32 v62, 1.0, v59
	v_add_f32_e32 v59, 1.0, v59
	v_mul_f32_e32 v59, v62, v59
	v_sqrt_f32_e32 v59, v59
	v_cvt_u32_f32_sdwa v62, v63 dst_sel:BYTE_3 dst_unused:UNUSED_PAD src0_sel:DWORD
	v_add_f32_e32 v49, 1.0, v49
	v_add_f32_e32 v52, 1.0, v52
	v_mul_f32_e32 v59, v73, v59
	v_mul_f32_e32 v59, v59, v125
	v_or3_b32 v72, v116, v72, v62
	v_cvt_pk_bf16_f32 v62, v87, v57
	v_cvt_pk_bf16_f32 v63, v61, v59
	global_store_dwordx2 v[128:129], v[62:63], off offset:8
	global_store_dword v[130:131], v72, off offset:4
	v_mul_f32_e32 v63, 0x3b808081, v48
	v_mul_f32_e32 v63, v86, v63
	v_exp_f32_e32 v63, v63
	v_rcp_f32_e32 v49, v49
	v_rcp_f32_e32 v52, v52
	v_lshlrev_b32_e32 v57, 16, v110
	v_sub_f32_e32 v72, 1.0, v63
	v_add_f32_e32 v63, 1.0, v63
	v_mul_f32_e32 v63, v72, v63
	v_sqrt_f32_e32 v63, v63
	v_mul_f32_e32 v49, 0x437f0000, v49
	v_rndne_f32_e32 v49, v49
	v_cvt_u32_f32_e32 v48, v48
	v_mul_f32_e32 v52, v52, v63
	v_mul_f32_e32 v52, v52, v57
	v_mul_f32_e32 v57, 0x3b808081, v49
	v_cvt_u32_f32_e32 v49, v49
	v_add_f32_e32 v53, v53, v65
	v_mul_f32_e32 v57, v56, v57
	v_mul_f32_e32 v53, 0xbfb8aa3b, v53
	v_lshl_or_b32 v48, v49, 8, v48
	v_add_f32_e32 v49, v50, v70
	v_mul_f32_e32 v49, 0xbfb8aa3b, v49
	v_exp_f32_e32 v49, v49
	v_exp_f32_e32 v57, v57
	v_exp_f32_e32 v53, v53
	v_add_f32_e32 v51, v51, v71
	v_add_f32_e32 v49, 1.0, v49
	v_rcp_f32_e32 v49, v49
	v_sub_f32_e32 v63, 1.0, v57
	v_add_f32_e32 v57, 1.0, v57
	v_add_f32_e32 v50, v54, v66
	v_mul_f32_e32 v49, 0x437f0000, v49
	v_rndne_f32_e32 v49, v49
	v_mul_f32_e32 v54, 0x3b808081, v49
	v_mul_f32_e32 v51, 0xbfb8aa3b, v51
	v_add_f32_e32 v53, 1.0, v53
	v_mul_f32_e32 v57, v63, v57
	v_mul_f32_e32 v54, v60, v54
	v_exp_f32_e32 v51, v51
	v_rcp_f32_e32 v53, v53
	v_sqrt_f32_e32 v57, v57
	v_mul_f32_e32 v50, 0xbfb8aa3b, v50
	v_exp_f32_e32 v54, v54
	v_exp_f32_e32 v50, v50
	v_add_f32_e32 v40, v40, v68
	v_mul_f32_e32 v40, 0xbfb8aa3b, v40
	v_add_f32_e32 v51, 1.0, v51
	v_exp_f32_e32 v40, v40
	v_mul_f32_e32 v53, v53, v57
	v_sub_f32_e32 v57, 1.0, v54
	v_add_f32_e32 v54, 1.0, v54
	v_rcp_f32_e32 v51, v51
	v_add_f32_e32 v50, 1.0, v50
	v_mul_f32_e32 v54, v57, v54
	v_rcp_f32_e32 v50, v50
	v_sqrt_f32_e32 v54, v54
	v_add_f32_e32 v40, 1.0, v40
	v_mul_f32_e32 v51, 0x437f0000, v51
	v_rcp_f32_e32 v40, v40
	v_rndne_f32_e32 v51, v51
	v_mul_f32_e32 v50, v50, v54
	v_cvt_u32_f32_sdwa v49, v49 dst_sel:WORD_1 dst_unused:UNUSED_PAD src0_sel:DWORD
	v_add_f32_e32 v54, v55, v67
	v_mul_f32_e32 v55, 0x3b808081, v51
	v_cvt_u32_f32_sdwa v51, v51 dst_sel:BYTE_3 dst_unused:UNUSED_PAD src0_sel:DWORD
	v_mul_f32_e32 v40, 0x437f0000, v40
	v_and_b32_e32 v59, 0xffff0000, v110
	v_mul_f32_e32 v55, v58, v55
	v_rndne_f32_e32 v40, v40
	v_mul_f32_e32 v53, v53, v59
	v_mul_f32_e32 v54, 0xbfb8aa3b, v54
	v_exp_f32_e32 v55, v55
	v_or3_b32 v51, v48, v49, v51
	v_cvt_pk_bf16_f32 v48, v52, v53
	v_mul_f32_e32 v52, 0x3b808081, v40
	v_add_f32_e32 v41, v41, v69
	v_exp_f32_e32 v54, v54
	v_add_f32_e32 v44, v44, v64
	v_mul_f32_e32 v52, v86, v52
	v_mul_f32_e32 v41, 0xbfb8aa3b, v41
	v_mul_f32_e32 v44, 0xbfb8aa3b, v44
	v_exp_f32_e32 v52, v52
	v_exp_f32_e32 v41, v41
	v_exp_f32_e32 v44, v44
	v_sub_f32_e32 v57, 1.0, v55
	v_add_f32_e32 v55, 1.0, v55
	v_add_f32_e32 v54, 1.0, v54
	v_mul_f32_e32 v55, v57, v55
	v_rcp_f32_e32 v54, v54
	v_sqrt_f32_e32 v55, v55
	v_sub_f32_e32 v53, 1.0, v52
	v_add_f32_e32 v52, 1.0, v52
	v_add_f32_e32 v41, 1.0, v41
	v_add_f32_e32 v44, 1.0, v44
	v_mul_f32_e32 v52, v53, v52
	v_rcp_f32_e32 v41, v41
	v_rcp_f32_e32 v44, v44
	v_sqrt_f32_e32 v52, v52
	v_lshlrev_b32_e32 v61, 16, v111
	v_and_b32_e32 v62, 0xffff0000, v111
	v_mul_f32_e32 v54, v54, v55
	v_mul_f32_e32 v50, v50, v61
	v_mul_f32_e32 v54, v54, v62
	v_cvt_pk_bf16_f32 v49, v50, v54
	v_mul_f32_e32 v41, 0x437f0000, v41
	global_store_dwordx2 v[120:121], v[48:49], off offset:8
	global_store_dword v[122:123], v51, off offset:4
	v_lshlrev_b32_e32 v48, 16, v108
	v_mul_f32_e32 v44, v44, v52
	v_rndne_f32_e32 v41, v41
	v_mul_f32_e32 v44, v44, v48
	v_cvt_u32_f32_e32 v40, v40
	v_mul_f32_e32 v48, 0x3b808081, v41
	v_cvt_u32_f32_e32 v41, v41
	v_add_f32_e32 v45, v45, v65
	v_mul_f32_e32 v48, v56, v48
	v_mul_f32_e32 v45, 0xbfb8aa3b, v45
	v_lshl_or_b32 v40, v41, 8, v40
	v_add_f32_e32 v41, v42, v70
	v_mul_f32_e32 v41, 0xbfb8aa3b, v41
	v_exp_f32_e32 v41, v41
	v_exp_f32_e32 v48, v48
	v_exp_f32_e32 v45, v45
	v_add_f32_e32 v43, v43, v71
	v_add_f32_e32 v41, 1.0, v41
	v_rcp_f32_e32 v41, v41
	v_sub_f32_e32 v52, 1.0, v48
	v_add_f32_e32 v48, 1.0, v48
	v_add_f32_e32 v42, v46, v66
	v_mul_f32_e32 v41, 0x437f0000, v41
	v_rndne_f32_e32 v41, v41
	v_mul_f32_e32 v46, 0x3b808081, v41
	v_mul_f32_e32 v43, 0xbfb8aa3b, v43
	v_add_f32_e32 v45, 1.0, v45
	v_mul_f32_e32 v48, v52, v48
	v_mul_f32_e32 v46, v60, v46
	v_exp_f32_e32 v43, v43
	v_rcp_f32_e32 v45, v45
	v_sqrt_f32_e32 v48, v48
	v_mul_f32_e32 v42, 0xbfb8aa3b, v42
	v_exp_f32_e32 v46, v46
	v_exp_f32_e32 v42, v42
	v_add_f32_e32 v32, v32, v68
	v_mul_f32_e32 v32, 0xbfb8aa3b, v32
	v_add_f32_e32 v43, 1.0, v43
	v_exp_f32_e32 v32, v32
	v_mul_f32_e32 v45, v45, v48
	v_sub_f32_e32 v48, 1.0, v46
	v_add_f32_e32 v46, 1.0, v46
	v_rcp_f32_e32 v43, v43
	v_add_f32_e32 v42, 1.0, v42
	v_mul_f32_e32 v46, v48, v46
	v_rcp_f32_e32 v42, v42
	v_sqrt_f32_e32 v46, v46
	v_add_f32_e32 v32, 1.0, v32
	v_mul_f32_e32 v43, 0x437f0000, v43
	v_rcp_f32_e32 v32, v32
	v_rndne_f32_e32 v43, v43
	v_mul_f32_e32 v42, v42, v46
	v_cvt_u32_f32_sdwa v41, v41 dst_sel:WORD_1 dst_unused:UNUSED_PAD src0_sel:DWORD
	v_add_f32_e32 v46, v47, v67
	v_mul_f32_e32 v47, 0x3b808081, v43
	v_cvt_u32_f32_sdwa v43, v43 dst_sel:BYTE_3 dst_unused:UNUSED_PAD src0_sel:DWORD
	v_mul_f32_e32 v32, 0x437f0000, v32
	v_and_b32_e32 v49, 0xffff0000, v108
	v_mul_f32_e32 v47, v58, v47
	v_rndne_f32_e32 v32, v32
	v_mul_f32_e32 v45, v45, v49
	v_mul_f32_e32 v46, 0xbfb8aa3b, v46
	v_exp_f32_e32 v47, v47
	v_or3_b32 v43, v40, v41, v43
	v_cvt_pk_bf16_f32 v40, v44, v45
	v_mul_f32_e32 v44, 0x3b808081, v32
	v_add_f32_e32 v33, v33, v69
	v_exp_f32_e32 v46, v46
	v_add_f32_e32 v36, v36, v64
	v_mul_f32_e32 v44, v86, v44
	v_mul_f32_e32 v33, 0xbfb8aa3b, v33
	v_mul_f32_e32 v36, 0xbfb8aa3b, v36
	v_exp_f32_e32 v44, v44
	v_exp_f32_e32 v33, v33
	v_exp_f32_e32 v36, v36
	v_sub_f32_e32 v48, 1.0, v47
	v_add_f32_e32 v47, 1.0, v47
	v_add_f32_e32 v46, 1.0, v46
	v_mul_f32_e32 v47, v48, v47
	v_rcp_f32_e32 v46, v46
	v_sqrt_f32_e32 v47, v47
	v_sub_f32_e32 v45, 1.0, v44
	v_add_f32_e32 v44, 1.0, v44
	v_add_f32_e32 v33, 1.0, v33
	v_add_f32_e32 v36, 1.0, v36
	v_mul_f32_e32 v44, v45, v44
	v_rcp_f32_e32 v33, v33
	v_rcp_f32_e32 v36, v36
	v_sqrt_f32_e32 v44, v44
	v_lshlrev_b32_e32 v50, 16, v109
	v_and_b32_e32 v51, 0xffff0000, v109
	v_mul_f32_e32 v46, v46, v47
	v_mul_f32_e32 v42, v42, v50
	v_mul_f32_e32 v46, v46, v51
	v_cvt_pk_bf16_f32 v41, v42, v46
	v_mul_f32_e32 v33, 0x437f0000, v33
	global_store_dwordx2 v[112:113], v[40:41], off offset:8
	global_store_dword v[114:115], v43, off offset:4
	v_lshlrev_b32_e32 v40, 16, v102
	v_mul_f32_e32 v36, v36, v44
	v_rndne_f32_e32 v33, v33
	v_mul_f32_e32 v36, v36, v40
	v_cvt_u32_f32_e32 v32, v32
	v_mul_f32_e32 v40, 0x3b808081, v33
	v_cvt_u32_f32_e32 v33, v33
	v_add_f32_e32 v37, v37, v65
	v_mul_f32_e32 v40, v56, v40
	v_mul_f32_e32 v37, 0xbfb8aa3b, v37
	v_lshl_or_b32 v32, v33, 8, v32
	v_add_f32_e32 v33, v34, v70
	v_mul_f32_e32 v33, 0xbfb8aa3b, v33
	v_exp_f32_e32 v33, v33
	v_exp_f32_e32 v40, v40
	v_exp_f32_e32 v37, v37
	v_add_f32_e32 v35, v35, v71
	v_add_f32_e32 v33, 1.0, v33
	v_rcp_f32_e32 v33, v33
	v_sub_f32_e32 v44, 1.0, v40
	v_add_f32_e32 v40, 1.0, v40
	v_add_f32_e32 v34, v38, v66
	v_mul_f32_e32 v33, 0x437f0000, v33
	v_rndne_f32_e32 v33, v33
	v_mul_f32_e32 v38, 0x3b808081, v33
	v_mul_f32_e32 v35, 0xbfb8aa3b, v35
	v_add_f32_e32 v37, 1.0, v37
	v_mul_f32_e32 v40, v44, v40
	v_mul_f32_e32 v38, v60, v38
	v_exp_f32_e32 v35, v35
	v_rcp_f32_e32 v37, v37
	v_sqrt_f32_e32 v40, v40
	v_mul_f32_e32 v34, 0xbfb8aa3b, v34
	v_exp_f32_e32 v38, v38
	v_exp_f32_e32 v34, v34
	v_add_f32_e32 v24, v24, v68
	v_mul_f32_e32 v24, 0xbfb8aa3b, v24
	v_add_f32_e32 v35, 1.0, v35
	v_exp_f32_e32 v24, v24
	v_mul_f32_e32 v37, v37, v40
	v_sub_f32_e32 v40, 1.0, v38
	v_add_f32_e32 v38, 1.0, v38
	v_rcp_f32_e32 v35, v35
	v_add_f32_e32 v34, 1.0, v34
	v_mul_f32_e32 v38, v40, v38
	v_rcp_f32_e32 v34, v34
	v_sqrt_f32_e32 v38, v38
	v_add_f32_e32 v24, 1.0, v24
	v_mul_f32_e32 v35, 0x437f0000, v35
	v_rcp_f32_e32 v24, v24
	v_rndne_f32_e32 v35, v35
	v_mul_f32_e32 v34, v34, v38
	v_cvt_u32_f32_sdwa v33, v33 dst_sel:WORD_1 dst_unused:UNUSED_PAD src0_sel:DWORD
	v_add_f32_e32 v38, v39, v67
	v_mul_f32_e32 v39, 0x3b808081, v35
	v_cvt_u32_f32_sdwa v35, v35 dst_sel:BYTE_3 dst_unused:UNUSED_PAD src0_sel:DWORD
	v_mul_f32_e32 v24, 0x437f0000, v24
	v_and_b32_e32 v41, 0xffff0000, v102
	v_mul_f32_e32 v39, v58, v39
	v_rndne_f32_e32 v24, v24
	v_mul_f32_e32 v37, v37, v41
	v_mul_f32_e32 v38, 0xbfb8aa3b, v38
	v_exp_f32_e32 v39, v39
	v_or3_b32 v35, v32, v33, v35
	v_cvt_pk_bf16_f32 v32, v36, v37
	v_mul_f32_e32 v36, 0x3b808081, v24
	v_add_f32_e32 v25, v25, v69
	v_exp_f32_e32 v38, v38
	v_add_f32_e32 v28, v28, v64
	v_mul_f32_e32 v36, v86, v36
	v_mul_f32_e32 v25, 0xbfb8aa3b, v25
	v_mul_f32_e32 v28, 0xbfb8aa3b, v28
	v_exp_f32_e32 v36, v36
	v_exp_f32_e32 v25, v25
	v_exp_f32_e32 v28, v28
	v_sub_f32_e32 v40, 1.0, v39
	v_add_f32_e32 v39, 1.0, v39
	v_add_f32_e32 v38, 1.0, v38
	v_mul_f32_e32 v39, v40, v39
	v_rcp_f32_e32 v38, v38
	v_sqrt_f32_e32 v39, v39
	v_sub_f32_e32 v37, 1.0, v36
	v_add_f32_e32 v36, 1.0, v36
	v_add_f32_e32 v25, 1.0, v25
	v_add_f32_e32 v28, 1.0, v28
	v_mul_f32_e32 v36, v37, v36
	v_rcp_f32_e32 v25, v25
	v_rcp_f32_e32 v28, v28
	v_sqrt_f32_e32 v36, v36
	v_lshlrev_b32_e32 v42, 16, v103
	v_and_b32_e32 v43, 0xffff0000, v103
	v_mul_f32_e32 v38, v38, v39
	v_mul_f32_e32 v34, v34, v42
	v_mul_f32_e32 v38, v38, v43
	v_cvt_pk_bf16_f32 v33, v34, v38
	v_mul_f32_e32 v25, 0x437f0000, v25
	global_store_dwordx2 v[104:105], v[32:33], off offset:8
	global_store_dword v[106:107], v35, off offset:4
	v_lshlrev_b32_e32 v32, 16, v100
	v_mul_f32_e32 v28, v28, v36
	v_rndne_f32_e32 v25, v25
	v_mul_f32_e32 v28, v28, v32
	v_cvt_u32_f32_e32 v24, v24
	v_mul_f32_e32 v32, 0x3b808081, v25
	v_cvt_u32_f32_e32 v25, v25
	v_add_f32_e32 v29, v29, v65
	v_mul_f32_e32 v32, v56, v32
	v_mul_f32_e32 v29, 0xbfb8aa3b, v29
	v_lshl_or_b32 v24, v25, 8, v24
	v_add_f32_e32 v25, v26, v70
	v_mul_f32_e32 v25, 0xbfb8aa3b, v25
	v_exp_f32_e32 v25, v25
	v_exp_f32_e32 v32, v32
	v_exp_f32_e32 v29, v29
	v_add_f32_e32 v27, v27, v71
	v_add_f32_e32 v25, 1.0, v25
	v_rcp_f32_e32 v25, v25
	v_sub_f32_e32 v36, 1.0, v32
	v_add_f32_e32 v32, 1.0, v32
	v_add_f32_e32 v26, v30, v66
	v_mul_f32_e32 v25, 0x437f0000, v25
	v_rndne_f32_e32 v25, v25
	v_mul_f32_e32 v30, 0x3b808081, v25
	v_mul_f32_e32 v27, 0xbfb8aa3b, v27
	v_add_f32_e32 v29, 1.0, v29
	v_mul_f32_e32 v32, v36, v32
	v_mul_f32_e32 v30, v60, v30
	v_exp_f32_e32 v27, v27
	v_rcp_f32_e32 v29, v29
	v_sqrt_f32_e32 v32, v32
	v_mul_f32_e32 v26, 0xbfb8aa3b, v26
	v_exp_f32_e32 v30, v30
	v_exp_f32_e32 v26, v26
	v_add_f32_e32 v16, v16, v68
	v_mul_f32_e32 v16, 0xbfb8aa3b, v16
	v_add_f32_e32 v27, 1.0, v27
	v_exp_f32_e32 v16, v16
	v_mul_f32_e32 v29, v29, v32
	v_sub_f32_e32 v32, 1.0, v30
	v_add_f32_e32 v30, 1.0, v30
	v_rcp_f32_e32 v27, v27
	v_add_f32_e32 v26, 1.0, v26
	v_mul_f32_e32 v30, v32, v30
	v_rcp_f32_e32 v26, v26
	v_sqrt_f32_e32 v30, v30
	v_add_f32_e32 v16, 1.0, v16
	v_mul_f32_e32 v27, 0x437f0000, v27
	v_rcp_f32_e32 v16, v16
	v_rndne_f32_e32 v27, v27
	v_mul_f32_e32 v26, v26, v30
	v_cvt_u32_f32_sdwa v25, v25 dst_sel:WORD_1 dst_unused:UNUSED_PAD src0_sel:DWORD
	v_add_f32_e32 v30, v31, v67
	v_mul_f32_e32 v31, 0x3b808081, v27
	v_cvt_u32_f32_sdwa v27, v27 dst_sel:BYTE_3 dst_unused:UNUSED_PAD src0_sel:DWORD
	v_mul_f32_e32 v16, 0x437f0000, v16
	v_and_b32_e32 v33, 0xffff0000, v100
	v_mul_f32_e32 v31, v58, v31
	v_rndne_f32_e32 v16, v16
	v_mul_f32_e32 v29, v29, v33
	v_mul_f32_e32 v30, 0xbfb8aa3b, v30
	v_exp_f32_e32 v31, v31
	v_or3_b32 v27, v24, v25, v27
	v_cvt_pk_bf16_f32 v24, v28, v29
	v_mul_f32_e32 v28, 0x3b808081, v16
	v_add_f32_e32 v17, v17, v69
	v_exp_f32_e32 v30, v30
	v_add_f32_e32 v20, v20, v64
	v_mul_f32_e32 v28, v86, v28
	v_mul_f32_e32 v17, 0xbfb8aa3b, v17
	v_mul_f32_e32 v20, 0xbfb8aa3b, v20
	v_exp_f32_e32 v28, v28
	v_exp_f32_e32 v17, v17
	v_exp_f32_e32 v20, v20
	v_sub_f32_e32 v32, 1.0, v31
	v_add_f32_e32 v31, 1.0, v31
	v_add_f32_e32 v30, 1.0, v30
	v_mul_f32_e32 v31, v32, v31
	v_rcp_f32_e32 v30, v30
	v_sqrt_f32_e32 v31, v31
	v_sub_f32_e32 v29, 1.0, v28
	v_add_f32_e32 v28, 1.0, v28
	v_add_f32_e32 v17, 1.0, v17
	v_add_f32_e32 v20, 1.0, v20
	v_mul_f32_e32 v28, v29, v28
	v_rcp_f32_e32 v17, v17
	v_rcp_f32_e32 v20, v20
	v_sqrt_f32_e32 v28, v28
	v_lshlrev_b32_e32 v34, 16, v101
	v_and_b32_e32 v35, 0xffff0000, v101
	v_mul_f32_e32 v30, v30, v31
	v_mul_f32_e32 v26, v26, v34
	v_mul_f32_e32 v30, v30, v35
	v_cvt_pk_bf16_f32 v25, v26, v30
	v_mul_f32_e32 v17, 0x437f0000, v17
	global_store_dwordx2 v[96:97], v[24:25], off offset:8
	global_store_dword v[98:99], v27, off offset:4
	v_lshlrev_b32_e32 v24, 16, v94
	v_mul_f32_e32 v20, v20, v28
	v_rndne_f32_e32 v17, v17
	v_mul_f32_e32 v20, v20, v24
	v_cvt_u32_f32_e32 v16, v16
	v_mul_f32_e32 v24, 0x3b808081, v17
	v_cvt_u32_f32_e32 v17, v17
	v_add_f32_e32 v21, v21, v65
	v_mul_f32_e32 v24, v56, v24
	v_mul_f32_e32 v21, 0xbfb8aa3b, v21
	v_lshl_or_b32 v16, v17, 8, v16
	v_add_f32_e32 v17, v18, v70
	v_mul_f32_e32 v17, 0xbfb8aa3b, v17
	v_exp_f32_e32 v17, v17
	v_exp_f32_e32 v24, v24
	v_exp_f32_e32 v21, v21
	v_add_f32_e32 v19, v19, v71
	v_add_f32_e32 v17, 1.0, v17
	v_rcp_f32_e32 v17, v17
	v_sub_f32_e32 v28, 1.0, v24
	v_add_f32_e32 v24, 1.0, v24
	v_add_f32_e32 v18, v22, v66
	v_mul_f32_e32 v17, 0x437f0000, v17
	v_rndne_f32_e32 v17, v17
	v_mul_f32_e32 v22, 0x3b808081, v17
	v_mul_f32_e32 v19, 0xbfb8aa3b, v19
	v_add_f32_e32 v21, 1.0, v21
	v_mul_f32_e32 v24, v28, v24
	v_mul_f32_e32 v22, v60, v22
	v_exp_f32_e32 v19, v19
	v_rcp_f32_e32 v21, v21
	v_sqrt_f32_e32 v24, v24
	v_mul_f32_e32 v18, 0xbfb8aa3b, v18
	v_exp_f32_e32 v22, v22
	v_exp_f32_e32 v18, v18
	v_add_f32_e32 v8, v8, v68
	v_mul_f32_e32 v8, 0xbfb8aa3b, v8
	v_add_f32_e32 v19, 1.0, v19
	v_exp_f32_e32 v8, v8
	v_mul_f32_e32 v21, v21, v24
	v_sub_f32_e32 v24, 1.0, v22
	v_add_f32_e32 v22, 1.0, v22
	v_rcp_f32_e32 v19, v19
	v_add_f32_e32 v18, 1.0, v18
	v_mul_f32_e32 v22, v24, v22
	v_rcp_f32_e32 v18, v18
	v_sqrt_f32_e32 v22, v22
	v_add_f32_e32 v8, 1.0, v8
	v_mul_f32_e32 v19, 0x437f0000, v19
	v_rcp_f32_e32 v8, v8
	v_rndne_f32_e32 v19, v19
	v_mul_f32_e32 v18, v18, v22
	v_cvt_u32_f32_sdwa v17, v17 dst_sel:WORD_1 dst_unused:UNUSED_PAD src0_sel:DWORD
	v_add_f32_e32 v22, v23, v67
	v_mul_f32_e32 v23, 0x3b808081, v19
	v_cvt_u32_f32_sdwa v19, v19 dst_sel:BYTE_3 dst_unused:UNUSED_PAD src0_sel:DWORD
	v_mul_f32_e32 v8, 0x437f0000, v8
	v_and_b32_e32 v25, 0xffff0000, v94
	v_mul_f32_e32 v23, v58, v23
	v_rndne_f32_e32 v8, v8
	v_mul_f32_e32 v21, v21, v25
	v_mul_f32_e32 v22, 0xbfb8aa3b, v22
	v_exp_f32_e32 v23, v23
	v_or3_b32 v19, v16, v17, v19
	v_cvt_pk_bf16_f32 v16, v20, v21
	v_mul_f32_e32 v20, 0x3b808081, v8
	v_add_f32_e32 v9, v9, v69
	v_exp_f32_e32 v22, v22
	v_add_f32_e32 v12, v12, v64
	v_mul_f32_e32 v20, v86, v20
	v_mul_f32_e32 v9, 0xbfb8aa3b, v9
	v_mul_f32_e32 v12, 0xbfb8aa3b, v12
	v_exp_f32_e32 v20, v20
	v_exp_f32_e32 v9, v9
	v_exp_f32_e32 v12, v12
	v_sub_f32_e32 v24, 1.0, v23
	v_add_f32_e32 v23, 1.0, v23
	v_add_f32_e32 v22, 1.0, v22
	v_mul_f32_e32 v23, v24, v23
	v_rcp_f32_e32 v22, v22
	v_sqrt_f32_e32 v23, v23
	v_sub_f32_e32 v21, 1.0, v20
	v_add_f32_e32 v20, 1.0, v20
	v_add_f32_e32 v9, 1.0, v9
	v_add_f32_e32 v12, 1.0, v12
	v_mul_f32_e32 v20, v21, v20
	v_rcp_f32_e32 v9, v9
	v_rcp_f32_e32 v12, v12
	v_sqrt_f32_e32 v20, v20
	v_lshlrev_b32_e32 v26, 16, v95
	v_and_b32_e32 v27, 0xffff0000, v95
	v_mul_f32_e32 v22, v22, v23
	v_mul_f32_e32 v18, v18, v26
	v_mul_f32_e32 v22, v22, v27
	v_cvt_pk_bf16_f32 v17, v18, v22
	v_mul_f32_e32 v9, 0x437f0000, v9
	global_store_dwordx2 v[88:89], v[16:17], off offset:8
	global_store_dword v[90:91], v19, off offset:4
	v_lshlrev_b32_e32 v16, 16, v92
	v_mul_f32_e32 v12, v12, v20
	v_rndne_f32_e32 v9, v9
	v_mul_f32_e32 v12, v12, v16
	v_cvt_u32_f32_e32 v8, v8
	v_mul_f32_e32 v16, 0x3b808081, v9
	v_cvt_u32_f32_e32 v9, v9
	v_add_f32_e32 v13, v13, v65
	v_mul_f32_e32 v16, v56, v16
	v_mul_f32_e32 v13, 0xbfb8aa3b, v13
	v_lshl_or_b32 v8, v9, 8, v8
	v_add_f32_e32 v9, v10, v70
	v_mul_f32_e32 v9, 0xbfb8aa3b, v9
	v_exp_f32_e32 v9, v9
	v_exp_f32_e32 v16, v16
	v_exp_f32_e32 v13, v13
	v_add_f32_e32 v11, v11, v71
	v_add_f32_e32 v9, 1.0, v9
	v_rcp_f32_e32 v9, v9
	v_sub_f32_e32 v20, 1.0, v16
	v_add_f32_e32 v16, 1.0, v16
	v_add_f32_e32 v10, v14, v66
	v_mul_f32_e32 v9, 0x437f0000, v9
	v_rndne_f32_e32 v9, v9
	v_mul_f32_e32 v14, 0x3b808081, v9
	v_mul_f32_e32 v11, 0xbfb8aa3b, v11
	v_add_f32_e32 v13, 1.0, v13
	v_mul_f32_e32 v16, v20, v16
	v_mul_f32_e32 v14, v60, v14
	v_exp_f32_e32 v11, v11
	v_rcp_f32_e32 v13, v13
	v_sqrt_f32_e32 v16, v16
	v_mul_f32_e32 v10, 0xbfb8aa3b, v10
	v_exp_f32_e32 v14, v14
	v_exp_f32_e32 v10, v10
	v_add_f32_e32 v0, v0, v68
	v_mul_f32_e32 v0, 0xbfb8aa3b, v0
	v_add_f32_e32 v11, 1.0, v11
	v_exp_f32_e32 v0, v0
	v_mul_f32_e32 v13, v13, v16
	v_sub_f32_e32 v16, 1.0, v14
	v_add_f32_e32 v14, 1.0, v14
	v_rcp_f32_e32 v11, v11
	v_add_f32_e32 v10, 1.0, v10
	v_mul_f32_e32 v14, v16, v14
	v_rcp_f32_e32 v10, v10
	v_sqrt_f32_e32 v14, v14
	v_add_f32_e32 v0, 1.0, v0
	v_mul_f32_e32 v11, 0x437f0000, v11
	v_rcp_f32_e32 v0, v0
	v_rndne_f32_e32 v11, v11
	v_mul_f32_e32 v10, v10, v14
	v_cvt_u32_f32_sdwa v9, v9 dst_sel:WORD_1 dst_unused:UNUSED_PAD src0_sel:DWORD
	v_add_f32_e32 v14, v15, v67
	v_mul_f32_e32 v15, 0x3b808081, v11
	v_cvt_u32_f32_sdwa v11, v11 dst_sel:BYTE_3 dst_unused:UNUSED_PAD src0_sel:DWORD
	v_mul_f32_e32 v0, 0x437f0000, v0
	v_and_b32_e32 v17, 0xffff0000, v92
	v_mul_f32_e32 v15, v58, v15
	v_rndne_f32_e32 v0, v0
	v_mul_f32_e32 v13, v13, v17
	v_mul_f32_e32 v14, 0xbfb8aa3b, v14
	v_exp_f32_e32 v15, v15
	v_or3_b32 v11, v8, v9, v11
	v_cvt_pk_bf16_f32 v8, v12, v13
	v_mul_f32_e32 v12, 0x3b808081, v0
	v_add_f32_e32 v1, v1, v69
	v_exp_f32_e32 v14, v14
	v_add_f32_e32 v4, v4, v64
	v_mul_f32_e32 v12, v86, v12
	v_mul_f32_e32 v1, 0xbfb8aa3b, v1
	v_mul_f32_e32 v4, 0xbfb8aa3b, v4
	v_exp_f32_e32 v12, v12
	v_exp_f32_e32 v1, v1
	v_exp_f32_e32 v4, v4
	v_sub_f32_e32 v16, 1.0, v15
	v_add_f32_e32 v15, 1.0, v15
	v_add_f32_e32 v14, 1.0, v14
	v_mul_f32_e32 v15, v16, v15
	v_rcp_f32_e32 v14, v14
	v_sqrt_f32_e32 v15, v15
	v_sub_f32_e32 v13, 1.0, v12
	v_add_f32_e32 v12, 1.0, v12
	v_add_f32_e32 v1, 1.0, v1
	v_add_f32_e32 v4, 1.0, v4
	v_mul_f32_e32 v12, v13, v12
	v_rcp_f32_e32 v1, v1
	v_rcp_f32_e32 v4, v4
	v_sqrt_f32_e32 v12, v12
	v_lshlrev_b32_e32 v18, 16, v93
	v_and_b32_e32 v19, 0xffff0000, v93
	v_mul_f32_e32 v14, v14, v15
	v_mul_f32_e32 v10, v10, v18
	v_mul_f32_e32 v14, v14, v19
	v_cvt_pk_bf16_f32 v9, v10, v14
	v_mul_f32_e32 v1, 0x437f0000, v1
	global_store_dwordx2 v[80:81], v[8:9], off offset:8
	global_store_dword v[82:83], v11, off offset:4
	v_lshlrev_b32_e32 v8, 16, v84
	v_mul_f32_e32 v4, v4, v12
	v_rndne_f32_e32 v1, v1
	v_mul_f32_e32 v4, v4, v8
	v_cvt_u32_f32_e32 v0, v0
	v_mul_f32_e32 v8, 0x3b808081, v1
	v_cvt_u32_f32_e32 v1, v1
	v_add_f32_e32 v5, v5, v65
	v_mul_f32_e32 v8, v56, v8
	v_mul_f32_e32 v5, 0xbfb8aa3b, v5
	v_lshl_or_b32 v0, v1, 8, v0
	v_add_f32_e32 v1, v2, v70
	v_mul_f32_e32 v1, 0xbfb8aa3b, v1
	v_exp_f32_e32 v1, v1
	v_exp_f32_e32 v8, v8
	v_exp_f32_e32 v5, v5
	v_add_f32_e32 v3, v3, v71
	v_add_f32_e32 v1, 1.0, v1
	v_rcp_f32_e32 v1, v1
	v_sub_f32_e32 v12, 1.0, v8
	v_add_f32_e32 v8, 1.0, v8
	v_add_f32_e32 v2, v6, v66
	v_mul_f32_e32 v1, 0x437f0000, v1
	v_rndne_f32_e32 v1, v1
	v_mul_f32_e32 v6, 0x3b808081, v1
	v_mul_f32_e32 v3, 0xbfb8aa3b, v3
	v_add_f32_e32 v5, 1.0, v5
	v_mul_f32_e32 v8, v12, v8
	v_mul_f32_e32 v6, v60, v6
	v_exp_f32_e32 v3, v3
	v_rcp_f32_e32 v5, v5
	v_sqrt_f32_e32 v8, v8
	v_mul_f32_e32 v2, 0xbfb8aa3b, v2
	v_exp_f32_e32 v6, v6
	v_exp_f32_e32 v2, v2
	v_add_f32_e32 v3, 1.0, v3
	v_mul_f32_e32 v5, v5, v8
	v_sub_f32_e32 v8, 1.0, v6
	v_add_f32_e32 v6, 1.0, v6
	v_rcp_f32_e32 v3, v3
	v_add_f32_e32 v2, 1.0, v2
	v_mul_f32_e32 v6, v8, v6
	v_rcp_f32_e32 v2, v2
	v_sqrt_f32_e32 v6, v6
	v_mul_f32_e32 v3, 0x437f0000, v3
	v_rndne_f32_e32 v3, v3
	v_cvt_u32_f32_sdwa v1, v1 dst_sel:WORD_1 dst_unused:UNUSED_PAD src0_sel:DWORD
	v_mul_f32_e32 v2, v2, v6
	v_add_f32_e32 v6, v7, v67
	v_mul_f32_e32 v7, 0x3b808081, v3
	v_mul_f32_e32 v7, v58, v7
	v_mul_f32_e32 v6, 0xbfb8aa3b, v6
	v_exp_f32_e32 v7, v7
	v_exp_f32_e32 v6, v6
	v_cvt_u32_f32_sdwa v3, v3 dst_sel:BYTE_3 dst_unused:UNUSED_PAD src0_sel:DWORD
	v_and_b32_e32 v9, 0xffff0000, v84
	v_sub_f32_e32 v8, 1.0, v7
	v_add_f32_e32 v7, 1.0, v7
	v_add_f32_e32 v6, 1.0, v6
	v_mul_f32_e32 v7, v8, v7
	v_rcp_f32_e32 v6, v6
	v_sqrt_f32_e32 v7, v7
	v_lshlrev_b32_e32 v10, 16, v85
	v_and_b32_e32 v11, 0xffff0000, v85
	v_mul_f32_e32 v5, v5, v9
	v_mul_f32_e32 v6, v6, v7
	v_mul_f32_e32 v2, v2, v10
	v_mul_f32_e32 v6, v6, v11
	v_or3_b32 v3, v0, v1, v3
	v_cvt_pk_bf16_f32 v0, v4, v5
	v_cvt_pk_bf16_f32 v1, v2, v6
	global_store_dwordx2 v[76:77], v[0:1], off offset:8
	global_store_dword v[78:79], v3, off offset:4
	s_cbranch_vccz .LBB0_588

.LBB0_859:
	s_add_u32 s0, s8, 0xfff80080
	s_addc_u32 s1, s9, -1
	s_add_i32 s51, 0, 0x10000
	v_add_u32_e32 v60, s51, v249
	ds_read_b128 v[48:51], v60
	ds_read_b128 v[52:55], v60 offset:1024
	ds_read_b128 v[56:59], v60 offset:2048
	ds_read_b128 v[60:63], v60 offset:3072
	s_cmp_eq_u32 s50, 28
	s_cselect_b32 s81, s12, s1
	s_cselect_b32 s80, s13, s0
	s_cselect_b32 s1, s14, s49
	s_cselect_b32 s0, s15, s48
	ds_read_b128 v[64:67], v251
	ds_read_b128 v[68:71], v251 offset:1024
	ds_read_b128 v[72:75], v251 offset:2048
	ds_read_b128 v[76:79], v251 offset:3072
	ds_read_b128 v[176:179], v251 offset:4096
	ds_read_b128 v[180:183], v251 offset:5120
	ds_read_b128 v[184:187], v251 offset:6144
	ds_read_b128 v[188:191], v251 offset:7168
	s_waitcnt lgkmcnt(8)
	s_barrier
	s_waitcnt lgkmcnt(0)
	s_waitcnt lgkmcnt(0)
	v_mfma_f32_16x16x32_bf16 v[156:159], v[48:51], v[64:67], v[156:159]
	v_mfma_f32_16x16x32_bf16 v[152:155], v[56:59], v[64:67], v[152:155]
	v_mfma_f32_16x16x32_bf16 v[140:143], v[48:51], v[72:75], v[140:143]
	v_mfma_f32_16x16x32_bf16 v[136:139], v[56:59], v[72:75], v[136:139]
	v_mfma_f32_16x16x32_bf16 v[124:127], v[48:51], v[176:179], v[124:127]
	v_mfma_f32_16x16x32_bf16 v[120:123], v[56:59], v[176:179], v[120:123]
	v_mfma_f32_16x16x32_bf16 v[108:111], v[48:51], v[184:187], v[108:111]
	v_mfma_f32_16x16x32_bf16 v[104:107], v[56:59], v[184:187], v[104:107]
	v_mfma_f32_16x16x32_bf16 v[156:159], v[52:55], v[68:71], v[156:159]
	v_mfma_f32_16x16x32_bf16 v[152:155], v[60:63], v[68:71], v[152:155]
	v_mfma_f32_16x16x32_bf16 v[140:143], v[52:55], v[76:79], v[140:143]
	v_mfma_f32_16x16x32_bf16 v[136:139], v[60:63], v[76:79], v[136:139]
	v_mfma_f32_16x16x32_bf16 v[124:127], v[52:55], v[180:183], v[124:127]
	v_mfma_f32_16x16x32_bf16 v[120:123], v[60:63], v[180:183], v[120:123]
	v_mfma_f32_16x16x32_bf16 v[108:111], v[52:55], v[188:191], v[108:111]
	v_mfma_f32_16x16x32_bf16 v[104:107], v[60:63], v[188:191], v[104:107]
	s_barrier
	v_lshl_add_u64 v[192:193], s[8:9], 0, v[172:173]
	s_add_i32 m0, s20, 0xc000
	s_nop 0
	global_load_lds_dwordx4 v[192:193], off
	v_lshl_add_u64 v[192:193], s[8:9], 0, v[174:175]
	s_add_i32 m0, s20, 0xe000
	s_nop 0
	global_load_lds_dwordx4 v[192:193], off
	s_add_i32 s68, 0, 0x14000
	s_add_i32 s51, s51, s19
	v_add_u32_e32 v204, s68, v249
	v_lshl_add_u64 v[216:217], s[0:1], 0, v[160:161]
	s_mov_b32 m0, s51
	ds_read_b128 v[192:195], v204
	ds_read_b128 v[196:199], v204 offset:1024
	ds_read_b128 v[200:203], v204 offset:2048
	ds_read_b128 v[204:207], v204 offset:3072
	global_load_lds_dwordx4 v[216:217], off
	v_lshl_add_u64 v[218:219], s[0:1], 0, v[170:171]
	s_add_i32 m0, s51, 0x2000
	s_nop 0
	global_load_lds_dwordx4 v[218:219], off
	s_barrier
	s_waitcnt lgkmcnt(0)
	s_waitcnt lgkmcnt(0)
	v_mfma_f32_16x16x32_bf16 v[148:151], v[192:195], v[64:67], v[148:151]
	v_mfma_f32_16x16x32_bf16 v[64:67], v[200:203], v[64:67], v[144:147]
	v_mfma_f32_16x16x32_bf16 v[148:151], v[196:199], v[68:71], v[148:151]
	v_mfma_f32_16x16x32_bf16 v[64:67], v[204:207], v[68:71], v[64:67]
	v_mfma_f32_16x16x32_bf16 v[68:71], v[192:195], v[72:75], v[132:135]
	v_mfma_f32_16x16x32_bf16 v[72:75], v[200:203], v[72:75], v[128:131]
	v_mfma_f32_16x16x32_bf16 v[112:115], v[200:203], v[176:179], v[112:115]
	v_mfma_f32_16x16x32_bf16 v[100:103], v[192:195], v[184:187], v[100:103]
	v_mfma_f32_16x16x32_bf16 v[96:99], v[200:203], v[184:187], v[96:99]
	v_mfma_f32_16x16x32_bf16 v[68:71], v[196:199], v[76:79], v[68:71]
	v_mfma_f32_16x16x32_bf16 v[72:75], v[204:207], v[76:79], v[72:75]
	v_mfma_f32_16x16x32_bf16 v[76:79], v[192:195], v[176:179], v[116:119]
	v_mfma_f32_16x16x32_bf16 v[112:115], v[204:207], v[180:183], v[112:115]
	v_mfma_f32_16x16x32_bf16 v[100:103], v[196:199], v[188:191], v[100:103]
	v_mfma_f32_16x16x32_bf16 v[96:99], v[204:207], v[188:191], v[96:99]
	v_mfma_f32_16x16x32_bf16 v[76:79], v[196:199], v[180:183], v[76:79]
	s_mov_b32 m0, s20
	v_lshl_add_u64 v[220:221], s[80:81], 0, v[160:161]
	s_barrier
	ds_read_b128 v[116:119], v251 offset:16384
	ds_read_b128 v[128:131], v251 offset:17408
	ds_read_b128 v[132:135], v251 offset:18432
	ds_read_b128 v[144:147], v251 offset:19456
	ds_read_b128 v[176:179], v251 offset:20480
	ds_read_b128 v[180:183], v251 offset:21504
	ds_read_b128 v[184:187], v251 offset:22528
	ds_read_b128 v[188:191], v251 offset:23552
	global_load_lds_dwordx4 v[220:221], off
	v_lshl_add_u64 v[222:223], s[80:81], 0, v[170:171]
	s_mov_b32 m0, s21
	s_nop 0
	global_load_lds_dwordx4 v[222:223], off
	s_barrier
	s_waitcnt lgkmcnt(0)
	s_waitcnt lgkmcnt(0)
	v_mfma_f32_16x16x32_bf16 v[92:95], v[48:51], v[116:119], v[92:95]
	v_mfma_f32_16x16x32_bf16 v[88:91], v[56:59], v[116:119], v[88:91]
	v_mfma_f32_16x16x32_bf16 v[44:47], v[48:51], v[132:135], v[44:47]
	v_mfma_f32_16x16x32_bf16 v[40:43], v[56:59], v[132:135], v[40:43]
	v_mfma_f32_16x16x32_bf16 v[28:31], v[48:51], v[176:179], v[28:31]
	v_mfma_f32_16x16x32_bf16 v[24:27], v[56:59], v[176:179], v[24:27]
	v_mfma_f32_16x16x32_bf16 v[12:15], v[48:51], v[184:187], v[12:15]
	v_mfma_f32_16x16x32_bf16 v[8:11], v[56:59], v[184:187], v[8:11]
	v_mfma_f32_16x16x32_bf16 v[92:95], v[52:55], v[128:131], v[92:95]
	v_mfma_f32_16x16x32_bf16 v[88:91], v[60:63], v[128:131], v[88:91]
	v_mfma_f32_16x16x32_bf16 v[44:47], v[52:55], v[144:147], v[44:47]
	v_mfma_f32_16x16x32_bf16 v[40:43], v[60:63], v[144:147], v[40:43]
	v_mfma_f32_16x16x32_bf16 v[28:31], v[52:55], v[180:183], v[28:31]
	v_mfma_f32_16x16x32_bf16 v[24:27], v[60:63], v[180:183], v[24:27]
	v_mfma_f32_16x16x32_bf16 v[12:15], v[52:55], v[188:191], v[12:15]
	v_mfma_f32_16x16x32_bf16 v[8:11], v[60:63], v[188:191], v[8:11]
	s_barrier
	s_add_u32 s66, s0, 0x80000
	s_addc_u32 s67, s1, 0
	s_add_i32 s51, s68, s19
	v_lshl_add_u64 v[48:49], s[66:67], 0, v[160:161]
	s_mov_b32 m0, s51
	s_nop 0
	global_load_lds_dwordx4 v[48:49], off
	v_lshl_add_u64 v[48:49], s[66:67], 0, v[170:171]
	s_add_i32 m0, s51, 0x2000
	s_nop 0
	global_load_lds_dwordx4 v[48:49], off
	s_waitcnt vmcnt(6)
	s_barrier
	v_mfma_f32_16x16x32_bf16 v[36:39], v[192:195], v[132:135], v[36:39]
	v_mfma_f32_16x16x32_bf16 v[32:35], v[200:203], v[132:135], v[32:35]
	v_mfma_f32_16x16x32_bf16 v[20:23], v[192:195], v[176:179], v[20:23]
	v_mfma_f32_16x16x32_bf16 v[16:19], v[200:203], v[176:179], v[16:19]
	v_mfma_f32_16x16x32_bf16 v[4:7], v[192:195], v[184:187], v[4:7]
	v_mfma_f32_16x16x32_bf16 v[0:3], v[200:203], v[184:187], v[0:3]
	v_mfma_f32_16x16x32_bf16 v[48:51], v[192:195], v[116:119], v[84:87]
	v_mfma_f32_16x16x32_bf16 v[52:55], v[200:203], v[116:119], v[80:83]
	v_mfma_f32_16x16x32_bf16 v[36:39], v[196:199], v[144:147], v[36:39]
	v_mfma_f32_16x16x32_bf16 v[32:35], v[204:207], v[144:147], v[32:35]
	v_mfma_f32_16x16x32_bf16 v[20:23], v[196:199], v[180:183], v[20:23]
	v_mfma_f32_16x16x32_bf16 v[16:19], v[204:207], v[180:183], v[16:19]
	v_mfma_f32_16x16x32_bf16 v[4:7], v[196:199], v[188:191], v[4:7]
	v_mfma_f32_16x16x32_bf16 v[0:3], v[204:207], v[188:191], v[0:3]
	v_mfma_f32_16x16x32_bf16 v[48:51], v[196:199], v[128:131], v[48:51]
	v_mfma_f32_16x16x32_bf16 v[52:55], v[204:207], v[128:131], v[52:55]
	s_add_i32 s51, 0, 0x18000
	v_add_u32_e32 v84, s51, v249
	s_barrier
	ds_read_b128 v[56:59], v84
	ds_read_b128 v[60:63], v84 offset:1024
	ds_read_b128 v[80:83], v84 offset:2048
	ds_read_b128 v[84:87], v84 offset:3072
	ds_read_b128 v[116:119], v251 offset:32768
	ds_read_b128 v[128:131], v251 offset:33792
	ds_read_b128 v[176:179], v251 offset:34816
	ds_read_b128 v[180:183], v251 offset:35840
	ds_read_b128 v[184:187], v251 offset:36864
	ds_read_b128 v[188:191], v251 offset:37888
	ds_read_b128 v[192:195], v251 offset:38912
	ds_read_b128 v[196:199], v251 offset:39936
	s_waitcnt lgkmcnt(8)
	s_barrier
	s_waitcnt lgkmcnt(0)
	s_waitcnt lgkmcnt(0)
	v_mfma_f32_16x16x32_bf16 v[132:135], v[56:59], v[116:119], v[156:159]
	v_mfma_f32_16x16x32_bf16 v[156:159], v[60:63], v[128:131], v[132:135]
	v_mfma_f32_16x16x32_bf16 v[132:135], v[80:83], v[116:119], v[152:155]
	v_mfma_f32_16x16x32_bf16 v[152:155], v[84:87], v[128:131], v[132:135]
	v_mfma_f32_16x16x32_bf16 v[132:135], v[56:59], v[176:179], v[140:143]
	v_mfma_f32_16x16x32_bf16 v[140:143], v[60:63], v[180:183], v[132:135]
	v_mfma_f32_16x16x32_bf16 v[132:135], v[80:83], v[176:179], v[136:139]
	v_mfma_f32_16x16x32_bf16 v[124:127], v[56:59], v[184:187], v[124:127]
	v_mfma_f32_16x16x32_bf16 v[120:123], v[80:83], v[184:187], v[120:123]
	v_mfma_f32_16x16x32_bf16 v[108:111], v[56:59], v[192:195], v[108:111]
	v_mfma_f32_16x16x32_bf16 v[104:107], v[80:83], v[192:195], v[104:107]
	v_mfma_f32_16x16x32_bf16 v[136:139], v[84:87], v[180:183], v[132:135]
	v_mfma_f32_16x16x32_bf16 v[124:127], v[60:63], v[188:191], v[124:127]
	v_mfma_f32_16x16x32_bf16 v[120:123], v[84:87], v[188:191], v[120:123]
	v_mfma_f32_16x16x32_bf16 v[108:111], v[60:63], v[196:199], v[108:111]
	v_mfma_f32_16x16x32_bf16 v[104:107], v[84:87], v[196:199], v[104:107]
	s_barrier
	s_add_u32 s66, s80, 0x80000
	s_addc_u32 s67, s81, 0
	v_lshl_add_u64 v[132:133], s[66:67], 0, v[160:161]
	s_mov_b32 m0, s22
	s_nop 0
	global_load_lds_dwordx4 v[132:133], off
	v_lshl_add_u64 v[132:133], s[66:67], 0, v[170:171]
	s_mov_b32 m0, s23
	s_nop 0
	global_load_lds_dwordx4 v[132:133], off
	s_add_i32 s66, 0, 0x1c000
	v_add_u32_e32 v132, s66, v249
	s_add_i32 s51, s51, s19
	ds_read_b128 v[200:203], v132
	ds_read_b128 v[204:207], v132 offset:1024
	ds_read_b128 v[208:211], v132 offset:2048
	ds_read_b128 v[212:215], v132 offset:3072
	v_lshl_add_u64 v[132:133], v[216:217], 0, s[92:93]
	s_mov_b32 m0, s51
	s_nop 0
	global_load_lds_dwordx4 v[132:133], off
	v_lshl_add_u64 v[132:133], v[218:219], 0, s[92:93]
	s_add_i32 m0, s51, 0x2000
	s_nop 0
	global_load_lds_dwordx4 v[132:133], off
	s_barrier
	s_waitcnt lgkmcnt(0)
	s_waitcnt lgkmcnt(0)
	v_mfma_f32_16x16x32_bf16 v[64:67], v[208:211], v[116:119], v[64:67]
	v_mfma_f32_16x16x32_bf16 v[132:135], v[200:203], v[116:119], v[148:151]
	v_mfma_f32_16x16x32_bf16 v[144:147], v[212:215], v[128:131], v[64:67]
	v_mfma_f32_16x16x32_bf16 v[64:67], v[200:203], v[176:179], v[68:71]
	v_mfma_f32_16x16x32_bf16 v[148:151], v[204:207], v[128:131], v[132:135]
	v_mfma_f32_16x16x32_bf16 v[132:135], v[204:207], v[180:183], v[64:67]
	v_mfma_f32_16x16x32_bf16 v[64:67], v[208:211], v[176:179], v[72:75]
	v_mfma_f32_16x16x32_bf16 v[128:131], v[212:215], v[180:183], v[64:67]
	v_mfma_f32_16x16x32_bf16 v[64:67], v[200:203], v[184:187], v[76:79]
	v_mfma_f32_16x16x32_bf16 v[116:119], v[204:207], v[188:191], v[64:67]
	v_mfma_f32_16x16x32_bf16 v[64:67], v[208:211], v[184:187], v[112:115]
	v_mfma_f32_16x16x32_bf16 v[112:115], v[212:215], v[188:191], v[64:67]
	v_mfma_f32_16x16x32_bf16 v[64:67], v[200:203], v[192:195], v[100:103]
	v_mfma_f32_16x16x32_bf16 v[100:103], v[204:207], v[196:199], v[64:67]
	v_mfma_f32_16x16x32_bf16 v[64:67], v[208:211], v[192:195], v[96:99]
	v_mfma_f32_16x16x32_bf16 v[96:99], v[212:215], v[196:199], v[64:67]
	s_mov_b32 m0, s24
	v_lshl_add_u64 v[192:193], v[220:221], 0, s[92:93]
	s_barrier
	s_nop 2
	ds_read_b128 v[64:67], v251 offset:49152
	ds_read_b128 v[68:71], v251 offset:50176
	ds_read_b128 v[72:75], v251 offset:51200
	ds_read_b128 v[76:79], v251 offset:52224
	ds_read_b128 v[176:179], v251 offset:53248
	ds_read_b128 v[180:183], v251 offset:54272
	ds_read_b128 v[184:187], v251 offset:55296
	ds_read_b128 v[188:191], v251 offset:56320
	global_load_lds_dwordx4 v[192:193], off
	v_lshl_add_u64 v[192:193], v[222:223], 0, s[92:93]
	s_mov_b32 m0, s25
	s_nop 0
	global_load_lds_dwordx4 v[192:193], off
	s_barrier
	s_waitcnt lgkmcnt(0)
	s_waitcnt lgkmcnt(0)
	v_mfma_f32_16x16x32_bf16 v[92:95], v[56:59], v[64:67], v[92:95]
	v_mfma_f32_16x16x32_bf16 v[88:91], v[80:83], v[64:67], v[88:91]
	v_mfma_f32_16x16x32_bf16 v[44:47], v[56:59], v[72:75], v[44:47]
	v_mfma_f32_16x16x32_bf16 v[40:43], v[80:83], v[72:75], v[40:43]
	v_mfma_f32_16x16x32_bf16 v[28:31], v[56:59], v[176:179], v[28:31]
	v_mfma_f32_16x16x32_bf16 v[24:27], v[80:83], v[176:179], v[24:27]
	v_mfma_f32_16x16x32_bf16 v[12:15], v[56:59], v[184:187], v[12:15]
	v_mfma_f32_16x16x32_bf16 v[8:11], v[80:83], v[184:187], v[8:11]
	v_mfma_f32_16x16x32_bf16 v[92:95], v[60:63], v[68:71], v[92:95]
	v_mfma_f32_16x16x32_bf16 v[88:91], v[84:87], v[68:71], v[88:91]
	v_mfma_f32_16x16x32_bf16 v[44:47], v[60:63], v[76:79], v[44:47]
	v_mfma_f32_16x16x32_bf16 v[40:43], v[84:87], v[76:79], v[40:43]
	v_mfma_f32_16x16x32_bf16 v[28:31], v[60:63], v[180:183], v[28:31]
	v_mfma_f32_16x16x32_bf16 v[24:27], v[84:87], v[180:183], v[24:27]
	v_mfma_f32_16x16x32_bf16 v[12:15], v[60:63], v[188:191], v[12:15]
	v_mfma_f32_16x16x32_bf16 v[8:11], v[84:87], v[188:191], v[8:11]
	s_barrier
	s_add_u32 s0, s0, 0x80080
	s_addc_u32 s1, s1, 0
	s_add_i32 s51, s66, s19
	v_lshl_add_u64 v[56:57], s[0:1], 0, v[160:161]
	s_mov_b32 m0, s51
	s_nop 0
	global_load_lds_dwordx4 v[56:57], off
	v_lshl_add_u64 v[56:57], s[0:1], 0, v[170:171]
	s_add_i32 m0, s51, 0x2000
	s_nop 0
	global_load_lds_dwordx4 v[56:57], off
	s_waitcnt vmcnt(6)
	s_barrier
	v_mfma_f32_16x16x32_bf16 v[48:51], v[200:203], v[64:67], v[48:51]
	v_mfma_f32_16x16x32_bf16 v[84:87], v[204:207], v[68:71], v[48:51]
	v_mfma_f32_16x16x32_bf16 v[48:51], v[208:211], v[64:67], v[52:55]
	v_mfma_f32_16x16x32_bf16 v[36:39], v[200:203], v[72:75], v[36:39]
	v_mfma_f32_16x16x32_bf16 v[32:35], v[208:211], v[72:75], v[32:35]
	v_mfma_f32_16x16x32_bf16 v[20:23], v[200:203], v[176:179], v[20:23]
	v_mfma_f32_16x16x32_bf16 v[16:19], v[208:211], v[176:179], v[16:19]
	v_mfma_f32_16x16x32_bf16 v[4:7], v[200:203], v[184:187], v[4:7]
	v_mfma_f32_16x16x32_bf16 v[0:3], v[208:211], v[184:187], v[0:3]
	v_mfma_f32_16x16x32_bf16 v[80:83], v[212:215], v[68:71], v[48:51]
	v_mfma_f32_16x16x32_bf16 v[36:39], v[204:207], v[76:79], v[36:39]
	v_mfma_f32_16x16x32_bf16 v[32:35], v[212:215], v[76:79], v[32:35]
	v_mfma_f32_16x16x32_bf16 v[20:23], v[204:207], v[180:183], v[20:23]
	v_mfma_f32_16x16x32_bf16 v[16:19], v[212:215], v[180:183], v[16:19]
	v_mfma_f32_16x16x32_bf16 v[4:7], v[204:207], v[188:191], v[4:7]
	v_mfma_f32_16x16x32_bf16 v[0:3], v[212:215], v[188:191], v[0:3]
	s_add_i32 s50, s50, 2
	s_add_u32 s8, s8, 0x100
	s_addc_u32 s9, s9, 0
	s_add_u32 s48, s48, 0x100
	s_addc_u32 s49, s49, 0
	s_cmp_gt_u32 s50, 29
	s_barrier
	s_cbranch_scc0 .LBB0_859
	v_lshl_or_b32 v186, s27, 8, v250
	v_lshl_add_u32 v176, s43, 8, v248
	v_ashrrev_i32_e32 v187, 31, v186
	v_lshlrev_b64 v[218:219], 1, v[186:187]
	v_ashrrev_i32_e32 v177, 31, v176
	v_lshl_add_u64 v[48:49], s[28:29], 0, v[218:219]
	v_lshlrev_b64 v[238:239], 12, v[176:177]
	v_lshl_add_u64 v[50:51], v[48:49], 0, v[238:239]
	global_load_dwordx2 v[240:241], v[50:51], off
	global_load_dwordx2 v[234:235], v[50:51], off offset:32
	global_load_dwordx2 v[232:233], v[50:51], off offset:256
	global_load_dwordx2 v[230:231], v[50:51], off offset:288
	v_or_b32_e32 v50, 16, v176
	v_ashrrev_i32_e32 v51, 31, v50
	v_lshlrev_b64 v[220:221], 12, v[50:51]
	v_lshl_add_u64 v[48:49], v[48:49], 0, v[220:221]
	global_load_dwordx2 v[224:225], v[48:49], off
	global_load_dwordx2 v[216:217], v[48:49], off offset:32
	global_load_dwordx2 v[212:213], v[48:49], off offset:256
	global_load_dwordx2 v[206:207], v[48:49], off offset:288
	v_lshlrev_b64 v[48:49], 2, v[186:187]
	v_lshl_add_u64 v[50:51], s[44:45], 0, v[48:49]
	v_lshl_add_u64 v[52:53], s[46:47], 0, v[48:49]
	v_lshl_add_u64 v[178:179], v[176:177], 3, s[34:35]
	global_load_dwordx4 v[72:75], v[50:51], off
	global_load_dwordx4 v[76:79], v[52:53], off
	global_load_dwordx4 v[64:67], v[50:51], off offset:64
	global_load_dwordx4 v[68:71], v[52:53], off offset:64
	global_load_dwordx4 v[56:59], v[50:51], off offset:512
	global_load_dwordx4 v[60:63], v[52:53], off offset:512
	s_nop 0
	global_load_dwordx4 v[48:51], v[50:51], off offset:576
	s_nop 0
	global_load_dwordx4 v[52:55], v[52:53], off offset:576
	v_add_co_u32_e32 v204, vcc, s89, v178
	global_load_dwordx2 v[180:181], v[178:179], off
	s_nop 0
	v_addc_co_u32_e32 v205, vcc, 0, v179, vcc
	global_load_dwordx2 v[182:183], v[204:205], off
	global_load_dwordx2 v[228:229], v[178:179], off offset:128
	global_load_dwordx2 v[226:227], v[204:205], off offset:128
	global_load_dwordx2 v[202:203], v[178:179], off offset:256
	global_load_dwordx2 v[200:201], v[204:205], off offset:256
	global_load_dwordx2 v[198:199], v[178:179], off offset:384
	global_load_dwordx2 v[196:197], v[204:205], off offset:384
	v_cmp_lt_i32_e64 s[8:9], 0, v247
	s_mov_b64 s[12:13], -1
	v_cmp_eq_u32_e32 vcc, 1, v247
	s_waitcnt vmcnt(0)
	v_lshlrev_b32_e32 v242, 16, v240
	v_and_b32_e32 v240, 0xffff0000, v240
	v_lshlrev_b32_e32 v244, 16, v241
	v_and_b32_e32 v243, 0xffff0000, v241
	v_cvt_f32_u32_e32 v184, v182
	v_cvt_f32_u32_e32 v185, v180
	v_cvt_f32_i32_e32 v180, v183
	v_cvt_f32_i32_e32 v181, v181
	v_pk_fma_f32 v[180:181], v[184:185], s[88:89], v[180:181] op_sel_hi:[1,0,1]
	s_nop 0
	v_pk_mul_f32 v[236:237], v[180:181], s[94:95] op_sel_hi:[1,0]
	s_nop 0
	v_fma_f32 v180, -v237, v237, v236
	v_add_f32_e32 v180, 0x3727c5ac, v180
	v_rsq_f32_e32 v236, v180
	global_load_dwordx2 v[194:195], v[178:179], off offset:1024
	global_load_dwordx2 v[192:193], v[204:205], off offset:1024
	global_load_dwordx2 v[190:191], v[178:179], off offset:1152
	global_load_dwordx2 v[188:189], v[204:205], off offset:1152
	global_load_dwordx2 v[184:185], v[178:179], off offset:1280
	global_load_dwordx2 v[182:183], v[204:205], off offset:1280
	global_load_dwordx2 v[180:181], v[178:179], off offset:1408
	s_nop 0
	global_load_dwordx2 v[178:179], v[204:205], off offset:1408
	v_or_b32_e32 v204, 32, v176
	v_ashrrev_i32_e32 v205, 31, v204
	v_lshlrev_b64 v[204:205], 12, v[204:205]
	v_lshl_add_u64 v[204:205], s[28:29], 0, v[204:205]
	v_lshl_add_u64 v[204:205], v[204:205], 0, v[218:219]
	global_load_dwordx2 v[222:223], v[204:205], off
	global_load_dwordx2 v[214:215], v[204:205], off offset:32
	global_load_dwordx2 v[210:211], v[204:205], off offset:256
	global_load_dwordx2 v[208:209], v[204:205], off offset:288
	v_sub_f32_e32 v241, v240, v237
	v_sub_f32_e32 v240, v242, v237
	v_sub_f32_e32 v243, v243, v237
	v_sub_f32_e32 v242, v244, v237
	v_pk_mul_f32 v[242:243], v[242:243], v[236:237] op_sel_hi:[1,0]
	v_pk_mul_f32 v[240:241], v[240:241], v[236:237] op_sel_hi:[1,0]
	v_pk_fma_f32 v[242:243], v[74:75], v[242:243], v[78:79]
	v_pk_fma_f32 v[240:241], v[72:73], v[240:241], v[76:77]
	v_pk_fma_f32 v[242:243], v[242:243], s[62:63], v[158:159] op_sel_hi:[1,0,1]
	v_lshl_add_u64 v[158:159], s[28:29], 0, v[238:239]
	v_pk_fma_f32 v[240:241], v[240:241], s[62:63], v[156:157] op_sel_hi:[1,0,1]
	v_lshl_add_u64 v[158:159], v[158:159], 0, v[218:219]
	v_cvt_pk_bf16_f32 v156, v240, v241
	v_cvt_pk_bf16_f32 v157, v242, v243
	global_store_dwordx2 v[158:159], v[156:157], off
	v_pk_mov_b32 v[156:157], v[240:241], v[242:243] op_sel:[1,0]
	v_mov_b32_e32 v238, v240
	v_mov_b32_e32 v239, v243
	v_pk_add_f32 v[156:157], v[156:157], v[238:239]
	v_mul_f32_e32 v238, v243, v243
	v_add_f32_e32 v156, v156, v157
	v_add_f32_e32 v157, 0, v156
	v_mul_f32_e32 v156, v241, v241
	v_fmac_f32_e32 v156, v240, v240
	v_fmac_f32_e32 v238, v242, v242
	v_add_f32_e32 v156, v156, v238
	v_lshlrev_b32_e32 v238, 16, v234
	v_and_b32_e32 v234, 0xffff0000, v234
	v_lshlrev_b32_e32 v240, 16, v235
	v_and_b32_e32 v239, 0xffff0000, v235
	v_sub_f32_e32 v235, v234, v237
	v_sub_f32_e32 v234, v238, v237
	v_sub_f32_e32 v239, v239, v237
	v_sub_f32_e32 v238, v240, v237
	v_pk_mul_f32 v[238:239], v[238:239], v[236:237] op_sel_hi:[1,0]
	v_pk_mul_f32 v[234:235], v[234:235], v[236:237] op_sel_hi:[1,0]
	v_pk_fma_f32 v[238:239], v[66:67], v[238:239], v[70:71]
	v_pk_fma_f32 v[234:235], v[64:65], v[234:235], v[68:69]
	v_pk_fma_f32 v[154:155], v[238:239], s[62:63], v[154:155] op_sel_hi:[1,0,1]
	v_pk_fma_f32 v[152:153], v[234:235], s[62:63], v[152:153] op_sel_hi:[1,0,1]
	v_mov_b32_e32 v239, v155
	v_cvt_pk_bf16_f32 v234, v152, v153
	v_cvt_pk_bf16_f32 v235, v154, v155
	global_store_dwordx2 v[158:159], v[234:235], off offset:32
	v_pk_mov_b32 v[234:235], v[152:153], v[154:155] op_sel:[1,0]
	v_mul_f32_e32 v153, v153, v153
	v_mov_b32_e32 v238, v152
	v_fmac_f32_e32 v153, v152, v152
	v_mul_f32_e32 v152, v155, v155
	v_fmac_f32_e32 v152, v154, v154
	v_add_f32_e32 v152, v153, v152
	v_add_f32_e32 v156, v156, v152
	v_lshlrev_b32_e32 v152, 16, v232
	v_and_b32_e32 v153, 0xffff0000, v232
	v_lshlrev_b32_e32 v154, 16, v233
	v_and_b32_e32 v155, 0xffff0000, v233
	v_sub_f32_e32 v153, v153, v237
	v_sub_f32_e32 v152, v152, v237
	v_sub_f32_e32 v155, v155, v237
	v_sub_f32_e32 v154, v154, v237
	v_pk_mul_f32 v[154:155], v[154:155], v[236:237] op_sel_hi:[1,0]
	v_pk_mul_f32 v[152:153], v[152:153], v[236:237] op_sel_hi:[1,0]
	v_pk_fma_f32 v[154:155], v[58:59], v[154:155], v[62:63]
	v_pk_fma_f32 v[152:153], v[56:57], v[152:153], v[60:61]
	v_pk_fma_f32 v[150:151], v[154:155], s[62:63], v[150:151] op_sel_hi:[1,0,1]
	v_pk_fma_f32 v[148:149], v[152:153], s[62:63], v[148:149] op_sel_hi:[1,0,1]
	v_add_f32_e32 v155, v150, v151
	v_cvt_pk_bf16_f32 v152, v148, v149
	v_cvt_pk_bf16_f32 v153, v150, v151
	global_store_dwordx2 v[158:159], v[152:153], off offset:256
	v_add_f32_e32 v153, v148, v149
	v_mul_f32_e32 v149, v149, v149
	v_fmac_f32_e32 v149, v148, v148
	v_mul_f32_e32 v148, v151, v151
	v_fmac_f32_e32 v148, v150, v150
	v_add_f32_e32 v148, v149, v148
	v_add_f32_e32 v232, v148, v156
	v_lshlrev_b32_e32 v148, 16, v230
	v_and_b32_e32 v149, 0xffff0000, v230
	v_lshlrev_b32_e32 v150, 16, v231
	v_and_b32_e32 v151, 0xffff0000, v231
	v_sub_f32_e32 v149, v149, v237
	v_sub_f32_e32 v148, v148, v237
	v_sub_f32_e32 v151, v151, v237
	v_sub_f32_e32 v150, v150, v237
	v_pk_mul_f32 v[150:151], v[150:151], v[236:237] op_sel_hi:[1,0]
	v_pk_mul_f32 v[148:149], v[148:149], v[236:237] op_sel_hi:[1,0]
	v_pk_add_f32 v[234:235], v[234:235], v[238:239]
	v_pk_fma_f32 v[148:149], v[48:49], v[148:149], v[52:53]
	v_pk_fma_f32 v[150:151], v[50:51], v[150:151], v[54:55]
	v_pk_add_f32 v[234:235], v[234:235], v[234:235] op_sel_hi:[0,1]
	v_pk_fma_f32 v[146:147], v[150:151], s[62:63], v[146:147] op_sel_hi:[1,0,1]
	v_pk_fma_f32 v[144:145], v[148:149], s[62:63], v[144:145] op_sel_hi:[1,0,1]
	v_mov_b32_e32 v234, v146
	v_cvt_pk_bf16_f32 v148, v144, v145
	v_cvt_pk_bf16_f32 v149, v146, v147
	v_mov_b32_e32 v152, v144
	v_mov_b32_e32 v154, v145
	v_mov_b32_e32 v156, v147
	global_store_dwordx2 v[158:159], v[148:149], off offset:288
	v_pk_add_f32 v[148:149], v[152:153], v[154:155]
	v_pk_add_f32 v[150:151], v[234:235], v[156:157]
	v_mul_f32_e32 v145, v145, v145
	v_pk_add_f32 v[148:149], v[148:149], v[150:151]
	v_fmac_f32_e32 v145, v144, v144
	v_mul_f32_e32 v144, v147, v147
	v_pk_add_f32 v[148:149], v[148:149], v[148:149] op_sel:[0,1] op_sel_hi:[1,0]
	v_fmac_f32_e32 v144, v146, v146
	v_add_f32_e32 v144, v145, v144
	v_mov_b32_e32 v145, v148
	v_add_f32_e32 v144, v144, v232
	s_nop 0
	v_permlane16_swap_b32_e32 v148, v145
	v_add_f32_e32 v148, v148, v145
	v_mov_b32_e32 v145, v144
	s_nop 1
	v_permlane16_swap_b32_e32 v144, v145
	v_add_f32_e32 v146, v144, v145
	v_mov_b32_e32 v149, v148
	v_mov_b32_e32 v147, v146
	s_nop 0
	v_permlane32_swap_b32_e32 v148, v149
	v_permlane32_swap_b32_e32 v146, v147
	v_mov_b64_e32 v[144:145], 0x80000
	s_and_saveexec_b64 s[0:1], s[8:9]
	s_cbranch_execz .LBB0_864
	v_cmp_eq_u32_e64 s[8:9], 1, v247
	s_mov_b64 s[12:13], 0
	v_mov_b64_e32 v[144:145], 0x80000
	s_and_saveexec_b64 s[14:15], s[8:9]
	s_mov_b64 s[12:13], exec
	v_mov_b64_e32 v[144:145], 0xc0000
	s_or_b64 exec, exec, s[14:15]
	s_orn2_b64 s[12:13], s[12:13], exec
	v_mov_b32_e32 v148, v146
	v_mov_b32_e32 v149, v147

.LBB0_1056:
	s_add_u32 s0, s78, 0xfff80080
	s_addc_u32 s1, s79, -1
	s_add_i32 s50, 0, 0x10000
	v_add_u32_e32 v76, s50, v205
	ds_read_b128 v[64:67], v76
	ds_read_b128 v[68:71], v76 offset:1024
	ds_read_b128 v[72:75], v76 offset:2048
	ds_read_b128 v[76:79], v76 offset:3072
	s_cmp_eq_u32 s47, 28
	s_cselect_b32 s81, s14, s1
	s_cselect_b32 s80, s15, s0
	s_cselect_b32 s1, s16, s13
	s_cselect_b32 s0, s17, s12
	ds_read_b128 v[80:83], v207
	ds_read_b128 v[84:87], v207 offset:1024
	ds_read_b128 v[88:91], v207 offset:2048
	ds_read_b128 v[92:95], v207 offset:3072
	ds_read_b128 v[180:183], v207 offset:4096
	ds_read_b128 v[184:187], v207 offset:5120
	ds_read_b128 v[188:191], v207 offset:6144
	ds_read_b128 v[192:195], v207 offset:7168
	s_waitcnt lgkmcnt(8)
	s_barrier
	s_waitcnt lgkmcnt(0)
	s_waitcnt lgkmcnt(0)
	v_mfma_f32_16x16x32_bf16 v[156:159], v[64:67], v[80:83], v[156:159]
	v_mfma_f32_16x16x32_bf16 v[152:155], v[72:75], v[80:83], v[152:155]
	v_mfma_f32_16x16x32_bf16 v[148:151], v[64:67], v[88:91], v[148:151]
	v_mfma_f32_16x16x32_bf16 v[140:143], v[72:75], v[88:91], v[140:143]
	v_mfma_f32_16x16x32_bf16 v[132:135], v[64:67], v[180:183], v[132:135]
	v_mfma_f32_16x16x32_bf16 v[124:127], v[72:75], v[180:183], v[124:127]
	v_mfma_f32_16x16x32_bf16 v[116:119], v[64:67], v[188:191], v[116:119]
	v_mfma_f32_16x16x32_bf16 v[108:111], v[72:75], v[188:191], v[108:111]
	v_mfma_f32_16x16x32_bf16 v[156:159], v[68:71], v[84:87], v[156:159]
	v_mfma_f32_16x16x32_bf16 v[152:155], v[76:79], v[84:87], v[152:155]
	v_mfma_f32_16x16x32_bf16 v[148:151], v[68:71], v[92:95], v[148:151]
	v_mfma_f32_16x16x32_bf16 v[140:143], v[76:79], v[92:95], v[140:143]
	v_mfma_f32_16x16x32_bf16 v[132:135], v[68:71], v[184:187], v[132:135]
	v_mfma_f32_16x16x32_bf16 v[124:127], v[76:79], v[184:187], v[124:127]
	v_mfma_f32_16x16x32_bf16 v[116:119], v[68:71], v[192:195], v[116:119]
	v_mfma_f32_16x16x32_bf16 v[108:111], v[76:79], v[192:195], v[108:111]
	s_barrier
	v_lshl_add_u64 v[196:197], s[78:79], 0, v[176:177]
	s_add_i32 m0, s22, 0xc000
	s_nop 0
	global_load_lds_dwordx4 v[196:197], off
	v_lshl_add_u64 v[196:197], s[78:79], 0, v[178:179]
	s_add_i32 m0, s22, 0xe000
	s_nop 0
	global_load_lds_dwordx4 v[196:197], off
	s_add_i32 s66, 0, 0x14000
	s_add_i32 s50, s50, s21
	v_add_u32_e32 v212, s66, v205
	v_lshl_add_u64 v[224:225], s[0:1], 0, v[160:161]
	s_mov_b32 m0, s50
	ds_read_b128 v[196:199], v212
	ds_read_b128 v[200:203], v212 offset:1024
	ds_read_b128 v[208:211], v212 offset:2048
	ds_read_b128 v[212:215], v212 offset:3072
	global_load_lds_dwordx4 v[224:225], off
	v_lshl_add_u64 v[226:227], s[0:1], 0, v[170:171]
	s_add_i32 m0, s50, 0x2000
	s_nop 0
	global_load_lds_dwordx4 v[226:227], off
	s_barrier
	s_waitcnt lgkmcnt(0)
	s_waitcnt lgkmcnt(0)
	v_mfma_f32_16x16x32_bf16 v[144:147], v[196:199], v[80:83], v[144:147]
	v_mfma_f32_16x16x32_bf16 v[80:83], v[208:211], v[80:83], v[136:139]
	v_mfma_f32_16x16x32_bf16 v[144:147], v[200:203], v[84:87], v[144:147]
	v_mfma_f32_16x16x32_bf16 v[80:83], v[212:215], v[84:87], v[80:83]
	v_mfma_f32_16x16x32_bf16 v[84:87], v[196:199], v[88:91], v[128:131]
	v_mfma_f32_16x16x32_bf16 v[88:91], v[208:211], v[88:91], v[120:123]
	v_mfma_f32_16x16x32_bf16 v[104:107], v[208:211], v[180:183], v[104:107]
	v_mfma_f32_16x16x32_bf16 v[100:103], v[196:199], v[188:191], v[100:103]
	v_mfma_f32_16x16x32_bf16 v[96:99], v[208:211], v[188:191], v[96:99]
	v_mfma_f32_16x16x32_bf16 v[84:87], v[200:203], v[92:95], v[84:87]
	v_mfma_f32_16x16x32_bf16 v[88:91], v[212:215], v[92:95], v[88:91]
	v_mfma_f32_16x16x32_bf16 v[92:95], v[196:199], v[180:183], v[112:115]
	v_mfma_f32_16x16x32_bf16 v[104:107], v[212:215], v[184:187], v[104:107]
	v_mfma_f32_16x16x32_bf16 v[100:103], v[200:203], v[192:195], v[100:103]
	v_mfma_f32_16x16x32_bf16 v[96:99], v[212:215], v[192:195], v[96:99]
	v_mfma_f32_16x16x32_bf16 v[92:95], v[200:203], v[184:187], v[92:95]
	s_mov_b32 m0, s22
	v_lshl_add_u64 v[228:229], s[80:81], 0, v[174:175]
	s_barrier
	ds_read_b128 v[112:115], v207 offset:16384
	ds_read_b128 v[120:123], v207 offset:17408
	ds_read_b128 v[128:131], v207 offset:18432
	ds_read_b128 v[136:139], v207 offset:19456
	ds_read_b128 v[180:183], v207 offset:20480
	ds_read_b128 v[184:187], v207 offset:21504
	ds_read_b128 v[188:191], v207 offset:22528
	ds_read_b128 v[192:195], v207 offset:23552
	global_load_lds_dwordx4 v[228:229], off
	v_lshl_add_u64 v[230:231], s[80:81], 0, v[172:173]
	s_mov_b32 m0, s23
	s_nop 0
	global_load_lds_dwordx4 v[230:231], off
	s_barrier
	s_waitcnt lgkmcnt(0)
	s_waitcnt lgkmcnt(0)
	v_mfma_f32_16x16x32_bf16 v[60:63], v[64:67], v[112:115], v[60:63]
	v_mfma_f32_16x16x32_bf16 v[56:59], v[72:75], v[112:115], v[56:59]
	v_mfma_f32_16x16x32_bf16 v[44:47], v[64:67], v[128:131], v[44:47]
	v_mfma_f32_16x16x32_bf16 v[40:43], v[72:75], v[128:131], v[40:43]
	v_mfma_f32_16x16x32_bf16 v[28:31], v[64:67], v[180:183], v[28:31]
	v_mfma_f32_16x16x32_bf16 v[24:27], v[72:75], v[180:183], v[24:27]
	v_mfma_f32_16x16x32_bf16 v[12:15], v[64:67], v[188:191], v[12:15]
	v_mfma_f32_16x16x32_bf16 v[8:11], v[72:75], v[188:191], v[8:11]
	v_mfma_f32_16x16x32_bf16 v[60:63], v[68:71], v[120:123], v[60:63]
	v_mfma_f32_16x16x32_bf16 v[56:59], v[76:79], v[120:123], v[56:59]
	v_mfma_f32_16x16x32_bf16 v[44:47], v[68:71], v[136:139], v[44:47]
	v_mfma_f32_16x16x32_bf16 v[40:43], v[76:79], v[136:139], v[40:43]
	v_mfma_f32_16x16x32_bf16 v[28:31], v[68:71], v[184:187], v[28:31]
	v_mfma_f32_16x16x32_bf16 v[24:27], v[76:79], v[184:187], v[24:27]
	v_mfma_f32_16x16x32_bf16 v[12:15], v[68:71], v[192:195], v[12:15]
	v_mfma_f32_16x16x32_bf16 v[8:11], v[76:79], v[192:195], v[8:11]
	s_barrier
	s_add_u32 s50, s0, 0x80000
	s_addc_u32 s51, s1, 0
	s_add_i32 s66, s66, s21
	v_lshl_add_u64 v[64:65], s[50:51], 0, v[160:161]
	s_mov_b32 m0, s66
	s_nop 0
	global_load_lds_dwordx4 v[64:65], off
	v_lshl_add_u64 v[64:65], s[50:51], 0, v[170:171]
	s_add_i32 m0, s66, 0x2000
	s_nop 0
	global_load_lds_dwordx4 v[64:65], off
	v_add_u32_e32 v76, 0x18000, v205
	ds_read_b128 v[64:67], v76
	ds_read_b128 v[68:71], v76 offset:1024
	ds_read_b128 v[72:75], v76 offset:2048
	ds_read_b128 v[76:79], v76 offset:3072
	s_waitcnt vmcnt(6)
	s_barrier
	v_mfma_f32_16x16x32_bf16 v[52:55], v[196:199], v[112:115], v[52:55]
	v_mfma_f32_16x16x32_bf16 v[48:51], v[208:211], v[112:115], v[48:51]
	v_mfma_f32_16x16x32_bf16 v[36:39], v[196:199], v[128:131], v[36:39]
	v_mfma_f32_16x16x32_bf16 v[32:35], v[208:211], v[128:131], v[32:35]
	v_mfma_f32_16x16x32_bf16 v[20:23], v[196:199], v[180:183], v[20:23]
	v_mfma_f32_16x16x32_bf16 v[16:19], v[208:211], v[180:183], v[16:19]
	v_mfma_f32_16x16x32_bf16 v[4:7], v[196:199], v[188:191], v[4:7]
	v_mfma_f32_16x16x32_bf16 v[0:3], v[208:211], v[188:191], v[0:3]
	v_mfma_f32_16x16x32_bf16 v[52:55], v[200:203], v[120:123], v[52:55]
	v_mfma_f32_16x16x32_bf16 v[48:51], v[212:215], v[120:123], v[48:51]
	v_mfma_f32_16x16x32_bf16 v[36:39], v[200:203], v[136:139], v[36:39]
	v_mfma_f32_16x16x32_bf16 v[32:35], v[212:215], v[136:139], v[32:35]
	v_mfma_f32_16x16x32_bf16 v[20:23], v[200:203], v[184:187], v[20:23]
	v_mfma_f32_16x16x32_bf16 v[16:19], v[212:215], v[184:187], v[16:19]
	v_mfma_f32_16x16x32_bf16 v[4:7], v[200:203], v[192:195], v[4:7]
	v_mfma_f32_16x16x32_bf16 v[0:3], v[212:215], v[192:195], v[0:3]
	s_add_i32 s66, 0, 0x18000
	s_barrier
	ds_read_b128 v[112:115], v207 offset:32768
	ds_read_b128 v[120:123], v207 offset:33792
	ds_read_b128 v[180:183], v207 offset:34816
	ds_read_b128 v[184:187], v207 offset:35840
	ds_read_b128 v[188:191], v207 offset:36864
	ds_read_b128 v[192:195], v207 offset:37888
	ds_read_b128 v[196:199], v207 offset:38912
	ds_read_b128 v[200:203], v207 offset:39936
	s_waitcnt lgkmcnt(8)
	s_barrier
	s_waitcnt lgkmcnt(0)
	s_waitcnt lgkmcnt(0)
	v_mfma_f32_16x16x32_bf16 v[128:131], v[64:67], v[112:115], v[156:159]
	v_mfma_f32_16x16x32_bf16 v[156:159], v[68:71], v[120:123], v[128:131]
	v_mfma_f32_16x16x32_bf16 v[128:131], v[72:75], v[112:115], v[152:155]
	v_mfma_f32_16x16x32_bf16 v[152:155], v[76:79], v[120:123], v[128:131]
	v_mfma_f32_16x16x32_bf16 v[128:131], v[64:67], v[180:183], v[148:151]
	v_mfma_f32_16x16x32_bf16 v[148:151], v[68:71], v[184:187], v[128:131]
	v_mfma_f32_16x16x32_bf16 v[128:131], v[72:75], v[180:183], v[140:143]
	v_mfma_f32_16x16x32_bf16 v[140:143], v[76:79], v[184:187], v[128:131]
	v_mfma_f32_16x16x32_bf16 v[128:131], v[64:67], v[188:191], v[132:135]
	v_mfma_f32_16x16x32_bf16 v[124:127], v[72:75], v[188:191], v[124:127]
	v_mfma_f32_16x16x32_bf16 v[116:119], v[64:67], v[196:199], v[116:119]
	v_mfma_f32_16x16x32_bf16 v[108:111], v[72:75], v[196:199], v[108:111]
	v_mfma_f32_16x16x32_bf16 v[132:135], v[68:71], v[192:195], v[128:131]
	v_mfma_f32_16x16x32_bf16 v[124:127], v[76:79], v[192:195], v[124:127]
	v_mfma_f32_16x16x32_bf16 v[116:119], v[68:71], v[200:203], v[116:119]
	v_mfma_f32_16x16x32_bf16 v[108:111], v[76:79], v[200:203], v[108:111]
	s_barrier
	s_add_u32 s50, s80, 0x80000
	s_addc_u32 s51, s81, 0
	v_lshl_add_u64 v[128:129], s[50:51], 0, v[174:175]
	s_mov_b32 m0, s24
	s_nop 0
	global_load_lds_dwordx4 v[128:129], off
	v_lshl_add_u64 v[128:129], s[50:51], 0, v[172:173]
	s_mov_b32 m0, s25
	s_nop 0
	global_load_lds_dwordx4 v[128:129], off
	s_add_i32 s50, 0, 0x1c000
	v_add_u32_e32 v128, s50, v205
	s_add_i32 s51, s66, s21
	ds_read_b128 v[208:211], v128
	ds_read_b128 v[212:215], v128 offset:1024
	ds_read_b128 v[216:219], v128 offset:2048
	ds_read_b128 v[220:223], v128 offset:3072
	v_lshl_add_u64 v[128:129], v[224:225], 0, s[92:93]
	s_mov_b32 m0, s51
	s_nop 0
	global_load_lds_dwordx4 v[128:129], off
	v_lshl_add_u64 v[128:129], v[226:227], 0, s[92:93]
	s_add_i32 m0, s51, 0x2000
	s_nop 0
	global_load_lds_dwordx4 v[128:129], off
	s_barrier
	s_waitcnt lgkmcnt(0)
	s_waitcnt lgkmcnt(0)
	v_mfma_f32_16x16x32_bf16 v[80:83], v[216:219], v[112:115], v[80:83]
	v_mfma_f32_16x16x32_bf16 v[128:131], v[208:211], v[112:115], v[144:147]
	v_mfma_f32_16x16x32_bf16 v[136:139], v[220:223], v[120:123], v[80:83]
	v_mfma_f32_16x16x32_bf16 v[80:83], v[208:211], v[180:183], v[84:87]
	v_mfma_f32_16x16x32_bf16 v[144:147], v[212:215], v[120:123], v[128:131]
	v_mfma_f32_16x16x32_bf16 v[128:131], v[212:215], v[184:187], v[80:83]
	v_mfma_f32_16x16x32_bf16 v[80:83], v[216:219], v[180:183], v[88:91]
	v_mfma_f32_16x16x32_bf16 v[120:123], v[220:223], v[184:187], v[80:83]
	v_mfma_f32_16x16x32_bf16 v[80:83], v[208:211], v[188:191], v[92:95]
	v_mfma_f32_16x16x32_bf16 v[112:115], v[212:215], v[192:195], v[80:83]
	v_mfma_f32_16x16x32_bf16 v[80:83], v[216:219], v[188:191], v[104:107]
	v_mfma_f32_16x16x32_bf16 v[104:107], v[220:223], v[192:195], v[80:83]
	v_mfma_f32_16x16x32_bf16 v[80:83], v[208:211], v[196:199], v[100:103]
	v_mfma_f32_16x16x32_bf16 v[100:103], v[212:215], v[200:203], v[80:83]
	v_mfma_f32_16x16x32_bf16 v[80:83], v[216:219], v[196:199], v[96:99]
	v_mfma_f32_16x16x32_bf16 v[96:99], v[220:223], v[200:203], v[80:83]
	s_mov_b32 m0, s26
	v_lshl_add_u64 v[196:197], v[228:229], 0, s[92:93]
	s_barrier
	s_nop 2
	ds_read_b128 v[80:83], v207 offset:49152
	ds_read_b128 v[84:87], v207 offset:50176
	ds_read_b128 v[88:91], v207 offset:51200
	ds_read_b128 v[92:95], v207 offset:52224
	ds_read_b128 v[180:183], v207 offset:53248
	ds_read_b128 v[184:187], v207 offset:54272
	ds_read_b128 v[188:191], v207 offset:55296
	ds_read_b128 v[192:195], v207 offset:56320
	global_load_lds_dwordx4 v[196:197], off
	v_lshl_add_u64 v[196:197], v[230:231], 0, s[92:93]
	s_mov_b32 m0, s27
	s_nop 0
	global_load_lds_dwordx4 v[196:197], off
	s_barrier
	s_waitcnt lgkmcnt(0)
	s_waitcnt lgkmcnt(0)
	v_mfma_f32_16x16x32_bf16 v[60:63], v[64:67], v[80:83], v[60:63]
	v_mfma_f32_16x16x32_bf16 v[56:59], v[72:75], v[80:83], v[56:59]
	v_mfma_f32_16x16x32_bf16 v[44:47], v[64:67], v[88:91], v[44:47]
	v_mfma_f32_16x16x32_bf16 v[40:43], v[72:75], v[88:91], v[40:43]
	v_mfma_f32_16x16x32_bf16 v[28:31], v[64:67], v[180:183], v[28:31]
	v_mfma_f32_16x16x32_bf16 v[24:27], v[72:75], v[180:183], v[24:27]
	v_mfma_f32_16x16x32_bf16 v[12:15], v[64:67], v[188:191], v[12:15]
	v_mfma_f32_16x16x32_bf16 v[8:11], v[72:75], v[188:191], v[8:11]
	v_mfma_f32_16x16x32_bf16 v[60:63], v[68:71], v[84:87], v[60:63]
	v_mfma_f32_16x16x32_bf16 v[56:59], v[76:79], v[84:87], v[56:59]
	v_mfma_f32_16x16x32_bf16 v[44:47], v[68:71], v[92:95], v[44:47]
	v_mfma_f32_16x16x32_bf16 v[40:43], v[76:79], v[92:95], v[40:43]
	v_mfma_f32_16x16x32_bf16 v[28:31], v[68:71], v[184:187], v[28:31]
	v_mfma_f32_16x16x32_bf16 v[24:27], v[76:79], v[184:187], v[24:27]
	v_mfma_f32_16x16x32_bf16 v[12:15], v[68:71], v[192:195], v[12:15]
	v_mfma_f32_16x16x32_bf16 v[8:11], v[76:79], v[192:195], v[8:11]
	s_barrier
	s_add_u32 s0, s0, 0x80080
	s_addc_u32 s1, s1, 0
	s_add_i32 s50, s50, s21
	v_lshl_add_u64 v[64:65], s[0:1], 0, v[160:161]
	s_mov_b32 m0, s50
	s_nop 0
	global_load_lds_dwordx4 v[64:65], off
	v_lshl_add_u64 v[64:65], s[0:1], 0, v[170:171]
	s_add_i32 m0, s50, 0x2000
	s_nop 0
	global_load_lds_dwordx4 v[64:65], off
	s_waitcnt vmcnt(6)
	s_barrier
	v_mfma_f32_16x16x32_bf16 v[52:55], v[208:211], v[80:83], v[52:55]
	v_mfma_f32_16x16x32_bf16 v[48:51], v[216:219], v[80:83], v[48:51]
	v_mfma_f32_16x16x32_bf16 v[36:39], v[208:211], v[88:91], v[36:39]
	v_mfma_f32_16x16x32_bf16 v[32:35], v[216:219], v[88:91], v[32:35]
	v_mfma_f32_16x16x32_bf16 v[20:23], v[208:211], v[180:183], v[20:23]
	v_mfma_f32_16x16x32_bf16 v[16:19], v[216:219], v[180:183], v[16:19]
	v_mfma_f32_16x16x32_bf16 v[4:7], v[208:211], v[188:191], v[4:7]
	v_mfma_f32_16x16x32_bf16 v[0:3], v[216:219], v[188:191], v[0:3]
	v_mfma_f32_16x16x32_bf16 v[52:55], v[212:215], v[84:87], v[52:55]
	v_mfma_f32_16x16x32_bf16 v[48:51], v[220:223], v[84:87], v[48:51]
	v_mfma_f32_16x16x32_bf16 v[36:39], v[212:215], v[92:95], v[36:39]
	v_mfma_f32_16x16x32_bf16 v[32:35], v[220:223], v[92:95], v[32:35]
	v_mfma_f32_16x16x32_bf16 v[20:23], v[212:215], v[184:187], v[20:23]
	v_mfma_f32_16x16x32_bf16 v[16:19], v[220:223], v[184:187], v[16:19]
	v_mfma_f32_16x16x32_bf16 v[4:7], v[212:215], v[192:195], v[4:7]
	v_mfma_f32_16x16x32_bf16 v[0:3], v[220:223], v[192:195], v[0:3]
	s_add_i32 s47, s47, 2
	s_add_u32 s78, s78, 0x100
	s_addc_u32 s79, s79, 0
	s_add_u32 s12, s12, 0x100
	s_addc_u32 s13, s13, 0
	s_cmp_gt_u32 s47, 29
	s_barrier
	s_cbranch_scc0 .LBB0_1056
	v_lshl_or_b32 v182, s48, 8, v206
	v_ashrrev_i32_e32 v183, 31, v182
	v_lshlrev_b64 v[64:65], 2, v[182:183]
	v_lshl_add_u64 v[66:67], s[44:45], 0, v[64:65]
	v_lshl_add_u64 v[64:65], s[42:43], 0, v[64:65]
	global_load_dwordx4 v[72:75], v[66:67], off offset:16
	global_load_dwordx4 v[92:95], v[66:67], off
	global_load_dwordx4 v[68:71], v[64:65], off offset:16
	global_load_dwordx4 v[88:91], v[64:65], off
	v_or_b32_e32 v64, 0x80, v182
	v_lshl_add_u32 v180, s49, 8, v204
	v_ashrrev_i32_e32 v65, 31, v64
	v_or_b32_e32 v84, 0x84, v182
	v_lshlrev_b64 v[64:65], 2, v[64:65]
	v_ashrrev_i32_e32 v85, 31, v84
	v_ashrrev_i32_e32 v181, 31, v180
	v_lshl_add_u64 v[66:67], s[44:45], 0, v[64:65]
	v_lshl_add_u64 v[76:77], s[42:43], 0, v[64:65]
	v_lshl_add_u64 v[84:85], v[84:85], 2, s[44:45]
	v_lshl_add_u64 v[202:203], v[180:181], 3, s[8:9]
	global_load_dwordx4 v[80:83], v[66:67], off
	s_nop 0
	global_load_dwordx4 v[64:67], v[76:77], off offset:16
	s_nop 0
	global_load_dwordx4 v[76:79], v[76:77], off
	v_add_co_u32_e32 v200, vcc, s89, v202
	global_load_dwordx4 v[84:87], v[84:85], off
	s_nop 0
	v_addc_co_u32_e32 v201, vcc, 0, v203, vcc
	global_load_dwordx2 v[184:185], v[202:203], off
	global_load_dwordx2 v[186:187], v[200:201], off
	global_load_dwordx2 v[208:209], v[202:203], off offset:128
	global_load_dwordx2 v[210:211], v[200:201], off offset:128
	global_load_dwordx2 v[212:213], v[202:203], off offset:256
	global_load_dwordx2 v[214:215], v[200:201], off offset:256
	global_load_dwordx2 v[216:217], v[202:203], off offset:384
	global_load_dwordx2 v[218:219], v[200:201], off offset:384
	s_mov_b64 s[0:1], 0x200000
	v_readlane_b32 s66, v255, 7
	s_mov_b32 s48, s72
	s_mov_b32 s49, s46
	s_mov_b64 s[12:13], s[74:75]
	v_readlane_b32 s67, v255, 8
	s_waitcnt vmcnt(0)
	v_xor_b32_e32 v197, 0x80000000, v75
	v_xor_b32_e32 v196, 0x80000000, v74
	v_xor_b32_e32 v199, 0x80000000, v95
	v_xor_b32_e32 v198, 0x80000000, v94
	v_xor_b32_e32 v195, 0x80000000, v83
	v_xor_b32_e32 v194, 0x80000000, v82
	v_cvt_f32_u32_e32 v188, v186
	v_xor_b32_e32 v193, 0x80000000, v87
	v_xor_b32_e32 v192, 0x80000000, v86
	v_cvt_f32_u32_e32 v189, v184
	v_cvt_f32_i32_e32 v184, v187
	v_cvt_f32_i32_e32 v185, v185
	v_pk_fma_f32 v[184:185], v[188:189], s[88:89], v[184:185] op_sel_hi:[1,0,1]
	s_nop 0
	v_pk_mul_f32 v[220:221], v[184:185], s[94:95] op_sel_hi:[1,0]
	s_nop 0
	v_fma_f32 v184, -v221, v221, v220
	v_add_f32_e32 v184, 0x3727c5ac, v184
	v_rsq_f32_e32 v222, v184
	v_pk_fma_f32 v[74:75], v[196:197], v[220:221], v[154:155] op_sel:[0,1,0]
	v_pk_fma_f32 v[156:157], v[92:93], v[220:221], v[156:157] op_sel:[0,1,0] neg_lo:[1,0,0] neg_hi:[1,0,0]
	v_pk_fma_f32 v[94:95], v[198:199], v[220:221], v[158:159] op_sel:[0,1,0]
	v_pk_fma_f32 v[186:187], v[74:75], v[222:223], v[70:71] op_sel_hi:[1,0,1]
	v_pk_fma_f32 v[74:75], v[80:81], v[220:221], v[144:145] op_sel:[0,1,0] neg_lo:[1,0,0] neg_hi:[1,0,0]
	v_pk_fma_f32 v[82:83], v[194:195], v[220:221], v[146:147] op_sel:[0,1,0]
	v_pk_fma_f32 v[184:185], v[94:95], v[222:223], v[90:91] op_sel_hi:[1,0,1]
	v_pk_fma_f32 v[188:189], v[156:157], v[222:223], v[88:89] op_sel_hi:[1,0,1]
	v_pk_fma_f32 v[94:95], v[72:73], v[220:221], v[152:153] op_sel:[0,1,0] neg_lo:[1,0,0] neg_hi:[1,0,0]
	v_pk_fma_f32 v[152:153], v[82:83], v[222:223], v[78:79] op_sel_hi:[1,0,1]
	v_pk_fma_f32 v[156:157], v[74:75], v[222:223], v[76:77] op_sel_hi:[1,0,1]
	v_pk_fma_f32 v[74:75], v[84:85], v[220:221], v[136:137] op_sel:[0,1,0] neg_lo:[1,0,0] neg_hi:[1,0,0]
	v_pk_fma_f32 v[82:83], v[192:193], v[220:221], v[138:139] op_sel:[0,1,0]
	v_pk_fma_f32 v[158:159], v[74:75], v[222:223], v[64:65] op_sel_hi:[1,0,1]
	v_pk_fma_f32 v[154:155], v[82:83], v[222:223], v[66:67] op_sel_hi:[1,0,1]
	v_cvt_f32_u32_e32 v74, v210
	v_cvt_f32_u32_e32 v75, v208
	v_cvt_f32_i32_e32 v82, v211
	v_cvt_f32_i32_e32 v83, v209
	v_pk_fma_f32 v[190:191], v[94:95], v[222:223], v[68:69] op_sel_hi:[1,0,1]
	v_pk_fma_f32 v[74:75], v[74:75], s[88:89], v[82:83] op_sel_hi:[1,0,1]
	s_nop 0
	v_pk_mul_f32 v[74:75], v[74:75], s[94:95] op_sel_hi:[1,0]
	s_nop 0
	v_fma_f32 v82, -v75, v75, v74
	v_add_f32_e32 v82, 0x3727c5ac, v82
	v_rsq_f32_e32 v82, v82
	v_pk_fma_f32 v[86:87], v[92:93], v[74:75], v[148:149] op_sel:[0,1,0] neg_lo:[1,0,0] neg_hi:[1,0,0]
	v_pk_fma_f32 v[94:95], v[198:199], v[74:75], v[150:151] op_sel:[0,1,0]
	v_pk_fma_f32 v[148:149], v[86:87], v[82:83], v[88:89] op_sel_hi:[1,0,1]
	v_pk_fma_f32 v[86:87], v[72:73], v[74:75], v[140:141] op_sel:[0,1,0] neg_lo:[1,0,0] neg_hi:[1,0,0]
	v_pk_fma_f32 v[144:145], v[94:95], v[82:83], v[90:91] op_sel_hi:[1,0,1]
	v_pk_fma_f32 v[94:95], v[196:197], v[74:75], v[142:143] op_sel:[0,1,0]
	v_pk_fma_f32 v[150:151], v[86:87], v[82:83], v[68:69] op_sel_hi:[1,0,1]
	v_pk_fma_f32 v[86:87], v[80:81], v[74:75], v[128:129] op_sel:[0,1,0] neg_lo:[1,0,0] neg_hi:[1,0,0]
	v_pk_fma_f32 v[146:147], v[94:95], v[82:83], v[70:71] op_sel_hi:[1,0,1]
	v_pk_fma_f32 v[94:95], v[194:195], v[74:75], v[130:131] op_sel:[0,1,0]
	v_pk_fma_f32 v[140:141], v[86:87], v[82:83], v[76:77] op_sel_hi:[1,0,1]
	v_pk_fma_f32 v[86:87], v[84:85], v[74:75], v[120:121] op_sel:[0,1,0] neg_lo:[1,0,0] neg_hi:[1,0,0]
	v_pk_fma_f32 v[74:75], v[192:193], v[74:75], v[122:123] op_sel:[0,1,0]
	v_pk_fma_f32 v[136:137], v[94:95], v[82:83], v[78:79] op_sel_hi:[1,0,1]
	v_pk_fma_f32 v[138:139], v[74:75], v[82:83], v[66:67] op_sel_hi:[1,0,1]
	v_pk_fma_f32 v[142:143], v[86:87], v[82:83], v[64:65] op_sel_hi:[1,0,1]
	v_cvt_f32_u32_e32 v74, v214
	v_cvt_f32_u32_e32 v75, v212
	v_cvt_f32_i32_e32 v82, v215
	v_cvt_f32_i32_e32 v83, v213
	v_pk_fma_f32 v[74:75], v[74:75], s[88:89], v[82:83] op_sel_hi:[1,0,1]
	s_nop 0
	v_pk_mul_f32 v[74:75], v[74:75], s[94:95] op_sel_hi:[1,0]
	s_nop 0
	v_fma_f32 v82, -v75, v75, v74
	v_add_f32_e32 v82, 0x3727c5ac, v82
	v_rsq_f32_e32 v82, v82
	v_pk_fma_f32 v[86:87], v[92:93], v[74:75], v[132:133] op_sel:[0,1,0] neg_lo:[1,0,0] neg_hi:[1,0,0]
	v_pk_fma_f32 v[94:95], v[198:199], v[74:75], v[134:135] op_sel:[0,1,0]
	v_pk_fma_f32 v[130:131], v[86:87], v[82:83], v[88:89] op_sel_hi:[1,0,1]
	v_pk_fma_f32 v[86:87], v[72:73], v[74:75], v[124:125] op_sel:[0,1,0] neg_lo:[1,0,0] neg_hi:[1,0,0]
	v_pk_fma_f32 v[128:129], v[94:95], v[82:83], v[90:91] op_sel_hi:[1,0,1]
	v_pk_fma_f32 v[94:95], v[196:197], v[74:75], v[126:127] op_sel:[0,1,0]
	v_pk_fma_f32 v[132:133], v[86:87], v[82:83], v[68:69] op_sel_hi:[1,0,1]
	v_pk_fma_f32 v[86:87], v[80:81], v[74:75], v[112:113] op_sel:[0,1,0] neg_lo:[1,0,0] neg_hi:[1,0,0]
	v_pk_fma_f32 v[126:127], v[94:95], v[82:83], v[70:71] op_sel_hi:[1,0,1]
	v_pk_fma_f32 v[94:95], v[194:195], v[74:75], v[114:115] op_sel:[0,1,0]
	v_pk_fma_f32 v[122:123], v[86:87], v[82:83], v[76:77] op_sel_hi:[1,0,1]
	v_pk_fma_f32 v[86:87], v[84:85], v[74:75], v[104:105] op_sel:[0,1,0] neg_lo:[1,0,0] neg_hi:[1,0,0]
	v_pk_fma_f32 v[74:75], v[192:193], v[74:75], v[106:107] op_sel:[0,1,0]
	v_pk_fma_f32 v[114:115], v[94:95], v[82:83], v[78:79] op_sel_hi:[1,0,1]
	v_pk_fma_f32 v[120:121], v[74:75], v[82:83], v[66:67] op_sel_hi:[1,0,1]
	v_pk_fma_f32 v[124:125], v[86:87], v[82:83], v[64:65] op_sel_hi:[1,0,1]
	v_cvt_f32_u32_e32 v74, v218
	v_cvt_f32_u32_e32 v75, v216
	v_cvt_f32_i32_e32 v82, v219
	v_cvt_f32_i32_e32 v83, v217
	v_pk_fma_f32 v[74:75], v[74:75], s[88:89], v[82:83] op_sel_hi:[1,0,1]
	s_nop 0
	v_pk_mul_f32 v[82:83], v[74:75], s[94:95] op_sel_hi:[1,0]
	s_nop 0
	v_fma_f32 v74, -v83, v83, v82
	v_add_f32_e32 v74, 0x3727c5ac, v74
	v_rsq_f32_e32 v94, v74
	v_pk_fma_f32 v[74:75], v[92:93], v[82:83], v[116:117] op_sel:[0,1,0] neg_lo:[1,0,0] neg_hi:[1,0,0]
	v_pk_fma_f32 v[86:87], v[198:199], v[82:83], v[118:119] op_sel:[0,1,0]
	v_pk_fma_f32 v[96:97], v[84:85], v[82:83], v[96:97] op_sel:[0,1,0] neg_lo:[1,0,0] neg_hi:[1,0,0]
	v_pk_fma_f32 v[104:105], v[86:87], v[94:95], v[90:91] op_sel_hi:[1,0,1]
	v_pk_fma_f32 v[112:113], v[74:75], v[94:95], v[88:89] op_sel_hi:[1,0,1]
	v_pk_fma_f32 v[74:75], v[72:73], v[82:83], v[108:109] op_sel:[0,1,0] neg_lo:[1,0,0] neg_hi:[1,0,0]
	v_pk_fma_f32 v[86:87], v[196:197], v[82:83], v[110:111] op_sel:[0,1,0]
	v_pk_fma_f32 v[108:109], v[74:75], v[94:95], v[68:69] op_sel_hi:[1,0,1]
	v_pk_fma_f32 v[106:107], v[86:87], v[94:95], v[70:71] op_sel_hi:[1,0,1]
	v_pk_fma_f32 v[86:87], v[80:81], v[82:83], v[100:101] op_sel:[0,1,0] neg_lo:[1,0,0] neg_hi:[1,0,0]
	v_pk_fma_f32 v[74:75], v[194:195], v[82:83], v[102:103] op_sel:[0,1,0]
	v_pk_fma_f32 v[82:83], v[192:193], v[82:83], v[98:99] op_sel:[0,1,0]
	v_pk_fma_f32 v[74:75], v[74:75], v[94:95], v[78:79] op_sel_hi:[1,0,1]
	v_pk_fma_f32 v[86:87], v[86:87], v[94:95], v[76:77] op_sel_hi:[1,0,1]
	v_pk_fma_f32 v[82:83], v[82:83], v[94:95], v[66:67] op_sel_hi:[1,0,1]
	v_pk_fma_f32 v[94:95], v[96:97], v[94:95], v[64:65] op_sel_hi:[1,0,1]
	global_load_dwordx2 v[102:103], v[202:203], off offset:1024
	global_load_dwordx2 v[110:111], v[200:201], off offset:1024
	global_load_dwordx2 v[98:99], v[202:203], off offset:1152
	global_load_dwordx2 v[100:101], v[200:201], off offset:1152
	global_load_dwordx2 v[96:97], v[202:203], off offset:1280
	global_load_dwordx2 v[118:119], v[200:201], off offset:1280
	global_load_dwordx2 v[116:117], v[202:203], off offset:1408
	global_load_dwordx2 v[134:135], v[200:201], off offset:1408
	s_waitcnt vmcnt(0)
	v_cvt_f32_u32_e32 v201, v102
	v_cvt_f32_u32_e32 v200, v110
	v_cvt_f32_i32_e32 v102, v111
	v_cvt_f32_i32_e32 v103, v103
	v_cvt_f32_i32_e32 v99, v99
	v_cvt_f32_i32_e32 v97, v97
	v_pk_fma_f32 v[102:103], v[200:201], s[88:89], v[102:103] op_sel_hi:[1,0,1]
	s_nop 0
	v_pk_mul_f32 v[102:103], v[102:103], s[94:95] op_sel_hi:[1,0]
	s_nop 0
	v_fma_f32 v110, -v103, v103, v102
	v_add_f32_e32 v110, 0x3727c5ac, v110
	v_rsq_f32_e32 v110, v110
	v_pk_fma_f32 v[200:201], v[92:93], v[102:103], v[60:61] op_sel:[0,1,0] neg_lo:[1,0,0] neg_hi:[1,0,0]
	v_pk_fma_f32 v[60:61], v[198:199], v[102:103], v[62:63] op_sel:[0,1,0]
	v_pk_fma_f32 v[62:63], v[200:201], v[110:111], v[88:89] op_sel_hi:[1,0,1]
	v_pk_fma_f32 v[200:201], v[72:73], v[102:103], v[56:57] op_sel:[0,1,0] neg_lo:[1,0,0] neg_hi:[1,0,0]
	v_pk_fma_f32 v[56:57], v[196:197], v[102:103], v[58:59] op_sel:[0,1,0]
	v_pk_fma_f32 v[58:59], v[200:201], v[110:111], v[68:69] op_sel_hi:[1,0,1]
	v_pk_fma_f32 v[200:201], v[80:81], v[102:103], v[52:53] op_sel:[0,1,0] neg_lo:[1,0,0] neg_hi:[1,0,0]
	v_pk_fma_f32 v[52:53], v[194:195], v[102:103], v[54:55] op_sel:[0,1,0]
	v_pk_fma_f32 v[54:55], v[200:201], v[110:111], v[76:77] op_sel_hi:[1,0,1]
	v_pk_fma_f32 v[200:201], v[84:85], v[102:103], v[48:49] op_sel:[0,1,0] neg_lo:[1,0,0] neg_hi:[1,0,0]
	v_pk_fma_f32 v[48:49], v[192:193], v[102:103], v[50:51] op_sel:[0,1,0]
	v_cvt_f32_u32_e32 v102, v100
	v_cvt_f32_u32_e32 v103, v98
	v_cvt_f32_i32_e32 v98, v101
	v_pk_fma_f32 v[48:49], v[48:49], v[110:111], v[66:67] op_sel_hi:[1,0,1]
	v_pk_fma_f32 v[56:57], v[56:57], v[110:111], v[70:71] op_sel_hi:[1,0,1]
	v_pk_fma_f32 v[50:51], v[200:201], v[110:111], v[64:65] op_sel_hi:[1,0,1]
	v_pk_fma_f32 v[98:99], v[102:103], s[88:89], v[98:99] op_sel_hi:[1,0,1]
	v_pk_fma_f32 v[52:53], v[52:53], v[110:111], v[78:79] op_sel_hi:[1,0,1]
	v_pk_mul_f32 v[98:99], v[98:99], s[94:95] op_sel_hi:[1,0]
	v_pk_fma_f32 v[60:61], v[60:61], v[110:111], v[90:91] op_sel_hi:[1,0,1]
	v_fma_f32 v100, -v99, v99, v98
	v_add_f32_e32 v100, 0x3727c5ac, v100
	v_rsq_f32_e32 v100, v100
	v_pk_fma_f32 v[102:103], v[92:93], v[98:99], v[44:45] op_sel:[0,1,0] neg_lo:[1,0,0] neg_hi:[1,0,0]
	v_pk_fma_f32 v[44:45], v[198:199], v[98:99], v[46:47] op_sel:[0,1,0]
	v_max_f32_e32 v56, 0, v56
	v_pk_fma_f32 v[46:47], v[102:103], v[100:101], v[88:89] op_sel_hi:[1,0,1]
	v_pk_fma_f32 v[102:103], v[72:73], v[98:99], v[40:41] op_sel:[0,1,0] neg_lo:[1,0,0] neg_hi:[1,0,0]
	v_pk_fma_f32 v[40:41], v[196:197], v[98:99], v[42:43] op_sel:[0,1,0]
	v_pk_fma_f32 v[42:43], v[102:103], v[100:101], v[68:69] op_sel_hi:[1,0,1]
	v_pk_fma_f32 v[102:103], v[80:81], v[98:99], v[36:37] op_sel:[0,1,0] neg_lo:[1,0,0] neg_hi:[1,0,0]
	v_pk_fma_f32 v[36:37], v[194:195], v[98:99], v[38:39] op_sel:[0,1,0]
	v_pk_fma_f32 v[38:39], v[102:103], v[100:101], v[76:77] op_sel_hi:[1,0,1]
	v_pk_fma_f32 v[102:103], v[84:85], v[98:99], v[32:33] op_sel:[0,1,0] neg_lo:[1,0,0] neg_hi:[1,0,0]
	v_pk_fma_f32 v[32:33], v[192:193], v[98:99], v[34:35] op_sel:[0,1,0]
	v_cvt_f32_u32_e32 v98, v118
	v_cvt_f32_u32_e32 v99, v96
	v_cvt_f32_i32_e32 v96, v119
	v_pk_fma_f32 v[44:45], v[44:45], v[100:101], v[90:91] op_sel_hi:[1,0,1]
	v_pk_fma_f32 v[40:41], v[40:41], v[100:101], v[70:71] op_sel_hi:[1,0,1]
	v_pk_fma_f32 v[36:37], v[36:37], v[100:101], v[78:79] op_sel_hi:[1,0,1]
	v_pk_fma_f32 v[96:97], v[98:99], s[88:89], v[96:97] op_sel_hi:[1,0,1]
	v_pk_fma_f32 v[32:33], v[32:33], v[100:101], v[66:67] op_sel_hi:[1,0,1]
	v_pk_mul_f32 v[96:97], v[96:97], s[94:95] op_sel_hi:[1,0]
	v_pk_fma_f32 v[34:35], v[102:103], v[100:101], v[64:65] op_sel_hi:[1,0,1]
	v_fma_f32 v98, -v97, v97, v96
	v_add_f32_e32 v98, 0x3727c5ac, v98
	v_rsq_f32_e32 v98, v98
	v_pk_fma_f32 v[100:101], v[92:93], v[96:97], v[28:29] op_sel:[0,1,0] neg_lo:[1,0,0] neg_hi:[1,0,0]
	v_pk_fma_f32 v[28:29], v[198:199], v[96:97], v[30:31] op_sel:[0,1,0]
	v_max_f32_e32 v60, 0, v60
	v_pk_fma_f32 v[30:31], v[100:101], v[98:99], v[88:89] op_sel_hi:[1,0,1]
	v_pk_fma_f32 v[100:101], v[72:73], v[96:97], v[24:25] op_sel:[0,1,0] neg_lo:[1,0,0] neg_hi:[1,0,0]
	v_pk_fma_f32 v[24:25], v[196:197], v[96:97], v[26:27] op_sel:[0,1,0]
	v_pk_fma_f32 v[26:27], v[100:101], v[98:99], v[68:69] op_sel_hi:[1,0,1]
	v_pk_fma_f32 v[100:101], v[80:81], v[96:97], v[20:21] op_sel:[0,1,0] neg_lo:[1,0,0] neg_hi:[1,0,0]
	v_pk_fma_f32 v[20:21], v[194:195], v[96:97], v[22:23] op_sel:[0,1,0]
	v_pk_fma_f32 v[22:23], v[100:101], v[98:99], v[76:77] op_sel_hi:[1,0,1]
	v_pk_fma_f32 v[100:101], v[84:85], v[96:97], v[16:17] op_sel:[0,1,0] neg_lo:[1,0,0] neg_hi:[1,0,0]
	v_pk_fma_f32 v[16:17], v[192:193], v[96:97], v[18:19] op_sel:[0,1,0]
	v_pk_fma_f32 v[28:29], v[28:29], v[98:99], v[90:91] op_sel_hi:[1,0,1]
	v_pk_fma_f32 v[24:25], v[24:25], v[98:99], v[70:71] op_sel_hi:[1,0,1]
	v_pk_fma_f32 v[20:21], v[20:21], v[98:99], v[78:79] op_sel_hi:[1,0,1]
	v_pk_fma_f32 v[16:17], v[16:17], v[98:99], v[66:67] op_sel_hi:[1,0,1]
	v_pk_fma_f32 v[18:19], v[100:101], v[98:99], v[64:65] op_sel_hi:[1,0,1]
	v_cvt_f32_u32_e32 v96, v134
	v_cvt_f32_u32_e32 v97, v116
	v_cvt_f32_i32_e32 v98, v135
	v_cvt_f32_i32_e32 v99, v117
	v_max_f32_e32 v62, 0, v62
	v_max_f32_e32 v63, 0, v63
	v_mul_f32_e32 v60, v60, v60
	v_pk_fma_f32 v[96:97], v[96:97], s[88:89], v[98:99] op_sel_hi:[1,0,1]
	v_max_f32_e32 v57, 0, v57
	v_pk_mul_f32 v[96:97], v[96:97], s[94:95] op_sel_hi:[1,0]
	v_mul_f32_e32 v62, v62, v62
	v_fma_f32 v98, -v97, v97, v96
	v_add_f32_e32 v98, 0x3727c5ac, v98
	v_rsq_f32_e32 v98, v98
	v_pk_fma_f32 v[72:73], v[72:73], v[96:97], v[8:9] op_sel:[0,1,0] neg_lo:[1,0,0] neg_hi:[1,0,0]
	v_pk_fma_f32 v[8:9], v[196:197], v[96:97], v[10:11] op_sel:[0,1,0]
	v_mul_f32_e32 v63, v63, v63
	v_pk_fma_f32 v[10:11], v[72:73], v[98:99], v[68:69] op_sel_hi:[1,0,1]
	v_pk_fma_f32 v[68:69], v[80:81], v[96:97], v[4:5] op_sel:[0,1,0] neg_lo:[1,0,0] neg_hi:[1,0,0]
	v_pk_fma_f32 v[4:5], v[194:195], v[96:97], v[6:7] op_sel:[0,1,0]
	v_pk_fma_f32 v[6:7], v[68:69], v[98:99], v[76:77] op_sel_hi:[1,0,1]
	v_pk_fma_f32 v[68:69], v[84:85], v[96:97], v[0:1] op_sel:[0,1,0] neg_lo:[1,0,0] neg_hi:[1,0,0]
	v_pk_fma_f32 v[0:1], v[192:193], v[96:97], v[2:3] op_sel:[0,1,0]
	v_pk_fma_f32 v[8:9], v[8:9], v[98:99], v[70:71] op_sel_hi:[1,0,1]
	v_pk_fma_f32 v[0:1], v[0:1], v[98:99], v[66:67] op_sel_hi:[1,0,1]
	v_max_f32_e32 v67, 0, v190
	v_pk_fma_f32 v[2:3], v[68:69], v[98:99], v[64:65] op_sel_hi:[1,0,1]
	v_max_f32_e32 v66, 0, v188
	v_mul_f32_e32 v68, v67, v67
	v_max_f32_e32 v67, 0, v189
	v_max_f32_e32 v69, 0, v191
	v_max_f32_e32 v70, 0, v184
	v_max_f32_e32 v71, 0, v186
	v_lshlrev_b64 v[64:65], 14, v[180:181]
	v_mul_f32_e32 v66, v66, v66
	v_mul_f32_e32 v67, v67, v67
	v_mul_f32_e32 v69, v69, v69
	v_mul_f32_e32 v70, v70, v70
	v_mul_f32_e32 v71, v71, v71
	v_max_f32_e32 v72, 0, v185
	v_max_f32_e32 v73, 0, v187
	v_mul_f32_e32 v72, v72, v72
	v_mul_f32_e32 v73, v73, v73
	v_cvt_pk_bf16_f32 v66, v66, v67
	v_cvt_pk_bf16_f32 v67, v70, v72
	v_cvt_pk_bf16_f32 v68, v68, v69
	v_cvt_pk_bf16_f32 v69, v71, v73
	v_lshl_add_u64 v[64:65], s[36:37], 0, v[64:65]
	v_lshlrev_b64 v[70:71], 1, v[182:183]
	v_lshl_add_u64 v[64:65], v[64:65], 0, v[70:71]
	global_store_dwordx4 v[64:65], v[66:69], off nt
	v_max_f32_e32 v72, 0, v152
	v_max_f32_e32 v73, 0, v154
	v_max_f32_e32 v66, 0, v156
	v_max_f32_e32 v67, 0, v158
	v_mul_f32_e32 v66, v66, v66
	v_mul_f32_e32 v68, v67, v67
	v_max_f32_e32 v67, 0, v157
	v_max_f32_e32 v69, 0, v159
	v_mul_f32_e32 v67, v67, v67
	v_mul_f32_e32 v69, v69, v69
	v_max_f32_e32 v76, 0, v153
	v_max_f32_e32 v77, 0, v155
	v_cvt_pk_bf16_f32 v66, v66, v67
	v_mul_f32_e32 v72, v72, v72
	v_mul_f32_e32 v73, v73, v73
	v_mul_f32_e32 v76, v76, v76
	v_mul_f32_e32 v77, v77, v77
	v_cvt_pk_bf16_f32 v67, v72, v76
	v_cvt_pk_bf16_f32 v68, v68, v69
	v_cvt_pk_bf16_f32 v69, v73, v77
	global_store_dwordx4 v[64:65], v[66:69], off offset:256 nt
	v_pk_fma_f32 v[4:5], v[4:5], v[98:99], v[78:79] op_sel_hi:[1,0,1]
	v_max_f32_e32 v76, 0, v144
	v_or_b32_e32 v66, 16, v180
	v_ashrrev_i32_e32 v67, 31, v66
	v_lshlrev_b64 v[72:73], 14, v[66:67]
	v_max_f32_e32 v67, 0, v150
	v_max_f32_e32 v66, 0, v148
	v_mul_f32_e32 v68, v67, v67
	v_max_f32_e32 v67, 0, v149
	v_mul_f32_e32 v66, v66, v66
	v_max_f32_e32 v69, 0, v151
	v_mul_f32_e32 v67, v67, v67
	v_max_f32_e32 v78, 0, v145
	v_lshl_add_u64 v[72:73], s[36:37], 0, v[72:73]
	v_mul_f32_e32 v69, v69, v69
	v_max_f32_e32 v77, 0, v146
	v_mul_f32_e32 v76, v76, v76
	v_max_f32_e32 v79, 0, v147
	v_mul_f32_e32 v78, v78, v78
	v_cvt_pk_bf16_f32 v66, v66, v67
	v_cvt_pk_bf16_f32 v67, v76, v78
	v_lshl_add_u64 v[72:73], v[72:73], 0, v[70:71]
	v_mul_f32_e32 v77, v77, v77
	v_mul_f32_e32 v79, v79, v79
	v_cvt_pk_bf16_f32 v68, v68, v69
	v_cvt_pk_bf16_f32 v69, v77, v79
	global_store_dwordx4 v[72:73], v[66:69], off nt
	v_max_f32_e32 v76, 0, v136
	v_max_f32_e32 v77, 0, v138
	v_max_f32_e32 v66, 0, v140
	v_max_f32_e32 v67, 0, v142
	v_mul_f32_e32 v66, v66, v66
	v_mul_f32_e32 v68, v67, v67
	v_max_f32_e32 v67, 0, v141
	v_max_f32_e32 v69, 0, v143
	v_mul_f32_e32 v67, v67, v67
	v_mul_f32_e32 v69, v69, v69
	v_max_f32_e32 v78, 0, v137
	v_max_f32_e32 v79, 0, v139
	v_cvt_pk_bf16_f32 v66, v66, v67
	v_mul_f32_e32 v76, v76, v76
	v_mul_f32_e32 v77, v77, v77
	v_mul_f32_e32 v78, v78, v78
	v_mul_f32_e32 v79, v79, v79
	v_cvt_pk_bf16_f32 v67, v76, v78
	v_cvt_pk_bf16_f32 v68, v68, v69
	v_cvt_pk_bf16_f32 v69, v77, v79
	global_store_dwordx4 v[72:73], v[66:69], off offset:256 nt
	v_max_f32_e32 v76, 0, v128
	v_max_f32_e32 v78, 0, v129
	v_or_b32_e32 v66, 32, v180
	v_ashrrev_i32_e32 v67, 31, v66
	v_lshlrev_b64 v[72:73], 14, v[66:67]
	v_max_f32_e32 v67, 0, v132
	v_max_f32_e32 v66, 0, v130
	v_mul_f32_e32 v68, v67, v67
	v_max_f32_e32 v67, 0, v131
	v_mul_f32_e32 v66, v66, v66
	v_max_f32_e32 v69, 0, v133
	v_mul_f32_e32 v67, v67, v67
	v_lshl_add_u64 v[72:73], s[36:37], 0, v[72:73]
	v_mul_f32_e32 v69, v69, v69
	v_max_f32_e32 v77, 0, v126
	v_mul_f32_e32 v76, v76, v76
	v_max_f32_e32 v79, 0, v127
	v_mul_f32_e32 v78, v78, v78
	v_cvt_pk_bf16_f32 v66, v66, v67
	v_cvt_pk_bf16_f32 v67, v76, v78
	v_lshl_add_u64 v[72:73], v[72:73], 0, v[70:71]
	v_mul_f32_e32 v77, v77, v77
	v_mul_f32_e32 v79, v79, v79
	v_cvt_pk_bf16_f32 v68, v68, v69
	v_cvt_pk_bf16_f32 v69, v77, v79
	global_store_dwordx4 v[72:73], v[66:69], off nt
	v_max_f32_e32 v76, 0, v114
	v_max_f32_e32 v77, 0, v120
	v_max_f32_e32 v66, 0, v122
	v_max_f32_e32 v67, 0, v124
	v_mul_f32_e32 v66, v66, v66
	v_mul_f32_e32 v68, v67, v67
	v_max_f32_e32 v67, 0, v123
	v_max_f32_e32 v69, 0, v125
	v_mul_f32_e32 v67, v67, v67
	v_mul_f32_e32 v69, v69, v69
	v_max_f32_e32 v78, 0, v115
	v_max_f32_e32 v79, 0, v121
	v_cvt_pk_bf16_f32 v66, v66, v67
	v_mul_f32_e32 v76, v76, v76
	v_mul_f32_e32 v77, v77, v77
	v_mul_f32_e32 v78, v78, v78
	v_mul_f32_e32 v79, v79, v79
	v_cvt_pk_bf16_f32 v67, v76, v78
	v_cvt_pk_bf16_f32 v68, v68, v69
	v_cvt_pk_bf16_f32 v69, v77, v79
	global_store_dwordx4 v[72:73], v[66:69], off offset:256 nt
	v_max_f32_e32 v76, 0, v104
	v_max_f32_e32 v78, 0, v105
	v_or_b32_e32 v66, 48, v180
	v_ashrrev_i32_e32 v67, 31, v66
	v_lshlrev_b64 v[72:73], 14, v[66:67]
	v_max_f32_e32 v67, 0, v108
	v_max_f32_e32 v66, 0, v112
	v_mul_f32_e32 v68, v67, v67
	v_max_f32_e32 v67, 0, v113
	v_mul_f32_e32 v66, v66, v66
	v_max_f32_e32 v69, 0, v109
	v_mul_f32_e32 v67, v67, v67
	v_lshl_add_u64 v[72:73], s[36:37], 0, v[72:73]
	v_mul_f32_e32 v69, v69, v69
	v_max_f32_e32 v77, 0, v106
	v_mul_f32_e32 v76, v76, v76
	v_max_f32_e32 v79, 0, v107
	v_mul_f32_e32 v78, v78, v78
	v_cvt_pk_bf16_f32 v66, v66, v67
	v_cvt_pk_bf16_f32 v67, v76, v78
	v_lshl_add_u64 v[70:71], v[72:73], 0, v[70:71]
	v_mul_f32_e32 v77, v77, v77
	v_mul_f32_e32 v79, v79, v79
	v_cvt_pk_bf16_f32 v68, v68, v69
	v_cvt_pk_bf16_f32 v69, v77, v79
	global_store_dwordx4 v[70:71], v[66:69], off nt
	v_max_f32_e32 v72, 0, v74
	v_max_f32_e32 v73, 0, v82
	v_max_f32_e32 v66, 0, v86
	v_max_f32_e32 v67, 0, v94
	v_mul_f32_e32 v66, v66, v66
	v_mul_f32_e32 v68, v67, v67
	v_max_f32_e32 v67, 0, v87
	v_max_f32_e32 v69, 0, v95
	v_mul_f32_e32 v67, v67, v67
	v_mul_f32_e32 v69, v69, v69
	v_max_f32_e32 v74, 0, v75
	v_max_f32_e32 v75, 0, v83
	v_cvt_pk_bf16_f32 v66, v66, v67
	v_mul_f32_e32 v72, v72, v72
	v_mul_f32_e32 v73, v73, v73
	v_mul_f32_e32 v74, v74, v74
	v_mul_f32_e32 v75, v75, v75
	v_cvt_pk_bf16_f32 v67, v72, v74
	v_cvt_pk_bf16_f32 v68, v68, v69
	v_cvt_pk_bf16_f32 v69, v73, v75
	global_store_dwordx4 v[70:71], v[66:69], off offset:256 nt
	v_max_f32_e32 v58, 0, v58
	v_max_f32_e32 v59, 0, v59
	v_mul_f32_e32 v66, v56, v56
	v_max_f32_e32 v56, 0, v61
	v_mul_f32_e32 v61, v56, v56
	v_mul_f32_e32 v67, v57, v57
	v_cvt_pk_bf16_f32 v56, v62, v63
	v_cvt_pk_bf16_f32 v57, v60, v61
	v_lshl_add_u64 v[60:61], v[64:65], 0, s[0:1]
	s_mov_b32 s0, 0x200000
	v_add_co_u32_e32 v62, vcc, s0, v64
	v_mul_f32_e32 v58, v58, v58
	v_mul_f32_e32 v59, v59, v59
	v_addc_co_u32_e32 v63, vcc, 0, v65, vcc
	v_max_f32_e32 v48, 0, v48
	v_cvt_pk_bf16_f32 v58, v58, v59
	v_cvt_pk_bf16_f32 v59, v66, v67
	global_store_dwordx4 v[62:63], v[56:59], off nt
	v_max_f32_e32 v54, 0, v54
	v_max_f32_e32 v50, 0, v50
	v_max_f32_e32 v55, 0, v55
	v_max_f32_e32 v51, 0, v51
	v_mul_f32_e32 v56, v48, v48
	v_max_f32_e32 v48, 0, v53
	v_mul_f32_e32 v54, v54, v54
	v_mul_f32_e32 v50, v50, v50
	v_mul_f32_e32 v55, v55, v55
	v_mul_f32_e32 v51, v51, v51
	v_max_f32_e32 v52, 0, v52
	v_max_f32_e32 v49, 0, v49
	v_mul_f32_e32 v53, v48, v48
	v_cvt_pk_bf16_f32 v48, v54, v55
	v_max_f32_e32 v40, 0, v40
	v_mul_f32_e32 v52, v52, v52
	v_mul_f32_e32 v57, v49, v49
	v_cvt_pk_bf16_f32 v49, v52, v53
	v_cvt_pk_bf16_f32 v50, v50, v51
	v_cvt_pk_bf16_f32 v51, v56, v57
	global_store_dwordx4 v[60:61], v[48:51], off offset:256 nt
	v_max_f32_e32 v44, 0, v44
	v_max_f32_e32 v46, 0, v46
	v_mul_f32_e32 v48, v40, v40
	v_max_f32_e32 v40, 0, v45
	v_max_f32_e32 v47, 0, v47
	v_mul_f32_e32 v44, v44, v44
	v_max_f32_e32 v41, 0, v41
	v_mul_f32_e32 v45, v40, v40
	s_mov_b64 s[0:1], 0x240000
	v_mul_f32_e32 v46, v46, v46
	v_mul_f32_e32 v47, v47, v47
	v_mul_f32_e32 v49, v41, v41
	v_cvt_pk_bf16_f32 v40, v46, v47
	v_cvt_pk_bf16_f32 v41, v44, v45
	v_lshl_add_u64 v[44:45], v[64:65], 0, s[0:1]
	s_mov_b32 s0, 0x240000
	v_max_f32_e32 v42, 0, v42
	v_max_f32_e32 v43, 0, v43
	v_add_co_u32_e32 v46, vcc, s0, v64
	v_mul_f32_e32 v42, v42, v42
	v_mul_f32_e32 v43, v43, v43
	v_addc_co_u32_e32 v47, vcc, 0, v65, vcc
	v_max_f32_e32 v32, 0, v32
	v_cvt_pk_bf16_f32 v42, v42, v43
	v_cvt_pk_bf16_f32 v43, v48, v49
	global_store_dwordx4 v[46:47], v[40:43], off nt
	v_max_f32_e32 v38, 0, v38
	v_max_f32_e32 v34, 0, v34
	v_max_f32_e32 v39, 0, v39
	v_max_f32_e32 v35, 0, v35
	v_mul_f32_e32 v40, v32, v32
	v_max_f32_e32 v32, 0, v37
	v_mul_f32_e32 v38, v38, v38
	v_mul_f32_e32 v34, v34, v34
	v_mul_f32_e32 v39, v39, v39
	v_mul_f32_e32 v35, v35, v35
	v_max_f32_e32 v36, 0, v36
	v_max_f32_e32 v33, 0, v33
	v_mul_f32_e32 v37, v32, v32
	v_cvt_pk_bf16_f32 v32, v38, v39
	v_max_f32_e32 v24, 0, v24
	v_mul_f32_e32 v36, v36, v36
	v_mul_f32_e32 v41, v33, v33
	v_cvt_pk_bf16_f32 v33, v36, v37
	v_cvt_pk_bf16_f32 v34, v34, v35
	v_cvt_pk_bf16_f32 v35, v40, v41
	global_store_dwordx4 v[44:45], v[32:35], off offset:256 nt
	v_max_f32_e32 v28, 0, v28
	v_max_f32_e32 v30, 0, v30
	v_mul_f32_e32 v32, v24, v24
	v_max_f32_e32 v24, 0, v29
	v_max_f32_e32 v31, 0, v31
	v_mul_f32_e32 v28, v28, v28
	v_max_f32_e32 v25, 0, v25
	v_mul_f32_e32 v29, v24, v24
	s_mov_b64 s[0:1], 0x280000
	v_mul_f32_e32 v30, v30, v30
	v_mul_f32_e32 v31, v31, v31
	v_mul_f32_e32 v33, v25, v25
	v_cvt_pk_bf16_f32 v24, v30, v31
	v_cvt_pk_bf16_f32 v25, v28, v29
	v_lshl_add_u64 v[28:29], v[64:65], 0, s[0:1]
	s_mov_b32 s0, 0x280000
	v_max_f32_e32 v26, 0, v26
	v_max_f32_e32 v27, 0, v27
	v_add_co_u32_e32 v30, vcc, s0, v64
	v_mul_f32_e32 v26, v26, v26
	v_mul_f32_e32 v27, v27, v27
	v_addc_co_u32_e32 v31, vcc, 0, v65, vcc
	v_max_f32_e32 v16, 0, v16
	v_pk_fma_f32 v[92:93], v[92:93], v[96:97], v[12:13] op_sel:[0,1,0] neg_lo:[1,0,0] neg_hi:[1,0,0]
	v_pk_fma_f32 v[12:13], v[198:199], v[96:97], v[14:15] op_sel:[0,1,0]
	v_cvt_pk_bf16_f32 v26, v26, v27
	v_cvt_pk_bf16_f32 v27, v32, v33
	global_store_dwordx4 v[30:31], v[24:27], off nt
	v_max_f32_e32 v22, 0, v22
	v_max_f32_e32 v18, 0, v18
	v_max_f32_e32 v23, 0, v23
	v_max_f32_e32 v19, 0, v19
	v_mul_f32_e32 v24, v16, v16
	v_max_f32_e32 v16, 0, v21
	v_pk_fma_f32 v[12:13], v[12:13], v[98:99], v[90:91] op_sel_hi:[1,0,1]
	v_mul_f32_e32 v22, v22, v22
	v_mul_f32_e32 v18, v18, v18
	v_mul_f32_e32 v23, v23, v23
	v_mul_f32_e32 v19, v19, v19
	v_max_f32_e32 v20, 0, v20
	v_max_f32_e32 v17, 0, v17
	v_mul_f32_e32 v21, v16, v16
	v_cvt_pk_bf16_f32 v16, v22, v23
	v_max_f32_e32 v8, 0, v8
	v_pk_fma_f32 v[14:15], v[92:93], v[98:99], v[88:89] op_sel_hi:[1,0,1]
	v_mul_f32_e32 v20, v20, v20
	v_mul_f32_e32 v25, v17, v17
	v_cvt_pk_bf16_f32 v17, v20, v21
	v_cvt_pk_bf16_f32 v18, v18, v19
	v_cvt_pk_bf16_f32 v19, v24, v25
	global_store_dwordx4 v[28:29], v[16:19], off offset:256 nt
	v_max_f32_e32 v12, 0, v12
	v_max_f32_e32 v14, 0, v14
	v_mul_f32_e32 v16, v8, v8
	v_max_f32_e32 v8, 0, v13
	v_max_f32_e32 v15, 0, v15
	v_mul_f32_e32 v12, v12, v12
	v_max_f32_e32 v9, 0, v9
	v_mul_f32_e32 v13, v8, v8
	s_mov_b64 s[0:1], 0x2c0000
	v_mul_f32_e32 v14, v14, v14
	v_mul_f32_e32 v15, v15, v15
	v_mul_f32_e32 v17, v9, v9
	v_cvt_pk_bf16_f32 v8, v14, v15
	v_cvt_pk_bf16_f32 v9, v12, v13
	v_lshl_add_u64 v[12:13], v[64:65], 0, s[0:1]
	s_mov_b32 s0, 0x2c0000
	v_max_f32_e32 v10, 0, v10
	v_max_f32_e32 v11, 0, v11
	v_add_co_u32_e32 v14, vcc, s0, v64
	v_mul_f32_e32 v10, v10, v10
	v_mul_f32_e32 v11, v11, v11
	v_addc_co_u32_e32 v15, vcc, 0, v65, vcc
	v_max_f32_e32 v2, 0, v2
	v_max_f32_e32 v3, 0, v3
	v_max_f32_e32 v0, 0, v0
	v_cvt_pk_bf16_f32 v10, v10, v11
	v_cvt_pk_bf16_f32 v11, v16, v17
	global_store_dwordx4 v[14:15], v[8:11], off nt
	v_max_f32_e32 v6, 0, v6
	v_mul_f32_e32 v2, v2, v2
	v_max_f32_e32 v7, 0, v7
	v_mul_f32_e32 v3, v3, v3
	v_max_f32_e32 v4, 0, v4
	v_mul_f32_e32 v8, v0, v0
	v_max_f32_e32 v0, 0, v5
	v_max_f32_e32 v1, 0, v1
	s_and_b64 vcc, exec, s[6:7]
	s_mov_b64 s[0:1], s[76:77]
	v_mul_f32_e32 v6, v6, v6
	v_mul_f32_e32 v7, v7, v7
	v_mul_f32_e32 v4, v4, v4
	v_mul_f32_e32 v5, v0, v0
	v_mul_f32_e32 v9, v1, v1
	v_cvt_pk_bf16_f32 v0, v6, v7
	v_cvt_pk_bf16_f32 v1, v4, v5
	v_cvt_pk_bf16_f32 v2, v2, v3
	v_cvt_pk_bf16_f32 v3, v8, v9
	global_store_dwordx4 v[12:13], v[0:3], off offset:256 nt
	s_cbranch_vccz .LBB0_1049
	s_waitcnt vmcnt(0)
	v_readlane_b32 s38, v255, 9
	s_cmpk_gt_u32 s18, 0xff
	v_readlane_b32 s39, v255, 10
	s_cbranch_scc1 .LBB0_1060
	s_barrier

.LBB0_1227:
	s_add_u32 s67, s4, 0xffe00080
	s_addc_u32 s68, s5, -1
	s_add_i32 s71, 0, 0x10000
	v_add_u32_e32 v60, s71, v249
	ds_read_b128 v[48:51], v60
	ds_read_b128 v[52:55], v60 offset:1024
	ds_read_b128 v[56:59], v60 offset:2048
	ds_read_b128 v[60:63], v60 offset:3072
	s_cmpk_eq_i32 s66, 0x7c
	s_cselect_b32 s75, s12, s68
	s_cselect_b32 s74, s13, s67
	s_cselect_b32 s73, s14, s47
	s_cselect_b32 s72, s15, s45
	ds_read_b128 v[64:67], v251
	ds_read_b128 v[68:71], v251 offset:1024
	ds_read_b128 v[72:75], v251 offset:2048
	ds_read_b128 v[76:79], v251 offset:3072
	ds_read_b128 v[176:179], v251 offset:4096
	ds_read_b128 v[180:183], v251 offset:5120
	ds_read_b128 v[184:187], v251 offset:6144
	ds_read_b128 v[188:191], v251 offset:7168
	s_waitcnt lgkmcnt(8)
	s_barrier
	s_waitcnt lgkmcnt(0)
	s_waitcnt lgkmcnt(0)
	v_mfma_f32_16x16x32_bf16 v[156:159], v[48:51], v[64:67], v[156:159]
	v_mfma_f32_16x16x32_bf16 v[152:155], v[56:59], v[64:67], v[152:155]
	v_mfma_f32_16x16x32_bf16 v[140:143], v[48:51], v[72:75], v[140:143]
	v_mfma_f32_16x16x32_bf16 v[136:139], v[56:59], v[72:75], v[136:139]
	v_mfma_f32_16x16x32_bf16 v[124:127], v[48:51], v[176:179], v[124:127]
	v_mfma_f32_16x16x32_bf16 v[120:123], v[56:59], v[176:179], v[120:123]
	v_mfma_f32_16x16x32_bf16 v[108:111], v[48:51], v[184:187], v[108:111]
	v_mfma_f32_16x16x32_bf16 v[104:107], v[56:59], v[184:187], v[104:107]
	v_mfma_f32_16x16x32_bf16 v[156:159], v[52:55], v[68:71], v[156:159]
	v_mfma_f32_16x16x32_bf16 v[152:155], v[60:63], v[68:71], v[152:155]
	v_mfma_f32_16x16x32_bf16 v[140:143], v[52:55], v[76:79], v[140:143]
	v_mfma_f32_16x16x32_bf16 v[136:139], v[60:63], v[76:79], v[136:139]
	v_mfma_f32_16x16x32_bf16 v[124:127], v[52:55], v[180:183], v[124:127]
	v_mfma_f32_16x16x32_bf16 v[120:123], v[60:63], v[180:183], v[120:123]
	v_mfma_f32_16x16x32_bf16 v[108:111], v[52:55], v[188:191], v[108:111]
	v_mfma_f32_16x16x32_bf16 v[104:107], v[60:63], v[188:191], v[104:107]
	s_barrier
	v_lshl_add_u64 v[192:193], s[4:5], 0, v[172:173]
	s_add_i32 m0, s22, 0xc000
	s_nop 0
	global_load_lds_dwordx4 v[192:193], off
	v_lshl_add_u64 v[192:193], s[4:5], 0, v[174:175]
	s_add_i32 m0, s22, 0xe000
	s_nop 0
	global_load_lds_dwordx4 v[192:193], off
	s_add_i32 s67, 0, 0x14000
	s_add_i32 s68, s71, s21
	v_add_u32_e32 v204, s67, v249
	v_lshl_add_u64 v[216:217], s[72:73], 0, v[160:161]
	s_mov_b32 m0, s68
	ds_read_b128 v[192:195], v204
	ds_read_b128 v[196:199], v204 offset:1024
	ds_read_b128 v[200:203], v204 offset:2048
	ds_read_b128 v[204:207], v204 offset:3072
	global_load_lds_dwordx4 v[216:217], off
	v_lshl_add_u64 v[218:219], s[72:73], 0, v[170:171]
	s_add_i32 m0, s68, 0x2000
	s_nop 0
	global_load_lds_dwordx4 v[218:219], off
	s_barrier
	s_waitcnt lgkmcnt(0)
	s_waitcnt lgkmcnt(0)
	v_mfma_f32_16x16x32_bf16 v[148:151], v[192:195], v[64:67], v[148:151]
	v_mfma_f32_16x16x32_bf16 v[64:67], v[200:203], v[64:67], v[144:147]
	v_mfma_f32_16x16x32_bf16 v[148:151], v[196:199], v[68:71], v[148:151]
	v_mfma_f32_16x16x32_bf16 v[64:67], v[204:207], v[68:71], v[64:67]
	v_mfma_f32_16x16x32_bf16 v[68:71], v[192:195], v[72:75], v[132:135]
	v_mfma_f32_16x16x32_bf16 v[72:75], v[200:203], v[72:75], v[128:131]
	v_mfma_f32_16x16x32_bf16 v[112:115], v[200:203], v[176:179], v[112:115]
	v_mfma_f32_16x16x32_bf16 v[100:103], v[192:195], v[184:187], v[100:103]
	v_mfma_f32_16x16x32_bf16 v[96:99], v[200:203], v[184:187], v[96:99]
	v_mfma_f32_16x16x32_bf16 v[68:71], v[196:199], v[76:79], v[68:71]
	v_mfma_f32_16x16x32_bf16 v[72:75], v[204:207], v[76:79], v[72:75]
	v_mfma_f32_16x16x32_bf16 v[76:79], v[192:195], v[176:179], v[116:119]
	v_mfma_f32_16x16x32_bf16 v[112:115], v[204:207], v[180:183], v[112:115]
	v_mfma_f32_16x16x32_bf16 v[100:103], v[196:199], v[188:191], v[100:103]
	v_mfma_f32_16x16x32_bf16 v[96:99], v[204:207], v[188:191], v[96:99]
	v_mfma_f32_16x16x32_bf16 v[76:79], v[196:199], v[180:183], v[76:79]
	s_mov_b32 m0, s22
	v_lshl_add_u64 v[220:221], s[74:75], 0, v[160:161]
	s_barrier
	ds_read_b128 v[116:119], v251 offset:16384
	ds_read_b128 v[128:131], v251 offset:17408
	ds_read_b128 v[132:135], v251 offset:18432
	ds_read_b128 v[144:147], v251 offset:19456
	ds_read_b128 v[176:179], v251 offset:20480
	ds_read_b128 v[180:183], v251 offset:21504
	ds_read_b128 v[184:187], v251 offset:22528
	ds_read_b128 v[188:191], v251 offset:23552
	global_load_lds_dwordx4 v[220:221], off
	v_lshl_add_u64 v[222:223], s[74:75], 0, v[170:171]
	s_mov_b32 m0, s23
	s_nop 0
	global_load_lds_dwordx4 v[222:223], off
	s_barrier
	s_waitcnt lgkmcnt(0)
	s_waitcnt lgkmcnt(0)
	v_mfma_f32_16x16x32_bf16 v[92:95], v[48:51], v[116:119], v[92:95]
	v_mfma_f32_16x16x32_bf16 v[88:91], v[56:59], v[116:119], v[88:91]
	v_mfma_f32_16x16x32_bf16 v[44:47], v[48:51], v[132:135], v[44:47]
	v_mfma_f32_16x16x32_bf16 v[40:43], v[56:59], v[132:135], v[40:43]
	v_mfma_f32_16x16x32_bf16 v[28:31], v[48:51], v[176:179], v[28:31]
	v_mfma_f32_16x16x32_bf16 v[24:27], v[56:59], v[176:179], v[24:27]
	v_mfma_f32_16x16x32_bf16 v[12:15], v[48:51], v[184:187], v[12:15]
	v_mfma_f32_16x16x32_bf16 v[8:11], v[56:59], v[184:187], v[8:11]
	v_mfma_f32_16x16x32_bf16 v[92:95], v[52:55], v[128:131], v[92:95]
	v_mfma_f32_16x16x32_bf16 v[88:91], v[60:63], v[128:131], v[88:91]
	v_mfma_f32_16x16x32_bf16 v[44:47], v[52:55], v[144:147], v[44:47]
	v_mfma_f32_16x16x32_bf16 v[40:43], v[60:63], v[144:147], v[40:43]
	v_mfma_f32_16x16x32_bf16 v[28:31], v[52:55], v[180:183], v[28:31]
	v_mfma_f32_16x16x32_bf16 v[24:27], v[60:63], v[180:183], v[24:27]
	v_mfma_f32_16x16x32_bf16 v[12:15], v[52:55], v[188:191], v[12:15]
	v_mfma_f32_16x16x32_bf16 v[8:11], v[60:63], v[188:191], v[8:11]
	s_barrier
	s_add_u32 s76, s72, 0x200000
	s_addc_u32 s77, s73, 0
	s_add_i32 s67, s67, s21
	v_lshl_add_u64 v[48:49], s[76:77], 0, v[160:161]
	s_mov_b32 m0, s67
	s_nop 0
	global_load_lds_dwordx4 v[48:49], off
	v_lshl_add_u64 v[48:49], s[76:77], 0, v[170:171]
	s_add_i32 m0, s67, 0x2000
	s_nop 0
	global_load_lds_dwordx4 v[48:49], off
	s_waitcnt vmcnt(6)
	s_barrier
	v_mfma_f32_16x16x32_bf16 v[36:39], v[192:195], v[132:135], v[36:39]
	v_mfma_f32_16x16x32_bf16 v[32:35], v[200:203], v[132:135], v[32:35]
	v_mfma_f32_16x16x32_bf16 v[20:23], v[192:195], v[176:179], v[20:23]
	v_mfma_f32_16x16x32_bf16 v[16:19], v[200:203], v[176:179], v[16:19]
	v_mfma_f32_16x16x32_bf16 v[4:7], v[192:195], v[184:187], v[4:7]
	v_mfma_f32_16x16x32_bf16 v[0:3], v[200:203], v[184:187], v[0:3]
	v_mfma_f32_16x16x32_bf16 v[48:51], v[192:195], v[116:119], v[84:87]
	v_mfma_f32_16x16x32_bf16 v[52:55], v[200:203], v[116:119], v[80:83]
	v_mfma_f32_16x16x32_bf16 v[36:39], v[196:199], v[144:147], v[36:39]
	v_mfma_f32_16x16x32_bf16 v[32:35], v[204:207], v[144:147], v[32:35]
	v_mfma_f32_16x16x32_bf16 v[20:23], v[196:199], v[180:183], v[20:23]
	v_mfma_f32_16x16x32_bf16 v[16:19], v[204:207], v[180:183], v[16:19]
	v_mfma_f32_16x16x32_bf16 v[4:7], v[196:199], v[188:191], v[4:7]
	v_mfma_f32_16x16x32_bf16 v[0:3], v[204:207], v[188:191], v[0:3]
	v_mfma_f32_16x16x32_bf16 v[48:51], v[196:199], v[128:131], v[48:51]
	v_mfma_f32_16x16x32_bf16 v[52:55], v[204:207], v[128:131], v[52:55]
	s_add_i32 s67, 0, 0x18000
	v_add_u32_e32 v84, s67, v249
	s_barrier
	ds_read_b128 v[56:59], v84
	ds_read_b128 v[60:63], v84 offset:1024
	ds_read_b128 v[80:83], v84 offset:2048
	ds_read_b128 v[84:87], v84 offset:3072
	ds_read_b128 v[116:119], v251 offset:32768
	ds_read_b128 v[128:131], v251 offset:33792
	ds_read_b128 v[176:179], v251 offset:34816
	ds_read_b128 v[180:183], v251 offset:35840
	ds_read_b128 v[184:187], v251 offset:36864
	ds_read_b128 v[188:191], v251 offset:37888
	ds_read_b128 v[192:195], v251 offset:38912
	ds_read_b128 v[196:199], v251 offset:39936
	s_waitcnt lgkmcnt(8)
	s_barrier
	s_waitcnt lgkmcnt(0)
	s_waitcnt lgkmcnt(0)
	v_mfma_f32_16x16x32_bf16 v[132:135], v[56:59], v[116:119], v[156:159]
	v_mfma_f32_16x16x32_bf16 v[156:159], v[60:63], v[128:131], v[132:135]
	v_mfma_f32_16x16x32_bf16 v[132:135], v[80:83], v[116:119], v[152:155]
	v_mfma_f32_16x16x32_bf16 v[152:155], v[84:87], v[128:131], v[132:135]
	v_mfma_f32_16x16x32_bf16 v[132:135], v[56:59], v[176:179], v[140:143]
	v_mfma_f32_16x16x32_bf16 v[140:143], v[60:63], v[180:183], v[132:135]
	v_mfma_f32_16x16x32_bf16 v[132:135], v[80:83], v[176:179], v[136:139]
	v_mfma_f32_16x16x32_bf16 v[124:127], v[56:59], v[184:187], v[124:127]
	v_mfma_f32_16x16x32_bf16 v[120:123], v[80:83], v[184:187], v[120:123]
	v_mfma_f32_16x16x32_bf16 v[108:111], v[56:59], v[192:195], v[108:111]
	v_mfma_f32_16x16x32_bf16 v[104:107], v[80:83], v[192:195], v[104:107]
	v_mfma_f32_16x16x32_bf16 v[136:139], v[84:87], v[180:183], v[132:135]
	v_mfma_f32_16x16x32_bf16 v[124:127], v[60:63], v[188:191], v[124:127]
	v_mfma_f32_16x16x32_bf16 v[120:123], v[84:87], v[188:191], v[120:123]
	v_mfma_f32_16x16x32_bf16 v[108:111], v[60:63], v[196:199], v[108:111]
	v_mfma_f32_16x16x32_bf16 v[104:107], v[84:87], v[196:199], v[104:107]
	s_barrier
	s_add_u32 s74, s74, 0x200000
	s_addc_u32 s75, s75, 0
	v_lshl_add_u64 v[132:133], s[74:75], 0, v[160:161]
	s_mov_b32 m0, s24
	s_nop 0
	global_load_lds_dwordx4 v[132:133], off
	v_lshl_add_u64 v[132:133], s[74:75], 0, v[170:171]
	s_mov_b32 m0, s25
	s_nop 0
	global_load_lds_dwordx4 v[132:133], off
	s_add_i32 s68, 0, 0x1c000
	v_add_u32_e32 v132, s68, v249
	s_add_i32 s67, s67, s21
	ds_read_b128 v[200:203], v132
	ds_read_b128 v[204:207], v132 offset:1024
	ds_read_b128 v[208:211], v132 offset:2048
	ds_read_b128 v[212:215], v132 offset:3072
	v_lshl_add_u64 v[132:133], v[216:217], 0, s[92:93]
	s_mov_b32 m0, s67
	s_nop 0
	global_load_lds_dwordx4 v[132:133], off
	v_lshl_add_u64 v[132:133], v[218:219], 0, s[92:93]
	s_add_i32 m0, s67, 0x2000
	s_nop 0
	global_load_lds_dwordx4 v[132:133], off
	s_barrier
	s_waitcnt lgkmcnt(0)
	s_waitcnt lgkmcnt(0)
	v_mfma_f32_16x16x32_bf16 v[64:67], v[208:211], v[116:119], v[64:67]
	v_mfma_f32_16x16x32_bf16 v[132:135], v[200:203], v[116:119], v[148:151]
	v_mfma_f32_16x16x32_bf16 v[144:147], v[212:215], v[128:131], v[64:67]
	v_mfma_f32_16x16x32_bf16 v[64:67], v[200:203], v[176:179], v[68:71]
	v_mfma_f32_16x16x32_bf16 v[148:151], v[204:207], v[128:131], v[132:135]
	v_mfma_f32_16x16x32_bf16 v[132:135], v[204:207], v[180:183], v[64:67]
	v_mfma_f32_16x16x32_bf16 v[64:67], v[208:211], v[176:179], v[72:75]
	v_mfma_f32_16x16x32_bf16 v[128:131], v[212:215], v[180:183], v[64:67]
	v_mfma_f32_16x16x32_bf16 v[64:67], v[200:203], v[184:187], v[76:79]
	v_mfma_f32_16x16x32_bf16 v[116:119], v[204:207], v[188:191], v[64:67]
	v_mfma_f32_16x16x32_bf16 v[64:67], v[208:211], v[184:187], v[112:115]
	v_mfma_f32_16x16x32_bf16 v[112:115], v[212:215], v[188:191], v[64:67]
	v_mfma_f32_16x16x32_bf16 v[64:67], v[200:203], v[192:195], v[100:103]
	v_mfma_f32_16x16x32_bf16 v[100:103], v[204:207], v[196:199], v[64:67]
	v_mfma_f32_16x16x32_bf16 v[64:67], v[208:211], v[192:195], v[96:99]
	v_mfma_f32_16x16x32_bf16 v[96:99], v[212:215], v[196:199], v[64:67]
	s_mov_b32 m0, s26
	v_lshl_add_u64 v[192:193], v[220:221], 0, s[92:93]
	s_barrier
	s_nop 2
	ds_read_b128 v[64:67], v251 offset:49152
	ds_read_b128 v[68:71], v251 offset:50176
	ds_read_b128 v[72:75], v251 offset:51200
	ds_read_b128 v[76:79], v251 offset:52224
	ds_read_b128 v[176:179], v251 offset:53248
	ds_read_b128 v[180:183], v251 offset:54272
	ds_read_b128 v[184:187], v251 offset:55296
	ds_read_b128 v[188:191], v251 offset:56320
	global_load_lds_dwordx4 v[192:193], off
	v_lshl_add_u64 v[192:193], v[222:223], 0, s[92:93]
	s_mov_b32 m0, s27
	s_nop 0
	global_load_lds_dwordx4 v[192:193], off
	s_barrier
	s_waitcnt lgkmcnt(0)
	s_waitcnt lgkmcnt(0)
	v_mfma_f32_16x16x32_bf16 v[92:95], v[56:59], v[64:67], v[92:95]
	v_mfma_f32_16x16x32_bf16 v[88:91], v[80:83], v[64:67], v[88:91]
	v_mfma_f32_16x16x32_bf16 v[44:47], v[56:59], v[72:75], v[44:47]
	v_mfma_f32_16x16x32_bf16 v[40:43], v[80:83], v[72:75], v[40:43]
	v_mfma_f32_16x16x32_bf16 v[28:31], v[56:59], v[176:179], v[28:31]
	v_mfma_f32_16x16x32_bf16 v[24:27], v[80:83], v[176:179], v[24:27]
	v_mfma_f32_16x16x32_bf16 v[12:15], v[56:59], v[184:187], v[12:15]
	v_mfma_f32_16x16x32_bf16 v[8:11], v[80:83], v[184:187], v[8:11]
	v_mfma_f32_16x16x32_bf16 v[92:95], v[60:63], v[68:71], v[92:95]
	v_mfma_f32_16x16x32_bf16 v[88:91], v[84:87], v[68:71], v[88:91]
	v_mfma_f32_16x16x32_bf16 v[44:47], v[60:63], v[76:79], v[44:47]
	v_mfma_f32_16x16x32_bf16 v[40:43], v[84:87], v[76:79], v[40:43]
	v_mfma_f32_16x16x32_bf16 v[28:31], v[60:63], v[180:183], v[28:31]
	v_mfma_f32_16x16x32_bf16 v[24:27], v[84:87], v[180:183], v[24:27]
	v_mfma_f32_16x16x32_bf16 v[12:15], v[60:63], v[188:191], v[12:15]
	v_mfma_f32_16x16x32_bf16 v[8:11], v[84:87], v[188:191], v[8:11]
	s_barrier
	s_add_u32 s72, s72, 0x200080
	s_addc_u32 s73, s73, 0
	s_add_i32 s67, s68, s21
	v_lshl_add_u64 v[56:57], s[72:73], 0, v[160:161]
	s_mov_b32 m0, s67
	s_nop 0
	global_load_lds_dwordx4 v[56:57], off
	v_lshl_add_u64 v[56:57], s[72:73], 0, v[170:171]
	s_add_i32 m0, s67, 0x2000
	s_nop 0
	global_load_lds_dwordx4 v[56:57], off
	s_waitcnt vmcnt(6)
	s_barrier
	v_mfma_f32_16x16x32_bf16 v[48:51], v[200:203], v[64:67], v[48:51]
	v_mfma_f32_16x16x32_bf16 v[84:87], v[204:207], v[68:71], v[48:51]
	v_mfma_f32_16x16x32_bf16 v[48:51], v[208:211], v[64:67], v[52:55]
	v_mfma_f32_16x16x32_bf16 v[36:39], v[200:203], v[72:75], v[36:39]
	v_mfma_f32_16x16x32_bf16 v[32:35], v[208:211], v[72:75], v[32:35]
	v_mfma_f32_16x16x32_bf16 v[20:23], v[200:203], v[176:179], v[20:23]
	v_mfma_f32_16x16x32_bf16 v[16:19], v[208:211], v[176:179], v[16:19]
	v_mfma_f32_16x16x32_bf16 v[4:7], v[200:203], v[184:187], v[4:7]
	v_mfma_f32_16x16x32_bf16 v[0:3], v[208:211], v[184:187], v[0:3]
	v_mfma_f32_16x16x32_bf16 v[80:83], v[212:215], v[68:71], v[48:51]
	v_mfma_f32_16x16x32_bf16 v[36:39], v[204:207], v[76:79], v[36:39]
	v_mfma_f32_16x16x32_bf16 v[32:35], v[212:215], v[76:79], v[32:35]
	v_mfma_f32_16x16x32_bf16 v[20:23], v[204:207], v[180:183], v[20:23]
	v_mfma_f32_16x16x32_bf16 v[16:19], v[212:215], v[180:183], v[16:19]
	v_mfma_f32_16x16x32_bf16 v[4:7], v[204:207], v[188:191], v[4:7]
	v_mfma_f32_16x16x32_bf16 v[0:3], v[212:215], v[188:191], v[0:3]
	s_add_i32 s66, s66, 2
	s_add_u32 s4, s4, 0x100
	s_addc_u32 s5, s5, 0
	s_add_u32 s45, s45, 0x100
	s_addc_u32 s47, s47, 0
	s_cmpk_gt_u32 s66, 0x7d
	s_barrier
	s_cbranch_scc0 .LBB0_1227
	v_lshl_add_u32 v176, s17, 8, v248
	v_lshl_or_b32 v186, s16, 8, v250
	v_ashrrev_i32_e32 v187, 31, v186
	v_or_b32_e32 v178, 16, v176
	v_lshlrev_b64 v[216:217], 1, v[186:187]
	v_ashrrev_i32_e32 v177, 31, v176
	v_ashrrev_i32_e32 v179, 31, v178
	v_lshl_add_u64 v[48:49], s[28:29], 0, v[216:217]
	v_lshlrev_b64 v[238:239], 12, v[176:177]
	v_lshlrev_b64 v[220:221], 12, v[178:179]
	v_lshl_add_u64 v[50:51], v[48:49], 0, v[238:239]
	v_lshl_add_u64 v[48:49], v[48:49], 0, v[220:221]
	v_lshl_add_u64 v[180:181], v[176:177], 3, s[8:9]
	s_mov_b32 s4, 0x40000
	global_load_dwordx2 v[240:241], v[50:51], off
	global_load_dwordx2 v[234:235], v[50:51], off offset:32
	global_load_dwordx2 v[232:233], v[50:51], off offset:256
	global_load_dwordx2 v[230:231], v[50:51], off offset:288
	global_load_dwordx2 v[224:225], v[48:49], off
	global_load_dwordx2 v[214:215], v[48:49], off offset:32
	global_load_dwordx2 v[210:211], v[48:49], off offset:256
	global_load_dwordx2 v[206:207], v[48:49], off offset:288
	v_lshlrev_b64 v[48:49], 2, v[186:187]
	v_add_co_u32_e32 v204, vcc, s4, v180
	v_lshl_add_u64 v[50:51], s[6:7], 0, v[48:49]
	v_lshl_add_u64 v[52:53], s[42:43], 0, v[48:49]
	v_addc_co_u32_e32 v205, vcc, 0, v181, vcc
	global_load_dwordx4 v[72:75], v[50:51], off
	global_load_dwordx4 v[76:79], v[52:53], off
	global_load_dwordx4 v[64:67], v[50:51], off offset:64
	global_load_dwordx4 v[68:71], v[52:53], off offset:64
	global_load_dwordx4 v[56:59], v[50:51], off offset:512
	global_load_dwordx4 v[60:63], v[52:53], off offset:512
	s_nop 0
	global_load_dwordx4 v[48:51], v[50:51], off offset:576
	s_nop 0
	global_load_dwordx4 v[52:55], v[52:53], off offset:576
	v_lshl_add_u64 v[178:179], v[178:179], 3, s[8:9]
	global_load_dwordx2 v[182:183], v[180:181], off
	global_load_dwordx2 v[184:185], v[204:205], off
	global_load_dwordx2 v[228:229], v[178:179], off
	v_add_co_u32_e32 v178, vcc, s4, v178
	s_mov_b32 s89, 0x40000
	s_nop 0
	v_addc_co_u32_e32 v179, vcc, 0, v179, vcc
	global_load_dwordx2 v[226:227], v[178:179], off
	global_load_dwordx2 v[202:203], v[180:181], off offset:256
	global_load_dwordx2 v[200:201], v[204:205], off offset:256
	global_load_dwordx2 v[198:199], v[180:181], off offset:384
	global_load_dwordx2 v[196:197], v[204:205], off offset:384
	v_lshl_add_u64 v[238:239], s[28:29], 0, v[238:239]
	v_lshl_add_u64 v[238:239], v[238:239], 0, v[216:217]
	v_cmp_lt_i32_e64 s[4:5], 0, v247
	s_mov_b64 s[14:15], -1
	v_cmp_eq_u32_e32 vcc, 1, v247
	s_waitcnt vmcnt(0)
	v_lshlrev_b32_e32 v242, 16, v240
	v_and_b32_e32 v240, 0xffff0000, v240
	v_lshlrev_b32_e32 v244, 16, v241
	v_and_b32_e32 v243, 0xffff0000, v241
	v_cvt_f32_u32_e32 v179, v182
	v_cvt_f32_u32_e32 v178, v184
	v_cvt_f32_i32_e32 v182, v185
	v_cvt_f32_i32_e32 v183, v183
	v_pk_fma_f32 v[178:179], v[178:179], s[88:89], v[182:183] op_sel_hi:[1,0,1]
	s_nop 0
	v_pk_mul_f32 v[236:237], v[178:179], s[94:95] op_sel_hi:[1,0]
	s_nop 0
	v_fma_f32 v178, -v237, v237, v236
	v_add_f32_e32 v178, 0x3727c5ac, v178
	v_rsq_f32_e32 v236, v178
	global_load_dwordx2 v[194:195], v[180:181], off offset:1024
	global_load_dwordx2 v[192:193], v[204:205], off offset:1024
	global_load_dwordx2 v[190:191], v[180:181], off offset:1152
	global_load_dwordx2 v[188:189], v[204:205], off offset:1152
	global_load_dwordx2 v[184:185], v[180:181], off offset:1280
	global_load_dwordx2 v[182:183], v[204:205], off offset:1280
	s_nop 0
	global_load_dwordx2 v[180:181], v[180:181], off offset:1408
	s_nop 0
	global_load_dwordx2 v[178:179], v[204:205], off offset:1408
	v_or_b32_e32 v204, 32, v176
	v_ashrrev_i32_e32 v205, 31, v204
	v_lshlrev_b64 v[204:205], 12, v[204:205]
	v_lshl_add_u64 v[204:205], s[28:29], 0, v[204:205]
	v_lshl_add_u64 v[204:205], v[204:205], 0, v[216:217]
	global_load_dwordx2 v[222:223], v[204:205], off
	global_load_dwordx2 v[218:219], v[204:205], off offset:32
	global_load_dwordx2 v[212:213], v[204:205], off offset:256
	global_load_dwordx2 v[208:209], v[204:205], off offset:288
	v_sub_f32_e32 v241, v240, v237
	v_sub_f32_e32 v240, v242, v237
	v_sub_f32_e32 v243, v243, v237
	v_sub_f32_e32 v242, v244, v237
	v_pk_mul_f32 v[242:243], v[242:243], v[236:237] op_sel_hi:[1,0]
	v_pk_mul_f32 v[240:241], v[240:241], v[236:237] op_sel_hi:[1,0]
	v_pk_fma_f32 v[242:243], v[74:75], v[242:243], v[78:79]
	v_pk_fma_f32 v[240:241], v[72:73], v[240:241], v[76:77]
	v_pk_fma_f32 v[158:159], v[242:243], s[62:63], v[158:159] op_sel_hi:[1,0,1]
	v_pk_fma_f32 v[156:157], v[240:241], s[62:63], v[156:157] op_sel_hi:[1,0,1]
	v_mov_b32_e32 v243, v159
	v_cvt_pk_bf16_f32 v240, v156, v157
	v_cvt_pk_bf16_f32 v241, v158, v159
	global_store_dwordx2 v[238:239], v[240:241], off
	v_pk_mov_b32 v[240:241], v[156:157], v[158:159] op_sel:[1,0]
	v_mov_b32_e32 v242, v156
	v_mul_f32_e32 v157, v157, v157
	v_pk_add_f32 v[240:241], v[240:241], v[242:243]
	v_fmac_f32_e32 v157, v156, v156
	v_mul_f32_e32 v156, v159, v159
	v_add_f32_e32 v240, v240, v241
	v_fmac_f32_e32 v156, v158, v158
	v_add_f32_e32 v241, 0, v240
	v_add_f32_e32 v240, v157, v156
	v_lshlrev_b32_e32 v156, 16, v234
	v_and_b32_e32 v157, 0xffff0000, v234
	v_lshlrev_b32_e32 v158, 16, v235
	v_and_b32_e32 v159, 0xffff0000, v235
	v_sub_f32_e32 v157, v157, v237
	v_sub_f32_e32 v156, v156, v237
	v_sub_f32_e32 v159, v159, v237
	v_sub_f32_e32 v158, v158, v237
	v_pk_mul_f32 v[158:159], v[158:159], v[236:237] op_sel_hi:[1,0]
	v_pk_mul_f32 v[156:157], v[156:157], v[236:237] op_sel_hi:[1,0]
	v_pk_fma_f32 v[158:159], v[66:67], v[158:159], v[70:71]
	v_pk_fma_f32 v[156:157], v[64:65], v[156:157], v[68:69]
	v_pk_fma_f32 v[154:155], v[158:159], s[62:63], v[154:155] op_sel_hi:[1,0,1]
	v_pk_fma_f32 v[152:153], v[156:157], s[62:63], v[152:153] op_sel_hi:[1,0,1]
	v_mov_b32_e32 v159, v155
	v_cvt_pk_bf16_f32 v156, v152, v153
	v_cvt_pk_bf16_f32 v157, v154, v155
	global_store_dwordx2 v[238:239], v[156:157], off offset:32
	v_pk_mov_b32 v[156:157], v[152:153], v[154:155] op_sel:[1,0]
	v_mul_f32_e32 v153, v153, v153
	v_mov_b32_e32 v158, v152
	v_fmac_f32_e32 v153, v152, v152
	v_mul_f32_e32 v152, v155, v155
	v_pk_add_f32 v[156:157], v[156:157], v[158:159]
	v_fmac_f32_e32 v152, v154, v154
	v_pk_add_f32 v[156:157], v[156:157], v[156:157] op_sel_hi:[0,1]
	v_add_f32_e32 v152, v153, v152
	v_add_f32_e32 v156, v240, v152
	v_lshlrev_b32_e32 v152, 16, v232
	v_and_b32_e32 v153, 0xffff0000, v232
	v_lshlrev_b32_e32 v154, 16, v233
	v_and_b32_e32 v155, 0xffff0000, v233
	v_sub_f32_e32 v153, v153, v237
	v_sub_f32_e32 v152, v152, v237
	v_sub_f32_e32 v155, v155, v237
	v_sub_f32_e32 v154, v154, v237
	v_pk_mul_f32 v[154:155], v[154:155], v[236:237] op_sel_hi:[1,0]
	v_pk_mul_f32 v[152:153], v[152:153], v[236:237] op_sel_hi:[1,0]
	v_pk_fma_f32 v[154:155], v[58:59], v[154:155], v[62:63]
	v_pk_fma_f32 v[152:153], v[56:57], v[152:153], v[60:61]
	v_pk_fma_f32 v[150:151], v[154:155], s[62:63], v[150:151] op_sel_hi:[1,0,1]
	v_pk_fma_f32 v[148:149], v[152:153], s[62:63], v[148:149] op_sel_hi:[1,0,1]
	v_add_f32_e32 v155, v150, v151
	v_cvt_pk_bf16_f32 v152, v148, v149
	v_cvt_pk_bf16_f32 v153, v150, v151
	global_store_dwordx2 v[238:239], v[152:153], off offset:256
	v_add_f32_e32 v153, v148, v149
	v_mul_f32_e32 v149, v149, v149
	v_fmac_f32_e32 v149, v148, v148
	v_mul_f32_e32 v148, v151, v151
	v_fmac_f32_e32 v148, v150, v150
	v_add_f32_e32 v148, v149, v148
	v_add_f32_e32 v158, v148, v156
	v_lshlrev_b32_e32 v148, 16, v230
	v_and_b32_e32 v149, 0xffff0000, v230
	v_lshlrev_b32_e32 v150, 16, v231
	v_and_b32_e32 v151, 0xffff0000, v231
	v_sub_f32_e32 v149, v149, v237
	v_sub_f32_e32 v148, v148, v237
	v_sub_f32_e32 v151, v151, v237
	v_sub_f32_e32 v150, v150, v237
	v_pk_mul_f32 v[150:151], v[150:151], v[236:237] op_sel_hi:[1,0]
	v_pk_mul_f32 v[148:149], v[148:149], v[236:237] op_sel_hi:[1,0]
	v_pk_fma_f32 v[150:151], v[50:51], v[150:151], v[54:55]
	v_pk_fma_f32 v[148:149], v[48:49], v[148:149], v[52:53]
	v_pk_fma_f32 v[146:147], v[150:151], s[62:63], v[146:147] op_sel_hi:[1,0,1]
	v_pk_fma_f32 v[144:145], v[148:149], s[62:63], v[144:145] op_sel_hi:[1,0,1]
	v_mov_b32_e32 v156, v146
	v_cvt_pk_bf16_f32 v148, v144, v145
	v_cvt_pk_bf16_f32 v149, v146, v147
	v_mov_b32_e32 v152, v144
	v_mov_b32_e32 v154, v145
	v_mov_b32_e32 v240, v147
	global_store_dwordx2 v[238:239], v[148:149], off offset:288
	v_pk_add_f32 v[148:149], v[152:153], v[154:155]
	v_pk_add_f32 v[150:151], v[156:157], v[240:241]
	v_mul_f32_e32 v145, v145, v145
	v_pk_add_f32 v[148:149], v[148:149], v[150:151]
	v_fmac_f32_e32 v145, v144, v144
	v_mul_f32_e32 v144, v147, v147
	v_pk_add_f32 v[148:149], v[148:149], v[148:149] op_sel:[0,1] op_sel_hi:[1,0]
	v_fmac_f32_e32 v144, v146, v146
	v_add_f32_e32 v144, v145, v144
	v_mov_b32_e32 v145, v148
	v_add_f32_e32 v144, v144, v158
	s_nop 0
	v_permlane16_swap_b32_e32 v148, v145
	v_add_f32_e32 v148, v148, v145
	v_mov_b32_e32 v145, v144
	s_nop 1
	v_permlane16_swap_b32_e32 v144, v145
	v_add_f32_e32 v146, v144, v145
	v_mov_b32_e32 v149, v148
	v_mov_b32_e32 v147, v146
	s_nop 0
	v_permlane32_swap_b32_e32 v148, v149
	v_permlane32_swap_b32_e32 v146, v147
	v_mov_b64_e32 v[144:145], 0x100000
	s_and_saveexec_b64 s[12:13], s[4:5]
	v_readlane_b32 s66, v255, 7
	v_readlane_b32 s67, v255, 8
	s_cbranch_execz .LBB0_1232
	v_cmp_eq_u32_e64 s[4:5], 1, v247
	s_mov_b64 s[14:15], 0
	v_mov_b64_e32 v[144:145], 0x100000
	s_and_saveexec_b64 s[16:17], s[4:5]
	s_mov_b64 s[14:15], exec
	v_mov_b64_e32 v[144:145], 0x140000
	s_or_b64 exec, exec, s[16:17]
	s_orn2_b64 s[14:15], s[14:15], exec
	v_mov_b32_e32 v148, v146
	v_mov_b32_e32 v149, v147
